# GEMM K-loops: s_setprio 0 issued in the shadow before the last MFMA of each block instead of after the barrier
# baseline (speedup 1.0000x reference)
; #define PG8_STAGE(bufoff, gbase, voff) do { _Pragma("unroll") for (int _i = 0; _i < 2; ++_i) \
;         __builtin_amdgcn_global_load_lds((const unsigned*)((const char*)(gbase) + (voff)[_i]), (LAS unsigned*)(lds + (bufoff) + ldsw + _i * 8192), 16, 0, 0); } while (0)
; #define PG8_LDA(dst, b, h) do { _Pragma("unroll") for (int m = 0; m < 4; ++m) _Pragma("unroll") for (int k = 0; k < 2; ++k) dst[m][k] = *(const LAS bf16x8*)(lds + PG8_SA(b, h) + aoff + m * 2048 + k * 1024); } while (0)
; #define PG8_LDB(dst, b, h) do { _Pragma("unroll") for (int n = 0; n < 2; ++n) _Pragma("unroll") for (int k = 0; k < 2; ++k) dst[n][k] = *(const LAS bf16x8*)(lds + PG8_SB(b, h) + boff + n * 2048 + k * 1024); } while (0)
; #define PG8_MMA(ai, bj, At, Bt) do { __builtin_amdgcn_s_setprio(1); _Pragma("unroll") for (int m = 0; m < 4; ++m) _Pragma("unroll") for (int n = 0; n < 2; ++n) _Pragma("unroll") for (int k = 0; k < 2; ++k) \
;         acc[ai][bj][m][n] = __builtin_amdgcn_mfma_f32_16x16x32_bf16(Bt[n][k], At[m][k], acc[ai][bj][m][n], 0, 0, 0); __builtin_amdgcn_s_setprio(0); } while (0)
; #define PG8_WAIT_V(n) asm volatile("s_waitcnt vmcnt(" #n ")" ::: "memory")
; #define PG8_WAIT_L(n) asm volatile("s_waitcnt lgkmcnt(" #n ")" ::: "memory")
; #define PG8_BAR __builtin_amdgcn_s_barrier()
; template <class Map, class Epi>
; DI void gemm_phase(LAS unsigned char* lds, const Map& MP, const Epi& E, const int nM, const int nN, const int K, const int lda, const int ldb) {
;     ...
;             const char* a1 = cA + (size_t)(t + 1) * kstep;
;             const char* a2 = last ? nA : cA + (size_t)(t + 2) * kstep; const char* b2 = last ? nB : cB + (size_t)(t + 2) * kstep;
;             const char* a3 = a2 + kstep; const char* b3 = b2 + kstep;
;             PG8_LDB(B0, 0, 0); PG8_SCHED; PG8_LDA(At, 0, 0); PG8_STAGE(PG8_SA(1, 1), a1 + hstepA, voffA);
;             PG8_WAIT_L(8); PG8_BAR; PG8_WAIT_L(0); PG8_MMA(0, 0, At, B0); PG8_BAR; PG8_SCHED;
;             PG8_LDB(B1, 0, 1); PG8_STAGE(PG8_SB(0, 0), b2, voffB);
;             PG8_BAR; PG8_WAIT_L(0); PG8_MMA(0, 1, At, B1); PG8_BAR;
;             PG8_LDA(At, 0, 1); PG8_STAGE(PG8_SA(0, 0), a2, voffA);
;             PG8_BAR; PG8_WAIT_L(0); PG8_MMA(1, 0, At, B0); PG8_BAR; PG8_SCHED;
;             PG8_STAGE(PG8_SB(0, 1), b2 + hstepB, voffB);
;             PG8_WAIT_V(6); PG8_BAR; PG8_MMA(1, 1, At, B1); PG8_BAR;
.LBB1_229:
	s_add_u32 s26, s24, 0xfff80080
	s_addc_u32 s27, s25, -1
	s_cmp_eq_u32 s57, 4
	s_cselect_b32 s29, s17, s27
	s_cselect_b32 s28, s43, s26
	s_cselect_b32 s27, s53, s56
	s_cselect_b32 s26, s54, s55
	s_add_i32 m0, s2, 0xc000
	ds_read_b128 v[160:163], v168
	ds_read_b128 v[170:173], v168 offset:1024
	ds_read_b128 v[174:177], v168 offset:2048
	ds_read_b128 v[178:181], v168 offset:3072
	ds_read_b128 v[182:185], v168 offset:4096
	ds_read_b128 v[186:189], v168 offset:5120
	ds_read_b128 v[190:193], v168 offset:6144
	ds_read_b128 v[198:201], v168 offset:7168
	global_load_lds_dwordx4 v154, s[24:25]
	s_add_i32 m0, s2, 0xe000
	s_nop 0
	global_load_lds_dwordx4 v152, s[24:25]
	s_waitcnt lgkmcnt(8)
	s_setprio 1
	s_barrier
	s_waitcnt lgkmcnt(7)
	v_mfma_f32_16x16x32_bf16 v[140:143], v[72:75], v[160:163], v[140:143]
	v_mfma_f32_16x16x32_bf16 v[136:139], v[80:83], v[160:163], v[136:139]
	s_waitcnt lgkmcnt(5)
	v_mfma_f32_16x16x32_bf16 v[124:127], v[72:75], v[174:177], v[124:127]
	v_mfma_f32_16x16x32_bf16 v[120:123], v[80:83], v[174:177], v[120:123]
	s_waitcnt lgkmcnt(3)
	v_mfma_f32_16x16x32_bf16 v[108:111], v[72:75], v[182:185], v[108:111]
	v_mfma_f32_16x16x32_bf16 v[104:107], v[80:83], v[182:185], v[104:107]
	s_waitcnt lgkmcnt(1)
	v_mfma_f32_16x16x32_bf16 v[92:95], v[72:75], v[190:193], v[92:95]
	v_mfma_f32_16x16x32_bf16 v[88:91], v[80:83], v[190:193], v[88:91]
	v_mfma_f32_16x16x32_bf16 v[140:143], v[76:79], v[170:173], v[140:143]
	s_add_i32 s58, s48, s34
	v_mfma_f32_16x16x32_bf16 v[136:139], v[84:87], v[170:173], v[136:139]
	v_lshl_add_u64 v[194:195], s[26:27], 0, v[148:149]
	v_mfma_f32_16x16x32_bf16 v[124:127], v[76:79], v[178:181], v[124:127]
	v_lshl_add_u64 v[218:219], s[26:27], 0, v[144:145]
	v_mfma_f32_16x16x32_bf16 v[120:123], v[84:87], v[178:181], v[120:123]
	v_mfma_f32_16x16x32_bf16 v[108:111], v[76:79], v[186:189], v[108:111]
	v_mfma_f32_16x16x32_bf16 v[104:107], v[84:87], v[186:189], v[104:107]
	s_waitcnt lgkmcnt(0)
	v_mfma_f32_16x16x32_bf16 v[92:95], v[76:79], v[198:201], v[92:95]
	s_setprio 0
	v_mfma_f32_16x16x32_bf16 v[88:91], v[84:87], v[198:201], v[88:91]
	s_barrier
	s_mov_b32 m0, s58
	ds_read_b128 v[202:205], v169
	ds_read_b128 v[206:209], v169 offset:1024
	ds_read_b128 v[210:213], v169 offset:2048
	ds_read_b128 v[214:217], v169 offset:3072
	global_load_lds_dwordx4 v[194:195], off
	s_add_i32 m0, s58, 0x2000
	s_nop 0
	global_load_lds_dwordx4 v[218:219], off
	s_setprio 1
	s_barrier
	s_waitcnt lgkmcnt(3)
	v_mfma_f32_16x16x32_bf16 v[132:135], v[202:205], v[160:163], v[132:135]
	s_waitcnt lgkmcnt(1)
	v_mfma_f32_16x16x32_bf16 v[128:131], v[210:213], v[160:163], v[128:131]
	v_mfma_f32_16x16x32_bf16 v[116:119], v[202:205], v[174:177], v[116:119]
	v_mfma_f32_16x16x32_bf16 v[112:115], v[210:213], v[174:177], v[112:115]
	v_mfma_f32_16x16x32_bf16 v[100:103], v[202:205], v[182:185], v[100:103]
	v_mfma_f32_16x16x32_bf16 v[96:99], v[210:213], v[182:185], v[96:99]
	v_mfma_f32_16x16x32_bf16 v[68:71], v[202:205], v[190:193], v[68:71]
	v_mfma_f32_16x16x32_bf16 v[64:67], v[210:213], v[190:193], v[64:67]
	v_mfma_f32_16x16x32_bf16 v[132:135], v[206:209], v[170:173], v[132:135]
	v_lshl_add_u64 v[222:223], s[28:29], 0, v[146:147]
	s_mov_b32 m0, s2
	s_waitcnt lgkmcnt(0)
	v_mfma_f32_16x16x32_bf16 v[128:131], v[214:217], v[170:173], v[128:131]
	v_lshl_add_u64 v[220:221], s[28:29], 0, v[150:151]
	v_mfma_f32_16x16x32_bf16 v[116:119], v[206:209], v[178:181], v[116:119]
	v_mfma_f32_16x16x32_bf16 v[112:115], v[214:217], v[178:181], v[112:115]
	v_mfma_f32_16x16x32_bf16 v[100:103], v[206:209], v[186:189], v[100:103]
	v_mfma_f32_16x16x32_bf16 v[96:99], v[214:217], v[186:189], v[96:99]
	v_mfma_f32_16x16x32_bf16 v[68:71], v[206:209], v[198:201], v[68:71]
	s_setprio 0
	v_mfma_f32_16x16x32_bf16 v[64:67], v[214:217], v[198:201], v[64:67]
	s_barrier
	ds_read_b128 v[160:163], v168 offset:16384
	ds_read_b128 v[170:173], v168 offset:17408
	ds_read_b128 v[174:177], v168 offset:18432
	ds_read_b128 v[178:181], v168 offset:19456
	ds_read_b128 v[182:185], v168 offset:20480
	ds_read_b128 v[186:189], v168 offset:21504
	ds_read_b128 v[190:193], v168 offset:22528
	ds_read_b128 v[198:201], v168 offset:23552
	global_load_lds_dwordx4 v[220:221], off
	s_mov_b32 m0, s4
	s_nop 0
	global_load_lds_dwordx4 v[222:223], off
	s_waitcnt vmcnt(10)
	s_setprio 1
	s_barrier
	s_waitcnt lgkmcnt(7)
	v_mfma_f32_16x16x32_bf16 v[60:63], v[72:75], v[160:163], v[60:63]
	v_mfma_f32_16x16x32_bf16 v[56:59], v[80:83], v[160:163], v[56:59]
	s_waitcnt lgkmcnt(5)
	v_mfma_f32_16x16x32_bf16 v[44:47], v[72:75], v[174:177], v[44:47]
	v_mfma_f32_16x16x32_bf16 v[40:43], v[80:83], v[174:177], v[40:43]
	s_waitcnt lgkmcnt(3)
	v_mfma_f32_16x16x32_bf16 v[28:31], v[72:75], v[182:185], v[28:31]
	v_mfma_f32_16x16x32_bf16 v[24:27], v[80:83], v[182:185], v[24:27]
	s_waitcnt lgkmcnt(1)
	v_mfma_f32_16x16x32_bf16 v[12:15], v[72:75], v[190:193], v[12:15]
	v_mfma_f32_16x16x32_bf16 v[8:11], v[80:83], v[190:193], v[8:11]
	v_mfma_f32_16x16x32_bf16 v[60:63], v[76:79], v[170:173], v[60:63]
	s_add_u32 s58, s26, 0x20000
	s_addc_u32 s59, s27, 0
	v_mfma_f32_16x16x32_bf16 v[56:59], v[84:87], v[170:173], v[56:59]
	s_add_i32 s60, s49, s34
	v_mfma_f32_16x16x32_bf16 v[44:47], v[76:79], v[178:181], v[44:47]
	v_mfma_f32_16x16x32_bf16 v[40:43], v[84:87], v[178:181], v[40:43]
	v_mfma_f32_16x16x32_bf16 v[28:31], v[76:79], v[186:189], v[28:31]
	v_mfma_f32_16x16x32_bf16 v[24:27], v[84:87], v[186:189], v[24:27]
	s_waitcnt lgkmcnt(0)
	v_mfma_f32_16x16x32_bf16 v[12:15], v[76:79], v[198:201], v[12:15]
	s_setprio 0
	v_mfma_f32_16x16x32_bf16 v[8:11], v[84:87], v[198:201], v[8:11]
	s_barrier
; #define PG8_STAGE(bufoff, gbase, voff) do { _Pragma("unroll") for (int _i = 0; _i < 2; ++_i) \
;         __builtin_amdgcn_global_load_lds((const unsigned*)((const char*)(gbase) + (voff)[_i]), (LAS unsigned*)(lds + (bufoff) + ldsw + _i * 8192), 16, 0, 0); } while (0)
; #define PG8_LDA(dst, b, h) do { _Pragma("unroll") for (int m = 0; m < 4; ++m) _Pragma("unroll") for (int k = 0; k < 2; ++k) dst[m][k] = *(const LAS bf16x8*)(lds + PG8_SA(b, h) + aoff + m * 2048 + k * 1024); } while (0)
; #define PG8_LDB(dst, b, h) do { _Pragma("unroll") for (int n = 0; n < 2; ++n) _Pragma("unroll") for (int k = 0; k < 2; ++k) dst[n][k] = *(const LAS bf16x8*)(lds + PG8_SB(b, h) + boff + n * 2048 + k * 1024); } while (0)
; #define PG8_MMA(ai, bj, At, Bt) do { __builtin_amdgcn_s_setprio(1); _Pragma("unroll") for (int m = 0; m < 4; ++m) _Pragma("unroll") for (int n = 0; n < 2; ++n) _Pragma("unroll") for (int k = 0; k < 2; ++k) \
;         acc[ai][bj][m][n] = __builtin_amdgcn_mfma_f32_16x16x32_bf16(Bt[n][k], At[m][k], acc[ai][bj][m][n], 0, 0, 0); __builtin_amdgcn_s_setprio(0); } while (0)
; #define PG8_WAIT_V(n) asm volatile("s_waitcnt vmcnt(" #n ")" ::: "memory")
; #define PG8_WAIT_L(n) asm volatile("s_waitcnt lgkmcnt(" #n ")" ::: "memory")
; #define PG8_BAR __builtin_amdgcn_s_barrier()
; #define PG8_SCHED __builtin_amdgcn_sched_barrier(0)
; template <class Map, class Epi>
; DI void gemm_phase(LAS unsigned char* lds, const Map& MP, const Epi& E, const int nM, const int nN, const int K, const int lda, const int ldb) {
;     ...
;             PG8_WAIT_V(6); PG8_BAR; PG8_MMA(1, 1, At, B1); PG8_BAR;
;             PG8_LDB(B0, 1, 0); PG8_SCHED; PG8_LDA(At, 1, 0); PG8_STAGE(PG8_SA(0, 1), a2 + hstepA, voffA);
;             PG8_WAIT_L(8); PG8_BAR; PG8_WAIT_L(0); PG8_MMA(0, 0, At, B0); PG8_BAR; PG8_SCHED;
;             PG8_LDB(B1, 1, 1); PG8_STAGE(PG8_SB(1, 0), b3, voffB);
;             PG8_BAR; PG8_WAIT_L(0); PG8_MMA(0, 1, At, B1); PG8_BAR;
;             PG8_LDA(At, 1, 1); PG8_STAGE(PG8_SA(1, 0), a3, voffA);
	s_mov_b32 m0, s60
	s_nop 0
	global_load_lds_dwordx4 v148, s[58:59]
	s_add_i32 m0, s60, 0x2000
	s_nop 0
	global_load_lds_dwordx4 v144, s[58:59]
	s_waitcnt vmcnt(6)
	s_setprio 1
	s_barrier
	v_mfma_f32_16x16x32_bf16 v[52:55], v[202:205], v[160:163], v[52:55]
	v_mfma_f32_16x16x32_bf16 v[48:51], v[210:213], v[160:163], v[48:51]
	s_add_i32 s58, 0, 0x18000
	v_add_u32_e32 v84, s58, v166
	ds_read_b128 v[72:75], v84
	v_mfma_f32_16x16x32_bf16 v[36:39], v[202:205], v[174:177], v[36:39]
	v_mfma_f32_16x16x32_bf16 v[32:35], v[210:213], v[174:177], v[32:35]
	ds_read_b128 v[76:79], v84 offset:1024
	v_mfma_f32_16x16x32_bf16 v[20:23], v[202:205], v[182:185], v[20:23]
	v_mfma_f32_16x16x32_bf16 v[16:19], v[210:213], v[182:185], v[16:19]
	ds_read_b128 v[80:83], v84 offset:2048
	v_mfma_f32_16x16x32_bf16 v[4:7], v[202:205], v[190:193], v[4:7]
	v_mfma_f32_16x16x32_bf16 v[0:3], v[210:213], v[190:193], v[0:3]
	ds_read_b128 v[84:87], v84 offset:3072
	v_mfma_f32_16x16x32_bf16 v[52:55], v[206:209], v[170:173], v[52:55]
	s_add_u32 s28, s28, 0x80000
	s_addc_u32 s29, s29, 0
	v_mfma_f32_16x16x32_bf16 v[48:51], v[214:217], v[170:173], v[48:51]
	v_mfma_f32_16x16x32_bf16 v[36:39], v[206:209], v[178:181], v[36:39]
	v_mfma_f32_16x16x32_bf16 v[32:35], v[214:217], v[178:181], v[32:35]
	v_mfma_f32_16x16x32_bf16 v[20:23], v[206:209], v[186:189], v[20:23]
	v_mfma_f32_16x16x32_bf16 v[16:19], v[214:217], v[186:189], v[16:19]
	v_mfma_f32_16x16x32_bf16 v[4:7], v[206:209], v[198:201], v[4:7]
	s_setprio 0
	v_mfma_f32_16x16x32_bf16 v[0:3], v[214:217], v[198:201], v[0:3]
	s_barrier
	s_mov_b32 m0, s5
	ds_read_b128 v[160:163], v168 offset:32768
	ds_read_b128 v[170:173], v168 offset:33792
	ds_read_b128 v[174:177], v168 offset:34816
	ds_read_b128 v[178:181], v168 offset:35840
	ds_read_b128 v[182:185], v168 offset:36864
	ds_read_b128 v[186:189], v168 offset:37888
	ds_read_b128 v[190:193], v168 offset:38912
	ds_read_b128 v[198:201], v168 offset:39936
	global_load_lds_dwordx4 v150, s[28:29]
	s_mov_b32 m0, s23
	s_nop 0
	global_load_lds_dwordx4 v146, s[28:29]
	s_waitcnt lgkmcnt(8)
	s_setprio 1
	s_barrier
	s_waitcnt lgkmcnt(7)
	v_mfma_f32_16x16x32_bf16 v[140:143], v[72:75], v[160:163], v[140:143]
	v_mfma_f32_16x16x32_bf16 v[136:139], v[80:83], v[160:163], v[136:139]
	s_waitcnt lgkmcnt(5)
	v_mfma_f32_16x16x32_bf16 v[124:127], v[72:75], v[174:177], v[124:127]
	v_mfma_f32_16x16x32_bf16 v[120:123], v[80:83], v[174:177], v[120:123]
	s_waitcnt lgkmcnt(3)
	v_mfma_f32_16x16x32_bf16 v[108:111], v[72:75], v[182:185], v[108:111]
	v_mfma_f32_16x16x32_bf16 v[104:107], v[80:83], v[182:185], v[104:107]
	s_waitcnt lgkmcnt(1)
	v_mfma_f32_16x16x32_bf16 v[92:95], v[72:75], v[190:193], v[92:95]
	v_mfma_f32_16x16x32_bf16 v[88:91], v[80:83], v[190:193], v[88:91]
	v_mfma_f32_16x16x32_bf16 v[140:143], v[76:79], v[170:173], v[140:143]
	s_add_i32 s28, 0, 0x1c000
	v_mfma_f32_16x16x32_bf16 v[136:139], v[84:87], v[170:173], v[136:139]
	s_add_i32 s29, s58, s34
	v_mfma_f32_16x16x32_bf16 v[124:127], v[76:79], v[178:181], v[124:127]
	v_add_u32_e32 v196, s28, v166
	v_mfma_f32_16x16x32_bf16 v[120:123], v[84:87], v[178:181], v[120:123]
	v_lshl_add_u64 v[194:195], v[194:195], 0, s[12:13]
	v_mfma_f32_16x16x32_bf16 v[108:111], v[76:79], v[186:189], v[108:111]
	v_mfma_f32_16x16x32_bf16 v[104:107], v[84:87], v[186:189], v[104:107]
	s_waitcnt lgkmcnt(0)
	v_mfma_f32_16x16x32_bf16 v[92:95], v[76:79], v[198:201], v[92:95]
	s_setprio 0
	v_mfma_f32_16x16x32_bf16 v[88:91], v[84:87], v[198:201], v[88:91]
	s_barrier
	s_mov_b32 m0, s29
	ds_read_b128 v[202:205], v196
	ds_read_b128 v[206:209], v196 offset:1024
	ds_read_b128 v[210:213], v196 offset:2048
	ds_read_b128 v[214:217], v196 offset:3072
	global_load_lds_dwordx4 v[194:195], off
	v_lshl_add_u64 v[194:195], v[218:219], 0, s[12:13]
	s_add_i32 m0, s29, 0x2000
	s_nop 0
	global_load_lds_dwordx4 v[194:195], off
	s_setprio 1
	s_barrier
	s_waitcnt lgkmcnt(3)
	v_mfma_f32_16x16x32_bf16 v[132:135], v[202:205], v[160:163], v[132:135]
	s_waitcnt lgkmcnt(1)
	v_mfma_f32_16x16x32_bf16 v[128:131], v[210:213], v[160:163], v[128:131]
	v_mfma_f32_16x16x32_bf16 v[116:119], v[202:205], v[174:177], v[116:119]
	v_mfma_f32_16x16x32_bf16 v[112:115], v[210:213], v[174:177], v[112:115]
	v_mfma_f32_16x16x32_bf16 v[100:103], v[202:205], v[182:185], v[100:103]
	v_mfma_f32_16x16x32_bf16 v[96:99], v[210:213], v[182:185], v[96:99]
	v_mfma_f32_16x16x32_bf16 v[68:71], v[202:205], v[190:193], v[68:71]
	v_mfma_f32_16x16x32_bf16 v[64:67], v[210:213], v[190:193], v[64:67]
	v_mfma_f32_16x16x32_bf16 v[132:135], v[206:209], v[170:173], v[132:135]
	s_mov_b32 m0, s39
	s_waitcnt lgkmcnt(0)
	v_mfma_f32_16x16x32_bf16 v[128:131], v[214:217], v[170:173], v[128:131]
	v_lshl_add_u64 v[194:195], v[220:221], 0, s[12:13]
	v_mfma_f32_16x16x32_bf16 v[116:119], v[206:209], v[178:181], v[116:119]
	v_mfma_f32_16x16x32_bf16 v[112:115], v[214:217], v[178:181], v[112:115]
	v_mfma_f32_16x16x32_bf16 v[100:103], v[206:209], v[186:189], v[100:103]
	v_mfma_f32_16x16x32_bf16 v[96:99], v[214:217], v[186:189], v[96:99]
	v_mfma_f32_16x16x32_bf16 v[68:71], v[206:209], v[198:201], v[68:71]
	s_setprio 0
	v_mfma_f32_16x16x32_bf16 v[64:67], v[214:217], v[198:201], v[64:67]
	s_barrier
; #define PG8_STAGE(bufoff, gbase, voff) do { _Pragma("unroll") for (int _i = 0; _i < 2; ++_i) \
;         __builtin_amdgcn_global_load_lds((const unsigned*)((const char*)(gbase) + (voff)[_i]), (LAS unsigned*)(lds + (bufoff) + ldsw + _i * 8192), 16, 0, 0); } while (0)
; #define PG8_LDA(dst, b, h) do { _Pragma("unroll") for (int m = 0; m < 4; ++m) _Pragma("unroll") for (int k = 0; k < 2; ++k) dst[m][k] = *(const LAS bf16x8*)(lds + PG8_SA(b, h) + aoff + m * 2048 + k * 1024); } while (0)
; #define PG8_MMA(ai, bj, At, Bt) do { __builtin_amdgcn_s_setprio(1); _Pragma("unroll") for (int m = 0; m < 4; ++m) _Pragma("unroll") for (int n = 0; n < 2; ++n) _Pragma("unroll") for (int k = 0; k < 2; ++k) \
;         acc[ai][bj][m][n] = __builtin_amdgcn_mfma_f32_16x16x32_bf16(Bt[n][k], At[m][k], acc[ai][bj][m][n], 0, 0, 0); __builtin_amdgcn_s_setprio(0); } while (0)
; #define PG8_WAIT_V(n) asm volatile("s_waitcnt vmcnt(" #n ")" ::: "memory")
; #define PG8_WAIT_L(n) asm volatile("s_waitcnt lgkmcnt(" #n ")" ::: "memory")
; #define PG8_BAR __builtin_amdgcn_s_barrier()
; #define PG8_SCHED __builtin_amdgcn_sched_barrier(0)
;     DI void operator()(const f32x4 (&acc)[2][2][4][2], const Unit& u, int wr, int wc, int fr, int fq) const {
;         const int row0 = u.pm * BM + wr * 64 + fr, col0 = u.pn * BM + wc * 32 + 8 * fq;
;         f32x4 sc[2][2];
; #pragma unroll
;         for (int bj = 0; bj < 2; ++bj)
; #pragma unroll
;             for (int n = 0; n < 2; ++n) sc[bj][n] = scale ? *(const f32x4*)(scale + col0 + bj * HALF + 4 * n) : (f32x4){1.f, 1.f, 1.f, 1.f};
; #pragma unroll
; template <class Map, class Epi>
; DI void gemm_phase(LAS unsigned char* lds, const Map& MP, const Epi& E, const int nM, const int nN, const int K, const int lda, const int ldb) {
;     ...
;             PG8_LDA(At, 1, 1); PG8_STAGE(PG8_SA(1, 0), a3, voffA);
;             PG8_BAR; PG8_WAIT_L(0); PG8_MMA(1, 0, At, B0); PG8_BAR; PG8_SCHED;
;             PG8_STAGE(PG8_SB(1, 1), b3 + hstepB, voffB);
;             PG8_WAIT_V(6); PG8_BAR; PG8_MMA(1, 1, At, B1); PG8_BAR;
	ds_read_b128 v[160:163], v168 offset:49152
	ds_read_b128 v[170:173], v168 offset:50176
	ds_read_b128 v[174:177], v168 offset:51200
	ds_read_b128 v[178:181], v168 offset:52224
	ds_read_b128 v[182:185], v168 offset:53248
	ds_read_b128 v[186:189], v168 offset:54272
	ds_read_b128 v[190:193], v168 offset:55296
	ds_read_b128 v[198:201], v168 offset:56320
	global_load_lds_dwordx4 v[194:195], off
	v_lshl_add_u64 v[194:195], v[222:223], 0, s[12:13]
	s_mov_b32 m0, s46
	s_nop 0
	global_load_lds_dwordx4 v[194:195], off
	s_waitcnt vmcnt(10)
	s_setprio 1
	s_barrier
	s_waitcnt lgkmcnt(7)
	v_mfma_f32_16x16x32_bf16 v[60:63], v[72:75], v[160:163], v[60:63]
	v_mfma_f32_16x16x32_bf16 v[56:59], v[80:83], v[160:163], v[56:59]
	s_waitcnt lgkmcnt(5)
	v_mfma_f32_16x16x32_bf16 v[44:47], v[72:75], v[174:177], v[44:47]
	v_mfma_f32_16x16x32_bf16 v[40:43], v[80:83], v[174:177], v[40:43]
	s_waitcnt lgkmcnt(3)
	v_mfma_f32_16x16x32_bf16 v[28:31], v[72:75], v[182:185], v[28:31]
	v_mfma_f32_16x16x32_bf16 v[24:27], v[80:83], v[182:185], v[24:27]
	s_waitcnt lgkmcnt(1)
	v_mfma_f32_16x16x32_bf16 v[12:15], v[72:75], v[190:193], v[12:15]
	v_mfma_f32_16x16x32_bf16 v[8:11], v[80:83], v[190:193], v[8:11]
	v_mfma_f32_16x16x32_bf16 v[60:63], v[76:79], v[170:173], v[60:63]
	s_add_u32 s26, s26, 0x20080
	s_addc_u32 s27, s27, 0
	v_mfma_f32_16x16x32_bf16 v[56:59], v[84:87], v[170:173], v[56:59]
	s_add_i32 s28, s28, s34
	v_mfma_f32_16x16x32_bf16 v[44:47], v[76:79], v[178:181], v[44:47]
	v_mfma_f32_16x16x32_bf16 v[40:43], v[84:87], v[178:181], v[40:43]
	v_mfma_f32_16x16x32_bf16 v[28:31], v[76:79], v[186:189], v[28:31]
	v_mfma_f32_16x16x32_bf16 v[24:27], v[84:87], v[186:189], v[24:27]
	s_waitcnt lgkmcnt(0)
	v_mfma_f32_16x16x32_bf16 v[12:15], v[76:79], v[198:201], v[12:15]
	s_setprio 0
	v_mfma_f32_16x16x32_bf16 v[8:11], v[84:87], v[198:201], v[8:11]
	s_barrier
	s_mov_b32 m0, s28
	s_nop 0
	global_load_lds_dwordx4 v148, s[26:27]
	s_add_i32 m0, s28, 0x2000
	s_nop 0
	global_load_lds_dwordx4 v144, s[26:27]
	s_waitcnt vmcnt(6)
	s_setprio 1
	s_barrier
	v_mfma_f32_16x16x32_bf16 v[52:55], v[202:205], v[160:163], v[52:55]
	v_mfma_f32_16x16x32_bf16 v[48:51], v[210:213], v[160:163], v[48:51]
	ds_read_b128 v[72:75], v167
	v_mfma_f32_16x16x32_bf16 v[36:39], v[202:205], v[174:177], v[36:39]
	v_mfma_f32_16x16x32_bf16 v[32:35], v[210:213], v[174:177], v[32:35]
	ds_read_b128 v[76:79], v167 offset:1024
	v_mfma_f32_16x16x32_bf16 v[20:23], v[202:205], v[182:185], v[20:23]
	v_mfma_f32_16x16x32_bf16 v[16:19], v[210:213], v[182:185], v[16:19]
	ds_read_b128 v[80:83], v167 offset:2048
	v_mfma_f32_16x16x32_bf16 v[4:7], v[202:205], v[190:193], v[4:7]
	v_mfma_f32_16x16x32_bf16 v[0:3], v[210:213], v[190:193], v[0:3]
	ds_read_b128 v[84:87], v167 offset:3072
	v_mfma_f32_16x16x32_bf16 v[52:55], v[206:209], v[170:173], v[52:55]
	s_add_i32 s57, s57, 2
	v_mfma_f32_16x16x32_bf16 v[48:51], v[214:217], v[170:173], v[48:51]
	s_add_u32 s55, s55, 0x100
	s_addc_u32 s56, s56, 0
	v_mfma_f32_16x16x32_bf16 v[36:39], v[206:209], v[178:181], v[36:39]
	s_add_u32 s24, s24, 0x100
	s_addc_u32 s25, s25, 0
	v_mfma_f32_16x16x32_bf16 v[32:35], v[214:217], v[178:181], v[32:35]
	s_cmp_gt_u32 s57, 5
	v_mfma_f32_16x16x32_bf16 v[20:23], v[206:209], v[186:189], v[20:23]
	v_mfma_f32_16x16x32_bf16 v[16:19], v[214:217], v[186:189], v[16:19]
	v_mfma_f32_16x16x32_bf16 v[4:7], v[206:209], v[198:201], v[4:7]
	s_setprio 0
	v_mfma_f32_16x16x32_bf16 v[0:3], v[214:217], v[198:201], v[0:3]
	s_barrier
	s_cbranch_scc0 .LBB1_229
	s_waitcnt lgkmcnt(0)
	s_lshl_b32 s17, s42, 8
	v_mov_b32_e32 v170, v164
	v_mov_b32_e32 v72, v165
	s_or_b32 s17, s17, s38
	v_mov_b32_e32 v80, 1.0
	v_lshl_add_u32 v160, v72, 3, s17
	v_ashrrev_i32_e32 v161, 31, v160
	v_cndmask_b32_e64 v72, 0, 1, s[14:15]
	v_lshl_add_u64 v[162:163], v[160:161], 2, s[8:9]
	v_cmp_ne_u32_e64 s[42:43], 1, v72
	s_andn2_b64 vcc, exec, s[14:15]
	v_mov_b32_e32 v84, 1.0
	v_mov_b32_e32 v85, 1.0
	v_mov_b32_e32 v86, 1.0
	v_mov_b32_e32 v87, 1.0
	s_cbranch_vccnz .LBB1_232
	global_load_dwordx4 v[84:87], v[162:163], off

; #define PG8_STAGE(bufoff, gbase, voff) do { _Pragma("unroll") for (int _i = 0; _i < 2; ++_i) \
;         __builtin_amdgcn_global_load_lds((const unsigned*)((const char*)(gbase) + (voff)[_i]), (LAS unsigned*)(lds + (bufoff) + ldsw + _i * 8192), 16, 0, 0); } while (0)
; #define PG8_LDA(dst, b, h) do { _Pragma("unroll") for (int m = 0; m < 4; ++m) _Pragma("unroll") for (int k = 0; k < 2; ++k) dst[m][k] = *(const LAS bf16x8*)(lds + PG8_SA(b, h) + aoff + m * 2048 + k * 1024); } while (0)
; #define PG8_LDB(dst, b, h) do { _Pragma("unroll") for (int n = 0; n < 2; ++n) _Pragma("unroll") for (int k = 0; k < 2; ++k) dst[n][k] = *(const LAS bf16x8*)(lds + PG8_SB(b, h) + boff + n * 2048 + k * 1024); } while (0)
; #define PG8_MMA(ai, bj, At, Bt) do { __builtin_amdgcn_s_setprio(1); _Pragma("unroll") for (int m = 0; m < 4; ++m) _Pragma("unroll") for (int n = 0; n < 2; ++n) _Pragma("unroll") for (int k = 0; k < 2; ++k) \
;         acc[ai][bj][m][n] = __builtin_amdgcn_mfma_f32_16x16x32_bf16(Bt[n][k], At[m][k], acc[ai][bj][m][n], 0, 0, 0); __builtin_amdgcn_s_setprio(0); } while (0)
; #define PG8_WAIT_V(n) asm volatile("s_waitcnt vmcnt(" #n ")" ::: "memory")
; #define PG8_WAIT_L(n) asm volatile("s_waitcnt lgkmcnt(" #n ")" ::: "memory")
; #define PG8_BAR __builtin_amdgcn_s_barrier()
; template <class Map, class Epi>
; DI void gemm_phase(LAS unsigned char* lds, const Map& MP, const Epi& E, const int nM, const int nN, const int K, const int lda, const int ldb) {
;     ...
;             const char* a1 = cA + (size_t)(t + 1) * kstep;
;             const char* a2 = last ? nA : cA + (size_t)(t + 2) * kstep; const char* b2 = last ? nB : cB + (size_t)(t + 2) * kstep;
;             const char* a3 = a2 + kstep; const char* b3 = b2 + kstep;
;             PG8_LDB(B0, 0, 0); PG8_SCHED; PG8_LDA(At, 0, 0); PG8_STAGE(PG8_SA(1, 1), a1 + hstepA, voffA);
;             PG8_WAIT_L(8); PG8_BAR; PG8_WAIT_L(0); PG8_MMA(0, 0, At, B0); PG8_BAR; PG8_SCHED;
;             PG8_LDB(B1, 0, 1); PG8_STAGE(PG8_SB(0, 0), b2, voffB);
;             PG8_BAR; PG8_WAIT_L(0); PG8_MMA(0, 1, At, B1); PG8_BAR;
;             PG8_LDA(At, 0, 1); PG8_STAGE(PG8_SA(0, 0), a2, voffA);
;             PG8_BAR; PG8_WAIT_L(0); PG8_MMA(1, 0, At, B0); PG8_BAR; PG8_SCHED;
;             PG8_STAGE(PG8_SB(0, 1), b2 + hstepB, voffB);
;             PG8_WAIT_V(6); PG8_BAR; PG8_MMA(1, 1, At, B1); PG8_BAR;
.LBB1_380:
	s_add_u32 s28, s44, 0xfff80080
	s_addc_u32 s29, s45, -1
	s_cmp_eq_u32 vcc_hi, 28
	s_cselect_b32 s47, s23, s29
	s_cselect_b32 s46, s61, s28
	s_cselect_b32 s29, s21, vcc_lo
	s_cselect_b32 s28, s58, s59
	s_add_i32 m0, s38, 0xc000
	ds_read_b128 v[96:99], v190
	ds_read_b128 v[100:103], v190 offset:1024
	ds_read_b128 v[108:111], v190 offset:2048
	ds_read_b128 v[112:115], v190 offset:3072
	ds_read_b128 v[160:163], v190 offset:4096
	ds_read_b128 v[164:167], v190 offset:5120
	ds_read_b128 v[198:201], v190 offset:6144
	ds_read_b128 v[202:205], v190 offset:7168
	global_load_lds_dwordx4 v178, s[44:45]
	s_add_i32 m0, s38, 0xe000
	s_nop 0
	global_load_lds_dwordx4 v176, s[44:45]
	s_waitcnt lgkmcnt(8)
	s_setprio 1
	s_barrier
	s_waitcnt lgkmcnt(7)
	v_mfma_f32_16x16x32_bf16 v[148:151], v[80:83], v[96:99], v[148:151]
	v_mfma_f32_16x16x32_bf16 v[144:147], v[88:91], v[96:99], v[144:147]
	s_waitcnt lgkmcnt(5)
	v_mfma_f32_16x16x32_bf16 v[136:139], v[80:83], v[108:111], v[136:139]
	v_mfma_f32_16x16x32_bf16 v[128:131], v[88:91], v[108:111], v[128:131]
	s_waitcnt lgkmcnt(3)
	v_mfma_f32_16x16x32_bf16 v[120:123], v[80:83], v[160:163], v[120:123]
	v_mfma_f32_16x16x32_bf16 v[104:107], v[88:91], v[160:163], v[104:107]
	s_waitcnt lgkmcnt(1)
	v_mfma_f32_16x16x32_bf16 v[76:79], v[80:83], v[198:201], v[76:79]
	v_mfma_f32_16x16x32_bf16 v[72:75], v[88:91], v[198:201], v[72:75]
	v_mfma_f32_16x16x32_bf16 v[148:151], v[84:87], v[100:103], v[148:151]
	s_add_i32 s68, s5, s37
	v_mfma_f32_16x16x32_bf16 v[144:147], v[92:95], v[100:103], v[144:147]
	v_lshl_add_u64 v[184:185], s[28:29], 0, v[172:173]
	v_mfma_f32_16x16x32_bf16 v[136:139], v[84:87], v[112:115], v[136:139]
	v_lshl_add_u64 v[194:195], s[28:29], 0, v[168:169]
	v_mfma_f32_16x16x32_bf16 v[128:131], v[92:95], v[112:115], v[128:131]
	v_mfma_f32_16x16x32_bf16 v[120:123], v[84:87], v[164:167], v[120:123]
	v_mfma_f32_16x16x32_bf16 v[104:107], v[92:95], v[164:167], v[104:107]
	s_waitcnt lgkmcnt(0)
	v_mfma_f32_16x16x32_bf16 v[76:79], v[84:87], v[202:205], v[76:79]
	s_setprio 0
	v_mfma_f32_16x16x32_bf16 v[72:75], v[92:95], v[202:205], v[72:75]
	s_barrier
	s_mov_b32 m0, s68
	ds_read_b128 v[206:209], v191
	ds_read_b128 v[210:213], v191 offset:1024
	ds_read_b128 v[214:217], v191 offset:2048
	ds_read_b128 v[218:221], v191 offset:3072
	global_load_lds_dwordx4 v[184:185], off
	s_add_i32 m0, s68, 0x2000
	s_nop 0
	global_load_lds_dwordx4 v[194:195], off
	s_setprio 1
	s_barrier
	s_waitcnt lgkmcnt(3)
	v_mfma_f32_16x16x32_bf16 v[156:159], v[206:209], v[96:99], v[156:159]
	s_waitcnt lgkmcnt(1)
	v_mfma_f32_16x16x32_bf16 v[96:99], v[214:217], v[96:99], v[152:155]
	v_mfma_f32_16x16x32_bf16 v[156:159], v[210:213], v[100:103], v[156:159]
	s_waitcnt lgkmcnt(0)
	v_mfma_f32_16x16x32_bf16 v[96:99], v[218:221], v[100:103], v[96:99]
	v_mfma_f32_16x16x32_bf16 v[100:103], v[206:209], v[108:111], v[140:143]
	v_mfma_f32_16x16x32_bf16 v[108:111], v[214:217], v[108:111], v[132:135]
	v_mfma_f32_16x16x32_bf16 v[116:119], v[214:217], v[160:163], v[116:119]
	v_mfma_f32_16x16x32_bf16 v[68:71], v[206:209], v[198:201], v[68:71]
	v_mfma_f32_16x16x32_bf16 v[64:67], v[214:217], v[198:201], v[64:67]
	v_lshl_add_u64 v[234:235], s[46:47], 0, v[170:171]
	s_mov_b32 m0, s38
	v_mfma_f32_16x16x32_bf16 v[100:103], v[210:213], v[112:115], v[100:103]
	v_lshl_add_u64 v[226:227], s[46:47], 0, v[174:175]
	v_mfma_f32_16x16x32_bf16 v[108:111], v[218:221], v[112:115], v[108:111]
	v_mfma_f32_16x16x32_bf16 v[112:115], v[206:209], v[160:163], v[124:127]
	v_mfma_f32_16x16x32_bf16 v[116:119], v[218:221], v[164:167], v[116:119]
	v_mfma_f32_16x16x32_bf16 v[68:71], v[210:213], v[202:205], v[68:71]
	v_mfma_f32_16x16x32_bf16 v[64:67], v[218:221], v[202:205], v[64:67]
	s_setprio 0
	v_mfma_f32_16x16x32_bf16 v[112:115], v[210:213], v[164:167], v[112:115]
	s_barrier
	ds_read_b128 v[124:127], v190 offset:16384
	ds_read_b128 v[132:135], v190 offset:17408
	ds_read_b128 v[140:143], v190 offset:18432
	ds_read_b128 v[152:155], v190 offset:19456
	ds_read_b128 v[160:163], v190 offset:20480
	ds_read_b128 v[164:167], v190 offset:21504
	ds_read_b128 v[198:201], v190 offset:22528
	ds_read_b128 v[202:205], v190 offset:23552
	global_load_lds_dwordx4 v[226:227], off
	s_mov_b32 m0, s39
	s_nop 0
	global_load_lds_dwordx4 v[234:235], off
	s_waitcnt vmcnt(10)
	s_setprio 1
	s_barrier
	s_waitcnt lgkmcnt(7)
	v_mfma_f32_16x16x32_bf16 v[60:63], v[80:83], v[124:127], v[60:63]
	v_mfma_f32_16x16x32_bf16 v[48:51], v[88:91], v[124:127], v[48:51]
	s_waitcnt lgkmcnt(5)
	v_mfma_f32_16x16x32_bf16 v[40:43], v[80:83], v[140:143], v[40:43]
	v_mfma_f32_16x16x32_bf16 v[32:35], v[88:91], v[140:143], v[32:35]
	s_waitcnt lgkmcnt(3)
	v_mfma_f32_16x16x32_bf16 v[24:27], v[80:83], v[160:163], v[24:27]
	v_mfma_f32_16x16x32_bf16 v[16:19], v[88:91], v[160:163], v[16:19]
	s_waitcnt lgkmcnt(1)
	v_mfma_f32_16x16x32_bf16 v[12:15], v[80:83], v[198:201], v[12:15]
	v_mfma_f32_16x16x32_bf16 v[8:11], v[88:91], v[198:201], v[8:11]
	v_mfma_f32_16x16x32_bf16 v[60:63], v[84:87], v[132:135], v[60:63]
	s_add_u32 s68, s28, 0x80000
	s_addc_u32 s69, s29, 0
	v_mfma_f32_16x16x32_bf16 v[48:51], v[92:95], v[132:135], v[48:51]
	s_add_i32 s70, s2, s37
	v_mfma_f32_16x16x32_bf16 v[40:43], v[84:87], v[152:155], v[40:43]
	v_mfma_f32_16x16x32_bf16 v[32:35], v[92:95], v[152:155], v[32:35]
	v_mfma_f32_16x16x32_bf16 v[24:27], v[84:87], v[164:167], v[24:27]
	v_mfma_f32_16x16x32_bf16 v[16:19], v[92:95], v[164:167], v[16:19]
	s_waitcnt lgkmcnt(0)
	v_mfma_f32_16x16x32_bf16 v[12:15], v[84:87], v[202:205], v[12:15]
	s_setprio 0
	v_mfma_f32_16x16x32_bf16 v[8:11], v[92:95], v[202:205], v[8:11]
	s_barrier
; #define PG8_STAGE(bufoff, gbase, voff) do { _Pragma("unroll") for (int _i = 0; _i < 2; ++_i) \
;         __builtin_amdgcn_global_load_lds((const unsigned*)((const char*)(gbase) + (voff)[_i]), (LAS unsigned*)(lds + (bufoff) + ldsw + _i * 8192), 16, 0, 0); } while (0)
; #define PG8_LDA(dst, b, h) do { _Pragma("unroll") for (int m = 0; m < 4; ++m) _Pragma("unroll") for (int k = 0; k < 2; ++k) dst[m][k] = *(const LAS bf16x8*)(lds + PG8_SA(b, h) + aoff + m * 2048 + k * 1024); } while (0)
; #define PG8_LDB(dst, b, h) do { _Pragma("unroll") for (int n = 0; n < 2; ++n) _Pragma("unroll") for (int k = 0; k < 2; ++k) dst[n][k] = *(const LAS bf16x8*)(lds + PG8_SB(b, h) + boff + n * 2048 + k * 1024); } while (0)
; #define PG8_MMA(ai, bj, At, Bt) do { __builtin_amdgcn_s_setprio(1); _Pragma("unroll") for (int m = 0; m < 4; ++m) _Pragma("unroll") for (int n = 0; n < 2; ++n) _Pragma("unroll") for (int k = 0; k < 2; ++k) \
;         acc[ai][bj][m][n] = __builtin_amdgcn_mfma_f32_16x16x32_bf16(Bt[n][k], At[m][k], acc[ai][bj][m][n], 0, 0, 0); __builtin_amdgcn_s_setprio(0); } while (0)
; #define PG8_WAIT_V(n) asm volatile("s_waitcnt vmcnt(" #n ")" ::: "memory")
; #define PG8_WAIT_L(n) asm volatile("s_waitcnt lgkmcnt(" #n ")" ::: "memory")
; #define PG8_BAR __builtin_amdgcn_s_barrier()
; #define PG8_SCHED __builtin_amdgcn_sched_barrier(0)
; template <class Map, class Epi>
; DI void gemm_phase(LAS unsigned char* lds, const Map& MP, const Epi& E, const int nM, const int nN, const int K, const int lda, const int ldb) {
;     ...
;             PG8_WAIT_V(6); PG8_BAR; PG8_MMA(1, 1, At, B1); PG8_BAR;
;             PG8_LDB(B0, 1, 0); PG8_SCHED; PG8_LDA(At, 1, 0); PG8_STAGE(PG8_SA(0, 1), a2 + hstepA, voffA);
;             PG8_WAIT_L(8); PG8_BAR; PG8_WAIT_L(0); PG8_MMA(0, 0, At, B0); PG8_BAR; PG8_SCHED;
;             PG8_LDB(B1, 1, 1); PG8_STAGE(PG8_SB(1, 0), b3, voffB);
;             PG8_BAR; PG8_WAIT_L(0); PG8_MMA(0, 1, At, B1); PG8_BAR;
;             PG8_LDA(At, 1, 1); PG8_STAGE(PG8_SA(1, 0), a3, voffA);
;             PG8_BAR; PG8_WAIT_L(0); PG8_MMA(1, 0, At, B0); PG8_BAR; PG8_SCHED;
	s_mov_b32 m0, s70
	s_nop 0
	global_load_lds_dwordx4 v172, s[68:69]
	s_add_i32 m0, s70, 0x2000
	s_nop 0
	global_load_lds_dwordx4 v168, s[68:69]
	s_waitcnt vmcnt(6)
	s_setprio 1
	s_barrier
	v_mfma_f32_16x16x32_bf16 v[56:59], v[206:209], v[124:127], v[56:59]
	v_mfma_f32_16x16x32_bf16 v[52:55], v[214:217], v[124:127], v[52:55]
	s_add_i32 s68, 0, 0x18000
	v_add_u32_e32 v92, s68, v188
	ds_read_b128 v[80:83], v92
	v_mfma_f32_16x16x32_bf16 v[44:47], v[206:209], v[140:143], v[44:47]
	v_mfma_f32_16x16x32_bf16 v[36:39], v[214:217], v[140:143], v[36:39]
	ds_read_b128 v[84:87], v92 offset:1024
	v_mfma_f32_16x16x32_bf16 v[28:31], v[206:209], v[160:163], v[28:31]
	v_mfma_f32_16x16x32_bf16 v[20:23], v[214:217], v[160:163], v[20:23]
	ds_read_b128 v[88:91], v92 offset:2048
	v_mfma_f32_16x16x32_bf16 v[4:7], v[206:209], v[198:201], v[4:7]
	v_mfma_f32_16x16x32_bf16 v[0:3], v[214:217], v[198:201], v[0:3]
	ds_read_b128 v[92:95], v92 offset:3072
	v_mfma_f32_16x16x32_bf16 v[56:59], v[210:213], v[132:135], v[56:59]
	s_add_u32 s46, s46, 0x80000
	s_addc_u32 s47, s47, 0
	v_mfma_f32_16x16x32_bf16 v[52:55], v[218:221], v[132:135], v[52:55]
	v_mfma_f32_16x16x32_bf16 v[44:47], v[210:213], v[152:155], v[44:47]
	v_mfma_f32_16x16x32_bf16 v[36:39], v[218:221], v[152:155], v[36:39]
	v_mfma_f32_16x16x32_bf16 v[28:31], v[210:213], v[164:167], v[28:31]
	v_mfma_f32_16x16x32_bf16 v[20:23], v[218:221], v[164:167], v[20:23]
	v_mfma_f32_16x16x32_bf16 v[4:7], v[210:213], v[202:205], v[4:7]
	s_setprio 0
	v_mfma_f32_16x16x32_bf16 v[0:3], v[218:221], v[202:205], v[0:3]
	s_barrier
	s_mov_b32 m0, s56
	ds_read_b128 v[124:127], v190 offset:32768
	ds_read_b128 v[132:135], v190 offset:33792
	ds_read_b128 v[160:163], v190 offset:34816
	ds_read_b128 v[164:167], v190 offset:35840
	ds_read_b128 v[198:201], v190 offset:36864
	ds_read_b128 v[202:205], v190 offset:37888
	ds_read_b128 v[206:209], v190 offset:38912
	ds_read_b128 v[210:213], v190 offset:39936
	global_load_lds_dwordx4 v174, s[46:47]
	s_mov_b32 m0, s57
	s_nop 0
	global_load_lds_dwordx4 v170, s[46:47]
	s_waitcnt lgkmcnt(8)
	s_setprio 1
	s_barrier
	s_waitcnt lgkmcnt(7)
	v_mfma_f32_16x16x32_bf16 v[140:143], v[80:83], v[124:127], v[148:151]
	s_waitcnt lgkmcnt(6)
	v_mfma_f32_16x16x32_bf16 v[148:151], v[84:87], v[132:135], v[140:143]
	v_mfma_f32_16x16x32_bf16 v[140:143], v[88:91], v[124:127], v[144:147]
	s_waitcnt lgkmcnt(5)
	v_mfma_f32_16x16x32_bf16 v[136:139], v[80:83], v[160:163], v[136:139]
	v_mfma_f32_16x16x32_bf16 v[128:131], v[88:91], v[160:163], v[128:131]
	s_waitcnt lgkmcnt(3)
	v_mfma_f32_16x16x32_bf16 v[120:123], v[80:83], v[198:201], v[120:123]
	v_mfma_f32_16x16x32_bf16 v[104:107], v[88:91], v[198:201], v[104:107]
	s_waitcnt lgkmcnt(1)
	v_mfma_f32_16x16x32_bf16 v[76:79], v[80:83], v[206:209], v[76:79]
	v_mfma_f32_16x16x32_bf16 v[72:75], v[88:91], v[206:209], v[72:75]
	s_add_i32 s46, 0, 0x1c000
	v_mfma_f32_16x16x32_bf16 v[144:147], v[92:95], v[132:135], v[140:143]
	v_add_u32_e32 v140, s46, v188
	v_mfma_f32_16x16x32_bf16 v[136:139], v[84:87], v[164:167], v[136:139]
	s_add_i32 s47, s68, s37
	v_mfma_f32_16x16x32_bf16 v[128:131], v[92:95], v[164:167], v[128:131]
	v_mfma_f32_16x16x32_bf16 v[120:123], v[84:87], v[202:205], v[120:123]
	v_mfma_f32_16x16x32_bf16 v[104:107], v[92:95], v[202:205], v[104:107]
	s_waitcnt lgkmcnt(0)
	v_mfma_f32_16x16x32_bf16 v[76:79], v[84:87], v[210:213], v[76:79]
	s_setprio 0
	v_mfma_f32_16x16x32_bf16 v[72:75], v[92:95], v[210:213], v[72:75]
	s_barrier
	ds_read_b128 v[214:217], v140
	ds_read_b128 v[218:221], v140 offset:1024
	ds_read_b128 v[222:225], v140 offset:2048
	ds_read_b128 v[230:233], v140 offset:3072
	v_lshl_add_u64 v[140:141], v[184:185], 0, s[14:15]
	s_mov_b32 m0, s47
	s_nop 0
	global_load_lds_dwordx4 v[140:141], off
	v_lshl_add_u64 v[140:141], v[194:195], 0, s[14:15]
	s_add_i32 m0, s47, 0x2000
	s_nop 0
	global_load_lds_dwordx4 v[140:141], off
	s_setprio 1
	s_barrier
	s_waitcnt lgkmcnt(1)
	v_mfma_f32_16x16x32_bf16 v[96:99], v[222:225], v[124:127], v[96:99]
	v_mfma_f32_16x16x32_bf16 v[140:143], v[214:217], v[124:127], v[156:159]
	s_waitcnt lgkmcnt(0)
	v_mfma_f32_16x16x32_bf16 v[152:155], v[230:233], v[132:135], v[96:99]
	v_mfma_f32_16x16x32_bf16 v[96:99], v[214:217], v[160:163], v[100:103]
	v_mfma_f32_16x16x32_bf16 v[156:159], v[218:221], v[132:135], v[140:143]
	v_mfma_f32_16x16x32_bf16 v[140:143], v[218:221], v[164:167], v[96:99]
	v_mfma_f32_16x16x32_bf16 v[96:99], v[222:225], v[160:163], v[108:111]
	v_mfma_f32_16x16x32_bf16 v[132:135], v[230:233], v[164:167], v[96:99]
	v_mfma_f32_16x16x32_bf16 v[96:99], v[214:217], v[198:201], v[112:115]
	s_mov_b32 m0, s62
	v_mfma_f32_16x16x32_bf16 v[124:127], v[218:221], v[202:205], v[96:99]
	v_lshl_add_u64 v[184:185], v[226:227], 0, s[14:15]
	v_mfma_f32_16x16x32_bf16 v[96:99], v[222:225], v[198:201], v[116:119]
	v_mfma_f32_16x16x32_bf16 v[68:71], v[214:217], v[206:209], v[68:71]
	v_mfma_f32_16x16x32_bf16 v[64:67], v[222:225], v[206:209], v[64:67]
	v_mfma_f32_16x16x32_bf16 v[116:119], v[230:233], v[202:205], v[96:99]
	v_mfma_f32_16x16x32_bf16 v[68:71], v[218:221], v[210:213], v[68:71]
	s_setprio 0
	v_mfma_f32_16x16x32_bf16 v[64:67], v[230:233], v[210:213], v[64:67]
	s_barrier
	ds_read_b128 v[96:99], v190 offset:49152
	ds_read_b128 v[100:103], v190 offset:50176
	ds_read_b128 v[108:111], v190 offset:51200
	ds_read_b128 v[112:115], v190 offset:52224
	ds_read_b128 v[160:163], v190 offset:53248
	ds_read_b128 v[164:167], v190 offset:54272
	ds_read_b128 v[198:201], v190 offset:55296
	ds_read_b128 v[202:205], v190 offset:56320
	global_load_lds_dwordx4 v[184:185], off
	v_lshl_add_u64 v[184:185], v[234:235], 0, s[14:15]
	s_mov_b32 m0, s63
	s_nop 0
	global_load_lds_dwordx4 v[184:185], off
	s_waitcnt vmcnt(10)
	s_setprio 1
	s_barrier
; #define PG8_STAGE(bufoff, gbase, voff) do { _Pragma("unroll") for (int _i = 0; _i < 2; ++_i) \
;         __builtin_amdgcn_global_load_lds((const unsigned*)((const char*)(gbase) + (voff)[_i]), (LAS unsigned*)(lds + (bufoff) + ldsw + _i * 8192), 16, 0, 0); } while (0)
; #define PG8_MMA(ai, bj, At, Bt) do { __builtin_amdgcn_s_setprio(1); _Pragma("unroll") for (int m = 0; m < 4; ++m) _Pragma("unroll") for (int n = 0; n < 2; ++n) _Pragma("unroll") for (int k = 0; k < 2; ++k) \
;         acc[ai][bj][m][n] = __builtin_amdgcn_mfma_f32_16x16x32_bf16(Bt[n][k], At[m][k], acc[ai][bj][m][n], 0, 0, 0); __builtin_amdgcn_s_setprio(0); } while (0)
; #define PG8_WAIT_V(n) asm volatile("s_waitcnt vmcnt(" #n ")" ::: "memory")
; #define PG8_WAIT_L(n) asm volatile("s_waitcnt lgkmcnt(" #n ")" ::: "memory")
; #define PG8_BAR __builtin_amdgcn_s_barrier()
; #define PG8_SCHED __builtin_amdgcn_sched_barrier(0)
; template <class Map, class Epi>
; DI void gemm_phase(LAS unsigned char* lds, const Map& MP, const Epi& E, const int nM, const int nN, const int K, const int lda, const int ldb) {
;     ...
;             PG8_BAR; PG8_WAIT_L(0); PG8_MMA(1, 0, At, B0); PG8_BAR; PG8_SCHED;
;             PG8_STAGE(PG8_SB(1, 1), b3 + hstepB, voffB);
;             PG8_WAIT_V(6); PG8_BAR; PG8_MMA(1, 1, At, B1); PG8_BAR;
	s_waitcnt lgkmcnt(7)
	v_mfma_f32_16x16x32_bf16 v[60:63], v[80:83], v[96:99], v[60:63]
	v_mfma_f32_16x16x32_bf16 v[48:51], v[88:91], v[96:99], v[48:51]
	s_waitcnt lgkmcnt(5)
	v_mfma_f32_16x16x32_bf16 v[40:43], v[80:83], v[108:111], v[40:43]
	v_mfma_f32_16x16x32_bf16 v[32:35], v[88:91], v[108:111], v[32:35]
	s_waitcnt lgkmcnt(3)
	v_mfma_f32_16x16x32_bf16 v[24:27], v[80:83], v[160:163], v[24:27]
	v_mfma_f32_16x16x32_bf16 v[16:19], v[88:91], v[160:163], v[16:19]
	s_waitcnt lgkmcnt(1)
	v_mfma_f32_16x16x32_bf16 v[12:15], v[80:83], v[198:201], v[12:15]
	v_mfma_f32_16x16x32_bf16 v[8:11], v[88:91], v[198:201], v[8:11]
	v_mfma_f32_16x16x32_bf16 v[60:63], v[84:87], v[100:103], v[60:63]
	s_add_u32 s28, s28, 0x80080
	s_addc_u32 s29, s29, 0
	v_mfma_f32_16x16x32_bf16 v[48:51], v[92:95], v[100:103], v[48:51]
	s_add_i32 s46, s46, s37
	v_mfma_f32_16x16x32_bf16 v[40:43], v[84:87], v[112:115], v[40:43]
	v_mfma_f32_16x16x32_bf16 v[32:35], v[92:95], v[112:115], v[32:35]
	v_mfma_f32_16x16x32_bf16 v[24:27], v[84:87], v[164:167], v[24:27]
	v_mfma_f32_16x16x32_bf16 v[16:19], v[92:95], v[164:167], v[16:19]
	s_waitcnt lgkmcnt(0)
	v_mfma_f32_16x16x32_bf16 v[12:15], v[84:87], v[202:205], v[12:15]
	s_setprio 0
	v_mfma_f32_16x16x32_bf16 v[8:11], v[92:95], v[202:205], v[8:11]
	s_barrier
	s_mov_b32 m0, s46
	s_nop 0
	global_load_lds_dwordx4 v172, s[28:29]
	s_add_i32 m0, s46, 0x2000
	s_nop 0
	global_load_lds_dwordx4 v168, s[28:29]
	s_waitcnt vmcnt(6)
	s_setprio 1
	s_barrier
	v_mfma_f32_16x16x32_bf16 v[56:59], v[214:217], v[96:99], v[56:59]
	v_mfma_f32_16x16x32_bf16 v[52:55], v[222:225], v[96:99], v[52:55]
	ds_read_b128 v[80:83], v189
	v_mfma_f32_16x16x32_bf16 v[44:47], v[214:217], v[108:111], v[44:47]
	v_mfma_f32_16x16x32_bf16 v[36:39], v[222:225], v[108:111], v[36:39]
	ds_read_b128 v[84:87], v189 offset:1024
	v_mfma_f32_16x16x32_bf16 v[28:31], v[214:217], v[160:163], v[28:31]
	v_mfma_f32_16x16x32_bf16 v[20:23], v[222:225], v[160:163], v[20:23]
	ds_read_b128 v[88:91], v189 offset:2048
	v_mfma_f32_16x16x32_bf16 v[4:7], v[214:217], v[198:201], v[4:7]
	v_mfma_f32_16x16x32_bf16 v[0:3], v[222:225], v[198:201], v[0:3]
	ds_read_b128 v[92:95], v189 offset:3072
	v_mfma_f32_16x16x32_bf16 v[56:59], v[218:221], v[100:103], v[56:59]
	s_add_i32 vcc_hi, vcc_hi, 2
	v_mfma_f32_16x16x32_bf16 v[52:55], v[230:233], v[100:103], v[52:55]
	s_add_u32 s59, s59, 0x100
	s_addc_u32 vcc_lo, vcc_lo, 0
	v_mfma_f32_16x16x32_bf16 v[44:47], v[218:221], v[112:115], v[44:47]
	s_add_u32 s44, s44, 0x100
	s_addc_u32 s45, s45, 0
	v_mfma_f32_16x16x32_bf16 v[36:39], v[230:233], v[112:115], v[36:39]
	s_cmp_gt_u32 vcc_hi, 29
	v_mfma_f32_16x16x32_bf16 v[28:31], v[218:221], v[164:167], v[28:31]
	v_mfma_f32_16x16x32_bf16 v[20:23], v[230:233], v[164:167], v[20:23]
	v_mfma_f32_16x16x32_bf16 v[4:7], v[218:221], v[202:205], v[4:7]
	s_setprio 0
	v_mfma_f32_16x16x32_bf16 v[0:3], v[230:233], v[202:205], v[0:3]
	s_barrier
	s_cbranch_scc0 .LBB1_380
; DI float silu_mul(float g, float v) { return g * v * __builtin_amdgcn_rcpf(1.0f + __builtin_amdgcn_exp2f(-LOG2E * g)); }
;     DI void operator()(const f32x4 (&acc)[2][2][4][2], const Unit& u, int wr, int wc, int fr, int fq) const {
;         const int row0 = u.pm * BM + wr * 64 + fr, ch0 = u.pn * 128 + wc * 32 + 8 * fq;
;         f32x4 w0[2], w1[2], w2[2], bb[2];
; #pragma unroll
;         for (int n = 0; n < 2; ++n) { w0[n] = *(const f32x4*)(cw + ch0 + 4 * n); w1[n] = *(const f32x4*)(cw + DFF + ch0 + 4 * n); w2[n] = *(const f32x4*)(cw + 2 * DFF + ch0 + 4 * n); bb[n] = *(const f32x4*)(cb + ch0 + 4 * n); }
; #pragma unroll
;         for (int ai = 0; ai < 2; ++ai)
; #pragma unroll
;             for (int m = 0; m < 4; ++m) {
;                 const bool efirst = (m == 0) && (fr == 0), elast = (m == 3) && (fr == 15);
;                 const int row = row0 + ai * HALF + m * 16;
;                 f32x4 gc[2];
; #pragma unroll
;                 for (int n = 0; n < 2; ++n) {
;                     const f32x4 g = acc[ai][0][m][n];
;                     const f32x4 gprev = acc[ai][0][m > 0 ? m - 1 : 0][n], gnext = acc[ai][0][m < 3 ? m + 1 : 3][n];
;                     f32x4 up, dn;
; #pragma unroll
;                     for (int e = 0; e < 4; ++e) {
;                         const float pu = (m > 0 && fr == 15) ? gprev[e] : g[e];
;                         const float pd = (m < 3 && fr == 0) ? gnext[e] : g[e];
;                         up[e] = dpp_ror1(pu); dn[e] = dpp_ror15(pd);
;                     }
;                     if (efirst) up = (f32x4){0.f, 0.f, 0.f, 0.f};
;                     if (elast) dn = (f32x4){0.f, 0.f, 0.f, 0.f};
;                     gc[n] = w0[n] * up + w1[n] * g + w2[n] * dn + bb[n];
;                 }
;                 if (efirst || elast) {
;                     const size_t eo = (size_t)((row >> 6) * 2 + (elast ? 1 : 0)) * DFF + ch0;
; #pragma unroll
;                     for (int n = 0; n < 2; ++n) { *(f32x4*)(EP + eo + 4 * n) = gc[n]; *(f32x4*)(ER + eo + 4 * n) = acc[ai][0][m][n]; *(f32x4*)(EV + eo + 4 * n) = acc[ai][1][m][n]; }
;                 } else {
;                     const f32x4 v0 = acc[ai][1][m][0], v1 = acc[ai][1][m][1];
;                     u32x4 o;
;                     o[0] = pack2(silu_mul(gc[0][0], v0[0]), silu_mul(gc[0][1], v0[1])); o[1] = pack2(silu_mul(gc[0][2], v0[2]), silu_mul(gc[0][3], v0[3]));
	s_waitcnt lgkmcnt(0)
	s_lshl_b32 s23, s43, 7
	v_mov_b32_e32 v194, v186
	v_mov_b32_e32 v80, v187
	s_or_b32 s23, s23, s67
	v_lshl_add_u32 v184, v80, 3, s23
	v_ashrrev_i32_e32 v185, 31, v184
	v_lshlrev_b64 v[80:81], 2, v[184:185]
	v_lshl_add_u64 v[84:85], s[52:53], 0, v[80:81]
	v_lshl_add_u64 v[88:89], s[16:17], 0, v[80:81]
	v_lshl_add_u64 v[92:93], s[18:19], 0, v[80:81]
	v_lshl_add_u64 v[112:113], s[54:55], 0, v[80:81]
	global_load_dwordx4 v[80:83], v[84:85], off offset:16
	global_load_dwordx4 v[96:99], v[84:85], off
	s_nop 0
	global_load_dwordx4 v[84:87], v[88:89], off offset:16
	global_load_dwordx4 v[100:103], v[88:89], off
	s_nop 0
	global_load_dwordx4 v[88:91], v[92:93], off offset:16
	global_load_dwordx4 v[108:111], v[92:93], off
	s_nop 0
	global_load_dwordx4 v[92:95], v[112:113], off offset:16
	s_nop 0
	global_load_dwordx4 v[112:115], v[112:113], off
	v_cmp_eq_u32_e32 vcc, 0, v194
	s_nop 0
	s_nop 0
	v_cndmask_b32_e32 v161, v148, v136, vcc
	v_cndmask_b32_e32 v162, v149, v137, vcc
	v_cndmask_b32_e32 v163, v150, v138, vcc
	v_mov_b32_dpp v160, v161 row_ror:15 row_mask:0xf bank_mask:0xf
	s_nop 0
	s_nop 0
	v_mov_b32_dpp v161, v162 row_ror:15 row_mask:0xf bank_mask:0xf
	v_mov_b32_dpp v164, v150 row_ror:1 row_mask:0xf bank_mask:0xf
	v_cndmask_b32_e32 v165, v151, v139, vcc
	v_mov_b32_dpp v162, v163 row_ror:15 row_mask:0xf bank_mask:0xf
	v_mov_b32_dpp v195, v151 row_ror:1 row_mask:0xf bank_mask:0xf
	v_mov_b32_dpp v166, v148 row_ror:1 row_mask:0xf bank_mask:0xf
	v_mov_b32_dpp v167, v149 row_ror:1 row_mask:0xf bank_mask:0xf
	v_mov_b32_dpp v163, v165 row_ror:15 row_mask:0xf bank_mask:0xf
	v_cndmask_b32_e64 v165, v195, 0, vcc
	v_cndmask_b32_e64 v164, v164, 0, vcc
	v_cndmask_b32_e64 v167, v167, 0, vcc
	v_cndmask_b32_e64 v166, v166, 0, vcc
	s_nop 0
	s_nop 0
	v_mov_b32_dpp v195, v144 row_ror:1 row_mask:0xf bank_mask:0xf
	v_mov_b32_dpp v196, v145 row_ror:1 row_mask:0xf bank_mask:0xf
	v_mov_b32_dpp v198, v146 row_ror:1 row_mask:0xf bank_mask:0xf
	v_cndmask_b32_e32 v199, v147, v131, vcc
	v_mov_b32_dpp v200, v147 row_ror:1 row_mask:0xf bank_mask:0xf
	v_cndmask_b32_e64 v198, v198, 0, vcc
	v_cndmask_b32_e64 v201, v196, 0, vcc
	s_lshl_b32 s21, s42, 8
	s_add_i32 s21, s21, s49
	v_add_u32_e32 v193, s21, v194
	v_cmp_ne_u32_e64 s[46:47], 0, v194
	s_waitcnt vmcnt(0)
	v_pk_mul_f32 v[164:165], v[98:99], v[164:165]
	v_pk_mul_f32 v[166:167], v[96:97], v[166:167]
	v_pk_fma_f32 v[164:165], v[150:151], v[102:103], v[164:165]
	v_pk_fma_f32 v[166:167], v[148:149], v[100:101], v[166:167]
	v_pk_fma_f32 v[162:163], v[110:111], v[162:163], v[164:165]
	v_cndmask_b32_e32 v165, v144, v128, vcc
	v_pk_fma_f32 v[160:161], v[108:109], v[160:161], v[166:167]
	v_cndmask_b32_e32 v166, v145, v129, vcc
	v_mov_b32_dpp v164, v165 row_ror:15 row_mask:0xf bank_mask:0xf
	v_cndmask_b32_e32 v167, v146, v130, vcc
	v_pk_add_f32 v[162:163], v[114:115], v[162:163]
	v_mov_b32_dpp v165, v166 row_ror:15 row_mask:0xf bank_mask:0xf
	v_pk_add_f32 v[160:161], v[112:113], v[160:161]
	s_nop 0
	v_mov_b32_dpp v166, v167 row_ror:15 row_mask:0xf bank_mask:0xf
	s_nop 1
	v_mov_b32_dpp v167, v199 row_ror:15 row_mask:0xf bank_mask:0xf
	v_cndmask_b32_e64 v199, v200, 0, vcc
	v_cndmask_b32_e64 v200, v195, 0, vcc
	v_pk_mul_f32 v[200:201], v[80:81], v[200:201]
	v_pk_mul_f32 v[198:199], v[82:83], v[198:199]
	v_pk_fma_f32 v[200:201], v[144:145], v[84:85], v[200:201]
	v_pk_fma_f32 v[198:199], v[146:147], v[86:87], v[198:199]
	v_pk_fma_f32 v[164:165], v[88:89], v[164:165], v[200:201]
	v_pk_fma_f32 v[166:167], v[90:91], v[166:167], v[198:199]
	v_pk_add_f32 v[164:165], v[92:93], v[164:165]
	v_pk_add_f32 v[166:167], v[94:95], v[166:167]
	s_and_saveexec_b64 s[28:29], s[46:47]
	s_xor_b64 s[28:29], exec, s[28:29]
	s_cbranch_execz .LBB1_383
	v_mul_f32_e32 v195, 0xbfb8aa3b, v160
	v_exp_f32_e32 v195, v195
	v_mul_f32_e32 v196, 0xbfb8aa3b, v161
	v_exp_f32_e32 v196, v196
	v_pk_mul_f32 v[160:161], v[156:157], v[160:161]
	v_add_f32_e32 v195, 1.0, v195
	v_rcp_f32_e32 v198, v195
	v_add_f32_e32 v196, 1.0, v196
	v_mul_f32_e32 v195, 0xbfb8aa3b, v162
	v_rcp_f32_e32 v199, v196
	v_exp_f32_e32 v195, v195
	v_mul_f32_e32 v196, 0xbfb8aa3b, v163
	v_exp_f32_e32 v196, v196
	v_pk_mul_f32 v[160:161], v[160:161], v[198:199]
	v_add_f32_e32 v195, 1.0, v195
	v_rcp_f32_e32 v200, v195
	v_add_f32_e32 v195, 1.0, v196
	v_rcp_f32_e32 v201, v195
	v_cvt_pk_bf16_f32 v160, v160, v161
	v_mul_f32_e32 v161, 0xbfb8aa3b, v164
	v_exp_f32_e32 v195, v161
	v_mul_f32_e32 v161, 0xbfb8aa3b, v165
	v_exp_f32_e32 v196, v161
	v_pk_mul_f32 v[162:163], v[158:159], v[162:163]
	v_pk_mul_f32 v[164:165], v[152:153], v[164:165]
	v_pk_mul_f32 v[162:163], v[162:163], v[200:201]
	s_nop 0
	v_cvt_pk_bf16_f32 v161, v162, v163
	v_add_f32_e32 v162, 1.0, v195
	v_mul_f32_e32 v195, 0xbfb8aa3b, v166
	v_add_f32_e32 v163, 1.0, v196
	v_exp_f32_e32 v195, v195
	v_mul_f32_e32 v196, 0xbfb8aa3b, v167
	v_exp_f32_e32 v196, v196
	v_rcp_f32_e32 v162, v162
	v_add_f32_e32 v195, 1.0, v195
	v_rcp_f32_e32 v198, v195
	v_add_f32_e32 v195, 1.0, v196
	v_rcp_f32_e32 v163, v163
	v_rcp_f32_e32 v199, v195
	v_pk_mul_f32 v[166:167], v[154:155], v[166:167]
	v_pk_mul_f32 v[162:163], v[164:165], v[162:163]
	v_pk_mul_f32 v[164:165], v[166:167], v[198:199]
	v_cvt_pk_bf16_f32 v162, v162, v163
	v_cvt_pk_bf16_f32 v163, v164, v165
	v_mov_b64_e32 v[164:165], s[6:7]
	v_mad_i64_i32 v[164:165], s[42:43], v193, s30, v[164:165]
	v_lshl_add_u64 v[164:165], v[184:185], 1, v[164:165]
	global_store_dwordx4 v[164:165], v[160:163], off

; #define PG8_STAGE(bufoff, gbase, voff) do { _Pragma("unroll") for (int _i = 0; _i < 2; ++_i) \
;         __builtin_amdgcn_global_load_lds((const unsigned*)((const char*)(gbase) + (voff)[_i]), (LAS unsigned*)(lds + (bufoff) + ldsw + _i * 8192), 16, 0, 0); } while (0)
; #define PG8_LDA(dst, b, h) do { _Pragma("unroll") for (int m = 0; m < 4; ++m) _Pragma("unroll") for (int k = 0; k < 2; ++k) dst[m][k] = *(const LAS bf16x8*)(lds + PG8_SA(b, h) + aoff + m * 2048 + k * 1024); } while (0)
; #define PG8_LDB(dst, b, h) do { _Pragma("unroll") for (int n = 0; n < 2; ++n) _Pragma("unroll") for (int k = 0; k < 2; ++k) dst[n][k] = *(const LAS bf16x8*)(lds + PG8_SB(b, h) + boff + n * 2048 + k * 1024); } while (0)
; #define PG8_MMA(ai, bj, At, Bt) do { __builtin_amdgcn_s_setprio(1); _Pragma("unroll") for (int m = 0; m < 4; ++m) _Pragma("unroll") for (int n = 0; n < 2; ++n) _Pragma("unroll") for (int k = 0; k < 2; ++k) \
;         acc[ai][bj][m][n] = __builtin_amdgcn_mfma_f32_16x16x32_bf16(Bt[n][k], At[m][k], acc[ai][bj][m][n], 0, 0, 0); __builtin_amdgcn_s_setprio(0); } while (0)
; #define PG8_WAIT_V(n) asm volatile("s_waitcnt vmcnt(" #n ")" ::: "memory")
; #define PG8_WAIT_L(n) asm volatile("s_waitcnt lgkmcnt(" #n ")" ::: "memory")
; #define PG8_BAR __builtin_amdgcn_s_barrier()
; template <class Map, class Epi>
; DI void gemm_phase(LAS unsigned char* lds, const Map& MP, const Epi& E, const int nM, const int nN, const int K, const int lda, const int ldb) {
;     ...
;             const char* a1 = cA + (size_t)(t + 1) * kstep;
;             const char* a2 = last ? nA : cA + (size_t)(t + 2) * kstep; const char* b2 = last ? nB : cB + (size_t)(t + 2) * kstep;
;             const char* a3 = a2 + kstep; const char* b3 = b2 + kstep;
;             PG8_LDB(B0, 0, 0); PG8_SCHED; PG8_LDA(At, 0, 0); PG8_STAGE(PG8_SA(1, 1), a1 + hstepA, voffA);
;             PG8_WAIT_L(8); PG8_BAR; PG8_WAIT_L(0); PG8_MMA(0, 0, At, B0); PG8_BAR; PG8_SCHED;
;             PG8_LDB(B1, 0, 1); PG8_STAGE(PG8_SB(0, 0), b2, voffB);
;             PG8_BAR; PG8_WAIT_L(0); PG8_MMA(0, 1, At, B1); PG8_BAR;
;             PG8_LDA(At, 0, 1); PG8_STAGE(PG8_SA(0, 0), a2, voffA);
;             PG8_BAR; PG8_WAIT_L(0); PG8_MMA(1, 0, At, B0); PG8_BAR; PG8_SCHED;
;             PG8_STAGE(PG8_SB(0, 1), b2 + hstepB, voffB);
;             PG8_WAIT_V(6); PG8_BAR; PG8_MMA(1, 1, At, B1); PG8_BAR;
.LBB1_550:
	s_add_u32 s10, s8, 0x100
	s_addc_u32 s11, s9, 0
	s_cmpk_eq_i32 s3, 0x54
	s_cselect_b32 s15, s43, s11
	s_cselect_b32 s14, s42, s10
	s_cselect_b32 s13, s7, s38
	s_cselect_b32 s12, s6, s5
	s_add_i32 m0, s24, 0xc000
	ds_read_b128 v[168:171], v150
	ds_read_b128 v[172:175], v150 offset:1024
	ds_read_b128 v[176:179], v150 offset:2048
	ds_read_b128 v[180:183], v150 offset:3072
	ds_read_b128 v[184:187], v150 offset:4096
	ds_read_b128 v[188:191], v150 offset:5120
	ds_read_b128 v[192:195], v150 offset:6144
	ds_read_b128 v[198:201], v150 offset:7168
	global_load_lds_dwordx4 v138, s[8:9]
	s_add_i32 m0, s24, 0xe000
	s_nop 0
	global_load_lds_dwordx4 v136, s[8:9]
	s_waitcnt lgkmcnt(8)
	s_setprio 1
	s_barrier
	s_waitcnt lgkmcnt(7)
	v_mfma_f32_16x16x32_bf16 v[124:127], v[152:155], v[168:171], v[124:127]
	v_mfma_f32_16x16x32_bf16 v[120:123], v[160:163], v[168:171], v[120:123]
	s_waitcnt lgkmcnt(5)
	v_mfma_f32_16x16x32_bf16 v[108:111], v[152:155], v[176:179], v[108:111]
	v_mfma_f32_16x16x32_bf16 v[104:107], v[160:163], v[176:179], v[104:107]
	s_waitcnt lgkmcnt(3)
	v_mfma_f32_16x16x32_bf16 v[92:95], v[152:155], v[184:187], v[92:95]
	v_mfma_f32_16x16x32_bf16 v[88:91], v[160:163], v[184:187], v[88:91]
	s_waitcnt lgkmcnt(1)
	v_mfma_f32_16x16x32_bf16 v[76:79], v[152:155], v[192:195], v[76:79]
	v_mfma_f32_16x16x32_bf16 v[72:75], v[160:163], v[192:195], v[72:75]
	v_mfma_f32_16x16x32_bf16 v[124:127], v[156:159], v[172:175], v[124:127]
	s_add_i32 s8, s35, s22
	v_mfma_f32_16x16x32_bf16 v[120:123], v[164:167], v[172:175], v[120:123]
	v_lshl_add_u64 v[144:145], s[12:13], 0, v[132:133]
	v_mfma_f32_16x16x32_bf16 v[108:111], v[156:159], v[180:183], v[108:111]
	v_lshl_add_u64 v[218:219], s[12:13], 0, v[128:129]
	v_mfma_f32_16x16x32_bf16 v[104:107], v[164:167], v[180:183], v[104:107]
	v_mfma_f32_16x16x32_bf16 v[92:95], v[156:159], v[188:191], v[92:95]
	v_mfma_f32_16x16x32_bf16 v[88:91], v[164:167], v[188:191], v[88:91]
	s_waitcnt lgkmcnt(0)
	v_mfma_f32_16x16x32_bf16 v[76:79], v[156:159], v[198:201], v[76:79]
	s_setprio 0
	v_mfma_f32_16x16x32_bf16 v[72:75], v[164:167], v[198:201], v[72:75]
	s_barrier
	s_mov_b32 m0, s8
	ds_read_b128 v[202:205], v151
	ds_read_b128 v[206:209], v151 offset:1024
	ds_read_b128 v[210:213], v151 offset:2048
	ds_read_b128 v[214:217], v151 offset:3072
	global_load_lds_dwordx4 v[144:145], off
	s_add_i32 m0, s8, 0x2000
	s_nop 0
	global_load_lds_dwordx4 v[218:219], off
	s_setprio 1
	s_barrier
	s_waitcnt lgkmcnt(3)
	v_mfma_f32_16x16x32_bf16 v[116:119], v[202:205], v[168:171], v[116:119]
	s_waitcnt lgkmcnt(1)
	v_mfma_f32_16x16x32_bf16 v[112:115], v[210:213], v[168:171], v[112:115]
	v_mfma_f32_16x16x32_bf16 v[100:103], v[202:205], v[176:179], v[100:103]
	v_mfma_f32_16x16x32_bf16 v[96:99], v[210:213], v[176:179], v[96:99]
	v_mfma_f32_16x16x32_bf16 v[84:87], v[202:205], v[184:187], v[84:87]
	v_mfma_f32_16x16x32_bf16 v[80:83], v[210:213], v[184:187], v[80:83]
	v_mfma_f32_16x16x32_bf16 v[68:71], v[202:205], v[192:195], v[68:71]
	v_mfma_f32_16x16x32_bf16 v[64:67], v[210:213], v[192:195], v[64:67]
	v_mfma_f32_16x16x32_bf16 v[116:119], v[206:209], v[172:175], v[116:119]
	v_lshl_add_u64 v[222:223], s[14:15], 0, v[130:131]
	s_mov_b32 m0, s24
	s_waitcnt lgkmcnt(0)
	v_mfma_f32_16x16x32_bf16 v[112:115], v[214:217], v[172:175], v[112:115]
	v_lshl_add_u64 v[220:221], s[14:15], 0, v[134:135]
	v_mfma_f32_16x16x32_bf16 v[100:103], v[206:209], v[180:183], v[100:103]
	v_mfma_f32_16x16x32_bf16 v[96:99], v[214:217], v[180:183], v[96:99]
	v_mfma_f32_16x16x32_bf16 v[84:87], v[206:209], v[188:191], v[84:87]
	v_mfma_f32_16x16x32_bf16 v[80:83], v[214:217], v[188:191], v[80:83]
	v_mfma_f32_16x16x32_bf16 v[68:71], v[206:209], v[198:201], v[68:71]
	s_setprio 0
	v_mfma_f32_16x16x32_bf16 v[64:67], v[214:217], v[198:201], v[64:67]
	s_barrier
	ds_read_b128 v[168:171], v150 offset:16384
	ds_read_b128 v[172:175], v150 offset:17408
	ds_read_b128 v[176:179], v150 offset:18432
	ds_read_b128 v[180:183], v150 offset:19456
	ds_read_b128 v[184:187], v150 offset:20480
	ds_read_b128 v[188:191], v150 offset:21504
	ds_read_b128 v[192:195], v150 offset:22528
	ds_read_b128 v[198:201], v150 offset:23552
	global_load_lds_dwordx4 v[220:221], off
	s_mov_b32 m0, s25
	s_nop 0
	global_load_lds_dwordx4 v[222:223], off
	s_waitcnt vmcnt(10)
	s_setprio 1
	s_barrier
	s_waitcnt lgkmcnt(7)
	v_mfma_f32_16x16x32_bf16 v[60:63], v[152:155], v[168:171], v[60:63]
	v_mfma_f32_16x16x32_bf16 v[56:59], v[160:163], v[168:171], v[56:59]
	s_waitcnt lgkmcnt(5)
	v_mfma_f32_16x16x32_bf16 v[44:47], v[152:155], v[176:179], v[44:47]
	v_mfma_f32_16x16x32_bf16 v[40:43], v[160:163], v[176:179], v[40:43]
	s_waitcnt lgkmcnt(3)
	v_mfma_f32_16x16x32_bf16 v[28:31], v[152:155], v[184:187], v[28:31]
	v_mfma_f32_16x16x32_bf16 v[24:27], v[160:163], v[184:187], v[24:27]
	s_waitcnt lgkmcnt(1)
	v_mfma_f32_16x16x32_bf16 v[12:15], v[152:155], v[192:195], v[12:15]
	v_mfma_f32_16x16x32_bf16 v[8:11], v[160:163], v[192:195], v[8:11]
	v_mfma_f32_16x16x32_bf16 v[60:63], v[156:159], v[172:175], v[60:63]
	s_add_u32 s8, s12, 0x160000
	s_addc_u32 s9, s13, 0
	v_mfma_f32_16x16x32_bf16 v[56:59], v[164:167], v[172:175], v[56:59]
	s_add_i32 s39, s36, s22
	v_mfma_f32_16x16x32_bf16 v[44:47], v[156:159], v[180:183], v[44:47]
	v_mfma_f32_16x16x32_bf16 v[40:43], v[164:167], v[180:183], v[40:43]
	v_mfma_f32_16x16x32_bf16 v[28:31], v[156:159], v[188:191], v[28:31]
	v_mfma_f32_16x16x32_bf16 v[24:27], v[164:167], v[188:191], v[24:27]
	s_waitcnt lgkmcnt(0)
	v_mfma_f32_16x16x32_bf16 v[12:15], v[156:159], v[198:201], v[12:15]
	s_setprio 0
	v_mfma_f32_16x16x32_bf16 v[8:11], v[164:167], v[198:201], v[8:11]
	s_barrier
; #define PG8_STAGE(bufoff, gbase, voff) do { _Pragma("unroll") for (int _i = 0; _i < 2; ++_i) \
;         __builtin_amdgcn_global_load_lds((const unsigned*)((const char*)(gbase) + (voff)[_i]), (LAS unsigned*)(lds + (bufoff) + ldsw + _i * 8192), 16, 0, 0); } while (0)
; #define PG8_LDA(dst, b, h) do { _Pragma("unroll") for (int m = 0; m < 4; ++m) _Pragma("unroll") for (int k = 0; k < 2; ++k) dst[m][k] = *(const LAS bf16x8*)(lds + PG8_SA(b, h) + aoff + m * 2048 + k * 1024); } while (0)
; #define PG8_LDB(dst, b, h) do { _Pragma("unroll") for (int n = 0; n < 2; ++n) _Pragma("unroll") for (int k = 0; k < 2; ++k) dst[n][k] = *(const LAS bf16x8*)(lds + PG8_SB(b, h) + boff + n * 2048 + k * 1024); } while (0)
; #define PG8_MMA(ai, bj, At, Bt) do { __builtin_amdgcn_s_setprio(1); _Pragma("unroll") for (int m = 0; m < 4; ++m) _Pragma("unroll") for (int n = 0; n < 2; ++n) _Pragma("unroll") for (int k = 0; k < 2; ++k) \
;         acc[ai][bj][m][n] = __builtin_amdgcn_mfma_f32_16x16x32_bf16(Bt[n][k], At[m][k], acc[ai][bj][m][n], 0, 0, 0); __builtin_amdgcn_s_setprio(0); } while (0)
; #define PG8_WAIT_V(n) asm volatile("s_waitcnt vmcnt(" #n ")" ::: "memory")
; #define PG8_WAIT_L(n) asm volatile("s_waitcnt lgkmcnt(" #n ")" ::: "memory")
; #define PG8_BAR __builtin_amdgcn_s_barrier()
; #define PG8_SCHED __builtin_amdgcn_sched_barrier(0)
; template <class Map, class Epi>
; DI void gemm_phase(LAS unsigned char* lds, const Map& MP, const Epi& E, const int nM, const int nN, const int K, const int lda, const int ldb) {
;     ...
;             PG8_WAIT_V(6); PG8_BAR; PG8_MMA(1, 1, At, B1); PG8_BAR;
;             PG8_LDB(B0, 1, 0); PG8_SCHED; PG8_LDA(At, 1, 0); PG8_STAGE(PG8_SA(0, 1), a2 + hstepA, voffA);
;             PG8_WAIT_L(8); PG8_BAR; PG8_WAIT_L(0); PG8_MMA(0, 0, At, B0); PG8_BAR; PG8_SCHED;
;             PG8_LDB(B1, 1, 1); PG8_STAGE(PG8_SB(1, 0), b3, voffB);
;             PG8_BAR; PG8_WAIT_L(0); PG8_MMA(0, 1, At, B1); PG8_BAR;
;             PG8_LDA(At, 1, 1); PG8_STAGE(PG8_SA(1, 0), a3, voffA);
;             PG8_BAR; PG8_WAIT_L(0); PG8_MMA(1, 0, At, B0); PG8_BAR; PG8_SCHED;
	s_mov_b32 m0, s39
	s_nop 0
	global_load_lds_dwordx4 v132, s[8:9]
	s_add_i32 m0, s39, 0x2000
	s_nop 0
	global_load_lds_dwordx4 v128, s[8:9]
	s_waitcnt vmcnt(6)
	s_setprio 1
	s_barrier
	v_mfma_f32_16x16x32_bf16 v[52:55], v[202:205], v[168:171], v[52:55]
	v_mfma_f32_16x16x32_bf16 v[48:51], v[210:213], v[168:171], v[48:51]
	s_add_i32 s39, 0, 0x18000
	v_add_u32_e32 v164, s39, v148
	ds_read_b128 v[152:155], v164
	v_mfma_f32_16x16x32_bf16 v[36:39], v[202:205], v[176:179], v[36:39]
	v_mfma_f32_16x16x32_bf16 v[32:35], v[210:213], v[176:179], v[32:35]
	ds_read_b128 v[156:159], v164 offset:1024
	v_mfma_f32_16x16x32_bf16 v[20:23], v[202:205], v[184:187], v[20:23]
	v_mfma_f32_16x16x32_bf16 v[16:19], v[210:213], v[184:187], v[16:19]
	ds_read_b128 v[160:163], v164 offset:2048
	v_mfma_f32_16x16x32_bf16 v[4:7], v[202:205], v[192:195], v[4:7]
	v_mfma_f32_16x16x32_bf16 v[0:3], v[210:213], v[192:195], v[0:3]
	ds_read_b128 v[164:167], v164 offset:3072
	v_mfma_f32_16x16x32_bf16 v[52:55], v[206:209], v[172:175], v[52:55]
	s_add_u32 s8, s14, 0x160000
	s_addc_u32 s9, s15, 0
	v_mfma_f32_16x16x32_bf16 v[48:51], v[214:217], v[172:175], v[48:51]
	v_mfma_f32_16x16x32_bf16 v[36:39], v[206:209], v[180:183], v[36:39]
	v_mfma_f32_16x16x32_bf16 v[32:35], v[214:217], v[180:183], v[32:35]
	v_mfma_f32_16x16x32_bf16 v[20:23], v[206:209], v[188:191], v[20:23]
	v_mfma_f32_16x16x32_bf16 v[16:19], v[214:217], v[188:191], v[16:19]
	v_mfma_f32_16x16x32_bf16 v[4:7], v[206:209], v[198:201], v[4:7]
	s_setprio 0
	v_mfma_f32_16x16x32_bf16 v[0:3], v[214:217], v[198:201], v[0:3]
	s_barrier
	s_mov_b32 m0, s26
	ds_read_b128 v[168:171], v150 offset:32768
	ds_read_b128 v[172:175], v150 offset:33792
	ds_read_b128 v[176:179], v150 offset:34816
	ds_read_b128 v[180:183], v150 offset:35840
	ds_read_b128 v[184:187], v150 offset:36864
	ds_read_b128 v[188:191], v150 offset:37888
	ds_read_b128 v[192:195], v150 offset:38912
	ds_read_b128 v[198:201], v150 offset:39936
	global_load_lds_dwordx4 v134, s[8:9]
	s_mov_b32 m0, s27
	s_nop 0
	global_load_lds_dwordx4 v130, s[8:9]
	s_waitcnt lgkmcnt(8)
	s_setprio 1
	s_barrier
	s_waitcnt lgkmcnt(7)
	v_mfma_f32_16x16x32_bf16 v[124:127], v[152:155], v[168:171], v[124:127]
	v_mfma_f32_16x16x32_bf16 v[120:123], v[160:163], v[168:171], v[120:123]
	s_waitcnt lgkmcnt(5)
	v_mfma_f32_16x16x32_bf16 v[108:111], v[152:155], v[176:179], v[108:111]
	v_mfma_f32_16x16x32_bf16 v[104:107], v[160:163], v[176:179], v[104:107]
	s_waitcnt lgkmcnt(3)
	v_mfma_f32_16x16x32_bf16 v[92:95], v[152:155], v[184:187], v[92:95]
	v_mfma_f32_16x16x32_bf16 v[88:91], v[160:163], v[184:187], v[88:91]
	s_waitcnt lgkmcnt(1)
	v_mfma_f32_16x16x32_bf16 v[76:79], v[152:155], v[192:195], v[76:79]
	v_mfma_f32_16x16x32_bf16 v[72:75], v[160:163], v[192:195], v[72:75]
	v_mfma_f32_16x16x32_bf16 v[124:127], v[156:159], v[172:175], v[124:127]
	s_add_i32 s14, 0, 0x1c000
	v_mfma_f32_16x16x32_bf16 v[120:123], v[164:167], v[172:175], v[120:123]
	s_add_i32 s8, s39, s22
	v_mfma_f32_16x16x32_bf16 v[108:111], v[156:159], v[180:183], v[108:111]
	v_add_u32_e32 v196, s14, v148
	v_mfma_f32_16x16x32_bf16 v[104:107], v[164:167], v[180:183], v[104:107]
	v_lshl_add_u64 v[144:145], v[144:145], 0, s[52:53]
	v_mfma_f32_16x16x32_bf16 v[92:95], v[156:159], v[188:191], v[92:95]
	v_mfma_f32_16x16x32_bf16 v[88:91], v[164:167], v[188:191], v[88:91]
	s_waitcnt lgkmcnt(0)
	v_mfma_f32_16x16x32_bf16 v[76:79], v[156:159], v[198:201], v[76:79]
	s_setprio 0
	v_mfma_f32_16x16x32_bf16 v[72:75], v[164:167], v[198:201], v[72:75]
	s_barrier
	s_mov_b32 m0, s8
	ds_read_b128 v[202:205], v196
	ds_read_b128 v[206:209], v196 offset:1024
	ds_read_b128 v[210:213], v196 offset:2048
	ds_read_b128 v[214:217], v196 offset:3072
	global_load_lds_dwordx4 v[144:145], off
	v_lshl_add_u64 v[144:145], v[218:219], 0, s[52:53]
	s_add_i32 m0, s8, 0x2000
	s_nop 0
	global_load_lds_dwordx4 v[144:145], off
	s_setprio 1
	s_barrier
	s_waitcnt lgkmcnt(3)
	v_mfma_f32_16x16x32_bf16 v[116:119], v[202:205], v[168:171], v[116:119]
	s_waitcnt lgkmcnt(1)
	v_mfma_f32_16x16x32_bf16 v[112:115], v[210:213], v[168:171], v[112:115]
	v_mfma_f32_16x16x32_bf16 v[100:103], v[202:205], v[176:179], v[100:103]
	v_mfma_f32_16x16x32_bf16 v[96:99], v[210:213], v[176:179], v[96:99]
	v_mfma_f32_16x16x32_bf16 v[84:87], v[202:205], v[184:187], v[84:87]
	v_mfma_f32_16x16x32_bf16 v[80:83], v[210:213], v[184:187], v[80:83]
	v_mfma_f32_16x16x32_bf16 v[68:71], v[202:205], v[192:195], v[68:71]
	v_mfma_f32_16x16x32_bf16 v[64:67], v[210:213], v[192:195], v[64:67]
	v_mfma_f32_16x16x32_bf16 v[116:119], v[206:209], v[172:175], v[116:119]
	s_mov_b32 m0, s30
	s_waitcnt lgkmcnt(0)
	v_mfma_f32_16x16x32_bf16 v[112:115], v[214:217], v[172:175], v[112:115]
	v_lshl_add_u64 v[144:145], v[220:221], 0, s[52:53]
	v_mfma_f32_16x16x32_bf16 v[100:103], v[206:209], v[180:183], v[100:103]
	v_mfma_f32_16x16x32_bf16 v[96:99], v[214:217], v[180:183], v[96:99]
	v_mfma_f32_16x16x32_bf16 v[84:87], v[206:209], v[188:191], v[84:87]
	v_mfma_f32_16x16x32_bf16 v[80:83], v[214:217], v[188:191], v[80:83]
	v_mfma_f32_16x16x32_bf16 v[68:71], v[206:209], v[198:201], v[68:71]
	s_setprio 0
	v_mfma_f32_16x16x32_bf16 v[64:67], v[214:217], v[198:201], v[64:67]
	s_barrier
	ds_read_b128 v[168:171], v150 offset:49152
	ds_read_b128 v[172:175], v150 offset:50176
	ds_read_b128 v[176:179], v150 offset:51200
	ds_read_b128 v[180:183], v150 offset:52224
	ds_read_b128 v[184:187], v150 offset:53248
	ds_read_b128 v[188:191], v150 offset:54272
	ds_read_b128 v[192:195], v150 offset:55296
	ds_read_b128 v[198:201], v150 offset:56320
	global_load_lds_dwordx4 v[144:145], off
	v_lshl_add_u64 v[144:145], v[222:223], 0, s[52:53]
	s_mov_b32 m0, s31
	s_nop 0
	global_load_lds_dwordx4 v[144:145], off
	s_waitcnt vmcnt(10)
	s_setprio 1
	s_barrier
; DI unsigned pack2(float a, float b) { f32x2 v = {a, b}; hwbf16x2 r = __builtin_convertvector(v, hwbf16x2); return __builtin_bit_cast(unsigned, r); }
; DI float bflo(unsigned w) { return __uint_as_float(w << 16); }
; DI float bfhi(unsigned w) { return __uint_as_float(w & 0xffff0000u); }
; #define PG8_STAGE(bufoff, gbase, voff) do { _Pragma("unroll") for (int _i = 0; _i < 2; ++_i) \
;         __builtin_amdgcn_global_load_lds((const unsigned*)((const char*)(gbase) + (voff)[_i]), (LAS unsigned*)(lds + (bufoff) + ldsw + _i * 8192), 16, 0, 0); } while (0)
; #define PG8_WAIT_V(n) asm volatile("s_waitcnt vmcnt(" #n ")" ::: "memory")
; #define PG8_WAIT_L(n) asm volatile("s_waitcnt lgkmcnt(" #n ")" ::: "memory")
;     DI void operator()(const f32x4 (&acc)[2][2][4][2], const Unit& u, int wr, int wc, int fr, int fq) const {
;     ...
;         for (int ai = 0; ai < 2; ++ai)
; #pragma unroll
;             for (int m = 0; m < 4; ++m) { const size_t ro = (size_t)(row0 + ai * HALF + m * 16) * D + col0;
; #pragma unroll
;                 for (int bj = 0; bj < 2; ++bj) {
;                     f32x4 x0, x1;
;                     if constexpr (IB) { const u32x4 w = *(const u32x4*)((const bf16_t*)Xin + ro + bj * HALF);
;                         x0 = (f32x4){bflo(w[0]), bfhi(w[0]), bflo(w[1]), bfhi(w[1])}; x1 = (f32x4){bflo(w[2]), bfhi(w[2]), bflo(w[3]), bfhi(w[3])}; }
;                     else { x0 = *(const f32x4*)((const float*)Xin + ro + bj * HALF); x1 = *(const f32x4*)((const float*)Xin + ro + bj * HALF + 4); }
;                     x0 += acc[ai][bj][m][0] * sc[bj][0]; x1 += acc[ai][bj][m][1] * sc[bj][1];
;                     if constexpr (OB) { u32x4 o; o[0] = pack2(x0[0], x0[1]); o[1] = pack2(x0[2], x0[3]); o[2] = pack2(x1[0], x1[1]); o[3] = pack2(x1[2], x1[3]);
;                         *(u32x4*)((bf16_t*)Xout + ro + bj * HALF) = o; }
;                     else { *(f32x4*)((float*)Xout + ro + bj * HALF) = x0; *(f32x4*)((float*)Xout + ro + bj * HALF + 4) = x1; } } }
; template <class Map, class Epi>
; DI void gemm_phase(LAS unsigned char* lds, const Map& MP, const Epi& E, const int nM, const int nN, const int K, const int lda, const int ldb) {
;     ...
;             PG8_BAR; PG8_WAIT_L(0); PG8_MMA(1, 0, At, B0); PG8_BAR; PG8_SCHED;
;             PG8_STAGE(PG8_SB(1, 1), b3 + hstepB, voffB);
;             PG8_WAIT_V(6); PG8_BAR; PG8_MMA(1, 1, At, B1); PG8_BAR;
	s_waitcnt lgkmcnt(7)
	v_mfma_f32_16x16x32_bf16 v[60:63], v[152:155], v[168:171], v[60:63]
	v_mfma_f32_16x16x32_bf16 v[56:59], v[160:163], v[168:171], v[56:59]
	s_waitcnt lgkmcnt(5)
	v_mfma_f32_16x16x32_bf16 v[44:47], v[152:155], v[176:179], v[44:47]
	v_mfma_f32_16x16x32_bf16 v[40:43], v[160:163], v[176:179], v[40:43]
	s_waitcnt lgkmcnt(3)
	v_mfma_f32_16x16x32_bf16 v[28:31], v[152:155], v[184:187], v[28:31]
	v_mfma_f32_16x16x32_bf16 v[24:27], v[160:163], v[184:187], v[24:27]
	s_waitcnt lgkmcnt(1)
	v_mfma_f32_16x16x32_bf16 v[12:15], v[152:155], v[192:195], v[12:15]
	v_mfma_f32_16x16x32_bf16 v[8:11], v[160:163], v[192:195], v[8:11]
	v_mfma_f32_16x16x32_bf16 v[60:63], v[156:159], v[172:175], v[60:63]
	s_add_u32 s8, s12, 0x160080
	s_addc_u32 s9, s13, 0
	v_mfma_f32_16x16x32_bf16 v[56:59], v[164:167], v[172:175], v[56:59]
	s_add_i32 s12, s14, s22
	v_mfma_f32_16x16x32_bf16 v[44:47], v[156:159], v[180:183], v[44:47]
	v_mfma_f32_16x16x32_bf16 v[40:43], v[164:167], v[180:183], v[40:43]
	v_mfma_f32_16x16x32_bf16 v[28:31], v[156:159], v[188:191], v[28:31]
	v_mfma_f32_16x16x32_bf16 v[24:27], v[164:167], v[188:191], v[24:27]
	s_waitcnt lgkmcnt(0)
	v_mfma_f32_16x16x32_bf16 v[12:15], v[156:159], v[198:201], v[12:15]
	s_setprio 0
	v_mfma_f32_16x16x32_bf16 v[8:11], v[164:167], v[198:201], v[8:11]
	s_barrier
	s_mov_b32 m0, s12
	s_nop 0
	global_load_lds_dwordx4 v132, s[8:9]
	s_add_i32 m0, s12, 0x2000
	s_nop 0
	global_load_lds_dwordx4 v128, s[8:9]
	s_waitcnt vmcnt(6)
	s_setprio 1
	s_barrier
	v_mfma_f32_16x16x32_bf16 v[52:55], v[202:205], v[168:171], v[52:55]
	v_mfma_f32_16x16x32_bf16 v[48:51], v[210:213], v[168:171], v[48:51]
	ds_read_b128 v[152:155], v149
	v_mfma_f32_16x16x32_bf16 v[36:39], v[202:205], v[176:179], v[36:39]
	v_mfma_f32_16x16x32_bf16 v[32:35], v[210:213], v[176:179], v[32:35]
	ds_read_b128 v[156:159], v149 offset:1024
	v_mfma_f32_16x16x32_bf16 v[20:23], v[202:205], v[184:187], v[20:23]
	v_mfma_f32_16x16x32_bf16 v[16:19], v[210:213], v[184:187], v[16:19]
	ds_read_b128 v[160:163], v149 offset:2048
	v_mfma_f32_16x16x32_bf16 v[4:7], v[202:205], v[192:195], v[4:7]
	v_mfma_f32_16x16x32_bf16 v[0:3], v[210:213], v[192:195], v[0:3]
	ds_read_b128 v[164:167], v149 offset:3072
	v_mfma_f32_16x16x32_bf16 v[52:55], v[206:209], v[172:175], v[52:55]
	s_add_i32 s3, s3, 2
	v_mfma_f32_16x16x32_bf16 v[48:51], v[214:217], v[172:175], v[48:51]
	s_add_u32 s5, s5, 0x100
	s_addc_u32 s38, s38, 0
	v_mfma_f32_16x16x32_bf16 v[36:39], v[206:209], v[180:183], v[36:39]
	s_cmpk_gt_u32 s3, 0x55
	v_mfma_f32_16x16x32_bf16 v[32:35], v[214:217], v[180:183], v[32:35]
	s_mov_b64 s[8:9], s[10:11]
	v_mfma_f32_16x16x32_bf16 v[20:23], v[206:209], v[188:191], v[20:23]
	v_mfma_f32_16x16x32_bf16 v[16:19], v[214:217], v[188:191], v[16:19]
	v_mfma_f32_16x16x32_bf16 v[4:7], v[206:209], v[198:201], v[4:7]
	s_setprio 0
	v_mfma_f32_16x16x32_bf16 v[0:3], v[214:217], v[198:201], v[0:3]
	s_barrier
	s_cbranch_scc0 .LBB1_550
	s_waitcnt lgkmcnt(0)
	v_mov_b32_e32 v144, v146
	v_mov_b32_e32 v152, v147
	s_lshl_b32 s2, s2, 8
	s_add_i32 s2, s2, s29
	s_lshl_b32 s3, s4, 8
	v_add_u32_e32 v152, s2, v152
	s_or_b32 s3, s3, s54
	v_ashrrev_i32_e32 v153, 31, v152
	v_lshl_add_u32 v144, v144, 3, s3
	v_lshlrev_b64 v[152:153], 12, v[152:153]
	v_ashrrev_i32_e32 v145, 31, v144
	v_lshl_add_u64 v[152:153], s[46:47], 0, v[152:153]
	v_lshl_add_u64 v[144:145], v[144:145], 1, v[152:153]
	global_load_dwordx4 v[160:163], v[144:145], off
	global_load_dwordx4 v[164:167], v[144:145], off offset:256
	s_mov_b64 s[98:99], 0x10000
	v_lshl_add_u64 v[154:155], v[144:145], 0, s[98:99]
	global_load_dwordx4 v[168:171], v[154:155], off
	global_load_dwordx4 v[172:175], v[154:155], off offset:256
	s_mov_b64 s[98:99], 0x20000
	v_lshl_add_u64 v[154:155], v[144:145], 0, s[98:99]
	global_load_dwordx4 v[176:179], v[154:155], off
	global_load_dwordx4 v[180:183], v[154:155], off offset:256
	s_mov_b64 s[98:99], 0x30000
	v_lshl_add_u64 v[154:155], v[144:145], 0, s[98:99]
	global_load_dwordx4 v[184:187], v[154:155], off
	global_load_dwordx4 v[188:191], v[154:155], off offset:256
	s_mov_b64 s[98:99], 0x80000
	v_lshl_add_u64 v[154:155], v[144:145], 0, s[98:99]
	global_load_dwordx4 v[192:195], v[154:155], off
	global_load_dwordx4 v[198:201], v[154:155], off offset:256
	s_mov_b64 s[98:99], 0x90000
	v_lshl_add_u64 v[154:155], v[144:145], 0, s[98:99]
	global_load_dwordx4 v[202:205], v[154:155], off
	global_load_dwordx4 v[206:209], v[154:155], off offset:256
	s_mov_b64 s[98:99], 0xa0000
	v_lshl_add_u64 v[154:155], v[144:145], 0, s[98:99]
	global_load_dwordx4 v[210:213], v[154:155], off
	global_load_dwordx4 v[214:217], v[154:155], off offset:256
	s_mov_b64 s[98:99], 0xb0000
	v_lshl_add_u64 v[154:155], v[144:145], 0, s[98:99]
	global_load_dwordx4 v[248:251], v[154:155], off
	global_load_dwordx4 v[252:255], v[154:155], off offset:256
	s_waitcnt vmcnt(15)
	s_nop 1
	v_mov_b32_e32 v152, v160
	v_mov_b32_e32 v153, v161
	v_mov_b32_e32 v154, v162
	v_mov_b32_e32 v155, v163
	s_mov_b64 s[2:3], 0x10000
	s_mov_b32 s4, s37
	s_mov_b64 s[10:11], s[6:7]
	s_mov_b64 s[8:9], s[42:43]
	s_waitcnt lgkmcnt(0)
	v_lshlrev_b32_e32 v156, 16, v152
	v_and_b32_e32 v157, 0xffff0000, v152
	v_lshlrev_b32_e32 v152, 16, v153
	v_and_b32_e32 v153, 0xffff0000, v153
	v_lshlrev_b32_e32 v158, 16, v154
	v_and_b32_e32 v159, 0xffff0000, v154
	v_lshlrev_b32_e32 v154, 16, v155
	v_and_b32_e32 v155, 0xffff0000, v155
	v_pk_add_f32 v[126:127], v[126:127], v[152:153]
	v_pk_add_f32 v[124:125], v[124:125], v[156:157]
	v_pk_add_f32 v[152:153], v[122:123], v[154:155]
	v_pk_add_f32 v[122:123], v[120:121], v[158:159]
	v_cvt_pk_bf16_f32 v120, v124, v125
	v_cvt_pk_bf16_f32 v121, v126, v127
	v_cvt_pk_bf16_f32 v122, v122, v123
	v_cvt_pk_bf16_f32 v123, v152, v153
	global_store_dwordx4 v[144:145], v[120:123], off
	s_waitcnt vmcnt(15)
; DI unsigned pack2(float a, float b) { f32x2 v = {a, b}; hwbf16x2 r = __builtin_convertvector(v, hwbf16x2); return __builtin_bit_cast(unsigned, r); }
; DI float bflo(unsigned w) { return __uint_as_float(w << 16); }
; DI float bfhi(unsigned w) { return __uint_as_float(w & 0xffff0000u); }
;     DI void operator()(const f32x4 (&acc)[2][2][4][2], const Unit& u, int wr, int wc, int fr, int fq) const {
;     ...
;         for (int ai = 0; ai < 2; ++ai)
; #pragma unroll
;             for (int m = 0; m < 4; ++m) { const size_t ro = (size_t)(row0 + ai * HALF + m * 16) * D + col0;
; #pragma unroll
;                 for (int bj = 0; bj < 2; ++bj) {
;                     f32x4 x0, x1;
;                     if constexpr (IB) { const u32x4 w = *(const u32x4*)((const bf16_t*)Xin + ro + bj * HALF);
;                         x0 = (f32x4){bflo(w[0]), bfhi(w[0]), bflo(w[1]), bfhi(w[1])}; x1 = (f32x4){bflo(w[2]), bfhi(w[2]), bflo(w[3]), bfhi(w[3])}; }
;                     else { x0 = *(const f32x4*)((const float*)Xin + ro + bj * HALF); x1 = *(const f32x4*)((const float*)Xin + ro + bj * HALF + 4); }
;                     x0 += acc[ai][bj][m][0] * sc[bj][0]; x1 += acc[ai][bj][m][1] * sc[bj][1];
;                     if constexpr (OB) { u32x4 o; o[0] = pack2(x0[0], x0[1]); o[1] = pack2(x0[2], x0[3]); o[2] = pack2(x1[0], x1[1]); o[3] = pack2(x1[2], x1[3]);
;                         *(u32x4*)((bf16_t*)Xout + ro + bj * HALF) = o; }
;                     else { *(f32x4*)((float*)Xout + ro + bj * HALF) = x0; *(f32x4*)((float*)Xout + ro + bj * HALF + 4) = x1; } } }
	s_nop 1
	v_mov_b32_e32 v120, v164
	v_mov_b32_e32 v121, v165
	v_mov_b32_e32 v122, v166
	v_mov_b32_e32 v123, v167
	s_waitcnt lgkmcnt(0)
	v_lshlrev_b32_e32 v124, 16, v120
	v_and_b32_e32 v125, 0xffff0000, v120
	v_lshlrev_b32_e32 v120, 16, v121
	v_and_b32_e32 v121, 0xffff0000, v121
	v_lshlrev_b32_e32 v126, 16, v122
	v_and_b32_e32 v127, 0xffff0000, v122
	v_lshlrev_b32_e32 v122, 16, v123
	v_and_b32_e32 v123, 0xffff0000, v123
	v_pk_add_f32 v[116:117], v[116:117], v[124:125]
	v_pk_add_f32 v[118:119], v[118:119], v[120:121]
	v_pk_add_f32 v[120:121], v[114:115], v[122:123]
	v_pk_add_f32 v[114:115], v[112:113], v[126:127]
	v_cvt_pk_bf16_f32 v112, v116, v117
	v_lshl_add_u64 v[116:117], v[144:145], 0, s[2:3]
	s_mov_b32 s2, 0x10000
	v_cvt_pk_bf16_f32 v113, v118, v119
	v_add_co_u32_e32 v118, vcc, s2, v144
	v_cvt_pk_bf16_f32 v114, v114, v115
	v_cvt_pk_bf16_f32 v115, v120, v121
	v_addc_co_u32_e32 v119, vcc, 0, v145, vcc
	global_store_dwordx4 v[144:145], v[112:115], off offset:256
	s_waitcnt vmcnt(15)
	s_nop 1
	v_mov_b32_e32 v112, v168
	v_mov_b32_e32 v113, v169
	v_mov_b32_e32 v114, v170
	v_mov_b32_e32 v115, v171
	s_mov_b64 s[2:3], 0x20000
	s_waitcnt lgkmcnt(0)
	v_lshlrev_b32_e32 v120, 16, v112
	v_and_b32_e32 v121, 0xffff0000, v112
	v_lshlrev_b32_e32 v112, 16, v113
	v_and_b32_e32 v113, 0xffff0000, v113
	v_lshlrev_b32_e32 v122, 16, v114
	v_and_b32_e32 v123, 0xffff0000, v114
	v_lshlrev_b32_e32 v114, 16, v115
	v_and_b32_e32 v115, 0xffff0000, v115
	v_pk_add_f32 v[110:111], v[110:111], v[112:113]
	v_pk_add_f32 v[108:109], v[108:109], v[120:121]
	v_pk_add_f32 v[112:113], v[106:107], v[114:115]
	v_pk_add_f32 v[106:107], v[104:105], v[122:123]
	v_cvt_pk_bf16_f32 v104, v108, v109
	v_cvt_pk_bf16_f32 v105, v110, v111
	v_cvt_pk_bf16_f32 v106, v106, v107
	v_cvt_pk_bf16_f32 v107, v112, v113
	global_store_dwordx4 v[118:119], v[104:107], off
	s_waitcnt vmcnt(15)
	s_nop 1
	v_mov_b32_e32 v104, v172
	v_mov_b32_e32 v105, v173
	v_mov_b32_e32 v106, v174
	v_mov_b32_e32 v107, v175
	s_waitcnt lgkmcnt(0)
	v_lshlrev_b32_e32 v108, 16, v104
	v_and_b32_e32 v109, 0xffff0000, v104
	v_lshlrev_b32_e32 v104, 16, v105
	v_and_b32_e32 v105, 0xffff0000, v105
	v_lshlrev_b32_e32 v110, 16, v106
	v_and_b32_e32 v111, 0xffff0000, v106
	v_lshlrev_b32_e32 v106, 16, v107
	v_and_b32_e32 v107, 0xffff0000, v107
	v_pk_add_f32 v[100:101], v[100:101], v[108:109]
	v_pk_add_f32 v[102:103], v[102:103], v[104:105]
	v_pk_add_f32 v[104:105], v[98:99], v[106:107]
	v_pk_add_f32 v[98:99], v[96:97], v[110:111]
	v_cvt_pk_bf16_f32 v96, v100, v101
	v_lshl_add_u64 v[100:101], v[144:145], 0, s[2:3]
	s_mov_b32 s2, 0x20000
	v_cvt_pk_bf16_f32 v97, v102, v103
	v_add_co_u32_e32 v102, vcc, s2, v144
	v_cvt_pk_bf16_f32 v98, v98, v99
	v_cvt_pk_bf16_f32 v99, v104, v105
	v_addc_co_u32_e32 v103, vcc, 0, v145, vcc
	global_store_dwordx4 v[116:117], v[96:99], off offset:256
	s_waitcnt vmcnt(15)
	s_nop 1
	v_mov_b32_e32 v96, v176
	v_mov_b32_e32 v97, v177
	v_mov_b32_e32 v98, v178
	v_mov_b32_e32 v99, v179
	s_mov_b64 s[2:3], 0x30000
	s_waitcnt lgkmcnt(0)
	v_lshlrev_b32_e32 v104, 16, v96
	v_and_b32_e32 v105, 0xffff0000, v96
	v_lshlrev_b32_e32 v96, 16, v97
	v_and_b32_e32 v97, 0xffff0000, v97
	v_lshlrev_b32_e32 v106, 16, v98
	v_and_b32_e32 v107, 0xffff0000, v98
	v_lshlrev_b32_e32 v98, 16, v99
	v_and_b32_e32 v99, 0xffff0000, v99
	v_pk_add_f32 v[94:95], v[94:95], v[96:97]
	v_pk_add_f32 v[92:93], v[92:93], v[104:105]
	v_pk_add_f32 v[96:97], v[90:91], v[98:99]
	v_pk_add_f32 v[90:91], v[88:89], v[106:107]
	v_cvt_pk_bf16_f32 v88, v92, v93
	v_cvt_pk_bf16_f32 v89, v94, v95
	v_cvt_pk_bf16_f32 v90, v90, v91
	v_cvt_pk_bf16_f32 v91, v96, v97
	global_store_dwordx4 v[102:103], v[88:91], off
	s_waitcnt vmcnt(15)
	s_nop 1
	v_mov_b32_e32 v88, v180
	v_mov_b32_e32 v89, v181
	v_mov_b32_e32 v90, v182
	v_mov_b32_e32 v91, v183
	s_waitcnt lgkmcnt(0)
	v_lshlrev_b32_e32 v92, 16, v88
	v_and_b32_e32 v93, 0xffff0000, v88
	v_lshlrev_b32_e32 v88, 16, v89
	v_and_b32_e32 v89, 0xffff0000, v89
	v_lshlrev_b32_e32 v94, 16, v90
	v_and_b32_e32 v95, 0xffff0000, v90
	v_lshlrev_b32_e32 v90, 16, v91
	v_and_b32_e32 v91, 0xffff0000, v91
	v_pk_add_f32 v[86:87], v[86:87], v[88:89]
	v_pk_add_f32 v[84:85], v[84:85], v[92:93]
	v_pk_add_f32 v[88:89], v[82:83], v[90:91]
	v_pk_add_f32 v[82:83], v[80:81], v[94:95]
	v_cvt_pk_bf16_f32 v80, v84, v85
	v_cvt_pk_bf16_f32 v81, v86, v87
	v_cvt_pk_bf16_f32 v82, v82, v83
	v_cvt_pk_bf16_f32 v83, v88, v89
	global_store_dwordx4 v[100:101], v[80:83], off offset:256
	s_nop 1
	v_lshl_add_u64 v[80:81], v[144:145], 0, s[2:3]
	s_mov_b32 s2, 0x30000
	v_add_co_u32_e32 v86, vcc, s2, v144
	s_mov_b64 s[2:3], 0x80000
	s_nop 0
	v_addc_co_u32_e32 v87, vcc, 0, v145, vcc
	s_waitcnt vmcnt(15)
	s_nop 1
	v_mov_b32_e32 v82, v184
	v_mov_b32_e32 v83, v185
	v_mov_b32_e32 v84, v186
	v_mov_b32_e32 v85, v187
	s_waitcnt lgkmcnt(0)
	v_lshlrev_b32_e32 v88, 16, v82
	v_and_b32_e32 v89, 0xffff0000, v82
	v_lshlrev_b32_e32 v82, 16, v83
	v_and_b32_e32 v83, 0xffff0000, v83
	v_lshlrev_b32_e32 v90, 16, v84
	v_and_b32_e32 v91, 0xffff0000, v84
	v_lshlrev_b32_e32 v84, 16, v85
	v_and_b32_e32 v85, 0xffff0000, v85
	v_pk_add_f32 v[78:79], v[78:79], v[82:83]
	v_pk_add_f32 v[76:77], v[76:77], v[88:89]
	v_pk_add_f32 v[82:83], v[74:75], v[84:85]
	v_pk_add_f32 v[74:75], v[72:73], v[90:91]
	v_cvt_pk_bf16_f32 v72, v76, v77
	v_cvt_pk_bf16_f32 v73, v78, v79
	v_cvt_pk_bf16_f32 v74, v74, v75
	v_cvt_pk_bf16_f32 v75, v82, v83
	global_store_dwordx4 v[86:87], v[72:75], off
	s_waitcnt vmcnt(15)
	s_nop 1
	v_mov_b32_e32 v72, v188
	v_mov_b32_e32 v73, v189
	v_mov_b32_e32 v74, v190
	v_mov_b32_e32 v75, v191
	s_waitcnt lgkmcnt(0)
; DI unsigned pack2(float a, float b) { f32x2 v = {a, b}; hwbf16x2 r = __builtin_convertvector(v, hwbf16x2); return __builtin_bit_cast(unsigned, r); }
; DI float bflo(unsigned w) { return __uint_as_float(w << 16); }
; DI float bfhi(unsigned w) { return __uint_as_float(w & 0xffff0000u); }
;     DI void operator()(const f32x4 (&acc)[2][2][4][2], const Unit& u, int wr, int wc, int fr, int fq) const {
;     ...
;         for (int ai = 0; ai < 2; ++ai)
; #pragma unroll
;             for (int m = 0; m < 4; ++m) { const size_t ro = (size_t)(row0 + ai * HALF + m * 16) * D + col0;
; #pragma unroll
;                 for (int bj = 0; bj < 2; ++bj) {
;                     f32x4 x0, x1;
;                     if constexpr (IB) { const u32x4 w = *(const u32x4*)((const bf16_t*)Xin + ro + bj * HALF);
;                         x0 = (f32x4){bflo(w[0]), bfhi(w[0]), bflo(w[1]), bfhi(w[1])}; x1 = (f32x4){bflo(w[2]), bfhi(w[2]), bflo(w[3]), bfhi(w[3])}; }
;                     else { x0 = *(const f32x4*)((const float*)Xin + ro + bj * HALF); x1 = *(const f32x4*)((const float*)Xin + ro + bj * HALF + 4); }
;                     x0 += acc[ai][bj][m][0] * sc[bj][0]; x1 += acc[ai][bj][m][1] * sc[bj][1];
;                     if constexpr (OB) { u32x4 o; o[0] = pack2(x0[0], x0[1]); o[1] = pack2(x0[2], x0[3]); o[2] = pack2(x1[0], x1[1]); o[3] = pack2(x1[2], x1[3]);
;                         *(u32x4*)((bf16_t*)Xout + ro + bj * HALF) = o; }
;                     else { *(f32x4*)((float*)Xout + ro + bj * HALF) = x0; *(f32x4*)((float*)Xout + ro + bj * HALF + 4) = x1; } } }
	v_lshlrev_b32_e32 v76, 16, v72
	v_and_b32_e32 v77, 0xffff0000, v72
	v_lshlrev_b32_e32 v72, 16, v73
	v_and_b32_e32 v73, 0xffff0000, v73
	v_lshlrev_b32_e32 v78, 16, v74
	v_and_b32_e32 v79, 0xffff0000, v74
	v_lshlrev_b32_e32 v74, 16, v75
	v_and_b32_e32 v75, 0xffff0000, v75
	v_pk_add_f32 v[70:71], v[70:71], v[72:73]
	v_pk_add_f32 v[68:69], v[68:69], v[76:77]
	v_pk_add_f32 v[72:73], v[66:67], v[74:75]
	v_pk_add_f32 v[66:67], v[64:65], v[78:79]
	v_cvt_pk_bf16_f32 v64, v68, v69
	v_cvt_pk_bf16_f32 v65, v70, v71
	v_cvt_pk_bf16_f32 v66, v66, v67
	v_cvt_pk_bf16_f32 v67, v72, v73
	global_store_dwordx4 v[80:81], v[64:67], off offset:256
	s_nop 1
	v_lshl_add_u64 v[64:65], v[144:145], 0, s[2:3]
	s_mov_b32 s2, 0x80000
	v_add_co_u32_e32 v70, vcc, s2, v144
	s_mov_b64 s[2:3], 0x90000
	s_nop 0
	v_addc_co_u32_e32 v71, vcc, 0, v145, vcc
	s_waitcnt vmcnt(15)
	s_nop 1
	v_mov_b32_e32 v66, v192
	v_mov_b32_e32 v67, v193
	v_mov_b32_e32 v68, v194
	v_mov_b32_e32 v69, v195
	s_waitcnt lgkmcnt(0)
	v_lshlrev_b32_e32 v72, 16, v66
	v_and_b32_e32 v73, 0xffff0000, v66
	v_lshlrev_b32_e32 v66, 16, v67
	v_and_b32_e32 v67, 0xffff0000, v67
	v_lshlrev_b32_e32 v74, 16, v68
	v_and_b32_e32 v75, 0xffff0000, v68
	v_lshlrev_b32_e32 v68, 16, v69
	v_and_b32_e32 v69, 0xffff0000, v69
	v_pk_add_f32 v[62:63], v[62:63], v[66:67]
	v_pk_add_f32 v[60:61], v[60:61], v[72:73]
	v_pk_add_f32 v[66:67], v[58:59], v[68:69]
	v_pk_add_f32 v[58:59], v[56:57], v[74:75]
	v_cvt_pk_bf16_f32 v56, v60, v61
	v_cvt_pk_bf16_f32 v57, v62, v63
	v_cvt_pk_bf16_f32 v58, v58, v59
	v_cvt_pk_bf16_f32 v59, v66, v67
	global_store_dwordx4 v[70:71], v[56:59], off
	s_waitcnt vmcnt(15)
	s_nop 1
	v_mov_b32_e32 v56, v198
	v_mov_b32_e32 v57, v199
	v_mov_b32_e32 v58, v200
	v_mov_b32_e32 v59, v201
	s_waitcnt lgkmcnt(0)
	v_lshlrev_b32_e32 v60, 16, v56
	v_and_b32_e32 v61, 0xffff0000, v56
	v_lshlrev_b32_e32 v56, 16, v57
	v_and_b32_e32 v57, 0xffff0000, v57
	v_lshlrev_b32_e32 v62, 16, v58
	v_and_b32_e32 v63, 0xffff0000, v58
	v_lshlrev_b32_e32 v58, 16, v59
	v_and_b32_e32 v59, 0xffff0000, v59
	v_pk_add_f32 v[54:55], v[54:55], v[56:57]
	v_pk_add_f32 v[52:53], v[52:53], v[60:61]
	v_pk_add_f32 v[56:57], v[50:51], v[58:59]
	v_pk_add_f32 v[50:51], v[48:49], v[62:63]
	v_cvt_pk_bf16_f32 v48, v52, v53
	v_cvt_pk_bf16_f32 v49, v54, v55
	v_cvt_pk_bf16_f32 v50, v50, v51
	v_cvt_pk_bf16_f32 v51, v56, v57
	global_store_dwordx4 v[64:65], v[48:51], off offset:256
	s_nop 1
	v_lshl_add_u64 v[48:49], v[144:145], 0, s[2:3]
	s_mov_b32 s2, 0x90000
	v_add_co_u32_e32 v54, vcc, s2, v144
	s_mov_b64 s[2:3], 0xa0000
	s_nop 0
	v_addc_co_u32_e32 v55, vcc, 0, v145, vcc
	s_waitcnt vmcnt(15)
	s_nop 1
	v_mov_b32_e32 v50, v202
	v_mov_b32_e32 v51, v203
	v_mov_b32_e32 v52, v204
	v_mov_b32_e32 v53, v205
	s_waitcnt lgkmcnt(0)
	v_lshlrev_b32_e32 v56, 16, v50
	v_and_b32_e32 v57, 0xffff0000, v50
	v_lshlrev_b32_e32 v50, 16, v51
	v_and_b32_e32 v51, 0xffff0000, v51
	v_lshlrev_b32_e32 v58, 16, v52
	v_and_b32_e32 v59, 0xffff0000, v52
	v_lshlrev_b32_e32 v52, 16, v53
	v_and_b32_e32 v53, 0xffff0000, v53
	v_pk_add_f32 v[46:47], v[46:47], v[50:51]
	v_pk_add_f32 v[44:45], v[44:45], v[56:57]
	v_pk_add_f32 v[50:51], v[42:43], v[52:53]
	v_pk_add_f32 v[42:43], v[40:41], v[58:59]
	v_cvt_pk_bf16_f32 v40, v44, v45
	v_cvt_pk_bf16_f32 v41, v46, v47
	v_cvt_pk_bf16_f32 v42, v42, v43
	v_cvt_pk_bf16_f32 v43, v50, v51
	global_store_dwordx4 v[54:55], v[40:43], off
	s_waitcnt vmcnt(15)
	s_nop 1
	v_mov_b32_e32 v40, v206
	v_mov_b32_e32 v41, v207
	v_mov_b32_e32 v42, v208
	v_mov_b32_e32 v43, v209
	s_waitcnt lgkmcnt(0)
; DI unsigned pack2(float a, float b) { f32x2 v = {a, b}; hwbf16x2 r = __builtin_convertvector(v, hwbf16x2); return __builtin_bit_cast(unsigned, r); }
; DI float bflo(unsigned w) { return __uint_as_float(w << 16); }
; DI float bfhi(unsigned w) { return __uint_as_float(w & 0xffff0000u); }
;     DI const char* a(const Unit& u) const { return (const char*)(A + (size_t)u.pm * BM * lda); }
;     DI const char* a(const Unit& u) const { return (const char*)(A + (size_t)u.pm * BM * 2048 + (u.pn >> 1) * 512); }
;     DI void operator()(const f32x4 (&acc)[2][2][4][2], const Unit& u, int wr, int wc, int fr, int fq) const {
;     ...
;         for (int ai = 0; ai < 2; ++ai)
; #pragma unroll
;             for (int m = 0; m < 4; ++m) { const size_t ro = (size_t)(row0 + ai * HALF + m * 16) * D + col0;
; #pragma unroll
;                 for (int bj = 0; bj < 2; ++bj) {
;                     f32x4 x0, x1;
;                     if constexpr (IB) { const u32x4 w = *(const u32x4*)((const bf16_t*)Xin + ro + bj * HALF);
;                         x0 = (f32x4){bflo(w[0]), bfhi(w[0]), bflo(w[1]), bfhi(w[1])}; x1 = (f32x4){bflo(w[2]), bfhi(w[2]), bflo(w[3]), bfhi(w[3])}; }
;                     else { x0 = *(const f32x4*)((const float*)Xin + ro + bj * HALF); x1 = *(const f32x4*)((const float*)Xin + ro + bj * HALF + 4); }
;                     x0 += acc[ai][bj][m][0] * sc[bj][0]; x1 += acc[ai][bj][m][1] * sc[bj][1];
;                     if constexpr (OB) { u32x4 o; o[0] = pack2(x0[0], x0[1]); o[1] = pack2(x0[2], x0[3]); o[2] = pack2(x1[0], x1[1]); o[3] = pack2(x1[2], x1[3]);
;                         *(u32x4*)((bf16_t*)Xout + ro + bj * HALF) = o; }
;                     else { *(f32x4*)((float*)Xout + ro + bj * HALF) = x0; *(f32x4*)((float*)Xout + ro + bj * HALF + 4) = x1; } } }
; template <class Map, class Epi>
; DI void gemm_phase(LAS unsigned char* lds, const Map& MP, const Epi& E, const int nM, const int nN, const int K, const int lda, const int ldb) {
;     ...
;         if (!has_next) break;
; #pragma unroll
;         for (int a = 0; a < 2; ++a)
; #pragma unroll
;             for (int b = 0; b < 2; ++b)
; #pragma unroll
;                 for (int m = 0; m < 4; ++m)
; #pragma unroll
;                     for (int n = 0; n < 2; ++n) acc[a][b][m][n] = (f32x4){0.f, 0.f, 0.f, 0.f};
;         cur = nxt; cA = nA; cB = nB; ++ui;
;     }
;     PG8_WAIT_V(0);
;     if (wr == 0) PG8_BAR;
;     PG8_BAR;
	v_lshlrev_b32_e32 v44, 16, v40
	v_and_b32_e32 v45, 0xffff0000, v40
	v_lshlrev_b32_e32 v40, 16, v41
	v_and_b32_e32 v41, 0xffff0000, v41
	v_lshlrev_b32_e32 v46, 16, v42
	v_and_b32_e32 v47, 0xffff0000, v42
	v_lshlrev_b32_e32 v42, 16, v43
	v_and_b32_e32 v43, 0xffff0000, v43
	v_pk_add_f32 v[38:39], v[38:39], v[40:41]
	v_pk_add_f32 v[36:37], v[36:37], v[44:45]
	v_pk_add_f32 v[40:41], v[34:35], v[42:43]
	v_pk_add_f32 v[34:35], v[32:33], v[46:47]
	v_cvt_pk_bf16_f32 v32, v36, v37
	v_cvt_pk_bf16_f32 v33, v38, v39
	v_cvt_pk_bf16_f32 v34, v34, v35
	v_cvt_pk_bf16_f32 v35, v40, v41
	global_store_dwordx4 v[48:49], v[32:35], off offset:256
	s_nop 1
	v_lshl_add_u64 v[32:33], v[144:145], 0, s[2:3]
	s_mov_b32 s2, 0xa0000
	v_add_co_u32_e32 v38, vcc, s2, v144
	s_mov_b64 s[2:3], 0xb0000
	s_nop 0
	v_addc_co_u32_e32 v39, vcc, 0, v145, vcc
	s_waitcnt vmcnt(15)
	s_nop 1
	v_mov_b32_e32 v34, v210
	v_mov_b32_e32 v35, v211
	v_mov_b32_e32 v36, v212
	v_mov_b32_e32 v37, v213
	s_waitcnt lgkmcnt(0)
	v_lshlrev_b32_e32 v40, 16, v34
	v_and_b32_e32 v41, 0xffff0000, v34
	v_lshlrev_b32_e32 v34, 16, v35
	v_and_b32_e32 v35, 0xffff0000, v35
	v_lshlrev_b32_e32 v42, 16, v36
	v_and_b32_e32 v43, 0xffff0000, v36
	v_lshlrev_b32_e32 v36, 16, v37
	v_and_b32_e32 v37, 0xffff0000, v37
	v_pk_add_f32 v[30:31], v[30:31], v[34:35]
	v_pk_add_f32 v[28:29], v[28:29], v[40:41]
	v_pk_add_f32 v[34:35], v[26:27], v[36:37]
	v_pk_add_f32 v[26:27], v[24:25], v[42:43]
	v_cvt_pk_bf16_f32 v24, v28, v29
	v_cvt_pk_bf16_f32 v25, v30, v31
	v_cvt_pk_bf16_f32 v26, v26, v27
	v_cvt_pk_bf16_f32 v27, v34, v35
	global_store_dwordx4 v[38:39], v[24:27], off
	s_waitcnt vmcnt(15)
	s_nop 1
	v_mov_b32_e32 v24, v214
	v_mov_b32_e32 v25, v215
	v_mov_b32_e32 v26, v216
	v_mov_b32_e32 v27, v217
	s_waitcnt lgkmcnt(0)
	v_lshlrev_b32_e32 v28, 16, v24
	v_and_b32_e32 v29, 0xffff0000, v24
	v_lshlrev_b32_e32 v24, 16, v25
	v_and_b32_e32 v25, 0xffff0000, v25
	v_lshlrev_b32_e32 v30, 16, v26
	v_and_b32_e32 v31, 0xffff0000, v26
	v_lshlrev_b32_e32 v26, 16, v27
	v_and_b32_e32 v27, 0xffff0000, v27
	v_pk_add_f32 v[22:23], v[22:23], v[24:25]
	v_pk_add_f32 v[20:21], v[20:21], v[28:29]
	v_pk_add_f32 v[24:25], v[18:19], v[26:27]
	v_pk_add_f32 v[18:19], v[16:17], v[30:31]
	v_cvt_pk_bf16_f32 v16, v20, v21
	v_cvt_pk_bf16_f32 v17, v22, v23
	v_cvt_pk_bf16_f32 v18, v18, v19
	v_cvt_pk_bf16_f32 v19, v24, v25
	global_store_dwordx4 v[32:33], v[16:19], off offset:256
	s_nop 1
	v_lshl_add_u64 v[16:17], v[144:145], 0, s[2:3]
	s_mov_b32 s2, 0xb0000
	v_add_co_u32_e32 v22, vcc, s2, v144
	s_mov_b32 s2, s55
	s_nop 0
	v_addc_co_u32_e32 v23, vcc, 0, v145, vcc
	s_waitcnt vmcnt(15)
	s_nop 1
	v_mov_b32_e32 v18, v248
	v_mov_b32_e32 v19, v249
	v_mov_b32_e32 v20, v250
	v_mov_b32_e32 v21, v251
	s_and_b64 vcc, exec, s[40:41]
	s_waitcnt lgkmcnt(0)
	v_lshlrev_b32_e32 v24, 16, v18
	v_and_b32_e32 v25, 0xffff0000, v18
	v_lshlrev_b32_e32 v18, 16, v19
	v_and_b32_e32 v19, 0xffff0000, v19
	v_lshlrev_b32_e32 v26, 16, v20
	v_and_b32_e32 v27, 0xffff0000, v20
	v_lshlrev_b32_e32 v20, 16, v21
	v_and_b32_e32 v21, 0xffff0000, v21
	v_pk_add_f32 v[14:15], v[14:15], v[18:19]
	v_pk_add_f32 v[12:13], v[12:13], v[24:25]
	v_pk_add_f32 v[18:19], v[10:11], v[20:21]
	v_pk_add_f32 v[10:11], v[8:9], v[26:27]
	v_cvt_pk_bf16_f32 v8, v12, v13
	v_cvt_pk_bf16_f32 v9, v14, v15
	v_cvt_pk_bf16_f32 v10, v10, v11
	v_cvt_pk_bf16_f32 v11, v18, v19
	global_store_dwordx4 v[22:23], v[8:11], off
	s_waitcnt vmcnt(15)
	s_nop 1
	v_mov_b32_e32 v8, v252
	v_mov_b32_e32 v9, v253
	v_mov_b32_e32 v10, v254
	v_mov_b32_e32 v11, v255
	s_waitcnt lgkmcnt(0)
	v_lshlrev_b32_e32 v12, 16, v8
	v_and_b32_e32 v13, 0xffff0000, v8
	v_lshlrev_b32_e32 v8, 16, v9
	v_and_b32_e32 v9, 0xffff0000, v9
	v_lshlrev_b32_e32 v14, 16, v10
	v_and_b32_e32 v15, 0xffff0000, v10
	v_lshlrev_b32_e32 v10, 16, v11
	v_and_b32_e32 v11, 0xffff0000, v11
	v_pk_add_f32 v[6:7], v[6:7], v[8:9]
	v_pk_add_f32 v[4:5], v[4:5], v[12:13]
	v_pk_add_f32 v[8:9], v[2:3], v[10:11]
	v_pk_add_f32 v[2:3], v[0:1], v[14:15]
	v_cvt_pk_bf16_f32 v0, v4, v5
	v_cvt_pk_bf16_f32 v1, v6, v7
	v_cvt_pk_bf16_f32 v2, v2, v3
	v_cvt_pk_bf16_f32 v3, v8, v9
	global_store_dwordx4 v[16:17], v[0:3], off offset:256
	s_cbranch_vccz .LBB1_543
	s_waitcnt vmcnt(0)
	s_cmpk_gt_u32 s17, 0xff
	s_cbranch_scc1 .LBB1_554
	s_barrier

; #define PG8_STAGE(bufoff, gbase, voff) do { _Pragma("unroll") for (int _i = 0; _i < 2; ++_i) \
;         __builtin_amdgcn_global_load_lds((const unsigned*)((const char*)(gbase) + (voff)[_i]), (LAS unsigned*)(lds + (bufoff) + ldsw + _i * 8192), 16, 0, 0); } while (0)
; #define PG8_LDA(dst, b, h) do { _Pragma("unroll") for (int m = 0; m < 4; ++m) _Pragma("unroll") for (int k = 0; k < 2; ++k) dst[m][k] = *(const LAS bf16x8*)(lds + PG8_SA(b, h) + aoff + m * 2048 + k * 1024); } while (0)
; #define PG8_LDB(dst, b, h) do { _Pragma("unroll") for (int n = 0; n < 2; ++n) _Pragma("unroll") for (int k = 0; k < 2; ++k) dst[n][k] = *(const LAS bf16x8*)(lds + PG8_SB(b, h) + boff + n * 2048 + k * 1024); } while (0)
; #define PG8_MMA(ai, bj, At, Bt) do { __builtin_amdgcn_s_setprio(1); _Pragma("unroll") for (int m = 0; m < 4; ++m) _Pragma("unroll") for (int n = 0; n < 2; ++n) _Pragma("unroll") for (int k = 0; k < 2; ++k) \
;         acc[ai][bj][m][n] = __builtin_amdgcn_mfma_f32_16x16x32_bf16(Bt[n][k], At[m][k], acc[ai][bj][m][n], 0, 0, 0); __builtin_amdgcn_s_setprio(0); } while (0)
; #define PG8_WAIT_V(n) asm volatile("s_waitcnt vmcnt(" #n ")" ::: "memory")
; #define PG8_WAIT_L(n) asm volatile("s_waitcnt lgkmcnt(" #n ")" ::: "memory")
; template <class Map, class Epi>
; DI void gemm_phase(LAS unsigned char* lds, const Map& MP, const Epi& E, const int nM, const int nN, const int K, const int lda, const int ldb) {
;     ...
;         for (int t = 0; t < nt; t += 2) {
;             const bool last = (t == nt - 2);
;             const char* a1 = cA + (size_t)(t + 1) * kstep;
;             const char* a2 = last ? nA : cA + (size_t)(t + 2) * kstep; const char* b2 = last ? nB : cB + (size_t)(t + 2) * kstep;
;             const char* a3 = a2 + kstep; const char* b3 = b2 + kstep;
;             PG8_LDB(B0, 0, 0); PG8_SCHED; PG8_LDA(At, 0, 0); PG8_STAGE(PG8_SA(1, 1), a1 + hstepA, voffA);
;             PG8_WAIT_L(8); PG8_BAR; PG8_WAIT_L(0); PG8_MMA(0, 0, At, B0); PG8_BAR; PG8_SCHED;
;             PG8_LDB(B1, 0, 1); PG8_STAGE(PG8_SB(0, 0), b2, voffB);
;             PG8_BAR; PG8_WAIT_L(0); PG8_MMA(0, 1, At, B1); PG8_BAR;
;             PG8_LDA(At, 0, 1); PG8_STAGE(PG8_SA(0, 0), a2, voffA);
;             PG8_BAR; PG8_WAIT_L(0); PG8_MMA(1, 0, At, B0); PG8_BAR; PG8_SCHED;
;             PG8_STAGE(PG8_SB(0, 1), b2 + hstepB, voffB);
;             PG8_WAIT_V(6); PG8_BAR; PG8_MMA(1, 1, At, B1); PG8_BAR;
.LBB1_693:
	s_add_u32 s3, s20, 0xfff80080
	s_addc_u32 s22, s21, -1
	s_cmp_eq_u32 s54, 28
	s_cselect_b32 s25, s15, s22
	s_cselect_b32 s24, s48, s3
	s_cselect_b32 s23, s13, s53
	s_cselect_b32 s22, s49, s52
	s_add_i32 m0, s31, 0xc000
	ds_read_b128 v[166:169], v148
	ds_read_b128 v[170:173], v148 offset:1024
	ds_read_b128 v[174:177], v148 offset:2048
	ds_read_b128 v[178:181], v148 offset:3072
	ds_read_b128 v[182:185], v148 offset:4096
	ds_read_b128 v[186:189], v148 offset:5120
	ds_read_b128 v[190:193], v148 offset:6144
	ds_read_b128 v[198:201], v148 offset:7168
	global_load_lds_dwordx4 v138, s[20:21]
	s_add_i32 m0, s31, 0xe000
	s_nop 0
	global_load_lds_dwordx4 v136, s[20:21]
	s_waitcnt lgkmcnt(8)
	s_setprio 1
	s_barrier
	s_waitcnt lgkmcnt(7)
	v_mfma_f32_16x16x32_bf16 v[124:127], v[150:153], v[166:169], v[124:127]
	v_mfma_f32_16x16x32_bf16 v[120:123], v[158:161], v[166:169], v[120:123]
	s_waitcnt lgkmcnt(5)
	v_mfma_f32_16x16x32_bf16 v[116:119], v[150:153], v[174:177], v[116:119]
	v_mfma_f32_16x16x32_bf16 v[112:115], v[158:161], v[174:177], v[112:115]
	s_waitcnt lgkmcnt(3)
	v_mfma_f32_16x16x32_bf16 v[100:103], v[150:153], v[182:185], v[100:103]
	v_mfma_f32_16x16x32_bf16 v[96:99], v[158:161], v[182:185], v[96:99]
	s_waitcnt lgkmcnt(1)
	v_mfma_f32_16x16x32_bf16 v[84:87], v[150:153], v[190:193], v[84:87]
	v_mfma_f32_16x16x32_bf16 v[80:83], v[158:161], v[190:193], v[80:83]
	v_mfma_f32_16x16x32_bf16 v[124:127], v[154:157], v[170:173], v[124:127]
	s_add_i32 s3, s44, s29
	v_mfma_f32_16x16x32_bf16 v[120:123], v[162:165], v[170:173], v[120:123]
	v_lshl_add_u64 v[194:195], s[22:23], 0, v[132:133]
	v_mfma_f32_16x16x32_bf16 v[116:119], v[154:157], v[178:181], v[116:119]
	v_lshl_add_u64 v[218:219], s[22:23], 0, v[128:129]
	v_mfma_f32_16x16x32_bf16 v[112:115], v[162:165], v[178:181], v[112:115]
	v_mfma_f32_16x16x32_bf16 v[100:103], v[154:157], v[186:189], v[100:103]
	v_mfma_f32_16x16x32_bf16 v[96:99], v[162:165], v[186:189], v[96:99]
	s_waitcnt lgkmcnt(0)
	v_mfma_f32_16x16x32_bf16 v[84:87], v[154:157], v[198:201], v[84:87]
	s_setprio 0
	v_mfma_f32_16x16x32_bf16 v[80:83], v[162:165], v[198:201], v[80:83]
	s_barrier
	s_mov_b32 m0, s3
	ds_read_b128 v[202:205], v149
	ds_read_b128 v[206:209], v149 offset:1024
	ds_read_b128 v[210:213], v149 offset:2048
	ds_read_b128 v[214:217], v149 offset:3072
	global_load_lds_dwordx4 v[194:195], off
	s_add_i32 m0, s3, 0x2000
	s_nop 0
	global_load_lds_dwordx4 v[218:219], off
	s_setprio 1
	s_barrier
	s_waitcnt lgkmcnt(3)
	v_mfma_f32_16x16x32_bf16 v[108:111], v[202:205], v[166:169], v[108:111]
	s_waitcnt lgkmcnt(1)
	v_mfma_f32_16x16x32_bf16 v[104:107], v[210:213], v[166:169], v[104:107]
	v_mfma_f32_16x16x32_bf16 v[92:95], v[202:205], v[174:177], v[92:95]
	v_mfma_f32_16x16x32_bf16 v[88:91], v[210:213], v[174:177], v[88:91]
	v_mfma_f32_16x16x32_bf16 v[76:79], v[202:205], v[182:185], v[76:79]
	v_mfma_f32_16x16x32_bf16 v[72:75], v[210:213], v[182:185], v[72:75]
	v_mfma_f32_16x16x32_bf16 v[68:71], v[202:205], v[190:193], v[68:71]
	v_mfma_f32_16x16x32_bf16 v[64:67], v[210:213], v[190:193], v[64:67]
	v_mfma_f32_16x16x32_bf16 v[108:111], v[206:209], v[170:173], v[108:111]
	v_lshl_add_u64 v[222:223], s[24:25], 0, v[130:131]
	s_mov_b32 m0, s31
	s_waitcnt lgkmcnt(0)
	v_mfma_f32_16x16x32_bf16 v[104:107], v[214:217], v[170:173], v[104:107]
	v_lshl_add_u64 v[220:221], s[24:25], 0, v[134:135]
	v_mfma_f32_16x16x32_bf16 v[92:95], v[206:209], v[178:181], v[92:95]
	v_mfma_f32_16x16x32_bf16 v[88:91], v[214:217], v[178:181], v[88:91]
	v_mfma_f32_16x16x32_bf16 v[76:79], v[206:209], v[186:189], v[76:79]
	v_mfma_f32_16x16x32_bf16 v[72:75], v[214:217], v[186:189], v[72:75]
	v_mfma_f32_16x16x32_bf16 v[68:71], v[206:209], v[198:201], v[68:71]
	s_setprio 0
	v_mfma_f32_16x16x32_bf16 v[64:67], v[214:217], v[198:201], v[64:67]
	s_barrier
	ds_read_b128 v[166:169], v148 offset:16384
	ds_read_b128 v[170:173], v148 offset:17408
	ds_read_b128 v[174:177], v148 offset:18432
	ds_read_b128 v[178:181], v148 offset:19456
	ds_read_b128 v[182:185], v148 offset:20480
	ds_read_b128 v[186:189], v148 offset:21504
	ds_read_b128 v[190:193], v148 offset:22528
	ds_read_b128 v[198:201], v148 offset:23552
	global_load_lds_dwordx4 v[220:221], off
	s_mov_b32 m0, s11
	s_nop 0
	global_load_lds_dwordx4 v[222:223], off
	s_waitcnt vmcnt(10)
	s_setprio 1
	s_barrier
	s_waitcnt lgkmcnt(7)
	v_mfma_f32_16x16x32_bf16 v[60:63], v[150:153], v[166:169], v[60:63]
	v_mfma_f32_16x16x32_bf16 v[56:59], v[158:161], v[166:169], v[56:59]
	s_waitcnt lgkmcnt(5)
	v_mfma_f32_16x16x32_bf16 v[52:55], v[150:153], v[174:177], v[52:55]
	v_mfma_f32_16x16x32_bf16 v[48:51], v[158:161], v[174:177], v[48:51]
	s_waitcnt lgkmcnt(3)
	v_mfma_f32_16x16x32_bf16 v[36:39], v[150:153], v[182:185], v[36:39]
	v_mfma_f32_16x16x32_bf16 v[32:35], v[158:161], v[182:185], v[32:35]
	s_waitcnt lgkmcnt(1)
	v_mfma_f32_16x16x32_bf16 v[20:23], v[150:153], v[190:193], v[20:23]
	v_mfma_f32_16x16x32_bf16 v[16:19], v[158:161], v[190:193], v[16:19]
	v_mfma_f32_16x16x32_bf16 v[60:63], v[154:157], v[170:173], v[60:63]
	s_add_u32 s56, s22, 0x80000
	s_addc_u32 s57, s23, 0
	v_mfma_f32_16x16x32_bf16 v[56:59], v[162:165], v[170:173], v[56:59]
	s_add_i32 s3, s45, s29
	v_mfma_f32_16x16x32_bf16 v[52:55], v[154:157], v[178:181], v[52:55]
	v_mfma_f32_16x16x32_bf16 v[48:51], v[162:165], v[178:181], v[48:51]
	v_mfma_f32_16x16x32_bf16 v[36:39], v[154:157], v[186:189], v[36:39]
	v_mfma_f32_16x16x32_bf16 v[32:35], v[162:165], v[186:189], v[32:35]
	s_waitcnt lgkmcnt(0)
	v_mfma_f32_16x16x32_bf16 v[20:23], v[154:157], v[198:201], v[20:23]
	s_setprio 0
	v_mfma_f32_16x16x32_bf16 v[16:19], v[162:165], v[198:201], v[16:19]
	s_barrier
; #define PG8_STAGE(bufoff, gbase, voff) do { _Pragma("unroll") for (int _i = 0; _i < 2; ++_i) \
;         __builtin_amdgcn_global_load_lds((const unsigned*)((const char*)(gbase) + (voff)[_i]), (LAS unsigned*)(lds + (bufoff) + ldsw + _i * 8192), 16, 0, 0); } while (0)
; #define PG8_LDA(dst, b, h) do { _Pragma("unroll") for (int m = 0; m < 4; ++m) _Pragma("unroll") for (int k = 0; k < 2; ++k) dst[m][k] = *(const LAS bf16x8*)(lds + PG8_SA(b, h) + aoff + m * 2048 + k * 1024); } while (0)
; #define PG8_LDB(dst, b, h) do { _Pragma("unroll") for (int n = 0; n < 2; ++n) _Pragma("unroll") for (int k = 0; k < 2; ++k) dst[n][k] = *(const LAS bf16x8*)(lds + PG8_SB(b, h) + boff + n * 2048 + k * 1024); } while (0)
; #define PG8_MMA(ai, bj, At, Bt) do { __builtin_amdgcn_s_setprio(1); _Pragma("unroll") for (int m = 0; m < 4; ++m) _Pragma("unroll") for (int n = 0; n < 2; ++n) _Pragma("unroll") for (int k = 0; k < 2; ++k) \
;         acc[ai][bj][m][n] = __builtin_amdgcn_mfma_f32_16x16x32_bf16(Bt[n][k], At[m][k], acc[ai][bj][m][n], 0, 0, 0); __builtin_amdgcn_s_setprio(0); } while (0)
; #define PG8_WAIT_V(n) asm volatile("s_waitcnt vmcnt(" #n ")" ::: "memory")
; #define PG8_WAIT_L(n) asm volatile("s_waitcnt lgkmcnt(" #n ")" ::: "memory")
; #define PG8_BAR __builtin_amdgcn_s_barrier()
; #define PG8_SCHED __builtin_amdgcn_sched_barrier(0)
; template <class Map, class Epi>
; DI void gemm_phase(LAS unsigned char* lds, const Map& MP, const Epi& E, const int nM, const int nN, const int K, const int lda, const int ldb) {
;     ...
;             PG8_LDB(B0, 0, 0); PG8_SCHED; PG8_LDA(At, 0, 0); PG8_STAGE(PG8_SA(1, 1), a1 + hstepA, voffA);
;             PG8_WAIT_L(8); PG8_BAR; PG8_WAIT_L(0); PG8_MMA(0, 0, At, B0); PG8_BAR; PG8_SCHED;
;             PG8_LDB(B1, 0, 1); PG8_STAGE(PG8_SB(0, 0), b2, voffB);
;             PG8_BAR; PG8_WAIT_L(0); PG8_MMA(0, 1, At, B1); PG8_BAR;
;             PG8_LDA(At, 0, 1); PG8_STAGE(PG8_SA(0, 0), a2, voffA);
;             PG8_BAR; PG8_WAIT_L(0); PG8_MMA(1, 0, At, B0); PG8_BAR; PG8_SCHED;
;             PG8_STAGE(PG8_SB(0, 1), b2 + hstepB, voffB);
;             PG8_WAIT_V(6); PG8_BAR; PG8_MMA(1, 1, At, B1); PG8_BAR;
;             PG8_LDB(B0, 1, 0); PG8_SCHED; PG8_LDA(At, 1, 0); PG8_STAGE(PG8_SA(0, 1), a2 + hstepA, voffA);
;             PG8_WAIT_L(8); PG8_BAR; PG8_WAIT_L(0); PG8_MMA(0, 0, At, B0); PG8_BAR; PG8_SCHED;
	s_mov_b32 m0, s3
	s_nop 0
	global_load_lds_dwordx4 v132, s[56:57]
	s_add_i32 m0, s3, 0x2000
	s_nop 0
	global_load_lds_dwordx4 v128, s[56:57]
	s_waitcnt vmcnt(6)
	s_setprio 1
	s_barrier
	v_mfma_f32_16x16x32_bf16 v[44:47], v[202:205], v[166:169], v[44:47]
	v_mfma_f32_16x16x32_bf16 v[40:43], v[210:213], v[166:169], v[40:43]
	s_add_i32 s3, 0, 0x18000
	v_add_u32_e32 v162, s3, v146
	ds_read_b128 v[150:153], v162
	v_mfma_f32_16x16x32_bf16 v[28:31], v[202:205], v[174:177], v[28:31]
	v_mfma_f32_16x16x32_bf16 v[24:27], v[210:213], v[174:177], v[24:27]
	ds_read_b128 v[154:157], v162 offset:1024
	v_mfma_f32_16x16x32_bf16 v[12:15], v[202:205], v[182:185], v[12:15]
	v_mfma_f32_16x16x32_bf16 v[8:11], v[210:213], v[182:185], v[8:11]
	ds_read_b128 v[158:161], v162 offset:2048
	v_mfma_f32_16x16x32_bf16 v[4:7], v[202:205], v[190:193], v[4:7]
	v_mfma_f32_16x16x32_bf16 v[0:3], v[210:213], v[190:193], v[0:3]
	ds_read_b128 v[162:165], v162 offset:3072
	v_mfma_f32_16x16x32_bf16 v[44:47], v[206:209], v[170:173], v[44:47]
	s_add_u32 s24, s24, 0x80000
	s_addc_u32 s25, s25, 0
	v_mfma_f32_16x16x32_bf16 v[40:43], v[214:217], v[170:173], v[40:43]
	v_mfma_f32_16x16x32_bf16 v[28:31], v[206:209], v[178:181], v[28:31]
	v_mfma_f32_16x16x32_bf16 v[24:27], v[214:217], v[178:181], v[24:27]
	v_mfma_f32_16x16x32_bf16 v[12:15], v[206:209], v[186:189], v[12:15]
	v_mfma_f32_16x16x32_bf16 v[8:11], v[214:217], v[186:189], v[8:11]
	v_mfma_f32_16x16x32_bf16 v[4:7], v[206:209], v[198:201], v[4:7]
	s_setprio 0
	v_mfma_f32_16x16x32_bf16 v[0:3], v[214:217], v[198:201], v[0:3]
	s_barrier
	s_mov_b32 m0, s34
	ds_read_b128 v[166:169], v148 offset:32768
	ds_read_b128 v[170:173], v148 offset:33792
	ds_read_b128 v[174:177], v148 offset:34816
	ds_read_b128 v[178:181], v148 offset:35840
	ds_read_b128 v[182:185], v148 offset:36864
	ds_read_b128 v[186:189], v148 offset:37888
	ds_read_b128 v[190:193], v148 offset:38912
	ds_read_b128 v[198:201], v148 offset:39936
	global_load_lds_dwordx4 v134, s[24:25]
	s_mov_b32 m0, s35
	s_nop 0
	global_load_lds_dwordx4 v130, s[24:25]
	s_waitcnt lgkmcnt(8)
	s_setprio 1
	s_barrier
	s_waitcnt lgkmcnt(7)
	v_mfma_f32_16x16x32_bf16 v[124:127], v[150:153], v[166:169], v[124:127]
	v_mfma_f32_16x16x32_bf16 v[120:123], v[158:161], v[166:169], v[120:123]
	s_waitcnt lgkmcnt(5)
	v_mfma_f32_16x16x32_bf16 v[116:119], v[150:153], v[174:177], v[116:119]
	v_mfma_f32_16x16x32_bf16 v[112:115], v[158:161], v[174:177], v[112:115]
	s_waitcnt lgkmcnt(3)
	v_mfma_f32_16x16x32_bf16 v[100:103], v[150:153], v[182:185], v[100:103]
	v_mfma_f32_16x16x32_bf16 v[96:99], v[158:161], v[182:185], v[96:99]
	s_waitcnt lgkmcnt(1)
	v_mfma_f32_16x16x32_bf16 v[84:87], v[150:153], v[190:193], v[84:87]
	v_mfma_f32_16x16x32_bf16 v[80:83], v[158:161], v[190:193], v[80:83]
	v_mfma_f32_16x16x32_bf16 v[124:127], v[154:157], v[170:173], v[124:127]
	s_add_i32 s24, 0, 0x1c000
	v_mfma_f32_16x16x32_bf16 v[120:123], v[162:165], v[170:173], v[120:123]
	s_add_i32 s3, s3, s29
	v_mfma_f32_16x16x32_bf16 v[116:119], v[154:157], v[178:181], v[116:119]
	v_add_u32_e32 v196, s24, v146
	v_mfma_f32_16x16x32_bf16 v[112:115], v[162:165], v[178:181], v[112:115]
	v_lshl_add_u64 v[194:195], v[194:195], 0, s[8:9]
	v_mfma_f32_16x16x32_bf16 v[100:103], v[154:157], v[186:189], v[100:103]
	v_mfma_f32_16x16x32_bf16 v[96:99], v[162:165], v[186:189], v[96:99]
	s_waitcnt lgkmcnt(0)
	v_mfma_f32_16x16x32_bf16 v[84:87], v[154:157], v[198:201], v[84:87]
	s_setprio 0
	v_mfma_f32_16x16x32_bf16 v[80:83], v[162:165], v[198:201], v[80:83]
	s_barrier
	s_mov_b32 m0, s3
	ds_read_b128 v[202:205], v196
	ds_read_b128 v[206:209], v196 offset:1024
	ds_read_b128 v[210:213], v196 offset:2048
	ds_read_b128 v[214:217], v196 offset:3072
	global_load_lds_dwordx4 v[194:195], off
	v_lshl_add_u64 v[194:195], v[218:219], 0, s[8:9]
	s_add_i32 m0, s3, 0x2000
	s_nop 0
	global_load_lds_dwordx4 v[194:195], off
	s_setprio 1
	s_barrier
	s_waitcnt lgkmcnt(3)
	v_mfma_f32_16x16x32_bf16 v[108:111], v[202:205], v[166:169], v[108:111]
	s_waitcnt lgkmcnt(1)
	v_mfma_f32_16x16x32_bf16 v[104:107], v[210:213], v[166:169], v[104:107]
	v_mfma_f32_16x16x32_bf16 v[92:95], v[202:205], v[174:177], v[92:95]
	v_mfma_f32_16x16x32_bf16 v[88:91], v[210:213], v[174:177], v[88:91]
	v_mfma_f32_16x16x32_bf16 v[76:79], v[202:205], v[182:185], v[76:79]
	v_mfma_f32_16x16x32_bf16 v[72:75], v[210:213], v[182:185], v[72:75]
	v_mfma_f32_16x16x32_bf16 v[68:71], v[202:205], v[190:193], v[68:71]
	v_mfma_f32_16x16x32_bf16 v[64:67], v[210:213], v[190:193], v[64:67]
	v_mfma_f32_16x16x32_bf16 v[108:111], v[206:209], v[170:173], v[108:111]
	s_mov_b32 m0, s39
	s_waitcnt lgkmcnt(0)
	v_mfma_f32_16x16x32_bf16 v[104:107], v[214:217], v[170:173], v[104:107]
	v_lshl_add_u64 v[194:195], v[220:221], 0, s[8:9]
	v_mfma_f32_16x16x32_bf16 v[92:95], v[206:209], v[178:181], v[92:95]
	v_mfma_f32_16x16x32_bf16 v[88:91], v[214:217], v[178:181], v[88:91]
	v_mfma_f32_16x16x32_bf16 v[76:79], v[206:209], v[186:189], v[76:79]
	v_mfma_f32_16x16x32_bf16 v[72:75], v[214:217], v[186:189], v[72:75]
	v_mfma_f32_16x16x32_bf16 v[68:71], v[206:209], v[198:201], v[68:71]
	s_setprio 0
	v_mfma_f32_16x16x32_bf16 v[64:67], v[214:217], v[198:201], v[64:67]
	s_barrier
	ds_read_b128 v[166:169], v148 offset:49152
	ds_read_b128 v[170:173], v148 offset:50176
	ds_read_b128 v[174:177], v148 offset:51200
	ds_read_b128 v[178:181], v148 offset:52224
	ds_read_b128 v[182:185], v148 offset:53248
	ds_read_b128 v[186:189], v148 offset:54272
	ds_read_b128 v[190:193], v148 offset:55296
	ds_read_b128 v[198:201], v148 offset:56320
	global_load_lds_dwordx4 v[194:195], off
	v_lshl_add_u64 v[194:195], v[222:223], 0, s[8:9]
	s_mov_b32 m0, s42
	s_nop 0
	global_load_lds_dwordx4 v[194:195], off
	s_waitcnt vmcnt(10)
	s_setprio 1
	s_barrier
; #define PG8_STAGE(bufoff, gbase, voff) do { _Pragma("unroll") for (int _i = 0; _i < 2; ++_i) \
;         __builtin_amdgcn_global_load_lds((const unsigned*)((const char*)(gbase) + (voff)[_i]), (LAS unsigned*)(lds + (bufoff) + ldsw + _i * 8192), 16, 0, 0); } while (0)
; #define PG8_LDA(dst, b, h) do { _Pragma("unroll") for (int m = 0; m < 4; ++m) _Pragma("unroll") for (int k = 0; k < 2; ++k) dst[m][k] = *(const LAS bf16x8*)(lds + PG8_SA(b, h) + aoff + m * 2048 + k * 1024); } while (0)
; #define PG8_LDB(dst, b, h) do { _Pragma("unroll") for (int n = 0; n < 2; ++n) _Pragma("unroll") for (int k = 0; k < 2; ++k) dst[n][k] = *(const LAS bf16x8*)(lds + PG8_SB(b, h) + boff + n * 2048 + k * 1024); } while (0)
; #define PG8_MMA(ai, bj, At, Bt) do { __builtin_amdgcn_s_setprio(1); _Pragma("unroll") for (int m = 0; m < 4; ++m) _Pragma("unroll") for (int n = 0; n < 2; ++n) _Pragma("unroll") for (int k = 0; k < 2; ++k) \
;         acc[ai][bj][m][n] = __builtin_amdgcn_mfma_f32_16x16x32_bf16(Bt[n][k], At[m][k], acc[ai][bj][m][n], 0, 0, 0); __builtin_amdgcn_s_setprio(0); } while (0)
; #define PG8_WAIT_V(n) asm volatile("s_waitcnt vmcnt(" #n ")" ::: "memory")
; #define PG8_WAIT_L(n) asm volatile("s_waitcnt lgkmcnt(" #n ")" ::: "memory")
; #define PG8_BAR __builtin_amdgcn_s_barrier()
; #define PG8_SCHED __builtin_amdgcn_sched_barrier(0)
; template <class Map, class Epi>
; DI void gemm_phase(LAS unsigned char* lds, const Map& MP, const Epi& E, const int nM, const int nN, const int K, const int lda, const int ldb) {
;     ...
;             const char* a2 = last ? nA : cA + (size_t)(t + 2) * kstep; const char* b2 = last ? nB : cB + (size_t)(t + 2) * kstep;
;     ...
;             PG8_WAIT_L(8); PG8_BAR; PG8_WAIT_L(0); PG8_MMA(0, 0, At, B0); PG8_BAR; PG8_SCHED;
;             PG8_LDB(B1, 1, 1); PG8_STAGE(PG8_SB(1, 0), b3, voffB);
;             PG8_BAR; PG8_WAIT_L(0); PG8_MMA(0, 1, At, B1); PG8_BAR;
;             PG8_LDA(At, 1, 1); PG8_STAGE(PG8_SA(1, 0), a3, voffA);
;             PG8_BAR; PG8_WAIT_L(0); PG8_MMA(1, 0, At, B0); PG8_BAR; PG8_SCHED;
;             PG8_STAGE(PG8_SB(1, 1), b3 + hstepB, voffB);
;             PG8_WAIT_V(6); PG8_BAR; PG8_MMA(1, 1, At, B1); PG8_BAR;
	s_waitcnt lgkmcnt(7)
	v_mfma_f32_16x16x32_bf16 v[60:63], v[150:153], v[166:169], v[60:63]
	v_mfma_f32_16x16x32_bf16 v[56:59], v[158:161], v[166:169], v[56:59]
	s_waitcnt lgkmcnt(5)
	v_mfma_f32_16x16x32_bf16 v[52:55], v[150:153], v[174:177], v[52:55]
	v_mfma_f32_16x16x32_bf16 v[48:51], v[158:161], v[174:177], v[48:51]
	s_waitcnt lgkmcnt(3)
	v_mfma_f32_16x16x32_bf16 v[36:39], v[150:153], v[182:185], v[36:39]
	v_mfma_f32_16x16x32_bf16 v[32:35], v[158:161], v[182:185], v[32:35]
	s_waitcnt lgkmcnt(1)
	v_mfma_f32_16x16x32_bf16 v[20:23], v[150:153], v[190:193], v[20:23]
	v_mfma_f32_16x16x32_bf16 v[16:19], v[158:161], v[190:193], v[16:19]
	v_mfma_f32_16x16x32_bf16 v[60:63], v[154:157], v[170:173], v[60:63]
	s_add_u32 s22, s22, 0x80080
	s_addc_u32 s23, s23, 0
	v_mfma_f32_16x16x32_bf16 v[56:59], v[162:165], v[170:173], v[56:59]
	s_add_i32 s3, s24, s29
	v_mfma_f32_16x16x32_bf16 v[52:55], v[154:157], v[178:181], v[52:55]
	v_mfma_f32_16x16x32_bf16 v[48:51], v[162:165], v[178:181], v[48:51]
	v_mfma_f32_16x16x32_bf16 v[36:39], v[154:157], v[186:189], v[36:39]
	v_mfma_f32_16x16x32_bf16 v[32:35], v[162:165], v[186:189], v[32:35]
	s_waitcnt lgkmcnt(0)
	v_mfma_f32_16x16x32_bf16 v[20:23], v[154:157], v[198:201], v[20:23]
	s_setprio 0
	v_mfma_f32_16x16x32_bf16 v[16:19], v[162:165], v[198:201], v[16:19]
	s_barrier
	s_mov_b32 m0, s3
	s_nop 0
	global_load_lds_dwordx4 v132, s[22:23]
	s_add_i32 m0, s3, 0x2000
	s_nop 0
	global_load_lds_dwordx4 v128, s[22:23]
	s_waitcnt vmcnt(6)
	s_setprio 1
	s_barrier
	v_mfma_f32_16x16x32_bf16 v[44:47], v[202:205], v[166:169], v[44:47]
	v_mfma_f32_16x16x32_bf16 v[40:43], v[210:213], v[166:169], v[40:43]
	ds_read_b128 v[150:153], v147
	v_mfma_f32_16x16x32_bf16 v[28:31], v[202:205], v[174:177], v[28:31]
	v_mfma_f32_16x16x32_bf16 v[24:27], v[210:213], v[174:177], v[24:27]
	ds_read_b128 v[154:157], v147 offset:1024
	v_mfma_f32_16x16x32_bf16 v[12:15], v[202:205], v[182:185], v[12:15]
	v_mfma_f32_16x16x32_bf16 v[8:11], v[210:213], v[182:185], v[8:11]
	ds_read_b128 v[158:161], v147 offset:2048
	v_mfma_f32_16x16x32_bf16 v[4:7], v[202:205], v[190:193], v[4:7]
	v_mfma_f32_16x16x32_bf16 v[0:3], v[210:213], v[190:193], v[0:3]
	ds_read_b128 v[162:165], v147 offset:3072
	v_mfma_f32_16x16x32_bf16 v[44:47], v[206:209], v[170:173], v[44:47]
	s_add_i32 s54, s54, 2
	v_mfma_f32_16x16x32_bf16 v[40:43], v[214:217], v[170:173], v[40:43]
	s_add_u32 s52, s52, 0x100
	s_addc_u32 s53, s53, 0
	v_mfma_f32_16x16x32_bf16 v[28:31], v[206:209], v[178:181], v[28:31]
	s_add_u32 s20, s20, 0x100
	s_addc_u32 s21, s21, 0
	v_mfma_f32_16x16x32_bf16 v[24:27], v[214:217], v[178:181], v[24:27]
	s_cmp_gt_u32 s54, 29
	v_mfma_f32_16x16x32_bf16 v[12:15], v[206:209], v[186:189], v[12:15]
	v_mfma_f32_16x16x32_bf16 v[8:11], v[214:217], v[186:189], v[8:11]
	v_mfma_f32_16x16x32_bf16 v[4:7], v[206:209], v[198:201], v[4:7]
	s_setprio 0
	v_mfma_f32_16x16x32_bf16 v[0:3], v[214:217], v[198:201], v[0:3]
	s_barrier
	s_cbranch_scc0 .LBB1_693
; DI unsigned pack2(float a, float b) { f32x2 v = {a, b}; hwbf16x2 r = __builtin_convertvector(v, hwbf16x2); return __builtin_bit_cast(unsigned, r); }
; #define PG8_WAIT_V(n) asm volatile("s_waitcnt vmcnt(" #n ")" ::: "memory")
; #define PG8_BAR __builtin_amdgcn_s_barrier()
;     DI void operator()(const f32x4 (&acc)[2][2][4][2], const Unit& u, int wr, int wc, int fr, int fq) const {
;         bf16_t* O = O1; int ldc = ldc1, pn = u.pn; if (pn >= split) { O = O2; ldc = ldc2; pn -= split; }
;         const int row0 = u.pm * BM + wr * 64 + fr, col0 = pn * BM + wc * 32 + 8 * fq;
; #pragma unroll
;         for (int ai = 0; ai < 2; ++ai)
; #pragma unroll
;             for (int m = 0; m < 4; ++m) { bf16_t* rowp = O + (size_t)(row0 + ai * HALF + m * 16) * ldc + col0;
; #pragma unroll
;                 for (int bj = 0; bj < 2; ++bj) { const f32x4 v0 = acc[ai][bj][m][0], v1 = acc[ai][bj][m][1];
;                     u32x4 o; o[0] = pack2(v0[0], v0[1]); o[1] = pack2(v0[2], v0[3]); o[2] = pack2(v1[0], v1[1]); o[3] = pack2(v1[2], v1[3]);
;                     *(u32x4*)(rowp + bj * HALF) = o; } }
; template <class Map, class Epi>
; DI void gemm_phase(LAS unsigned char* lds, const Map& MP, const Epi& E, const int nM, const int nN, const int K, const int lda, const int ldb) {
;     ...
;         cur = nxt; cA = nA; cB = nB; ++ui;
;     }
;     PG8_WAIT_V(0);
;     if (wr == 0) PG8_BAR;
;     PG8_BAR;
	s_waitcnt lgkmcnt(0)
	s_lshl_b32 s3, s10, 8
	v_mov_b32_e32 v150, v144
	v_mov_b32_e32 v151, v145
	s_add_i32 s3, s3, s37
	v_cvt_pk_bf16_f32 v68, v68, v69
	v_add_u32_e32 v154, s3, v150
	s_lshl_b32 s3, s47, 8
	s_or_b32 s3, s3, s38
	v_lshl_add_u32 v150, v151, 3, s3
	v_ashrrev_i32_e32 v151, 31, v150
	v_lshl_add_u64 v[150:151], v[150:151], 1, s[6:7]
	v_cvt_pk_bf16_f32 v69, v70, v71
	v_cvt_pk_bf16_f32 v70, v64, v65
	v_add_u32_e32 v64, 0x80, v154
	v_mad_i64_i32 v[152:153], s[20:21], v154, s46, v[150:151]
	v_cvt_pk_bf16_f32 v108, v108, v109
	v_cvt_pk_bf16_f32 v109, v110, v111
	v_cvt_pk_bf16_f32 v110, v104, v105
	v_cvt_pk_bf16_f32 v111, v106, v107
	v_add_u32_e32 v104, 16, v154
	v_mad_i64_i32 v[64:65], s[20:21], v64, s46, v[150:151]
	v_cvt_pk_bf16_f32 v44, v44, v45
	v_cvt_pk_bf16_f32 v45, v46, v47
	v_cvt_pk_bf16_f32 v46, v40, v41
	v_cvt_pk_bf16_f32 v47, v42, v43
	v_add_u32_e32 v40, 0x90, v154
	global_store_dwordx4 v[152:153], v[108:111], off offset:256
	v_cvt_pk_bf16_f32 v92, v92, v93
	v_cvt_pk_bf16_f32 v93, v94, v95
	v_mad_i64_i32 v[108:109], s[20:21], v104, s46, v[150:151]
	v_cvt_pk_bf16_f32 v94, v88, v89
	v_cvt_pk_bf16_f32 v95, v90, v91
	v_add_u32_e32 v88, 32, v154
	global_store_dwordx4 v[64:65], v[44:47], off offset:256
	v_cvt_pk_bf16_f32 v28, v28, v29
	v_cvt_pk_bf16_f32 v29, v30, v31
	v_mad_i64_i32 v[44:45], s[20:21], v40, s46, v[150:151]
	v_cvt_pk_bf16_f32 v30, v24, v25
	v_cvt_pk_bf16_f32 v31, v26, v27
	v_add_u32_e32 v24, 0xa0, v154
	global_store_dwordx4 v[108:109], v[92:95], off offset:256
	v_cvt_pk_bf16_f32 v76, v76, v77
	v_cvt_pk_bf16_f32 v77, v78, v79
	v_mad_i64_i32 v[92:93], s[20:21], v88, s46, v[150:151]
	v_cvt_pk_bf16_f32 v78, v72, v73
	v_cvt_pk_bf16_f32 v79, v74, v75
	v_add_u32_e32 v72, 48, v154
	global_store_dwordx4 v[44:45], v[28:31], off offset:256
	v_cvt_pk_bf16_f32 v12, v12, v13
	v_cvt_pk_bf16_f32 v13, v14, v15
	v_mad_i64_i32 v[28:29], s[20:21], v24, s46, v[150:151]
	v_cvt_pk_bf16_f32 v14, v8, v9
	v_cvt_pk_bf16_f32 v15, v10, v11
	v_add_u32_e32 v8, 0xb0, v154
	global_store_dwordx4 v[92:93], v[76:79], off offset:256
	global_store_dwordx4 v[28:29], v[12:15], off offset:256
	v_cvt_pk_bf16_f32 v124, v124, v125
	v_mad_i64_i32 v[76:77], s[20:21], v72, s46, v[150:151]
	v_mad_i64_i32 v[12:13], s[20:21], v8, s46, v[150:151]
	v_cvt_pk_bf16_f32 v125, v126, v127
	v_cvt_pk_bf16_f32 v126, v120, v121
	v_cvt_pk_bf16_f32 v127, v122, v123
	v_cvt_pk_bf16_f32 v104, v116, v117
	v_cvt_pk_bf16_f32 v105, v118, v119
	v_cvt_pk_bf16_f32 v106, v112, v113
	v_cvt_pk_bf16_f32 v107, v114, v115
	v_cvt_pk_bf16_f32 v88, v100, v101
	v_cvt_pk_bf16_f32 v89, v102, v103
	v_cvt_pk_bf16_f32 v90, v96, v97
	v_cvt_pk_bf16_f32 v91, v98, v99
	v_cvt_pk_bf16_f32 v72, v84, v85
	v_cvt_pk_bf16_f32 v73, v86, v87
	v_cvt_pk_bf16_f32 v74, v80, v81
	v_cvt_pk_bf16_f32 v75, v82, v83
	v_cvt_pk_bf16_f32 v71, v66, v67
	v_cvt_pk_bf16_f32 v60, v60, v61
	v_cvt_pk_bf16_f32 v61, v62, v63
	v_cvt_pk_bf16_f32 v62, v56, v57
	v_cvt_pk_bf16_f32 v63, v58, v59
	v_cvt_pk_bf16_f32 v40, v52, v53
	v_cvt_pk_bf16_f32 v41, v54, v55
	v_cvt_pk_bf16_f32 v42, v48, v49
	v_cvt_pk_bf16_f32 v43, v50, v51
	v_cvt_pk_bf16_f32 v24, v36, v37
	v_cvt_pk_bf16_f32 v25, v38, v39
	v_cvt_pk_bf16_f32 v26, v32, v33
	v_cvt_pk_bf16_f32 v27, v34, v35
	v_cvt_pk_bf16_f32 v8, v20, v21
	v_cvt_pk_bf16_f32 v9, v22, v23
	v_cvt_pk_bf16_f32 v10, v16, v17
	v_cvt_pk_bf16_f32 v11, v18, v19
	v_cvt_pk_bf16_f32 v4, v4, v5
	v_cvt_pk_bf16_f32 v5, v6, v7
	v_cvt_pk_bf16_f32 v6, v0, v1
	v_cvt_pk_bf16_f32 v7, v2, v3
	s_and_b64 vcc, exec, s[40:41]
	s_mov_b32 s47, s12
	s_mov_b32 s10, s14
	s_mov_b64 s[20:21], s[18:19]
	s_mov_b64 s[22:23], s[16:17]
	global_store_dwordx4 v[152:153], v[124:127], off
	global_store_dwordx4 v[108:109], v[104:107], off
	global_store_dwordx4 v[92:93], v[88:91], off
	global_store_dwordx4 v[76:77], v[72:75], off
	global_store_dwordx4 v[76:77], v[68:71], off offset:256
	global_store_dwordx4 v[64:65], v[60:63], off
	global_store_dwordx4 v[44:45], v[40:43], off
	global_store_dwordx4 v[28:29], v[24:27], off
	global_store_dwordx4 v[12:13], v[8:11], off
	global_store_dwordx4 v[12:13], v[4:7], off offset:256
	s_cbranch_vccz .LBB1_690
	s_waitcnt vmcnt(0)
	s_cmpk_gt_u32 s4, 0xff
	s_cbranch_scc1 .LBB1_697
	s_barrier

; #define PG8_STAGE(bufoff, gbase, voff) do { _Pragma("unroll") for (int _i = 0; _i < 2; ++_i) \
;         __builtin_amdgcn_global_load_lds((const unsigned*)((const char*)(gbase) + (voff)[_i]), (LAS unsigned*)(lds + (bufoff) + ldsw + _i * 8192), 16, 0, 0); } while (0)
; #define PG8_LDA(dst, b, h) do { _Pragma("unroll") for (int m = 0; m < 4; ++m) _Pragma("unroll") for (int k = 0; k < 2; ++k) dst[m][k] = *(const LAS bf16x8*)(lds + PG8_SA(b, h) + aoff + m * 2048 + k * 1024); } while (0)
; #define PG8_LDB(dst, b, h) do { _Pragma("unroll") for (int n = 0; n < 2; ++n) _Pragma("unroll") for (int k = 0; k < 2; ++k) dst[n][k] = *(const LAS bf16x8*)(lds + PG8_SB(b, h) + boff + n * 2048 + k * 1024); } while (0)
; #define PG8_MMA(ai, bj, At, Bt) do { __builtin_amdgcn_s_setprio(1); _Pragma("unroll") for (int m = 0; m < 4; ++m) _Pragma("unroll") for (int n = 0; n < 2; ++n) _Pragma("unroll") for (int k = 0; k < 2; ++k) \
;         acc[ai][bj][m][n] = __builtin_amdgcn_mfma_f32_16x16x32_bf16(Bt[n][k], At[m][k], acc[ai][bj][m][n], 0, 0, 0); __builtin_amdgcn_s_setprio(0); } while (0)
; #define PG8_WAIT_V(n) asm volatile("s_waitcnt vmcnt(" #n ")" ::: "memory")
; #define PG8_WAIT_L(n) asm volatile("s_waitcnt lgkmcnt(" #n ")" ::: "memory")
; template <class Map, class Epi>
; DI void gemm_phase(LAS unsigned char* lds, const Map& MP, const Epi& E, const int nM, const int nN, const int K, const int lda, const int ldb) {
;     ...
;         for (int t = 0; t < nt; t += 2) {
;             const bool last = (t == nt - 2);
;             const char* a1 = cA + (size_t)(t + 1) * kstep;
;             const char* a2 = last ? nA : cA + (size_t)(t + 2) * kstep; const char* b2 = last ? nB : cB + (size_t)(t + 2) * kstep;
;             const char* a3 = a2 + kstep; const char* b3 = b2 + kstep;
;             PG8_LDB(B0, 0, 0); PG8_SCHED; PG8_LDA(At, 0, 0); PG8_STAGE(PG8_SA(1, 1), a1 + hstepA, voffA);
;             PG8_WAIT_L(8); PG8_BAR; PG8_WAIT_L(0); PG8_MMA(0, 0, At, B0); PG8_BAR; PG8_SCHED;
;             PG8_LDB(B1, 0, 1); PG8_STAGE(PG8_SB(0, 0), b2, voffB);
;             PG8_BAR; PG8_WAIT_L(0); PG8_MMA(0, 1, At, B1); PG8_BAR;
;             PG8_LDA(At, 0, 1); PG8_STAGE(PG8_SA(0, 0), a2, voffA);
;             PG8_BAR; PG8_WAIT_L(0); PG8_MMA(1, 0, At, B0); PG8_BAR; PG8_SCHED;
;             PG8_STAGE(PG8_SB(0, 1), b2 + hstepB, voffB);
;             PG8_WAIT_V(6); PG8_BAR; PG8_MMA(1, 1, At, B1); PG8_BAR;
.LBB1_925:
	s_add_u32 s3, s10, 0xfff80080
	s_addc_u32 s12, s11, -1
	s_cmp_eq_u32 s48, 28
	s_cselect_b32 s15, s4, s12
	s_cselect_b32 s14, s5, s3
	s_cselect_b32 s13, s37, s47
	s_cselect_b32 s12, s38, s39
	s_add_i32 m0, s24, 0xc000
	ds_read_b128 v[168:171], v150
	ds_read_b128 v[172:175], v150 offset:1024
	ds_read_b128 v[176:179], v150 offset:2048
	ds_read_b128 v[180:183], v150 offset:3072
	ds_read_b128 v[184:187], v150 offset:4096
	ds_read_b128 v[188:191], v150 offset:5120
	ds_read_b128 v[192:195], v150 offset:6144
	ds_read_b128 v[198:201], v150 offset:7168
	global_load_lds_dwordx4 v138, s[10:11]
	s_add_i32 m0, s24, 0xe000
	s_nop 0
	global_load_lds_dwordx4 v136, s[10:11]
	s_waitcnt lgkmcnt(8)
	s_setprio 1
	s_barrier
	s_waitcnt lgkmcnt(7)
	v_mfma_f32_16x16x32_bf16 v[124:127], v[152:155], v[168:171], v[124:127]
	v_mfma_f32_16x16x32_bf16 v[120:123], v[160:163], v[168:171], v[120:123]
	s_waitcnt lgkmcnt(5)
	v_mfma_f32_16x16x32_bf16 v[108:111], v[152:155], v[176:179], v[108:111]
	v_mfma_f32_16x16x32_bf16 v[104:107], v[160:163], v[176:179], v[104:107]
	s_waitcnt lgkmcnt(3)
	v_mfma_f32_16x16x32_bf16 v[92:95], v[152:155], v[184:187], v[92:95]
	v_mfma_f32_16x16x32_bf16 v[88:91], v[160:163], v[184:187], v[88:91]
	s_waitcnt lgkmcnt(1)
	v_mfma_f32_16x16x32_bf16 v[76:79], v[152:155], v[192:195], v[76:79]
	v_mfma_f32_16x16x32_bf16 v[72:75], v[160:163], v[192:195], v[72:75]
	v_mfma_f32_16x16x32_bf16 v[124:127], v[156:159], v[172:175], v[124:127]
	s_add_i32 s3, s35, s22
	v_mfma_f32_16x16x32_bf16 v[120:123], v[164:167], v[172:175], v[120:123]
	v_lshl_add_u64 v[144:145], s[12:13], 0, v[132:133]
	v_mfma_f32_16x16x32_bf16 v[108:111], v[156:159], v[180:183], v[108:111]
	v_lshl_add_u64 v[218:219], s[12:13], 0, v[128:129]
	v_mfma_f32_16x16x32_bf16 v[104:107], v[164:167], v[180:183], v[104:107]
	v_mfma_f32_16x16x32_bf16 v[92:95], v[156:159], v[188:191], v[92:95]
	v_mfma_f32_16x16x32_bf16 v[88:91], v[164:167], v[188:191], v[88:91]
	s_waitcnt lgkmcnt(0)
	v_mfma_f32_16x16x32_bf16 v[76:79], v[156:159], v[198:201], v[76:79]
	s_setprio 0
	v_mfma_f32_16x16x32_bf16 v[72:75], v[164:167], v[198:201], v[72:75]
	s_barrier
	s_mov_b32 m0, s3
	ds_read_b128 v[202:205], v151
	ds_read_b128 v[206:209], v151 offset:1024
	ds_read_b128 v[210:213], v151 offset:2048
	ds_read_b128 v[214:217], v151 offset:3072
	global_load_lds_dwordx4 v[144:145], off
	s_add_i32 m0, s3, 0x2000
	s_nop 0
	global_load_lds_dwordx4 v[218:219], off
	s_setprio 1
	s_barrier
	s_waitcnt lgkmcnt(3)
	v_mfma_f32_16x16x32_bf16 v[116:119], v[202:205], v[168:171], v[116:119]
	s_waitcnt lgkmcnt(1)
	v_mfma_f32_16x16x32_bf16 v[112:115], v[210:213], v[168:171], v[112:115]
	v_mfma_f32_16x16x32_bf16 v[100:103], v[202:205], v[176:179], v[100:103]
	v_mfma_f32_16x16x32_bf16 v[96:99], v[210:213], v[176:179], v[96:99]
	v_mfma_f32_16x16x32_bf16 v[84:87], v[202:205], v[184:187], v[84:87]
	v_mfma_f32_16x16x32_bf16 v[80:83], v[210:213], v[184:187], v[80:83]
	v_mfma_f32_16x16x32_bf16 v[68:71], v[202:205], v[192:195], v[68:71]
	v_mfma_f32_16x16x32_bf16 v[64:67], v[210:213], v[192:195], v[64:67]
	v_mfma_f32_16x16x32_bf16 v[116:119], v[206:209], v[172:175], v[116:119]
	v_lshl_add_u64 v[222:223], s[14:15], 0, v[130:131]
	s_mov_b32 m0, s24
	s_waitcnt lgkmcnt(0)
	v_mfma_f32_16x16x32_bf16 v[112:115], v[214:217], v[172:175], v[112:115]
	v_lshl_add_u64 v[220:221], s[14:15], 0, v[134:135]
	v_mfma_f32_16x16x32_bf16 v[100:103], v[206:209], v[180:183], v[100:103]
	v_mfma_f32_16x16x32_bf16 v[96:99], v[214:217], v[180:183], v[96:99]
	v_mfma_f32_16x16x32_bf16 v[84:87], v[206:209], v[188:191], v[84:87]
	v_mfma_f32_16x16x32_bf16 v[80:83], v[214:217], v[188:191], v[80:83]
	v_mfma_f32_16x16x32_bf16 v[68:71], v[206:209], v[198:201], v[68:71]
	s_setprio 0
	v_mfma_f32_16x16x32_bf16 v[64:67], v[214:217], v[198:201], v[64:67]
	s_barrier
	ds_read_b128 v[168:171], v150 offset:16384
	ds_read_b128 v[172:175], v150 offset:17408
	ds_read_b128 v[176:179], v150 offset:18432
	ds_read_b128 v[180:183], v150 offset:19456
	ds_read_b128 v[184:187], v150 offset:20480
	ds_read_b128 v[188:191], v150 offset:21504
	ds_read_b128 v[192:195], v150 offset:22528
	ds_read_b128 v[198:201], v150 offset:23552
	global_load_lds_dwordx4 v[220:221], off
	s_mov_b32 m0, s9
	s_nop 0
	global_load_lds_dwordx4 v[222:223], off
	s_waitcnt vmcnt(10)
	s_setprio 1
	s_barrier
	s_waitcnt lgkmcnt(7)
	v_mfma_f32_16x16x32_bf16 v[60:63], v[152:155], v[168:171], v[60:63]
	v_mfma_f32_16x16x32_bf16 v[56:59], v[160:163], v[168:171], v[56:59]
	s_waitcnt lgkmcnt(5)
	v_mfma_f32_16x16x32_bf16 v[44:47], v[152:155], v[176:179], v[44:47]
	v_mfma_f32_16x16x32_bf16 v[40:43], v[160:163], v[176:179], v[40:43]
	s_waitcnt lgkmcnt(3)
	v_mfma_f32_16x16x32_bf16 v[28:31], v[152:155], v[184:187], v[28:31]
	v_mfma_f32_16x16x32_bf16 v[24:27], v[160:163], v[184:187], v[24:27]
	s_waitcnt lgkmcnt(1)
	v_mfma_f32_16x16x32_bf16 v[12:15], v[152:155], v[192:195], v[12:15]
	v_mfma_f32_16x16x32_bf16 v[8:11], v[160:163], v[192:195], v[8:11]
	v_mfma_f32_16x16x32_bf16 v[60:63], v[156:159], v[172:175], v[60:63]
	s_add_u32 s56, s12, 0x80000
	s_addc_u32 s57, s13, 0
	v_mfma_f32_16x16x32_bf16 v[56:59], v[164:167], v[172:175], v[56:59]
	s_add_i32 s3, s36, s22
	v_mfma_f32_16x16x32_bf16 v[44:47], v[156:159], v[180:183], v[44:47]
	v_mfma_f32_16x16x32_bf16 v[40:43], v[164:167], v[180:183], v[40:43]
	v_mfma_f32_16x16x32_bf16 v[28:31], v[156:159], v[188:191], v[28:31]
	v_mfma_f32_16x16x32_bf16 v[24:27], v[164:167], v[188:191], v[24:27]
	s_waitcnt lgkmcnt(0)
	v_mfma_f32_16x16x32_bf16 v[12:15], v[156:159], v[198:201], v[12:15]
	s_setprio 0
	v_mfma_f32_16x16x32_bf16 v[8:11], v[164:167], v[198:201], v[8:11]
	s_barrier
; #define PG8_STAGE(bufoff, gbase, voff) do { _Pragma("unroll") for (int _i = 0; _i < 2; ++_i) \
;         __builtin_amdgcn_global_load_lds((const unsigned*)((const char*)(gbase) + (voff)[_i]), (LAS unsigned*)(lds + (bufoff) + ldsw + _i * 8192), 16, 0, 0); } while (0)
; #define PG8_LDA(dst, b, h) do { _Pragma("unroll") for (int m = 0; m < 4; ++m) _Pragma("unroll") for (int k = 0; k < 2; ++k) dst[m][k] = *(const LAS bf16x8*)(lds + PG8_SA(b, h) + aoff + m * 2048 + k * 1024); } while (0)
; #define PG8_LDB(dst, b, h) do { _Pragma("unroll") for (int n = 0; n < 2; ++n) _Pragma("unroll") for (int k = 0; k < 2; ++k) dst[n][k] = *(const LAS bf16x8*)(lds + PG8_SB(b, h) + boff + n * 2048 + k * 1024); } while (0)
; #define PG8_MMA(ai, bj, At, Bt) do { __builtin_amdgcn_s_setprio(1); _Pragma("unroll") for (int m = 0; m < 4; ++m) _Pragma("unroll") for (int n = 0; n < 2; ++n) _Pragma("unroll") for (int k = 0; k < 2; ++k) \
;         acc[ai][bj][m][n] = __builtin_amdgcn_mfma_f32_16x16x32_bf16(Bt[n][k], At[m][k], acc[ai][bj][m][n], 0, 0, 0); __builtin_amdgcn_s_setprio(0); } while (0)
; #define PG8_WAIT_V(n) asm volatile("s_waitcnt vmcnt(" #n ")" ::: "memory")
; #define PG8_WAIT_L(n) asm volatile("s_waitcnt lgkmcnt(" #n ")" ::: "memory")
; #define PG8_BAR __builtin_amdgcn_s_barrier()
; #define PG8_SCHED __builtin_amdgcn_sched_barrier(0)
; template <class Map, class Epi>
; DI void gemm_phase(LAS unsigned char* lds, const Map& MP, const Epi& E, const int nM, const int nN, const int K, const int lda, const int ldb) {
;     ...
;             PG8_LDB(B0, 0, 0); PG8_SCHED; PG8_LDA(At, 0, 0); PG8_STAGE(PG8_SA(1, 1), a1 + hstepA, voffA);
;             PG8_WAIT_L(8); PG8_BAR; PG8_WAIT_L(0); PG8_MMA(0, 0, At, B0); PG8_BAR; PG8_SCHED;
;             PG8_LDB(B1, 0, 1); PG8_STAGE(PG8_SB(0, 0), b2, voffB);
;             PG8_BAR; PG8_WAIT_L(0); PG8_MMA(0, 1, At, B1); PG8_BAR;
;             PG8_LDA(At, 0, 1); PG8_STAGE(PG8_SA(0, 0), a2, voffA);
;             PG8_BAR; PG8_WAIT_L(0); PG8_MMA(1, 0, At, B0); PG8_BAR; PG8_SCHED;
;             PG8_STAGE(PG8_SB(0, 1), b2 + hstepB, voffB);
;             PG8_WAIT_V(6); PG8_BAR; PG8_MMA(1, 1, At, B1); PG8_BAR;
;             PG8_LDB(B0, 1, 0); PG8_SCHED; PG8_LDA(At, 1, 0); PG8_STAGE(PG8_SA(0, 1), a2 + hstepA, voffA);
;             PG8_WAIT_L(8); PG8_BAR; PG8_WAIT_L(0); PG8_MMA(0, 0, At, B0); PG8_BAR; PG8_SCHED;
	s_mov_b32 m0, s3
	s_nop 0
	global_load_lds_dwordx4 v132, s[56:57]
	s_add_i32 m0, s3, 0x2000
	s_nop 0
	global_load_lds_dwordx4 v128, s[56:57]
	s_waitcnt vmcnt(6)
	s_setprio 1
	s_barrier
	v_mfma_f32_16x16x32_bf16 v[52:55], v[202:205], v[168:171], v[52:55]
	v_mfma_f32_16x16x32_bf16 v[48:51], v[210:213], v[168:171], v[48:51]
	s_add_i32 s3, 0, 0x18000
	v_add_u32_e32 v164, s3, v148
	ds_read_b128 v[152:155], v164
	v_mfma_f32_16x16x32_bf16 v[36:39], v[202:205], v[176:179], v[36:39]
	v_mfma_f32_16x16x32_bf16 v[32:35], v[210:213], v[176:179], v[32:35]
	ds_read_b128 v[156:159], v164 offset:1024
	v_mfma_f32_16x16x32_bf16 v[20:23], v[202:205], v[184:187], v[20:23]
	v_mfma_f32_16x16x32_bf16 v[16:19], v[210:213], v[184:187], v[16:19]
	ds_read_b128 v[160:163], v164 offset:2048
	v_mfma_f32_16x16x32_bf16 v[4:7], v[202:205], v[192:195], v[4:7]
	v_mfma_f32_16x16x32_bf16 v[0:3], v[210:213], v[192:195], v[0:3]
	ds_read_b128 v[164:167], v164 offset:3072
	v_mfma_f32_16x16x32_bf16 v[52:55], v[206:209], v[172:175], v[52:55]
	s_add_u32 s14, s14, 0x80000
	s_addc_u32 s15, s15, 0
	v_mfma_f32_16x16x32_bf16 v[48:51], v[214:217], v[172:175], v[48:51]
	v_mfma_f32_16x16x32_bf16 v[36:39], v[206:209], v[180:183], v[36:39]
	v_mfma_f32_16x16x32_bf16 v[32:35], v[214:217], v[180:183], v[32:35]
	v_mfma_f32_16x16x32_bf16 v[20:23], v[206:209], v[188:191], v[20:23]
	v_mfma_f32_16x16x32_bf16 v[16:19], v[214:217], v[188:191], v[16:19]
	v_mfma_f32_16x16x32_bf16 v[4:7], v[206:209], v[198:201], v[4:7]
	s_setprio 0
	v_mfma_f32_16x16x32_bf16 v[0:3], v[214:217], v[198:201], v[0:3]
	s_barrier
	s_mov_b32 m0, s25
	ds_read_b128 v[168:171], v150 offset:32768
	ds_read_b128 v[172:175], v150 offset:33792
	ds_read_b128 v[176:179], v150 offset:34816
	ds_read_b128 v[180:183], v150 offset:35840
	ds_read_b128 v[184:187], v150 offset:36864
	ds_read_b128 v[188:191], v150 offset:37888
	ds_read_b128 v[192:195], v150 offset:38912
	ds_read_b128 v[198:201], v150 offset:39936
	global_load_lds_dwordx4 v134, s[14:15]
	s_mov_b32 m0, s26
	s_nop 0
	global_load_lds_dwordx4 v130, s[14:15]
	s_waitcnt lgkmcnt(8)
	s_setprio 1
	s_barrier
	s_waitcnt lgkmcnt(7)
	v_mfma_f32_16x16x32_bf16 v[124:127], v[152:155], v[168:171], v[124:127]
	v_mfma_f32_16x16x32_bf16 v[120:123], v[160:163], v[168:171], v[120:123]
	s_waitcnt lgkmcnt(5)
	v_mfma_f32_16x16x32_bf16 v[108:111], v[152:155], v[176:179], v[108:111]
	v_mfma_f32_16x16x32_bf16 v[104:107], v[160:163], v[176:179], v[104:107]
	s_waitcnt lgkmcnt(3)
	v_mfma_f32_16x16x32_bf16 v[92:95], v[152:155], v[184:187], v[92:95]
	v_mfma_f32_16x16x32_bf16 v[88:91], v[160:163], v[184:187], v[88:91]
	s_waitcnt lgkmcnt(1)
	v_mfma_f32_16x16x32_bf16 v[76:79], v[152:155], v[192:195], v[76:79]
	v_mfma_f32_16x16x32_bf16 v[72:75], v[160:163], v[192:195], v[72:75]
	v_mfma_f32_16x16x32_bf16 v[124:127], v[156:159], v[172:175], v[124:127]
	s_add_i32 s14, 0, 0x1c000
	v_mfma_f32_16x16x32_bf16 v[120:123], v[164:167], v[172:175], v[120:123]
	s_add_i32 s3, s3, s22
	v_mfma_f32_16x16x32_bf16 v[108:111], v[156:159], v[180:183], v[108:111]
	v_add_u32_e32 v196, s14, v148
	v_mfma_f32_16x16x32_bf16 v[104:107], v[164:167], v[180:183], v[104:107]
	v_lshl_add_u64 v[144:145], v[144:145], 0, s[44:45]
	v_mfma_f32_16x16x32_bf16 v[92:95], v[156:159], v[188:191], v[92:95]
	v_mfma_f32_16x16x32_bf16 v[88:91], v[164:167], v[188:191], v[88:91]
	s_waitcnt lgkmcnt(0)
	v_mfma_f32_16x16x32_bf16 v[76:79], v[156:159], v[198:201], v[76:79]
	s_setprio 0
	v_mfma_f32_16x16x32_bf16 v[72:75], v[164:167], v[198:201], v[72:75]
	s_barrier
	s_mov_b32 m0, s3
	ds_read_b128 v[202:205], v196
	ds_read_b128 v[206:209], v196 offset:1024
	ds_read_b128 v[210:213], v196 offset:2048
	ds_read_b128 v[214:217], v196 offset:3072
	global_load_lds_dwordx4 v[144:145], off
	v_lshl_add_u64 v[144:145], v[218:219], 0, s[44:45]
	s_add_i32 m0, s3, 0x2000
	s_nop 0
	global_load_lds_dwordx4 v[144:145], off
	s_setprio 1
	s_barrier
	s_waitcnt lgkmcnt(3)
	v_mfma_f32_16x16x32_bf16 v[116:119], v[202:205], v[168:171], v[116:119]
	s_waitcnt lgkmcnt(1)
	v_mfma_f32_16x16x32_bf16 v[112:115], v[210:213], v[168:171], v[112:115]
	v_mfma_f32_16x16x32_bf16 v[100:103], v[202:205], v[176:179], v[100:103]
	v_mfma_f32_16x16x32_bf16 v[96:99], v[210:213], v[176:179], v[96:99]
	v_mfma_f32_16x16x32_bf16 v[84:87], v[202:205], v[184:187], v[84:87]
	v_mfma_f32_16x16x32_bf16 v[80:83], v[210:213], v[184:187], v[80:83]
	v_mfma_f32_16x16x32_bf16 v[68:71], v[202:205], v[192:195], v[68:71]
	v_mfma_f32_16x16x32_bf16 v[64:67], v[210:213], v[192:195], v[64:67]
	v_mfma_f32_16x16x32_bf16 v[116:119], v[206:209], v[172:175], v[116:119]
	s_mov_b32 m0, s30
	s_waitcnt lgkmcnt(0)
	v_mfma_f32_16x16x32_bf16 v[112:115], v[214:217], v[172:175], v[112:115]
	v_lshl_add_u64 v[144:145], v[220:221], 0, s[44:45]
	v_mfma_f32_16x16x32_bf16 v[100:103], v[206:209], v[180:183], v[100:103]
	v_mfma_f32_16x16x32_bf16 v[96:99], v[214:217], v[180:183], v[96:99]
	v_mfma_f32_16x16x32_bf16 v[84:87], v[206:209], v[188:191], v[84:87]
	v_mfma_f32_16x16x32_bf16 v[80:83], v[214:217], v[188:191], v[80:83]
	v_mfma_f32_16x16x32_bf16 v[68:71], v[206:209], v[198:201], v[68:71]
	s_setprio 0
	v_mfma_f32_16x16x32_bf16 v[64:67], v[214:217], v[198:201], v[64:67]
	s_barrier
	ds_read_b128 v[168:171], v150 offset:49152
	ds_read_b128 v[172:175], v150 offset:50176
	ds_read_b128 v[176:179], v150 offset:51200
	ds_read_b128 v[180:183], v150 offset:52224
	ds_read_b128 v[184:187], v150 offset:53248
	ds_read_b128 v[188:191], v150 offset:54272
	ds_read_b128 v[192:195], v150 offset:55296
	ds_read_b128 v[198:201], v150 offset:56320
	global_load_lds_dwordx4 v[144:145], off
	v_lshl_add_u64 v[144:145], v[222:223], 0, s[44:45]
	s_mov_b32 m0, s31
	s_nop 0
	global_load_lds_dwordx4 v[144:145], off
	s_waitcnt vmcnt(10)
	s_setprio 1
	s_barrier
; DI unsigned pack2(float a, float b) { f32x2 v = {a, b}; hwbf16x2 r = __builtin_convertvector(v, hwbf16x2); return __builtin_bit_cast(unsigned, r); }
; DI float bflo(unsigned w) { return __uint_as_float(w << 16); }
; DI float bfhi(unsigned w) { return __uint_as_float(w & 0xffff0000u); }
; #define PG8_WAIT_V(n) asm volatile("s_waitcnt vmcnt(" #n ")" ::: "memory")
; #define PG8_BAR __builtin_amdgcn_s_barrier()
;     DI void operator()(const f32x4 (&acc)[2][2][4][2], const Unit& u, int wr, int wc, int fr, int fq) const {
;     ...
;         for (int ai = 0; ai < 2; ++ai)
; #pragma unroll
;             for (int m = 0; m < 4; ++m) { const size_t ro = (size_t)(row0 + ai * HALF + m * 16) * D + col0;
; #pragma unroll
;                 for (int bj = 0; bj < 2; ++bj) {
;                     f32x4 x0, x1;
;                     if constexpr (IB) { const u32x4 w = *(const u32x4*)((const bf16_t*)Xin + ro + bj * HALF);
;                         x0 = (f32x4){bflo(w[0]), bfhi(w[0]), bflo(w[1]), bfhi(w[1])}; x1 = (f32x4){bflo(w[2]), bfhi(w[2]), bflo(w[3]), bfhi(w[3])}; }
;                     else { x0 = *(const f32x4*)((const float*)Xin + ro + bj * HALF); x1 = *(const f32x4*)((const float*)Xin + ro + bj * HALF + 4); }
;                     x0 += acc[ai][bj][m][0] * sc[bj][0]; x1 += acc[ai][bj][m][1] * sc[bj][1];
;                     if constexpr (OB) { u32x4 o; o[0] = pack2(x0[0], x0[1]); o[1] = pack2(x0[2], x0[3]); o[2] = pack2(x1[0], x1[1]); o[3] = pack2(x1[2], x1[3]);
;                         *(u32x4*)((bf16_t*)Xout + ro + bj * HALF) = o; }
;                     else { *(f32x4*)((float*)Xout + ro + bj * HALF) = x0; *(f32x4*)((float*)Xout + ro + bj * HALF + 4) = x1; } } }
; template <class Map, class Epi>
; DI void gemm_phase(LAS unsigned char* lds, const Map& MP, const Epi& E, const int nM, const int nN, const int K, const int lda, const int ldb) {
;     ...
;             PG8_WAIT_L(8); PG8_BAR; PG8_WAIT_L(0); PG8_MMA(0, 0, At, B0); PG8_BAR; PG8_SCHED;
;             PG8_LDB(B1, 1, 1); PG8_STAGE(PG8_SB(1, 0), b3, voffB);
;             PG8_BAR; PG8_WAIT_L(0); PG8_MMA(0, 1, At, B1); PG8_BAR;
;             PG8_LDA(At, 1, 1); PG8_STAGE(PG8_SA(1, 0), a3, voffA);
;             PG8_BAR; PG8_WAIT_L(0); PG8_MMA(1, 0, At, B0); PG8_BAR; PG8_SCHED;
;             PG8_STAGE(PG8_SB(1, 1), b3 + hstepB, voffB);
;             PG8_WAIT_V(6); PG8_BAR; PG8_MMA(1, 1, At, B1); PG8_BAR;
	s_waitcnt lgkmcnt(7)
	v_mfma_f32_16x16x32_bf16 v[60:63], v[152:155], v[168:171], v[60:63]
	v_mfma_f32_16x16x32_bf16 v[56:59], v[160:163], v[168:171], v[56:59]
	s_waitcnt lgkmcnt(5)
	v_mfma_f32_16x16x32_bf16 v[44:47], v[152:155], v[176:179], v[44:47]
	v_mfma_f32_16x16x32_bf16 v[40:43], v[160:163], v[176:179], v[40:43]
	s_waitcnt lgkmcnt(3)
	v_mfma_f32_16x16x32_bf16 v[28:31], v[152:155], v[184:187], v[28:31]
	v_mfma_f32_16x16x32_bf16 v[24:27], v[160:163], v[184:187], v[24:27]
	s_waitcnt lgkmcnt(1)
	v_mfma_f32_16x16x32_bf16 v[12:15], v[152:155], v[192:195], v[12:15]
	v_mfma_f32_16x16x32_bf16 v[8:11], v[160:163], v[192:195], v[8:11]
	v_mfma_f32_16x16x32_bf16 v[60:63], v[156:159], v[172:175], v[60:63]
	s_add_u32 s12, s12, 0x80080
	s_addc_u32 s13, s13, 0
	v_mfma_f32_16x16x32_bf16 v[56:59], v[164:167], v[172:175], v[56:59]
	s_add_i32 s3, s14, s22
	v_mfma_f32_16x16x32_bf16 v[44:47], v[156:159], v[180:183], v[44:47]
	v_mfma_f32_16x16x32_bf16 v[40:43], v[164:167], v[180:183], v[40:43]
	v_mfma_f32_16x16x32_bf16 v[28:31], v[156:159], v[188:191], v[28:31]
	v_mfma_f32_16x16x32_bf16 v[24:27], v[164:167], v[188:191], v[24:27]
	s_waitcnt lgkmcnt(0)
	v_mfma_f32_16x16x32_bf16 v[12:15], v[156:159], v[198:201], v[12:15]
	s_setprio 0
	v_mfma_f32_16x16x32_bf16 v[8:11], v[164:167], v[198:201], v[8:11]
	s_barrier
	s_mov_b32 m0, s3
	s_nop 0
	global_load_lds_dwordx4 v132, s[12:13]
	s_add_i32 m0, s3, 0x2000
	s_nop 0
	global_load_lds_dwordx4 v128, s[12:13]
	s_waitcnt vmcnt(6)
	s_setprio 1
	s_barrier
	v_mfma_f32_16x16x32_bf16 v[52:55], v[202:205], v[168:171], v[52:55]
	v_mfma_f32_16x16x32_bf16 v[48:51], v[210:213], v[168:171], v[48:51]
	ds_read_b128 v[152:155], v149
	v_mfma_f32_16x16x32_bf16 v[36:39], v[202:205], v[176:179], v[36:39]
	v_mfma_f32_16x16x32_bf16 v[32:35], v[210:213], v[176:179], v[32:35]
	ds_read_b128 v[156:159], v149 offset:1024
	v_mfma_f32_16x16x32_bf16 v[20:23], v[202:205], v[184:187], v[20:23]
	v_mfma_f32_16x16x32_bf16 v[16:19], v[210:213], v[184:187], v[16:19]
	ds_read_b128 v[160:163], v149 offset:2048
	v_mfma_f32_16x16x32_bf16 v[4:7], v[202:205], v[192:195], v[4:7]
	v_mfma_f32_16x16x32_bf16 v[0:3], v[210:213], v[192:195], v[0:3]
	ds_read_b128 v[164:167], v149 offset:3072
	v_mfma_f32_16x16x32_bf16 v[52:55], v[206:209], v[172:175], v[52:55]
	s_add_i32 s48, s48, 2
	v_mfma_f32_16x16x32_bf16 v[48:51], v[214:217], v[172:175], v[48:51]
	s_add_u32 s39, s39, 0x100
	s_addc_u32 s47, s47, 0
	v_mfma_f32_16x16x32_bf16 v[36:39], v[206:209], v[180:183], v[36:39]
	s_add_u32 s10, s10, 0x100
	s_addc_u32 s11, s11, 0
	v_mfma_f32_16x16x32_bf16 v[32:35], v[214:217], v[180:183], v[32:35]
	s_cmp_gt_u32 s48, 29
	v_mfma_f32_16x16x32_bf16 v[20:23], v[206:209], v[188:191], v[20:23]
	v_mfma_f32_16x16x32_bf16 v[16:19], v[214:217], v[188:191], v[16:19]
	v_mfma_f32_16x16x32_bf16 v[4:7], v[206:209], v[198:201], v[4:7]
	s_setprio 0
	v_mfma_f32_16x16x32_bf16 v[0:3], v[214:217], v[198:201], v[0:3]
	s_barrier
	s_cbranch_scc0 .LBB1_925
	s_waitcnt lgkmcnt(0)
	v_mov_b32_e32 v152, v147
	v_mov_b32_e32 v144, v146
	s_lshl_b32 s2, s2, 8
	s_or_b32 s2, s2, s29
	v_lshl_add_u32 v144, v144, 3, s2
	s_lshl_b32 s2, s8, 8
	s_add_i32 s2, s2, s28
	v_add_u32_e32 v152, s2, v152
	v_ashrrev_i32_e32 v153, 31, v152
	v_lshlrev_b64 v[152:153], 12, v[152:153]
	v_ashrrev_i32_e32 v145, 31, v144
	v_lshl_add_u64 v[152:153], s[42:43], 0, v[152:153]
	v_lshl_add_u64 v[144:145], v[144:145], 1, v[152:153]
	global_load_dwordx4 v[160:163], v[144:145], off
	global_load_dwordx4 v[164:167], v[144:145], off offset:256
	s_mov_b64 s[98:99], 0x10000
	v_lshl_add_u64 v[154:155], v[144:145], 0, s[98:99]
	global_load_dwordx4 v[168:171], v[154:155], off
	global_load_dwordx4 v[172:175], v[154:155], off offset:256
	s_mov_b64 s[98:99], 0x20000
	v_lshl_add_u64 v[154:155], v[144:145], 0, s[98:99]
	global_load_dwordx4 v[176:179], v[154:155], off
	global_load_dwordx4 v[180:183], v[154:155], off offset:256
	s_mov_b64 s[98:99], 0x30000
	v_lshl_add_u64 v[154:155], v[144:145], 0, s[98:99]
	global_load_dwordx4 v[184:187], v[154:155], off
	global_load_dwordx4 v[188:191], v[154:155], off offset:256
	s_mov_b64 s[98:99], 0x80000
	v_lshl_add_u64 v[154:155], v[144:145], 0, s[98:99]
	global_load_dwordx4 v[192:195], v[154:155], off
	global_load_dwordx4 v[198:201], v[154:155], off offset:256
	s_mov_b64 s[98:99], 0x90000
	v_lshl_add_u64 v[154:155], v[144:145], 0, s[98:99]
	global_load_dwordx4 v[202:205], v[154:155], off
	global_load_dwordx4 v[206:209], v[154:155], off offset:256
	s_mov_b64 s[98:99], 0xa0000
	v_lshl_add_u64 v[154:155], v[144:145], 0, s[98:99]
	global_load_dwordx4 v[210:213], v[154:155], off
	global_load_dwordx4 v[214:217], v[154:155], off offset:256
	s_mov_b64 s[98:99], 0xb0000
	v_lshl_add_u64 v[154:155], v[144:145], 0, s[98:99]
	global_load_dwordx4 v[248:251], v[154:155], off
	global_load_dwordx4 v[252:255], v[154:155], off offset:256
	s_waitcnt vmcnt(15)
	s_nop 1
	v_mov_b32_e32 v152, v160
	v_mov_b32_e32 v153, v161
	v_mov_b32_e32 v154, v162
	v_mov_b32_e32 v155, v163
	s_mov_b64 s[2:3], 0x10000
	s_mov_b32 s8, s52
	s_mov_b64 s[10:11], s[6:7]
	s_mov_b64 s[12:13], s[54:55]
	s_waitcnt lgkmcnt(0)
	v_lshlrev_b32_e32 v156, 16, v152
	v_and_b32_e32 v157, 0xffff0000, v152
	v_lshlrev_b32_e32 v152, 16, v153
	v_and_b32_e32 v153, 0xffff0000, v153
	v_lshlrev_b32_e32 v158, 16, v154
	v_and_b32_e32 v159, 0xffff0000, v154
	v_lshlrev_b32_e32 v154, 16, v155
	v_and_b32_e32 v155, 0xffff0000, v155
	v_pk_add_f32 v[126:127], v[126:127], v[152:153]
	v_pk_add_f32 v[124:125], v[124:125], v[156:157]
	v_pk_add_f32 v[152:153], v[122:123], v[154:155]
	v_pk_add_f32 v[122:123], v[120:121], v[158:159]
	v_cvt_pk_bf16_f32 v120, v124, v125
	v_cvt_pk_bf16_f32 v121, v126, v127
	v_cvt_pk_bf16_f32 v122, v122, v123
	v_cvt_pk_bf16_f32 v123, v152, v153
	global_store_dwordx4 v[144:145], v[120:123], off
	s_waitcnt vmcnt(15)
; DI unsigned pack2(float a, float b) { f32x2 v = {a, b}; hwbf16x2 r = __builtin_convertvector(v, hwbf16x2); return __builtin_bit_cast(unsigned, r); }
; DI float bflo(unsigned w) { return __uint_as_float(w << 16); }
; DI float bfhi(unsigned w) { return __uint_as_float(w & 0xffff0000u); }
;     DI void operator()(const f32x4 (&acc)[2][2][4][2], const Unit& u, int wr, int wc, int fr, int fq) const {
;     ...
;         for (int ai = 0; ai < 2; ++ai)
; #pragma unroll
;             for (int m = 0; m < 4; ++m) { const size_t ro = (size_t)(row0 + ai * HALF + m * 16) * D + col0;
; #pragma unroll
;                 for (int bj = 0; bj < 2; ++bj) {
;                     f32x4 x0, x1;
;                     if constexpr (IB) { const u32x4 w = *(const u32x4*)((const bf16_t*)Xin + ro + bj * HALF);
;                         x0 = (f32x4){bflo(w[0]), bfhi(w[0]), bflo(w[1]), bfhi(w[1])}; x1 = (f32x4){bflo(w[2]), bfhi(w[2]), bflo(w[3]), bfhi(w[3])}; }
;                     else { x0 = *(const f32x4*)((const float*)Xin + ro + bj * HALF); x1 = *(const f32x4*)((const float*)Xin + ro + bj * HALF + 4); }
;                     x0 += acc[ai][bj][m][0] * sc[bj][0]; x1 += acc[ai][bj][m][1] * sc[bj][1];
;                     if constexpr (OB) { u32x4 o; o[0] = pack2(x0[0], x0[1]); o[1] = pack2(x0[2], x0[3]); o[2] = pack2(x1[0], x1[1]); o[3] = pack2(x1[2], x1[3]);
;                         *(u32x4*)((bf16_t*)Xout + ro + bj * HALF) = o; }
;                     else { *(f32x4*)((float*)Xout + ro + bj * HALF) = x0; *(f32x4*)((float*)Xout + ro + bj * HALF + 4) = x1; } } }
	s_nop 1
	v_mov_b32_e32 v120, v164
	v_mov_b32_e32 v121, v165
	v_mov_b32_e32 v122, v166
	v_mov_b32_e32 v123, v167
	s_waitcnt lgkmcnt(0)
	v_lshlrev_b32_e32 v124, 16, v120
	v_and_b32_e32 v125, 0xffff0000, v120
	v_lshlrev_b32_e32 v120, 16, v121
	v_and_b32_e32 v121, 0xffff0000, v121
	v_lshlrev_b32_e32 v126, 16, v122
	v_and_b32_e32 v127, 0xffff0000, v122
	v_lshlrev_b32_e32 v122, 16, v123
	v_and_b32_e32 v123, 0xffff0000, v123
	v_pk_add_f32 v[116:117], v[116:117], v[124:125]
	v_pk_add_f32 v[118:119], v[118:119], v[120:121]
	v_pk_add_f32 v[120:121], v[114:115], v[122:123]
	v_pk_add_f32 v[114:115], v[112:113], v[126:127]
	v_cvt_pk_bf16_f32 v112, v116, v117
	v_lshl_add_u64 v[116:117], v[144:145], 0, s[2:3]
	s_mov_b32 s2, 0x10000
	v_cvt_pk_bf16_f32 v113, v118, v119
	v_add_co_u32_e32 v118, vcc, s2, v144
	v_cvt_pk_bf16_f32 v114, v114, v115
	v_cvt_pk_bf16_f32 v115, v120, v121
	v_addc_co_u32_e32 v119, vcc, 0, v145, vcc
	global_store_dwordx4 v[144:145], v[112:115], off offset:256
	s_waitcnt vmcnt(15)
	s_nop 1
	v_mov_b32_e32 v112, v168
	v_mov_b32_e32 v113, v169
	v_mov_b32_e32 v114, v170
	v_mov_b32_e32 v115, v171
	s_mov_b64 s[2:3], 0x20000
	s_waitcnt lgkmcnt(0)
	v_lshlrev_b32_e32 v120, 16, v112
	v_and_b32_e32 v121, 0xffff0000, v112
	v_lshlrev_b32_e32 v112, 16, v113
	v_and_b32_e32 v113, 0xffff0000, v113
	v_lshlrev_b32_e32 v122, 16, v114
	v_and_b32_e32 v123, 0xffff0000, v114
	v_lshlrev_b32_e32 v114, 16, v115
	v_and_b32_e32 v115, 0xffff0000, v115
	v_pk_add_f32 v[110:111], v[110:111], v[112:113]
	v_pk_add_f32 v[108:109], v[108:109], v[120:121]
	v_pk_add_f32 v[112:113], v[106:107], v[114:115]
	v_pk_add_f32 v[106:107], v[104:105], v[122:123]
	v_cvt_pk_bf16_f32 v104, v108, v109
	v_cvt_pk_bf16_f32 v105, v110, v111
	v_cvt_pk_bf16_f32 v106, v106, v107
	v_cvt_pk_bf16_f32 v107, v112, v113
	global_store_dwordx4 v[118:119], v[104:107], off
	s_waitcnt vmcnt(15)
	s_nop 1
	v_mov_b32_e32 v104, v172
	v_mov_b32_e32 v105, v173
	v_mov_b32_e32 v106, v174
	v_mov_b32_e32 v107, v175
	s_waitcnt lgkmcnt(0)
	v_lshlrev_b32_e32 v108, 16, v104
	v_and_b32_e32 v109, 0xffff0000, v104
	v_lshlrev_b32_e32 v104, 16, v105
	v_and_b32_e32 v105, 0xffff0000, v105
	v_lshlrev_b32_e32 v110, 16, v106
	v_and_b32_e32 v111, 0xffff0000, v106
	v_lshlrev_b32_e32 v106, 16, v107
	v_and_b32_e32 v107, 0xffff0000, v107
	v_pk_add_f32 v[100:101], v[100:101], v[108:109]
	v_pk_add_f32 v[102:103], v[102:103], v[104:105]
	v_pk_add_f32 v[104:105], v[98:99], v[106:107]
	v_pk_add_f32 v[98:99], v[96:97], v[110:111]
	v_cvt_pk_bf16_f32 v96, v100, v101
	v_lshl_add_u64 v[100:101], v[144:145], 0, s[2:3]
	s_mov_b32 s2, 0x20000
	v_cvt_pk_bf16_f32 v97, v102, v103
	v_add_co_u32_e32 v102, vcc, s2, v144
	v_cvt_pk_bf16_f32 v98, v98, v99
	v_cvt_pk_bf16_f32 v99, v104, v105
	v_addc_co_u32_e32 v103, vcc, 0, v145, vcc
	global_store_dwordx4 v[116:117], v[96:99], off offset:256
	s_waitcnt vmcnt(15)
	s_nop 1
	v_mov_b32_e32 v96, v176
	v_mov_b32_e32 v97, v177
	v_mov_b32_e32 v98, v178
	v_mov_b32_e32 v99, v179
	s_mov_b64 s[2:3], 0x30000
	s_waitcnt lgkmcnt(0)
	v_lshlrev_b32_e32 v104, 16, v96
	v_and_b32_e32 v105, 0xffff0000, v96
	v_lshlrev_b32_e32 v96, 16, v97
	v_and_b32_e32 v97, 0xffff0000, v97
	v_lshlrev_b32_e32 v106, 16, v98
	v_and_b32_e32 v107, 0xffff0000, v98
	v_lshlrev_b32_e32 v98, 16, v99
	v_and_b32_e32 v99, 0xffff0000, v99
	v_pk_add_f32 v[94:95], v[94:95], v[96:97]
	v_pk_add_f32 v[92:93], v[92:93], v[104:105]
	v_pk_add_f32 v[96:97], v[90:91], v[98:99]
	v_pk_add_f32 v[90:91], v[88:89], v[106:107]
	v_cvt_pk_bf16_f32 v88, v92, v93
	v_cvt_pk_bf16_f32 v89, v94, v95
	v_cvt_pk_bf16_f32 v90, v90, v91
	v_cvt_pk_bf16_f32 v91, v96, v97
	global_store_dwordx4 v[102:103], v[88:91], off
	s_waitcnt vmcnt(15)
	s_nop 1
	v_mov_b32_e32 v88, v180
	v_mov_b32_e32 v89, v181
	v_mov_b32_e32 v90, v182
	v_mov_b32_e32 v91, v183
	s_waitcnt lgkmcnt(0)
	v_lshlrev_b32_e32 v92, 16, v88
	v_and_b32_e32 v93, 0xffff0000, v88
	v_lshlrev_b32_e32 v88, 16, v89
	v_and_b32_e32 v89, 0xffff0000, v89
	v_lshlrev_b32_e32 v94, 16, v90
	v_and_b32_e32 v95, 0xffff0000, v90
	v_lshlrev_b32_e32 v90, 16, v91
	v_and_b32_e32 v91, 0xffff0000, v91
	v_pk_add_f32 v[86:87], v[86:87], v[88:89]
	v_pk_add_f32 v[84:85], v[84:85], v[92:93]
	v_pk_add_f32 v[88:89], v[82:83], v[90:91]
	v_pk_add_f32 v[82:83], v[80:81], v[94:95]
	v_cvt_pk_bf16_f32 v80, v84, v85
	v_cvt_pk_bf16_f32 v81, v86, v87
	v_cvt_pk_bf16_f32 v82, v82, v83
	v_cvt_pk_bf16_f32 v83, v88, v89
	global_store_dwordx4 v[100:101], v[80:83], off offset:256
	s_nop 1
	v_lshl_add_u64 v[80:81], v[144:145], 0, s[2:3]
	s_mov_b32 s2, 0x30000
	v_add_co_u32_e32 v86, vcc, s2, v144
	s_mov_b64 s[2:3], 0x80000
	s_nop 0
	v_addc_co_u32_e32 v87, vcc, 0, v145, vcc
	s_waitcnt vmcnt(15)
	s_nop 1
	v_mov_b32_e32 v82, v184
	v_mov_b32_e32 v83, v185
	v_mov_b32_e32 v84, v186
	v_mov_b32_e32 v85, v187
	s_waitcnt lgkmcnt(0)
	v_lshlrev_b32_e32 v88, 16, v82
	v_and_b32_e32 v89, 0xffff0000, v82
	v_lshlrev_b32_e32 v82, 16, v83
	v_and_b32_e32 v83, 0xffff0000, v83
	v_lshlrev_b32_e32 v90, 16, v84
	v_and_b32_e32 v91, 0xffff0000, v84
	v_lshlrev_b32_e32 v84, 16, v85
	v_and_b32_e32 v85, 0xffff0000, v85
	v_pk_add_f32 v[78:79], v[78:79], v[82:83]
	v_pk_add_f32 v[76:77], v[76:77], v[88:89]
	v_pk_add_f32 v[82:83], v[74:75], v[84:85]
	v_pk_add_f32 v[74:75], v[72:73], v[90:91]
	v_cvt_pk_bf16_f32 v72, v76, v77
	v_cvt_pk_bf16_f32 v73, v78, v79
	v_cvt_pk_bf16_f32 v74, v74, v75
	v_cvt_pk_bf16_f32 v75, v82, v83
	global_store_dwordx4 v[86:87], v[72:75], off
	s_waitcnt vmcnt(15)
	s_nop 1
	v_mov_b32_e32 v72, v188
	v_mov_b32_e32 v73, v189
	v_mov_b32_e32 v74, v190
	v_mov_b32_e32 v75, v191
	s_waitcnt lgkmcnt(0)
; DI unsigned pack2(float a, float b) { f32x2 v = {a, b}; hwbf16x2 r = __builtin_convertvector(v, hwbf16x2); return __builtin_bit_cast(unsigned, r); }
; DI float bflo(unsigned w) { return __uint_as_float(w << 16); }
; DI float bfhi(unsigned w) { return __uint_as_float(w & 0xffff0000u); }
;     DI void operator()(const f32x4 (&acc)[2][2][4][2], const Unit& u, int wr, int wc, int fr, int fq) const {
;     ...
;         for (int ai = 0; ai < 2; ++ai)
; #pragma unroll
;             for (int m = 0; m < 4; ++m) { const size_t ro = (size_t)(row0 + ai * HALF + m * 16) * D + col0;
; #pragma unroll
;                 for (int bj = 0; bj < 2; ++bj) {
;                     f32x4 x0, x1;
;                     if constexpr (IB) { const u32x4 w = *(const u32x4*)((const bf16_t*)Xin + ro + bj * HALF);
;                         x0 = (f32x4){bflo(w[0]), bfhi(w[0]), bflo(w[1]), bfhi(w[1])}; x1 = (f32x4){bflo(w[2]), bfhi(w[2]), bflo(w[3]), bfhi(w[3])}; }
;                     else { x0 = *(const f32x4*)((const float*)Xin + ro + bj * HALF); x1 = *(const f32x4*)((const float*)Xin + ro + bj * HALF + 4); }
;                     x0 += acc[ai][bj][m][0] * sc[bj][0]; x1 += acc[ai][bj][m][1] * sc[bj][1];
;                     if constexpr (OB) { u32x4 o; o[0] = pack2(x0[0], x0[1]); o[1] = pack2(x0[2], x0[3]); o[2] = pack2(x1[0], x1[1]); o[3] = pack2(x1[2], x1[3]);
;                         *(u32x4*)((bf16_t*)Xout + ro + bj * HALF) = o; }
;                     else { *(f32x4*)((float*)Xout + ro + bj * HALF) = x0; *(f32x4*)((float*)Xout + ro + bj * HALF + 4) = x1; } } }
	v_lshlrev_b32_e32 v76, 16, v72
	v_and_b32_e32 v77, 0xffff0000, v72
	v_lshlrev_b32_e32 v72, 16, v73
	v_and_b32_e32 v73, 0xffff0000, v73
	v_lshlrev_b32_e32 v78, 16, v74
	v_and_b32_e32 v79, 0xffff0000, v74
	v_lshlrev_b32_e32 v74, 16, v75
	v_and_b32_e32 v75, 0xffff0000, v75
	v_pk_add_f32 v[70:71], v[70:71], v[72:73]
	v_pk_add_f32 v[68:69], v[68:69], v[76:77]
	v_pk_add_f32 v[72:73], v[66:67], v[74:75]
	v_pk_add_f32 v[66:67], v[64:65], v[78:79]
	v_cvt_pk_bf16_f32 v64, v68, v69
	v_cvt_pk_bf16_f32 v65, v70, v71
	v_cvt_pk_bf16_f32 v66, v66, v67
	v_cvt_pk_bf16_f32 v67, v72, v73
	global_store_dwordx4 v[80:81], v[64:67], off offset:256
	s_nop 1
	v_lshl_add_u64 v[64:65], v[144:145], 0, s[2:3]
	s_mov_b32 s2, 0x80000
	v_add_co_u32_e32 v70, vcc, s2, v144
	s_mov_b64 s[2:3], 0x90000
	s_nop 0
	v_addc_co_u32_e32 v71, vcc, 0, v145, vcc
	s_waitcnt vmcnt(15)
	s_nop 1
	v_mov_b32_e32 v66, v192
	v_mov_b32_e32 v67, v193
	v_mov_b32_e32 v68, v194
	v_mov_b32_e32 v69, v195
	s_waitcnt lgkmcnt(0)
	v_lshlrev_b32_e32 v72, 16, v66
	v_and_b32_e32 v73, 0xffff0000, v66
	v_lshlrev_b32_e32 v66, 16, v67
	v_and_b32_e32 v67, 0xffff0000, v67
	v_lshlrev_b32_e32 v74, 16, v68
	v_and_b32_e32 v75, 0xffff0000, v68
	v_lshlrev_b32_e32 v68, 16, v69
	v_and_b32_e32 v69, 0xffff0000, v69
	v_pk_add_f32 v[62:63], v[62:63], v[66:67]
	v_pk_add_f32 v[60:61], v[60:61], v[72:73]
	v_pk_add_f32 v[66:67], v[58:59], v[68:69]
	v_pk_add_f32 v[58:59], v[56:57], v[74:75]
	v_cvt_pk_bf16_f32 v56, v60, v61
	v_cvt_pk_bf16_f32 v57, v62, v63
	v_cvt_pk_bf16_f32 v58, v58, v59
	v_cvt_pk_bf16_f32 v59, v66, v67
	global_store_dwordx4 v[70:71], v[56:59], off
	s_waitcnt vmcnt(15)
	s_nop 1
	v_mov_b32_e32 v56, v198
	v_mov_b32_e32 v57, v199
	v_mov_b32_e32 v58, v200
	v_mov_b32_e32 v59, v201
	s_waitcnt lgkmcnt(0)
	v_lshlrev_b32_e32 v60, 16, v56
	v_and_b32_e32 v61, 0xffff0000, v56
	v_lshlrev_b32_e32 v56, 16, v57
	v_and_b32_e32 v57, 0xffff0000, v57
	v_lshlrev_b32_e32 v62, 16, v58
	v_and_b32_e32 v63, 0xffff0000, v58
	v_lshlrev_b32_e32 v58, 16, v59
	v_and_b32_e32 v59, 0xffff0000, v59
	v_pk_add_f32 v[54:55], v[54:55], v[56:57]
	v_pk_add_f32 v[52:53], v[52:53], v[60:61]
	v_pk_add_f32 v[56:57], v[50:51], v[58:59]
	v_pk_add_f32 v[50:51], v[48:49], v[62:63]
	v_cvt_pk_bf16_f32 v48, v52, v53
	v_cvt_pk_bf16_f32 v49, v54, v55
	v_cvt_pk_bf16_f32 v50, v50, v51
	v_cvt_pk_bf16_f32 v51, v56, v57
	global_store_dwordx4 v[64:65], v[48:51], off offset:256
	s_nop 1
	v_lshl_add_u64 v[48:49], v[144:145], 0, s[2:3]
	s_mov_b32 s2, 0x90000
	v_add_co_u32_e32 v54, vcc, s2, v144
	s_mov_b64 s[2:3], 0xa0000
	s_nop 0
	v_addc_co_u32_e32 v55, vcc, 0, v145, vcc
	s_waitcnt vmcnt(15)
	s_nop 1
	v_mov_b32_e32 v50, v202
	v_mov_b32_e32 v51, v203
	v_mov_b32_e32 v52, v204
	v_mov_b32_e32 v53, v205
	s_waitcnt lgkmcnt(0)
	v_lshlrev_b32_e32 v56, 16, v50
	v_and_b32_e32 v57, 0xffff0000, v50
	v_lshlrev_b32_e32 v50, 16, v51
	v_and_b32_e32 v51, 0xffff0000, v51
	v_lshlrev_b32_e32 v58, 16, v52
	v_and_b32_e32 v59, 0xffff0000, v52
	v_lshlrev_b32_e32 v52, 16, v53
	v_and_b32_e32 v53, 0xffff0000, v53
	v_pk_add_f32 v[46:47], v[46:47], v[50:51]
	v_pk_add_f32 v[44:45], v[44:45], v[56:57]
	v_pk_add_f32 v[50:51], v[42:43], v[52:53]
	v_pk_add_f32 v[42:43], v[40:41], v[58:59]
	v_cvt_pk_bf16_f32 v40, v44, v45
	v_cvt_pk_bf16_f32 v41, v46, v47
	v_cvt_pk_bf16_f32 v42, v42, v43
	v_cvt_pk_bf16_f32 v43, v50, v51
	global_store_dwordx4 v[54:55], v[40:43], off
	s_waitcnt vmcnt(15)
	s_nop 1
	v_mov_b32_e32 v40, v206
	v_mov_b32_e32 v41, v207
	v_mov_b32_e32 v42, v208
	v_mov_b32_e32 v43, v209
	s_waitcnt lgkmcnt(0)
; DI unsigned pack2(float a, float b) { f32x2 v = {a, b}; hwbf16x2 r = __builtin_convertvector(v, hwbf16x2); return __builtin_bit_cast(unsigned, r); }
; DI float bflo(unsigned w) { return __uint_as_float(w << 16); }
; DI float bfhi(unsigned w) { return __uint_as_float(w & 0xffff0000u); }
;     DI const char* a(const Unit& u) const { return (const char*)(A + (size_t)u.pm * BM * lda); }
;     DI const char* a(const Unit& u) const { return (const char*)(A + (size_t)u.pm * BM * 2048 + (u.pn >> 1) * 512); }
;     DI void operator()(const f32x4 (&acc)[2][2][4][2], const Unit& u, int wr, int wc, int fr, int fq) const {
;     ...
;         for (int ai = 0; ai < 2; ++ai)
; #pragma unroll
;             for (int m = 0; m < 4; ++m) { const size_t ro = (size_t)(row0 + ai * HALF + m * 16) * D + col0;
; #pragma unroll
;                 for (int bj = 0; bj < 2; ++bj) {
;                     f32x4 x0, x1;
;                     if constexpr (IB) { const u32x4 w = *(const u32x4*)((const bf16_t*)Xin + ro + bj * HALF);
;                         x0 = (f32x4){bflo(w[0]), bfhi(w[0]), bflo(w[1]), bfhi(w[1])}; x1 = (f32x4){bflo(w[2]), bfhi(w[2]), bflo(w[3]), bfhi(w[3])}; }
;                     else { x0 = *(const f32x4*)((const float*)Xin + ro + bj * HALF); x1 = *(const f32x4*)((const float*)Xin + ro + bj * HALF + 4); }
;                     x0 += acc[ai][bj][m][0] * sc[bj][0]; x1 += acc[ai][bj][m][1] * sc[bj][1];
;                     if constexpr (OB) { u32x4 o; o[0] = pack2(x0[0], x0[1]); o[1] = pack2(x0[2], x0[3]); o[2] = pack2(x1[0], x1[1]); o[3] = pack2(x1[2], x1[3]);
;                         *(u32x4*)((bf16_t*)Xout + ro + bj * HALF) = o; }
;                     else { *(f32x4*)((float*)Xout + ro + bj * HALF) = x0; *(f32x4*)((float*)Xout + ro + bj * HALF + 4) = x1; } } }
; template <class Map, class Epi>
; DI void gemm_phase(LAS unsigned char* lds, const Map& MP, const Epi& E, const int nM, const int nN, const int K, const int lda, const int ldb) {
;     ...
;         if (!has_next) break;
; #pragma unroll
;         for (int a = 0; a < 2; ++a)
; #pragma unroll
;             for (int b = 0; b < 2; ++b)
; #pragma unroll
;                 for (int m = 0; m < 4; ++m)
; #pragma unroll
;                     for (int n = 0; n < 2; ++n) acc[a][b][m][n] = (f32x4){0.f, 0.f, 0.f, 0.f};
;         cur = nxt; cA = nA; cB = nB; ++ui;
;     }
;     PG8_WAIT_V(0);
;     if (wr == 0) PG8_BAR;
;     PG8_BAR;
	v_lshlrev_b32_e32 v44, 16, v40
	v_and_b32_e32 v45, 0xffff0000, v40
	v_lshlrev_b32_e32 v40, 16, v41
	v_and_b32_e32 v41, 0xffff0000, v41
	v_lshlrev_b32_e32 v46, 16, v42
	v_and_b32_e32 v47, 0xffff0000, v42
	v_lshlrev_b32_e32 v42, 16, v43
	v_and_b32_e32 v43, 0xffff0000, v43
	v_pk_add_f32 v[38:39], v[38:39], v[40:41]
	v_pk_add_f32 v[36:37], v[36:37], v[44:45]
	v_pk_add_f32 v[40:41], v[34:35], v[42:43]
	v_pk_add_f32 v[34:35], v[32:33], v[46:47]
	v_cvt_pk_bf16_f32 v32, v36, v37
	v_cvt_pk_bf16_f32 v33, v38, v39
	v_cvt_pk_bf16_f32 v34, v34, v35
	v_cvt_pk_bf16_f32 v35, v40, v41
	global_store_dwordx4 v[48:49], v[32:35], off offset:256
	s_nop 1
	v_lshl_add_u64 v[32:33], v[144:145], 0, s[2:3]
	s_mov_b32 s2, 0xa0000
	v_add_co_u32_e32 v38, vcc, s2, v144
	s_mov_b64 s[2:3], 0xb0000
	s_nop 0
	v_addc_co_u32_e32 v39, vcc, 0, v145, vcc
	s_waitcnt vmcnt(15)
	s_nop 1
	v_mov_b32_e32 v34, v210
	v_mov_b32_e32 v35, v211
	v_mov_b32_e32 v36, v212
	v_mov_b32_e32 v37, v213
	s_waitcnt lgkmcnt(0)
	v_lshlrev_b32_e32 v40, 16, v34
	v_and_b32_e32 v41, 0xffff0000, v34
	v_lshlrev_b32_e32 v34, 16, v35
	v_and_b32_e32 v35, 0xffff0000, v35
	v_lshlrev_b32_e32 v42, 16, v36
	v_and_b32_e32 v43, 0xffff0000, v36
	v_lshlrev_b32_e32 v36, 16, v37
	v_and_b32_e32 v37, 0xffff0000, v37
	v_pk_add_f32 v[30:31], v[30:31], v[34:35]
	v_pk_add_f32 v[28:29], v[28:29], v[40:41]
	v_pk_add_f32 v[34:35], v[26:27], v[36:37]
	v_pk_add_f32 v[26:27], v[24:25], v[42:43]
	v_cvt_pk_bf16_f32 v24, v28, v29
	v_cvt_pk_bf16_f32 v25, v30, v31
	v_cvt_pk_bf16_f32 v26, v26, v27
	v_cvt_pk_bf16_f32 v27, v34, v35
	global_store_dwordx4 v[38:39], v[24:27], off
	s_waitcnt vmcnt(15)
	s_nop 1
	v_mov_b32_e32 v24, v214
	v_mov_b32_e32 v25, v215
	v_mov_b32_e32 v26, v216
	v_mov_b32_e32 v27, v217
	s_waitcnt lgkmcnt(0)
	v_lshlrev_b32_e32 v28, 16, v24
	v_and_b32_e32 v29, 0xffff0000, v24
	v_lshlrev_b32_e32 v24, 16, v25
	v_and_b32_e32 v25, 0xffff0000, v25
	v_lshlrev_b32_e32 v30, 16, v26
	v_and_b32_e32 v31, 0xffff0000, v26
	v_lshlrev_b32_e32 v26, 16, v27
	v_and_b32_e32 v27, 0xffff0000, v27
	v_pk_add_f32 v[22:23], v[22:23], v[24:25]
	v_pk_add_f32 v[20:21], v[20:21], v[28:29]
	v_pk_add_f32 v[24:25], v[18:19], v[26:27]
	v_pk_add_f32 v[18:19], v[16:17], v[30:31]
	v_cvt_pk_bf16_f32 v16, v20, v21
	v_cvt_pk_bf16_f32 v17, v22, v23
	v_cvt_pk_bf16_f32 v18, v18, v19
	v_cvt_pk_bf16_f32 v19, v24, v25
	global_store_dwordx4 v[32:33], v[16:19], off offset:256
	s_nop 1
	v_lshl_add_u64 v[16:17], v[144:145], 0, s[2:3]
	s_mov_b32 s2, 0xb0000
	v_add_co_u32_e32 v22, vcc, s2, v144
	s_mov_b32 s2, s46
	s_nop 0
	v_addc_co_u32_e32 v23, vcc, 0, v145, vcc
	s_waitcnt vmcnt(15)
	s_nop 1
	v_mov_b32_e32 v18, v248
	v_mov_b32_e32 v19, v249
	v_mov_b32_e32 v20, v250
	v_mov_b32_e32 v21, v251
	s_and_b64 vcc, exec, s[40:41]
	s_waitcnt lgkmcnt(0)
	v_lshlrev_b32_e32 v24, 16, v18
	v_and_b32_e32 v25, 0xffff0000, v18
	v_lshlrev_b32_e32 v18, 16, v19
	v_and_b32_e32 v19, 0xffff0000, v19
	v_lshlrev_b32_e32 v26, 16, v20
	v_and_b32_e32 v27, 0xffff0000, v20
	v_lshlrev_b32_e32 v20, 16, v21
	v_and_b32_e32 v21, 0xffff0000, v21
	v_pk_add_f32 v[14:15], v[14:15], v[18:19]
	v_pk_add_f32 v[12:13], v[12:13], v[24:25]
	v_pk_add_f32 v[18:19], v[10:11], v[20:21]
	v_pk_add_f32 v[10:11], v[8:9], v[26:27]
	v_cvt_pk_bf16_f32 v8, v12, v13
	v_cvt_pk_bf16_f32 v9, v14, v15
	v_cvt_pk_bf16_f32 v10, v10, v11
	v_cvt_pk_bf16_f32 v11, v18, v19
	global_store_dwordx4 v[22:23], v[8:11], off
	s_waitcnt vmcnt(15)
	s_nop 1
	v_mov_b32_e32 v8, v252
	v_mov_b32_e32 v9, v253
	v_mov_b32_e32 v10, v254
	v_mov_b32_e32 v11, v255
	s_waitcnt lgkmcnt(0)
	v_lshlrev_b32_e32 v12, 16, v8
	v_and_b32_e32 v13, 0xffff0000, v8
	v_lshlrev_b32_e32 v8, 16, v9
	v_and_b32_e32 v9, 0xffff0000, v9
	v_lshlrev_b32_e32 v14, 16, v10
	v_and_b32_e32 v15, 0xffff0000, v10
	v_lshlrev_b32_e32 v10, 16, v11
	v_and_b32_e32 v11, 0xffff0000, v11
	v_pk_add_f32 v[6:7], v[6:7], v[8:9]
	v_pk_add_f32 v[4:5], v[4:5], v[12:13]
	v_pk_add_f32 v[8:9], v[2:3], v[10:11]
	v_pk_add_f32 v[2:3], v[0:1], v[14:15]
	v_cvt_pk_bf16_f32 v0, v4, v5
	v_cvt_pk_bf16_f32 v1, v6, v7
	v_cvt_pk_bf16_f32 v2, v2, v3
	v_cvt_pk_bf16_f32 v3, v8, v9
	global_store_dwordx4 v[16:17], v[0:3], off offset:256
	s_cbranch_vccz .LBB1_922
	s_waitcnt vmcnt(0)
	s_cmpk_gt_u32 s17, 0xff
	s_cbranch_scc1 .LBB1_929
	s_barrier

; #define PG8_STAGE(bufoff, gbase, voff) do { _Pragma("unroll") for (int _i = 0; _i < 2; ++_i) \
;         __builtin_amdgcn_global_load_lds((const unsigned*)((const char*)(gbase) + (voff)[_i]), (LAS unsigned*)(lds + (bufoff) + ldsw + _i * 8192), 16, 0, 0); } while (0)
; #define PG8_LDA(dst, b, h) do { _Pragma("unroll") for (int m = 0; m < 4; ++m) _Pragma("unroll") for (int k = 0; k < 2; ++k) dst[m][k] = *(const LAS bf16x8*)(lds + PG8_SA(b, h) + aoff + m * 2048 + k * 1024); } while (0)
; #define PG8_LDB(dst, b, h) do { _Pragma("unroll") for (int n = 0; n < 2; ++n) _Pragma("unroll") for (int k = 0; k < 2; ++k) dst[n][k] = *(const LAS bf16x8*)(lds + PG8_SB(b, h) + boff + n * 2048 + k * 1024); } while (0)
; #define PG8_MMA(ai, bj, At, Bt) do { __builtin_amdgcn_s_setprio(1); _Pragma("unroll") for (int m = 0; m < 4; ++m) _Pragma("unroll") for (int n = 0; n < 2; ++n) _Pragma("unroll") for (int k = 0; k < 2; ++k) \
;         acc[ai][bj][m][n] = __builtin_amdgcn_mfma_f32_16x16x32_bf16(Bt[n][k], At[m][k], acc[ai][bj][m][n], 0, 0, 0); __builtin_amdgcn_s_setprio(0); } while (0)
; #define PG8_WAIT_V(n) asm volatile("s_waitcnt vmcnt(" #n ")" ::: "memory")
; #define PG8_WAIT_L(n) asm volatile("s_waitcnt lgkmcnt(" #n ")" ::: "memory")
; template <class Map, class Epi>
; DI void gemm_phase(LAS unsigned char* lds, const Map& MP, const Epi& E, const int nM, const int nN, const int K, const int lda, const int ldb) {
;     ...
;         for (int t = 0; t < nt; t += 2) {
;             const bool last = (t == nt - 2);
;             const char* a1 = cA + (size_t)(t + 1) * kstep;
;             const char* a2 = last ? nA : cA + (size_t)(t + 2) * kstep; const char* b2 = last ? nB : cB + (size_t)(t + 2) * kstep;
;             const char* a3 = a2 + kstep; const char* b3 = b2 + kstep;
;             PG8_LDB(B0, 0, 0); PG8_SCHED; PG8_LDA(At, 0, 0); PG8_STAGE(PG8_SA(1, 1), a1 + hstepA, voffA);
;             PG8_WAIT_L(8); PG8_BAR; PG8_WAIT_L(0); PG8_MMA(0, 0, At, B0); PG8_BAR; PG8_SCHED;
;             PG8_LDB(B1, 0, 1); PG8_STAGE(PG8_SB(0, 0), b2, voffB);
;             PG8_BAR; PG8_WAIT_L(0); PG8_MMA(0, 1, At, B1); PG8_BAR;
;             PG8_LDA(At, 0, 1); PG8_STAGE(PG8_SA(0, 0), a2, voffA);
;             PG8_BAR; PG8_WAIT_L(0); PG8_MMA(1, 0, At, B0); PG8_BAR; PG8_SCHED;
;             PG8_STAGE(PG8_SB(0, 1), b2 + hstepB, voffB);
;             PG8_WAIT_V(6); PG8_BAR; PG8_MMA(1, 1, At, B1); PG8_BAR;
.LBB1_1069:
	s_add_u32 s24, s42, 0xfff80080
	s_addc_u32 s25, s43, -1
	s_cmp_eq_u32 s3, 28
	s_cselect_b32 s47, s23, s25
	s_cselect_b32 s46, s58, s24
	s_cselect_b32 s25, s21, vcc_hi
	s_cselect_b32 s24, s59, vcc_lo
	s_add_i32 m0, s38, 0xc000
	ds_read_b128 v[96:99], v190
	ds_read_b128 v[100:103], v190 offset:1024
	ds_read_b128 v[108:111], v190 offset:2048
	ds_read_b128 v[112:115], v190 offset:3072
	ds_read_b128 v[160:163], v190 offset:4096
	ds_read_b128 v[164:167], v190 offset:5120
	ds_read_b128 v[198:201], v190 offset:6144
	ds_read_b128 v[202:205], v190 offset:7168
	global_load_lds_dwordx4 v178, s[42:43]
	s_add_i32 m0, s38, 0xe000
	s_nop 0
	global_load_lds_dwordx4 v176, s[42:43]
	s_waitcnt lgkmcnt(8)
	s_setprio 1
	s_barrier
	s_waitcnt lgkmcnt(7)
	v_mfma_f32_16x16x32_bf16 v[148:151], v[80:83], v[96:99], v[148:151]
	v_mfma_f32_16x16x32_bf16 v[144:147], v[88:91], v[96:99], v[144:147]
	s_waitcnt lgkmcnt(5)
	v_mfma_f32_16x16x32_bf16 v[136:139], v[80:83], v[108:111], v[136:139]
	v_mfma_f32_16x16x32_bf16 v[128:131], v[88:91], v[108:111], v[128:131]
	s_waitcnt lgkmcnt(3)
	v_mfma_f32_16x16x32_bf16 v[120:123], v[80:83], v[160:163], v[120:123]
	v_mfma_f32_16x16x32_bf16 v[104:107], v[88:91], v[160:163], v[104:107]
	s_waitcnt lgkmcnt(1)
	v_mfma_f32_16x16x32_bf16 v[76:79], v[80:83], v[198:201], v[76:79]
	v_mfma_f32_16x16x32_bf16 v[72:75], v[88:91], v[198:201], v[72:75]
	v_mfma_f32_16x16x32_bf16 v[148:151], v[84:87], v[100:103], v[148:151]
	s_add_i32 s68, s31, s66
	v_mfma_f32_16x16x32_bf16 v[144:147], v[92:95], v[100:103], v[144:147]
	v_lshl_add_u64 v[184:185], s[24:25], 0, v[172:173]
	v_mfma_f32_16x16x32_bf16 v[136:139], v[84:87], v[112:115], v[136:139]
	v_lshl_add_u64 v[194:195], s[24:25], 0, v[168:169]
	v_mfma_f32_16x16x32_bf16 v[128:131], v[92:95], v[112:115], v[128:131]
	v_mfma_f32_16x16x32_bf16 v[120:123], v[84:87], v[164:167], v[120:123]
	v_mfma_f32_16x16x32_bf16 v[104:107], v[92:95], v[164:167], v[104:107]
	s_waitcnt lgkmcnt(0)
	v_mfma_f32_16x16x32_bf16 v[76:79], v[84:87], v[202:205], v[76:79]
	s_setprio 0
	v_mfma_f32_16x16x32_bf16 v[72:75], v[92:95], v[202:205], v[72:75]
	s_barrier
	s_mov_b32 m0, s68
	ds_read_b128 v[206:209], v191
	ds_read_b128 v[210:213], v191 offset:1024
	ds_read_b128 v[214:217], v191 offset:2048
	ds_read_b128 v[218:221], v191 offset:3072
	global_load_lds_dwordx4 v[184:185], off
	s_add_i32 m0, s68, 0x2000
	s_nop 0
	global_load_lds_dwordx4 v[194:195], off
	s_setprio 1
	s_barrier
	s_waitcnt lgkmcnt(3)
	v_mfma_f32_16x16x32_bf16 v[156:159], v[206:209], v[96:99], v[156:159]
	s_waitcnt lgkmcnt(1)
	v_mfma_f32_16x16x32_bf16 v[96:99], v[214:217], v[96:99], v[152:155]
	v_mfma_f32_16x16x32_bf16 v[156:159], v[210:213], v[100:103], v[156:159]
	s_waitcnt lgkmcnt(0)
	v_mfma_f32_16x16x32_bf16 v[96:99], v[218:221], v[100:103], v[96:99]
	v_mfma_f32_16x16x32_bf16 v[100:103], v[206:209], v[108:111], v[140:143]
	v_mfma_f32_16x16x32_bf16 v[108:111], v[214:217], v[108:111], v[132:135]
	v_mfma_f32_16x16x32_bf16 v[116:119], v[214:217], v[160:163], v[116:119]
	v_mfma_f32_16x16x32_bf16 v[68:71], v[206:209], v[198:201], v[68:71]
	v_mfma_f32_16x16x32_bf16 v[64:67], v[214:217], v[198:201], v[64:67]
	v_lshl_add_u64 v[234:235], s[46:47], 0, v[170:171]
	s_mov_b32 m0, s38
	v_mfma_f32_16x16x32_bf16 v[100:103], v[210:213], v[112:115], v[100:103]
	v_lshl_add_u64 v[226:227], s[46:47], 0, v[174:175]
	v_mfma_f32_16x16x32_bf16 v[108:111], v[218:221], v[112:115], v[108:111]
	v_mfma_f32_16x16x32_bf16 v[112:115], v[206:209], v[160:163], v[124:127]
	v_mfma_f32_16x16x32_bf16 v[116:119], v[218:221], v[164:167], v[116:119]
	v_mfma_f32_16x16x32_bf16 v[68:71], v[210:213], v[202:205], v[68:71]
	v_mfma_f32_16x16x32_bf16 v[64:67], v[218:221], v[202:205], v[64:67]
	s_setprio 0
	v_mfma_f32_16x16x32_bf16 v[112:115], v[210:213], v[164:167], v[112:115]
	s_barrier
	ds_read_b128 v[124:127], v190 offset:16384
	ds_read_b128 v[132:135], v190 offset:17408
	ds_read_b128 v[140:143], v190 offset:18432
	ds_read_b128 v[152:155], v190 offset:19456
	ds_read_b128 v[160:163], v190 offset:20480
	ds_read_b128 v[164:167], v190 offset:21504
	ds_read_b128 v[198:201], v190 offset:22528
	ds_read_b128 v[202:205], v190 offset:23552
	global_load_lds_dwordx4 v[226:227], off
	s_mov_b32 m0, s39
	s_nop 0
	global_load_lds_dwordx4 v[234:235], off
	s_waitcnt vmcnt(10)
	s_setprio 1
	s_barrier
	s_waitcnt lgkmcnt(7)
	v_mfma_f32_16x16x32_bf16 v[60:63], v[80:83], v[124:127], v[60:63]
	v_mfma_f32_16x16x32_bf16 v[48:51], v[88:91], v[124:127], v[48:51]
	s_waitcnt lgkmcnt(5)
	v_mfma_f32_16x16x32_bf16 v[40:43], v[80:83], v[140:143], v[40:43]
	v_mfma_f32_16x16x32_bf16 v[32:35], v[88:91], v[140:143], v[32:35]
	s_waitcnt lgkmcnt(3)
	v_mfma_f32_16x16x32_bf16 v[24:27], v[80:83], v[160:163], v[24:27]
	v_mfma_f32_16x16x32_bf16 v[16:19], v[88:91], v[160:163], v[16:19]
	s_waitcnt lgkmcnt(1)
	v_mfma_f32_16x16x32_bf16 v[12:15], v[80:83], v[198:201], v[12:15]
	v_mfma_f32_16x16x32_bf16 v[8:11], v[88:91], v[198:201], v[8:11]
	v_mfma_f32_16x16x32_bf16 v[60:63], v[84:87], v[132:135], v[60:63]
	s_add_u32 s68, s24, 0x80000
	s_addc_u32 s69, s25, 0
	v_mfma_f32_16x16x32_bf16 v[48:51], v[92:95], v[132:135], v[48:51]
	s_add_i32 s70, s2, s66
	v_mfma_f32_16x16x32_bf16 v[40:43], v[84:87], v[152:155], v[40:43]
	v_mfma_f32_16x16x32_bf16 v[32:35], v[92:95], v[152:155], v[32:35]
	v_mfma_f32_16x16x32_bf16 v[24:27], v[84:87], v[164:167], v[24:27]
	v_mfma_f32_16x16x32_bf16 v[16:19], v[92:95], v[164:167], v[16:19]
	s_waitcnt lgkmcnt(0)
	v_mfma_f32_16x16x32_bf16 v[12:15], v[84:87], v[202:205], v[12:15]
	s_setprio 0
	v_mfma_f32_16x16x32_bf16 v[8:11], v[92:95], v[202:205], v[8:11]
	s_barrier
; #define PG8_STAGE(bufoff, gbase, voff) do { _Pragma("unroll") for (int _i = 0; _i < 2; ++_i) \
;         __builtin_amdgcn_global_load_lds((const unsigned*)((const char*)(gbase) + (voff)[_i]), (LAS unsigned*)(lds + (bufoff) + ldsw + _i * 8192), 16, 0, 0); } while (0)
; #define PG8_LDA(dst, b, h) do { _Pragma("unroll") for (int m = 0; m < 4; ++m) _Pragma("unroll") for (int k = 0; k < 2; ++k) dst[m][k] = *(const LAS bf16x8*)(lds + PG8_SA(b, h) + aoff + m * 2048 + k * 1024); } while (0)
; #define PG8_LDB(dst, b, h) do { _Pragma("unroll") for (int n = 0; n < 2; ++n) _Pragma("unroll") for (int k = 0; k < 2; ++k) dst[n][k] = *(const LAS bf16x8*)(lds + PG8_SB(b, h) + boff + n * 2048 + k * 1024); } while (0)
; #define PG8_MMA(ai, bj, At, Bt) do { __builtin_amdgcn_s_setprio(1); _Pragma("unroll") for (int m = 0; m < 4; ++m) _Pragma("unroll") for (int n = 0; n < 2; ++n) _Pragma("unroll") for (int k = 0; k < 2; ++k) \
;         acc[ai][bj][m][n] = __builtin_amdgcn_mfma_f32_16x16x32_bf16(Bt[n][k], At[m][k], acc[ai][bj][m][n], 0, 0, 0); __builtin_amdgcn_s_setprio(0); } while (0)
; #define PG8_WAIT_V(n) asm volatile("s_waitcnt vmcnt(" #n ")" ::: "memory")
; #define PG8_WAIT_L(n) asm volatile("s_waitcnt lgkmcnt(" #n ")" ::: "memory")
; #define PG8_BAR __builtin_amdgcn_s_barrier()
; #define PG8_SCHED __builtin_amdgcn_sched_barrier(0)
; template <class Map, class Epi>
; DI void gemm_phase(LAS unsigned char* lds, const Map& MP, const Epi& E, const int nM, const int nN, const int K, const int lda, const int ldb) {
;     ...
;             PG8_LDB(B0, 0, 0); PG8_SCHED; PG8_LDA(At, 0, 0); PG8_STAGE(PG8_SA(1, 1), a1 + hstepA, voffA);
;             PG8_WAIT_L(8); PG8_BAR; PG8_WAIT_L(0); PG8_MMA(0, 0, At, B0); PG8_BAR; PG8_SCHED;
;             PG8_LDB(B1, 0, 1); PG8_STAGE(PG8_SB(0, 0), b2, voffB);
;             PG8_BAR; PG8_WAIT_L(0); PG8_MMA(0, 1, At, B1); PG8_BAR;
;             PG8_LDA(At, 0, 1); PG8_STAGE(PG8_SA(0, 0), a2, voffA);
;             PG8_BAR; PG8_WAIT_L(0); PG8_MMA(1, 0, At, B0); PG8_BAR; PG8_SCHED;
;             PG8_STAGE(PG8_SB(0, 1), b2 + hstepB, voffB);
;             PG8_WAIT_V(6); PG8_BAR; PG8_MMA(1, 1, At, B1); PG8_BAR;
;             PG8_LDB(B0, 1, 0); PG8_SCHED; PG8_LDA(At, 1, 0); PG8_STAGE(PG8_SA(0, 1), a2 + hstepA, voffA);
;             PG8_WAIT_L(8); PG8_BAR; PG8_WAIT_L(0); PG8_MMA(0, 0, At, B0); PG8_BAR; PG8_SCHED;
	s_mov_b32 m0, s70
	s_nop 0
	global_load_lds_dwordx4 v172, s[68:69]
	s_add_i32 m0, s70, 0x2000
	s_nop 0
	global_load_lds_dwordx4 v168, s[68:69]
	s_waitcnt vmcnt(6)
	s_setprio 1
	s_barrier
	v_mfma_f32_16x16x32_bf16 v[56:59], v[206:209], v[124:127], v[56:59]
	v_mfma_f32_16x16x32_bf16 v[52:55], v[214:217], v[124:127], v[52:55]
	s_add_i32 s68, 0, 0x18000
	v_add_u32_e32 v92, s68, v188
	ds_read_b128 v[80:83], v92
	v_mfma_f32_16x16x32_bf16 v[44:47], v[206:209], v[140:143], v[44:47]
	v_mfma_f32_16x16x32_bf16 v[36:39], v[214:217], v[140:143], v[36:39]
	ds_read_b128 v[84:87], v92 offset:1024
	v_mfma_f32_16x16x32_bf16 v[28:31], v[206:209], v[160:163], v[28:31]
	v_mfma_f32_16x16x32_bf16 v[20:23], v[214:217], v[160:163], v[20:23]
	ds_read_b128 v[88:91], v92 offset:2048
	v_mfma_f32_16x16x32_bf16 v[4:7], v[206:209], v[198:201], v[4:7]
	v_mfma_f32_16x16x32_bf16 v[0:3], v[214:217], v[198:201], v[0:3]
	ds_read_b128 v[92:95], v92 offset:3072
	v_mfma_f32_16x16x32_bf16 v[56:59], v[210:213], v[132:135], v[56:59]
	s_add_u32 s46, s46, 0x80000
	s_addc_u32 s47, s47, 0
	v_mfma_f32_16x16x32_bf16 v[52:55], v[218:221], v[132:135], v[52:55]
	v_mfma_f32_16x16x32_bf16 v[44:47], v[210:213], v[152:155], v[44:47]
	v_mfma_f32_16x16x32_bf16 v[36:39], v[218:221], v[152:155], v[36:39]
	v_mfma_f32_16x16x32_bf16 v[28:31], v[210:213], v[164:167], v[28:31]
	v_mfma_f32_16x16x32_bf16 v[20:23], v[218:221], v[164:167], v[20:23]
	v_mfma_f32_16x16x32_bf16 v[4:7], v[210:213], v[202:205], v[4:7]
	s_setprio 0
	v_mfma_f32_16x16x32_bf16 v[0:3], v[218:221], v[202:205], v[0:3]
	s_barrier
	s_mov_b32 m0, s56
	ds_read_b128 v[124:127], v190 offset:32768
	ds_read_b128 v[132:135], v190 offset:33792
	ds_read_b128 v[160:163], v190 offset:34816
	ds_read_b128 v[164:167], v190 offset:35840
	ds_read_b128 v[198:201], v190 offset:36864
	ds_read_b128 v[202:205], v190 offset:37888
	ds_read_b128 v[206:209], v190 offset:38912
	ds_read_b128 v[210:213], v190 offset:39936
	global_load_lds_dwordx4 v174, s[46:47]
	s_mov_b32 m0, s57
	s_nop 0
	global_load_lds_dwordx4 v170, s[46:47]
	s_waitcnt lgkmcnt(8)
	s_setprio 1
	s_barrier
	s_waitcnt lgkmcnt(7)
	v_mfma_f32_16x16x32_bf16 v[140:143], v[80:83], v[124:127], v[148:151]
	s_waitcnt lgkmcnt(6)
	v_mfma_f32_16x16x32_bf16 v[148:151], v[84:87], v[132:135], v[140:143]
	v_mfma_f32_16x16x32_bf16 v[140:143], v[88:91], v[124:127], v[144:147]
	s_waitcnt lgkmcnt(5)
	v_mfma_f32_16x16x32_bf16 v[136:139], v[80:83], v[160:163], v[136:139]
	v_mfma_f32_16x16x32_bf16 v[128:131], v[88:91], v[160:163], v[128:131]
	s_waitcnt lgkmcnt(3)
	v_mfma_f32_16x16x32_bf16 v[120:123], v[80:83], v[198:201], v[120:123]
	v_mfma_f32_16x16x32_bf16 v[104:107], v[88:91], v[198:201], v[104:107]
	s_waitcnt lgkmcnt(1)
	v_mfma_f32_16x16x32_bf16 v[76:79], v[80:83], v[206:209], v[76:79]
	v_mfma_f32_16x16x32_bf16 v[72:75], v[88:91], v[206:209], v[72:75]
	s_add_i32 s46, 0, 0x1c000
	v_mfma_f32_16x16x32_bf16 v[144:147], v[92:95], v[132:135], v[140:143]
	v_add_u32_e32 v140, s46, v188
	v_mfma_f32_16x16x32_bf16 v[136:139], v[84:87], v[164:167], v[136:139]
	s_add_i32 s47, s68, s66
	v_mfma_f32_16x16x32_bf16 v[128:131], v[92:95], v[164:167], v[128:131]
	v_mfma_f32_16x16x32_bf16 v[120:123], v[84:87], v[202:205], v[120:123]
	v_mfma_f32_16x16x32_bf16 v[104:107], v[92:95], v[202:205], v[104:107]
	s_waitcnt lgkmcnt(0)
	v_mfma_f32_16x16x32_bf16 v[76:79], v[84:87], v[210:213], v[76:79]
	s_setprio 0
	v_mfma_f32_16x16x32_bf16 v[72:75], v[92:95], v[210:213], v[72:75]
	s_barrier
	ds_read_b128 v[214:217], v140
	ds_read_b128 v[218:221], v140 offset:1024
	ds_read_b128 v[222:225], v140 offset:2048
	ds_read_b128 v[230:233], v140 offset:3072
	v_lshl_add_u64 v[140:141], v[184:185], 0, s[14:15]
	s_mov_b32 m0, s47
	s_nop 0
	global_load_lds_dwordx4 v[140:141], off
	v_lshl_add_u64 v[140:141], v[194:195], 0, s[14:15]
	s_add_i32 m0, s47, 0x2000
	s_nop 0
	global_load_lds_dwordx4 v[140:141], off
	s_setprio 1
	s_barrier
	s_waitcnt lgkmcnt(1)
	v_mfma_f32_16x16x32_bf16 v[96:99], v[222:225], v[124:127], v[96:99]
	v_mfma_f32_16x16x32_bf16 v[140:143], v[214:217], v[124:127], v[156:159]
	s_waitcnt lgkmcnt(0)
	v_mfma_f32_16x16x32_bf16 v[152:155], v[230:233], v[132:135], v[96:99]
	v_mfma_f32_16x16x32_bf16 v[96:99], v[214:217], v[160:163], v[100:103]
	v_mfma_f32_16x16x32_bf16 v[156:159], v[218:221], v[132:135], v[140:143]
	v_mfma_f32_16x16x32_bf16 v[140:143], v[218:221], v[164:167], v[96:99]
	v_mfma_f32_16x16x32_bf16 v[96:99], v[222:225], v[160:163], v[108:111]
	v_mfma_f32_16x16x32_bf16 v[132:135], v[230:233], v[164:167], v[96:99]
	v_mfma_f32_16x16x32_bf16 v[96:99], v[214:217], v[198:201], v[112:115]
	s_mov_b32 m0, s63
	v_mfma_f32_16x16x32_bf16 v[124:127], v[218:221], v[202:205], v[96:99]
	v_lshl_add_u64 v[184:185], v[226:227], 0, s[14:15]
	v_mfma_f32_16x16x32_bf16 v[96:99], v[222:225], v[198:201], v[116:119]
	v_mfma_f32_16x16x32_bf16 v[68:71], v[214:217], v[206:209], v[68:71]
	v_mfma_f32_16x16x32_bf16 v[64:67], v[222:225], v[206:209], v[64:67]
	v_mfma_f32_16x16x32_bf16 v[116:119], v[230:233], v[202:205], v[96:99]
	v_mfma_f32_16x16x32_bf16 v[68:71], v[218:221], v[210:213], v[68:71]
	s_setprio 0
	v_mfma_f32_16x16x32_bf16 v[64:67], v[230:233], v[210:213], v[64:67]
	s_barrier
	ds_read_b128 v[96:99], v190 offset:49152
	ds_read_b128 v[100:103], v190 offset:50176
	ds_read_b128 v[108:111], v190 offset:51200
	ds_read_b128 v[112:115], v190 offset:52224
	ds_read_b128 v[160:163], v190 offset:53248
	ds_read_b128 v[164:167], v190 offset:54272
	ds_read_b128 v[198:201], v190 offset:55296
	ds_read_b128 v[202:205], v190 offset:56320
	global_load_lds_dwordx4 v[184:185], off
	v_lshl_add_u64 v[184:185], v[234:235], 0, s[14:15]
	s_mov_b32 m0, s4
	s_nop 0
	global_load_lds_dwordx4 v[184:185], off
	s_waitcnt vmcnt(10)
	s_setprio 1
	s_barrier
; #define PG8_STAGE(bufoff, gbase, voff) do { _Pragma("unroll") for (int _i = 0; _i < 2; ++_i) \
;         __builtin_amdgcn_global_load_lds((const unsigned*)((const char*)(gbase) + (voff)[_i]), (LAS unsigned*)(lds + (bufoff) + ldsw + _i * 8192), 16, 0, 0); } while (0)
; #define PG8_LDA(dst, b, h) do { _Pragma("unroll") for (int m = 0; m < 4; ++m) _Pragma("unroll") for (int k = 0; k < 2; ++k) dst[m][k] = *(const LAS bf16x8*)(lds + PG8_SA(b, h) + aoff + m * 2048 + k * 1024); } while (0)
; #define PG8_LDB(dst, b, h) do { _Pragma("unroll") for (int n = 0; n < 2; ++n) _Pragma("unroll") for (int k = 0; k < 2; ++k) dst[n][k] = *(const LAS bf16x8*)(lds + PG8_SB(b, h) + boff + n * 2048 + k * 1024); } while (0)
; #define PG8_MMA(ai, bj, At, Bt) do { __builtin_amdgcn_s_setprio(1); _Pragma("unroll") for (int m = 0; m < 4; ++m) _Pragma("unroll") for (int n = 0; n < 2; ++n) _Pragma("unroll") for (int k = 0; k < 2; ++k) \
;         acc[ai][bj][m][n] = __builtin_amdgcn_mfma_f32_16x16x32_bf16(Bt[n][k], At[m][k], acc[ai][bj][m][n], 0, 0, 0); __builtin_amdgcn_s_setprio(0); } while (0)
; #define PG8_WAIT_V(n) asm volatile("s_waitcnt vmcnt(" #n ")" ::: "memory")
; #define PG8_WAIT_L(n) asm volatile("s_waitcnt lgkmcnt(" #n ")" ::: "memory")
; #define PG8_BAR __builtin_amdgcn_s_barrier()
; #define PG8_SCHED __builtin_amdgcn_sched_barrier(0)
; template <class Map, class Epi>
; DI void gemm_phase(LAS unsigned char* lds, const Map& MP, const Epi& E, const int nM, const int nN, const int K, const int lda, const int ldb) {
;     ...
;             const char* a2 = last ? nA : cA + (size_t)(t + 2) * kstep; const char* b2 = last ? nB : cB + (size_t)(t + 2) * kstep;
;     ...
;             PG8_WAIT_L(8); PG8_BAR; PG8_WAIT_L(0); PG8_MMA(0, 0, At, B0); PG8_BAR; PG8_SCHED;
;             PG8_LDB(B1, 1, 1); PG8_STAGE(PG8_SB(1, 0), b3, voffB);
;             PG8_BAR; PG8_WAIT_L(0); PG8_MMA(0, 1, At, B1); PG8_BAR;
;             PG8_LDA(At, 1, 1); PG8_STAGE(PG8_SA(1, 0), a3, voffA);
;             PG8_BAR; PG8_WAIT_L(0); PG8_MMA(1, 0, At, B0); PG8_BAR; PG8_SCHED;
;             PG8_STAGE(PG8_SB(1, 1), b3 + hstepB, voffB);
;             PG8_WAIT_V(6); PG8_BAR; PG8_MMA(1, 1, At, B1); PG8_BAR;
	s_waitcnt lgkmcnt(7)
	v_mfma_f32_16x16x32_bf16 v[60:63], v[80:83], v[96:99], v[60:63]
	v_mfma_f32_16x16x32_bf16 v[48:51], v[88:91], v[96:99], v[48:51]
	s_waitcnt lgkmcnt(5)
	v_mfma_f32_16x16x32_bf16 v[40:43], v[80:83], v[108:111], v[40:43]
	v_mfma_f32_16x16x32_bf16 v[32:35], v[88:91], v[108:111], v[32:35]
	s_waitcnt lgkmcnt(3)
	v_mfma_f32_16x16x32_bf16 v[24:27], v[80:83], v[160:163], v[24:27]
	v_mfma_f32_16x16x32_bf16 v[16:19], v[88:91], v[160:163], v[16:19]
	s_waitcnt lgkmcnt(1)
	v_mfma_f32_16x16x32_bf16 v[12:15], v[80:83], v[198:201], v[12:15]
	v_mfma_f32_16x16x32_bf16 v[8:11], v[88:91], v[198:201], v[8:11]
	v_mfma_f32_16x16x32_bf16 v[60:63], v[84:87], v[100:103], v[60:63]
	s_add_u32 s24, s24, 0x80080
	s_addc_u32 s25, s25, 0
	v_mfma_f32_16x16x32_bf16 v[48:51], v[92:95], v[100:103], v[48:51]
	s_add_i32 s46, s46, s66
	v_mfma_f32_16x16x32_bf16 v[40:43], v[84:87], v[112:115], v[40:43]
	v_mfma_f32_16x16x32_bf16 v[32:35], v[92:95], v[112:115], v[32:35]
	v_mfma_f32_16x16x32_bf16 v[24:27], v[84:87], v[164:167], v[24:27]
	v_mfma_f32_16x16x32_bf16 v[16:19], v[92:95], v[164:167], v[16:19]
	s_waitcnt lgkmcnt(0)
	v_mfma_f32_16x16x32_bf16 v[12:15], v[84:87], v[202:205], v[12:15]
	s_setprio 0
	v_mfma_f32_16x16x32_bf16 v[8:11], v[92:95], v[202:205], v[8:11]
	s_barrier
	s_mov_b32 m0, s46
	s_nop 0
	global_load_lds_dwordx4 v172, s[24:25]
	s_add_i32 m0, s46, 0x2000
	s_nop 0
	global_load_lds_dwordx4 v168, s[24:25]
	s_waitcnt vmcnt(6)
	s_setprio 1
	s_barrier
	v_mfma_f32_16x16x32_bf16 v[56:59], v[214:217], v[96:99], v[56:59]
	v_mfma_f32_16x16x32_bf16 v[52:55], v[222:225], v[96:99], v[52:55]
	ds_read_b128 v[80:83], v189
	v_mfma_f32_16x16x32_bf16 v[44:47], v[214:217], v[108:111], v[44:47]
	v_mfma_f32_16x16x32_bf16 v[36:39], v[222:225], v[108:111], v[36:39]
	ds_read_b128 v[84:87], v189 offset:1024
	v_mfma_f32_16x16x32_bf16 v[28:31], v[214:217], v[160:163], v[28:31]
	v_mfma_f32_16x16x32_bf16 v[20:23], v[222:225], v[160:163], v[20:23]
	ds_read_b128 v[88:91], v189 offset:2048
	v_mfma_f32_16x16x32_bf16 v[4:7], v[214:217], v[198:201], v[4:7]
	v_mfma_f32_16x16x32_bf16 v[0:3], v[222:225], v[198:201], v[0:3]
	ds_read_b128 v[92:95], v189 offset:3072
	v_mfma_f32_16x16x32_bf16 v[56:59], v[218:221], v[100:103], v[56:59]
	s_add_i32 s3, s3, 2
	v_mfma_f32_16x16x32_bf16 v[52:55], v[230:233], v[100:103], v[52:55]
	s_add_u32 vcc_lo, vcc_lo, 0x100
	s_addc_u32 vcc_hi, vcc_hi, 0
	v_mfma_f32_16x16x32_bf16 v[44:47], v[218:221], v[112:115], v[44:47]
	s_add_u32 s42, s42, 0x100
	s_addc_u32 s43, s43, 0
	v_mfma_f32_16x16x32_bf16 v[36:39], v[230:233], v[112:115], v[36:39]
	s_cmp_gt_u32 s3, 29
	v_mfma_f32_16x16x32_bf16 v[28:31], v[218:221], v[164:167], v[28:31]
	v_mfma_f32_16x16x32_bf16 v[20:23], v[230:233], v[164:167], v[20:23]
	v_mfma_f32_16x16x32_bf16 v[4:7], v[218:221], v[202:205], v[4:7]
	s_setprio 0
	v_mfma_f32_16x16x32_bf16 v[0:3], v[230:233], v[202:205], v[0:3]
	s_barrier
	s_cbranch_scc0 .LBB1_1069
; DI float silu_mul(float g, float v) { return g * v * __builtin_amdgcn_rcpf(1.0f + __builtin_amdgcn_exp2f(-LOG2E * g)); }
;     DI void operator()(const f32x4 (&acc)[2][2][4][2], const Unit& u, int wr, int wc, int fr, int fq) const {
;         const int row0 = u.pm * BM + wr * 64 + fr, ch0 = u.pn * 128 + wc * 32 + 8 * fq;
;         f32x4 w0[2], w1[2], w2[2], bb[2];
; #pragma unroll
;         for (int n = 0; n < 2; ++n) { w0[n] = *(const f32x4*)(cw + ch0 + 4 * n); w1[n] = *(const f32x4*)(cw + DFF + ch0 + 4 * n); w2[n] = *(const f32x4*)(cw + 2 * DFF + ch0 + 4 * n); bb[n] = *(const f32x4*)(cb + ch0 + 4 * n); }
; #pragma unroll
;         for (int ai = 0; ai < 2; ++ai)
; #pragma unroll
;             for (int m = 0; m < 4; ++m) {
;                 const bool efirst = (m == 0) && (fr == 0), elast = (m == 3) && (fr == 15);
;                 const int row = row0 + ai * HALF + m * 16;
;                 f32x4 gc[2];
; #pragma unroll
;                 for (int n = 0; n < 2; ++n) {
;                     const f32x4 g = acc[ai][0][m][n];
;                     const f32x4 gprev = acc[ai][0][m > 0 ? m - 1 : 0][n], gnext = acc[ai][0][m < 3 ? m + 1 : 3][n];
;                     f32x4 up, dn;
; #pragma unroll
;                     for (int e = 0; e < 4; ++e) {
;                         const float pu = (m > 0 && fr == 15) ? gprev[e] : g[e];
;                         const float pd = (m < 3 && fr == 0) ? gnext[e] : g[e];
;                         up[e] = dpp_ror1(pu); dn[e] = dpp_ror15(pd);
;                     }
;                     if (efirst) up = (f32x4){0.f, 0.f, 0.f, 0.f};
;                     if (elast) dn = (f32x4){0.f, 0.f, 0.f, 0.f};
;                     gc[n] = w0[n] * up + w1[n] * g + w2[n] * dn + bb[n];
;                 }
;                 if (efirst || elast) {
;                     const size_t eo = (size_t)((row >> 6) * 2 + (elast ? 1 : 0)) * DFF + ch0;
; #pragma unroll
;                     for (int n = 0; n < 2; ++n) { *(f32x4*)(EP + eo + 4 * n) = gc[n]; *(f32x4*)(ER + eo + 4 * n) = acc[ai][0][m][n]; *(f32x4*)(EV + eo + 4 * n) = acc[ai][1][m][n]; }
;                 } else {
;                     const f32x4 v0 = acc[ai][1][m][0], v1 = acc[ai][1][m][1];
;                     u32x4 o;
;                     o[0] = pack2(silu_mul(gc[0][0], v0[0]), silu_mul(gc[0][1], v0[1])); o[1] = pack2(silu_mul(gc[0][2], v0[2]), silu_mul(gc[0][3], v0[3]));
	s_waitcnt lgkmcnt(0)
	s_lshl_b32 s21, s45, 7
	v_mov_b32_e32 v194, v186
	v_mov_b32_e32 v80, v187
	s_or_b32 s21, s21, s62
	v_lshl_add_u32 v184, v80, 3, s21
	v_ashrrev_i32_e32 v185, 31, v184
	v_lshlrev_b64 v[80:81], 2, v[184:185]
	v_lshl_add_u64 v[84:85], s[6:7], 0, v[80:81]
	v_lshl_add_u64 v[88:89], s[16:17], 0, v[80:81]
	v_lshl_add_u64 v[92:93], s[18:19], 0, v[80:81]
	v_lshl_add_u64 v[112:113], s[52:53], 0, v[80:81]
	global_load_dwordx4 v[80:83], v[84:85], off offset:16
	global_load_dwordx4 v[96:99], v[84:85], off
	s_nop 0
	global_load_dwordx4 v[84:87], v[88:89], off offset:16
	global_load_dwordx4 v[100:103], v[88:89], off
	s_nop 0
	global_load_dwordx4 v[88:91], v[92:93], off offset:16
	global_load_dwordx4 v[108:111], v[92:93], off
	s_nop 0
	global_load_dwordx4 v[92:95], v[112:113], off offset:16
	s_nop 0
	global_load_dwordx4 v[112:115], v[112:113], off
	v_cmp_eq_u32_e32 vcc, 0, v194
	s_nop 0
	s_nop 0
	v_cndmask_b32_e32 v161, v148, v136, vcc
	v_cndmask_b32_e32 v162, v149, v137, vcc
	v_cndmask_b32_e32 v163, v150, v138, vcc
	v_mov_b32_dpp v160, v161 row_ror:15 row_mask:0xf bank_mask:0xf
	s_nop 0
	s_nop 0
	v_mov_b32_dpp v161, v162 row_ror:15 row_mask:0xf bank_mask:0xf
	v_mov_b32_dpp v164, v150 row_ror:1 row_mask:0xf bank_mask:0xf
	v_cndmask_b32_e32 v165, v151, v139, vcc
	v_mov_b32_dpp v162, v163 row_ror:15 row_mask:0xf bank_mask:0xf
	v_mov_b32_dpp v195, v151 row_ror:1 row_mask:0xf bank_mask:0xf
	v_mov_b32_dpp v166, v148 row_ror:1 row_mask:0xf bank_mask:0xf
	v_mov_b32_dpp v167, v149 row_ror:1 row_mask:0xf bank_mask:0xf
	v_mov_b32_dpp v163, v165 row_ror:15 row_mask:0xf bank_mask:0xf
	v_cndmask_b32_e64 v165, v195, 0, vcc
	v_cndmask_b32_e64 v164, v164, 0, vcc
	v_cndmask_b32_e64 v167, v167, 0, vcc
	v_cndmask_b32_e64 v166, v166, 0, vcc
	s_nop 0
	s_nop 0
	v_mov_b32_dpp v195, v144 row_ror:1 row_mask:0xf bank_mask:0xf
	v_mov_b32_dpp v196, v145 row_ror:1 row_mask:0xf bank_mask:0xf
	v_mov_b32_dpp v198, v146 row_ror:1 row_mask:0xf bank_mask:0xf
	v_cndmask_b32_e32 v199, v147, v131, vcc
	v_mov_b32_dpp v200, v147 row_ror:1 row_mask:0xf bank_mask:0xf
	v_cndmask_b32_e64 v198, v198, 0, vcc
	v_cndmask_b32_e64 v201, v196, 0, vcc
	s_lshl_b32 s3, s44, 8
	s_add_i32 s3, s3, s49
	v_add_u32_e32 v193, s3, v194
	v_cmp_ne_u32_e64 s[46:47], 0, v194
	s_waitcnt vmcnt(0)
	v_pk_mul_f32 v[164:165], v[98:99], v[164:165]
	v_pk_mul_f32 v[166:167], v[96:97], v[166:167]
	v_pk_fma_f32 v[164:165], v[150:151], v[102:103], v[164:165]
	v_pk_fma_f32 v[166:167], v[148:149], v[100:101], v[166:167]
	v_pk_fma_f32 v[162:163], v[110:111], v[162:163], v[164:165]
	v_cndmask_b32_e32 v165, v144, v128, vcc
	v_pk_fma_f32 v[160:161], v[108:109], v[160:161], v[166:167]
	v_cndmask_b32_e32 v166, v145, v129, vcc
	v_mov_b32_dpp v164, v165 row_ror:15 row_mask:0xf bank_mask:0xf
	v_cndmask_b32_e32 v167, v146, v130, vcc
	v_pk_add_f32 v[162:163], v[114:115], v[162:163]
	v_mov_b32_dpp v165, v166 row_ror:15 row_mask:0xf bank_mask:0xf
	v_pk_add_f32 v[160:161], v[112:113], v[160:161]
	s_nop 0
	v_mov_b32_dpp v166, v167 row_ror:15 row_mask:0xf bank_mask:0xf
	s_nop 1
	v_mov_b32_dpp v167, v199 row_ror:15 row_mask:0xf bank_mask:0xf
	v_cndmask_b32_e64 v199, v200, 0, vcc
	v_cndmask_b32_e64 v200, v195, 0, vcc
	v_pk_mul_f32 v[200:201], v[80:81], v[200:201]
	v_pk_mul_f32 v[198:199], v[82:83], v[198:199]
	v_pk_fma_f32 v[200:201], v[144:145], v[84:85], v[200:201]
	v_pk_fma_f32 v[198:199], v[146:147], v[86:87], v[198:199]
	v_pk_fma_f32 v[164:165], v[88:89], v[164:165], v[200:201]
	v_pk_fma_f32 v[166:167], v[90:91], v[166:167], v[198:199]
	v_pk_add_f32 v[164:165], v[92:93], v[164:165]
	v_pk_add_f32 v[166:167], v[94:95], v[166:167]
	s_and_saveexec_b64 s[24:25], s[46:47]
	s_xor_b64 s[24:25], exec, s[24:25]
	s_cbranch_execz .LBB1_1072
	v_mul_f32_e32 v195, 0xbfb8aa3b, v160
	v_exp_f32_e32 v195, v195
	v_mul_f32_e32 v196, 0xbfb8aa3b, v161
	v_exp_f32_e32 v196, v196
	v_pk_mul_f32 v[160:161], v[156:157], v[160:161]
	v_add_f32_e32 v195, 1.0, v195
	v_rcp_f32_e32 v198, v195
	v_add_f32_e32 v196, 1.0, v196
	v_mul_f32_e32 v195, 0xbfb8aa3b, v162
	v_rcp_f32_e32 v199, v196
	v_exp_f32_e32 v195, v195
	v_mul_f32_e32 v196, 0xbfb8aa3b, v163
	v_exp_f32_e32 v196, v196
	v_pk_mul_f32 v[160:161], v[160:161], v[198:199]
	v_add_f32_e32 v195, 1.0, v195
	v_rcp_f32_e32 v200, v195
	v_add_f32_e32 v195, 1.0, v196
	v_rcp_f32_e32 v201, v195
	v_cvt_pk_bf16_f32 v160, v160, v161
	v_mul_f32_e32 v161, 0xbfb8aa3b, v164
	v_exp_f32_e32 v195, v161
	v_mul_f32_e32 v161, 0xbfb8aa3b, v165
	v_exp_f32_e32 v196, v161
	v_pk_mul_f32 v[162:163], v[158:159], v[162:163]
	v_pk_mul_f32 v[164:165], v[152:153], v[164:165]
	v_pk_mul_f32 v[162:163], v[162:163], v[200:201]
	s_nop 0
	v_cvt_pk_bf16_f32 v161, v162, v163
	v_add_f32_e32 v162, 1.0, v195
	v_mul_f32_e32 v195, 0xbfb8aa3b, v166
	v_add_f32_e32 v163, 1.0, v196
	v_exp_f32_e32 v195, v195
	v_mul_f32_e32 v196, 0xbfb8aa3b, v167
	v_exp_f32_e32 v196, v196
	v_rcp_f32_e32 v162, v162
	v_add_f32_e32 v195, 1.0, v195
	v_rcp_f32_e32 v198, v195
	v_add_f32_e32 v195, 1.0, v196
	v_rcp_f32_e32 v163, v163
	v_rcp_f32_e32 v199, v195
	v_pk_mul_f32 v[166:167], v[154:155], v[166:167]
	v_pk_mul_f32 v[162:163], v[164:165], v[162:163]
	v_pk_mul_f32 v[164:165], v[166:167], v[198:199]
	v_cvt_pk_bf16_f32 v162, v162, v163
	v_cvt_pk_bf16_f32 v163, v164, v165
	v_mov_b64_e32 v[164:165], s[54:55]
	v_mad_i64_i32 v[164:165], s[42:43], v193, s60, v[164:165]
	v_lshl_add_u64 v[164:165], v[184:185], 1, v[164:165]
	global_store_dwordx4 v[164:165], v[160:163], off

; #define PG8_STAGE(bufoff, gbase, voff) do { _Pragma("unroll") for (int _i = 0; _i < 2; ++_i) \
;         __builtin_amdgcn_global_load_lds((const unsigned*)((const char*)(gbase) + (voff)[_i]), (LAS unsigned*)(lds + (bufoff) + ldsw + _i * 8192), 16, 0, 0); } while (0)
; #define PG8_LDA(dst, b, h) do { _Pragma("unroll") for (int m = 0; m < 4; ++m) _Pragma("unroll") for (int k = 0; k < 2; ++k) dst[m][k] = *(const LAS bf16x8*)(lds + PG8_SA(b, h) + aoff + m * 2048 + k * 1024); } while (0)
; #define PG8_LDB(dst, b, h) do { _Pragma("unroll") for (int n = 0; n < 2; ++n) _Pragma("unroll") for (int k = 0; k < 2; ++k) dst[n][k] = *(const LAS bf16x8*)(lds + PG8_SB(b, h) + boff + n * 2048 + k * 1024); } while (0)
; #define PG8_MMA(ai, bj, At, Bt) do { __builtin_amdgcn_s_setprio(1); _Pragma("unroll") for (int m = 0; m < 4; ++m) _Pragma("unroll") for (int n = 0; n < 2; ++n) _Pragma("unroll") for (int k = 0; k < 2; ++k) \
;         acc[ai][bj][m][n] = __builtin_amdgcn_mfma_f32_16x16x32_bf16(Bt[n][k], At[m][k], acc[ai][bj][m][n], 0, 0, 0); __builtin_amdgcn_s_setprio(0); } while (0)
; #define PG8_WAIT_V(n) asm volatile("s_waitcnt vmcnt(" #n ")" ::: "memory")
; #define PG8_WAIT_L(n) asm volatile("s_waitcnt lgkmcnt(" #n ")" ::: "memory")
; template <class Map, class Epi>
; DI void gemm_phase(LAS unsigned char* lds, const Map& MP, const Epi& E, const int nM, const int nN, const int K, const int lda, const int ldb) {
;     ...
;         for (int t = 0; t < nt; t += 2) {
;             const bool last = (t == nt - 2);
;             const char* a1 = cA + (size_t)(t + 1) * kstep;
;             const char* a2 = last ? nA : cA + (size_t)(t + 2) * kstep; const char* b2 = last ? nB : cB + (size_t)(t + 2) * kstep;
;             const char* a3 = a2 + kstep; const char* b3 = b2 + kstep;
;             PG8_LDB(B0, 0, 0); PG8_SCHED; PG8_LDA(At, 0, 0); PG8_STAGE(PG8_SA(1, 1), a1 + hstepA, voffA);
;             PG8_WAIT_L(8); PG8_BAR; PG8_WAIT_L(0); PG8_MMA(0, 0, At, B0); PG8_BAR; PG8_SCHED;
;             PG8_LDB(B1, 0, 1); PG8_STAGE(PG8_SB(0, 0), b2, voffB);
;             PG8_BAR; PG8_WAIT_L(0); PG8_MMA(0, 1, At, B1); PG8_BAR;
;             PG8_LDA(At, 0, 1); PG8_STAGE(PG8_SA(0, 0), a2, voffA);
;             PG8_BAR; PG8_WAIT_L(0); PG8_MMA(1, 0, At, B0); PG8_BAR; PG8_SCHED;
;             PG8_STAGE(PG8_SB(0, 1), b2 + hstepB, voffB);
;             PG8_WAIT_V(6); PG8_BAR; PG8_MMA(1, 1, At, B1); PG8_BAR;
.LBB1_1239:
	s_add_u32 s10, s8, 0x100
	s_addc_u32 s11, s9, 0
	s_cmpk_eq_i32 s3, 0x54
	s_cselect_b32 s15, s43, s11
	s_cselect_b32 s14, s42, s10
	s_cselect_b32 s13, s7, s38
	s_cselect_b32 s12, s6, s5
	s_add_i32 m0, s24, 0xc000
	ds_read_b128 v[168:171], v150
	ds_read_b128 v[172:175], v150 offset:1024
	ds_read_b128 v[176:179], v150 offset:2048
	ds_read_b128 v[180:183], v150 offset:3072
	ds_read_b128 v[184:187], v150 offset:4096
	ds_read_b128 v[188:191], v150 offset:5120
	ds_read_b128 v[192:195], v150 offset:6144
	ds_read_b128 v[198:201], v150 offset:7168
	global_load_lds_dwordx4 v138, s[8:9]
	s_add_i32 m0, s24, 0xe000
	s_nop 0
	global_load_lds_dwordx4 v136, s[8:9]
	s_waitcnt lgkmcnt(8)
	s_setprio 1
	s_barrier
	s_waitcnt lgkmcnt(7)
	v_mfma_f32_16x16x32_bf16 v[124:127], v[152:155], v[168:171], v[124:127]
	v_mfma_f32_16x16x32_bf16 v[120:123], v[160:163], v[168:171], v[120:123]
	s_waitcnt lgkmcnt(5)
	v_mfma_f32_16x16x32_bf16 v[108:111], v[152:155], v[176:179], v[108:111]
	v_mfma_f32_16x16x32_bf16 v[104:107], v[160:163], v[176:179], v[104:107]
	s_waitcnt lgkmcnt(3)
	v_mfma_f32_16x16x32_bf16 v[92:95], v[152:155], v[184:187], v[92:95]
	v_mfma_f32_16x16x32_bf16 v[88:91], v[160:163], v[184:187], v[88:91]
	s_waitcnt lgkmcnt(1)
	v_mfma_f32_16x16x32_bf16 v[76:79], v[152:155], v[192:195], v[76:79]
	v_mfma_f32_16x16x32_bf16 v[72:75], v[160:163], v[192:195], v[72:75]
	v_mfma_f32_16x16x32_bf16 v[124:127], v[156:159], v[172:175], v[124:127]
	s_add_i32 s8, s35, s22
	v_mfma_f32_16x16x32_bf16 v[120:123], v[164:167], v[172:175], v[120:123]
	v_lshl_add_u64 v[144:145], s[12:13], 0, v[132:133]
	v_mfma_f32_16x16x32_bf16 v[108:111], v[156:159], v[180:183], v[108:111]
	v_lshl_add_u64 v[218:219], s[12:13], 0, v[128:129]
	v_mfma_f32_16x16x32_bf16 v[104:107], v[164:167], v[180:183], v[104:107]
	v_mfma_f32_16x16x32_bf16 v[92:95], v[156:159], v[188:191], v[92:95]
	v_mfma_f32_16x16x32_bf16 v[88:91], v[164:167], v[188:191], v[88:91]
	s_waitcnt lgkmcnt(0)
	v_mfma_f32_16x16x32_bf16 v[76:79], v[156:159], v[198:201], v[76:79]
	s_setprio 0
	v_mfma_f32_16x16x32_bf16 v[72:75], v[164:167], v[198:201], v[72:75]
	s_barrier
	s_mov_b32 m0, s8
	ds_read_b128 v[202:205], v151
	ds_read_b128 v[206:209], v151 offset:1024
	ds_read_b128 v[210:213], v151 offset:2048
	ds_read_b128 v[214:217], v151 offset:3072
	global_load_lds_dwordx4 v[144:145], off
	s_add_i32 m0, s8, 0x2000
	s_nop 0
	global_load_lds_dwordx4 v[218:219], off
	s_setprio 1
	s_barrier
	s_waitcnt lgkmcnt(3)
	v_mfma_f32_16x16x32_bf16 v[116:119], v[202:205], v[168:171], v[116:119]
	s_waitcnt lgkmcnt(1)
	v_mfma_f32_16x16x32_bf16 v[112:115], v[210:213], v[168:171], v[112:115]
	v_mfma_f32_16x16x32_bf16 v[100:103], v[202:205], v[176:179], v[100:103]
	v_mfma_f32_16x16x32_bf16 v[96:99], v[210:213], v[176:179], v[96:99]
	v_mfma_f32_16x16x32_bf16 v[84:87], v[202:205], v[184:187], v[84:87]
	v_mfma_f32_16x16x32_bf16 v[80:83], v[210:213], v[184:187], v[80:83]
	v_mfma_f32_16x16x32_bf16 v[68:71], v[202:205], v[192:195], v[68:71]
	v_mfma_f32_16x16x32_bf16 v[64:67], v[210:213], v[192:195], v[64:67]
	v_mfma_f32_16x16x32_bf16 v[116:119], v[206:209], v[172:175], v[116:119]
	v_lshl_add_u64 v[222:223], s[14:15], 0, v[130:131]
	s_mov_b32 m0, s24
	s_waitcnt lgkmcnt(0)
	v_mfma_f32_16x16x32_bf16 v[112:115], v[214:217], v[172:175], v[112:115]
	v_lshl_add_u64 v[220:221], s[14:15], 0, v[134:135]
	v_mfma_f32_16x16x32_bf16 v[100:103], v[206:209], v[180:183], v[100:103]
	v_mfma_f32_16x16x32_bf16 v[96:99], v[214:217], v[180:183], v[96:99]
	v_mfma_f32_16x16x32_bf16 v[84:87], v[206:209], v[188:191], v[84:87]
	v_mfma_f32_16x16x32_bf16 v[80:83], v[214:217], v[188:191], v[80:83]
	v_mfma_f32_16x16x32_bf16 v[68:71], v[206:209], v[198:201], v[68:71]
	s_setprio 0
	v_mfma_f32_16x16x32_bf16 v[64:67], v[214:217], v[198:201], v[64:67]
	s_barrier
	ds_read_b128 v[168:171], v150 offset:16384
	ds_read_b128 v[172:175], v150 offset:17408
	ds_read_b128 v[176:179], v150 offset:18432
	ds_read_b128 v[180:183], v150 offset:19456
	ds_read_b128 v[184:187], v150 offset:20480
	ds_read_b128 v[188:191], v150 offset:21504
	ds_read_b128 v[192:195], v150 offset:22528
	ds_read_b128 v[198:201], v150 offset:23552
	global_load_lds_dwordx4 v[220:221], off
	s_mov_b32 m0, s25
	s_nop 0
	global_load_lds_dwordx4 v[222:223], off
	s_waitcnt vmcnt(10)
	s_setprio 1
	s_barrier
	s_waitcnt lgkmcnt(7)
	v_mfma_f32_16x16x32_bf16 v[60:63], v[152:155], v[168:171], v[60:63]
	v_mfma_f32_16x16x32_bf16 v[56:59], v[160:163], v[168:171], v[56:59]
	s_waitcnt lgkmcnt(5)
	v_mfma_f32_16x16x32_bf16 v[44:47], v[152:155], v[176:179], v[44:47]
	v_mfma_f32_16x16x32_bf16 v[40:43], v[160:163], v[176:179], v[40:43]
	s_waitcnt lgkmcnt(3)
	v_mfma_f32_16x16x32_bf16 v[28:31], v[152:155], v[184:187], v[28:31]
	v_mfma_f32_16x16x32_bf16 v[24:27], v[160:163], v[184:187], v[24:27]
	s_waitcnt lgkmcnt(1)
	v_mfma_f32_16x16x32_bf16 v[12:15], v[152:155], v[192:195], v[12:15]
	v_mfma_f32_16x16x32_bf16 v[8:11], v[160:163], v[192:195], v[8:11]
	v_mfma_f32_16x16x32_bf16 v[60:63], v[156:159], v[172:175], v[60:63]
	s_add_u32 s8, s12, 0x160000
	s_addc_u32 s9, s13, 0
	v_mfma_f32_16x16x32_bf16 v[56:59], v[164:167], v[172:175], v[56:59]
	s_add_i32 s39, s36, s22
	v_mfma_f32_16x16x32_bf16 v[44:47], v[156:159], v[180:183], v[44:47]
	v_mfma_f32_16x16x32_bf16 v[40:43], v[164:167], v[180:183], v[40:43]
	v_mfma_f32_16x16x32_bf16 v[28:31], v[156:159], v[188:191], v[28:31]
	v_mfma_f32_16x16x32_bf16 v[24:27], v[164:167], v[188:191], v[24:27]
	s_waitcnt lgkmcnt(0)
	v_mfma_f32_16x16x32_bf16 v[12:15], v[156:159], v[198:201], v[12:15]
	s_setprio 0
	v_mfma_f32_16x16x32_bf16 v[8:11], v[164:167], v[198:201], v[8:11]
	s_barrier
; #define PG8_STAGE(bufoff, gbase, voff) do { _Pragma("unroll") for (int _i = 0; _i < 2; ++_i) \
;         __builtin_amdgcn_global_load_lds((const unsigned*)((const char*)(gbase) + (voff)[_i]), (LAS unsigned*)(lds + (bufoff) + ldsw + _i * 8192), 16, 0, 0); } while (0)
; #define PG8_LDA(dst, b, h) do { _Pragma("unroll") for (int m = 0; m < 4; ++m) _Pragma("unroll") for (int k = 0; k < 2; ++k) dst[m][k] = *(const LAS bf16x8*)(lds + PG8_SA(b, h) + aoff + m * 2048 + k * 1024); } while (0)
; #define PG8_LDB(dst, b, h) do { _Pragma("unroll") for (int n = 0; n < 2; ++n) _Pragma("unroll") for (int k = 0; k < 2; ++k) dst[n][k] = *(const LAS bf16x8*)(lds + PG8_SB(b, h) + boff + n * 2048 + k * 1024); } while (0)
; #define PG8_MMA(ai, bj, At, Bt) do { __builtin_amdgcn_s_setprio(1); _Pragma("unroll") for (int m = 0; m < 4; ++m) _Pragma("unroll") for (int n = 0; n < 2; ++n) _Pragma("unroll") for (int k = 0; k < 2; ++k) \
;         acc[ai][bj][m][n] = __builtin_amdgcn_mfma_f32_16x16x32_bf16(Bt[n][k], At[m][k], acc[ai][bj][m][n], 0, 0, 0); __builtin_amdgcn_s_setprio(0); } while (0)
; #define PG8_WAIT_V(n) asm volatile("s_waitcnt vmcnt(" #n ")" ::: "memory")
; #define PG8_WAIT_L(n) asm volatile("s_waitcnt lgkmcnt(" #n ")" ::: "memory")
; #define PG8_BAR __builtin_amdgcn_s_barrier()
; #define PG8_SCHED __builtin_amdgcn_sched_barrier(0)
; template <class Map, class Epi>
; DI void gemm_phase(LAS unsigned char* lds, const Map& MP, const Epi& E, const int nM, const int nN, const int K, const int lda, const int ldb) {
;     ...
;             PG8_LDB(B0, 0, 0); PG8_SCHED; PG8_LDA(At, 0, 0); PG8_STAGE(PG8_SA(1, 1), a1 + hstepA, voffA);
;             PG8_WAIT_L(8); PG8_BAR; PG8_WAIT_L(0); PG8_MMA(0, 0, At, B0); PG8_BAR; PG8_SCHED;
;             PG8_LDB(B1, 0, 1); PG8_STAGE(PG8_SB(0, 0), b2, voffB);
;             PG8_BAR; PG8_WAIT_L(0); PG8_MMA(0, 1, At, B1); PG8_BAR;
;             PG8_LDA(At, 0, 1); PG8_STAGE(PG8_SA(0, 0), a2, voffA);
;             PG8_BAR; PG8_WAIT_L(0); PG8_MMA(1, 0, At, B0); PG8_BAR; PG8_SCHED;
;             PG8_STAGE(PG8_SB(0, 1), b2 + hstepB, voffB);
;             PG8_WAIT_V(6); PG8_BAR; PG8_MMA(1, 1, At, B1); PG8_BAR;
;             PG8_LDB(B0, 1, 0); PG8_SCHED; PG8_LDA(At, 1, 0); PG8_STAGE(PG8_SA(0, 1), a2 + hstepA, voffA);
;             PG8_WAIT_L(8); PG8_BAR; PG8_WAIT_L(0); PG8_MMA(0, 0, At, B0); PG8_BAR; PG8_SCHED;
	s_mov_b32 m0, s39
	s_nop 0
	global_load_lds_dwordx4 v132, s[8:9]
	s_add_i32 m0, s39, 0x2000
	s_nop 0
	global_load_lds_dwordx4 v128, s[8:9]
	s_waitcnt vmcnt(6)
	s_setprio 1
	s_barrier
	v_mfma_f32_16x16x32_bf16 v[52:55], v[202:205], v[168:171], v[52:55]
	v_mfma_f32_16x16x32_bf16 v[48:51], v[210:213], v[168:171], v[48:51]
	s_add_i32 s39, 0, 0x18000
	v_add_u32_e32 v164, s39, v148
	ds_read_b128 v[152:155], v164
	v_mfma_f32_16x16x32_bf16 v[36:39], v[202:205], v[176:179], v[36:39]
	v_mfma_f32_16x16x32_bf16 v[32:35], v[210:213], v[176:179], v[32:35]
	ds_read_b128 v[156:159], v164 offset:1024
	v_mfma_f32_16x16x32_bf16 v[20:23], v[202:205], v[184:187], v[20:23]
	v_mfma_f32_16x16x32_bf16 v[16:19], v[210:213], v[184:187], v[16:19]
	ds_read_b128 v[160:163], v164 offset:2048
	v_mfma_f32_16x16x32_bf16 v[4:7], v[202:205], v[192:195], v[4:7]
	v_mfma_f32_16x16x32_bf16 v[0:3], v[210:213], v[192:195], v[0:3]
	ds_read_b128 v[164:167], v164 offset:3072
	v_mfma_f32_16x16x32_bf16 v[52:55], v[206:209], v[172:175], v[52:55]
	s_add_u32 s8, s14, 0x160000
	s_addc_u32 s9, s15, 0
	v_mfma_f32_16x16x32_bf16 v[48:51], v[214:217], v[172:175], v[48:51]
	v_mfma_f32_16x16x32_bf16 v[36:39], v[206:209], v[180:183], v[36:39]
	v_mfma_f32_16x16x32_bf16 v[32:35], v[214:217], v[180:183], v[32:35]
	v_mfma_f32_16x16x32_bf16 v[20:23], v[206:209], v[188:191], v[20:23]
	v_mfma_f32_16x16x32_bf16 v[16:19], v[214:217], v[188:191], v[16:19]
	v_mfma_f32_16x16x32_bf16 v[4:7], v[206:209], v[198:201], v[4:7]
	s_setprio 0
	v_mfma_f32_16x16x32_bf16 v[0:3], v[214:217], v[198:201], v[0:3]
	s_barrier
	s_mov_b32 m0, s26
	ds_read_b128 v[168:171], v150 offset:32768
	ds_read_b128 v[172:175], v150 offset:33792
	ds_read_b128 v[176:179], v150 offset:34816
	ds_read_b128 v[180:183], v150 offset:35840
	ds_read_b128 v[184:187], v150 offset:36864
	ds_read_b128 v[188:191], v150 offset:37888
	ds_read_b128 v[192:195], v150 offset:38912
	ds_read_b128 v[198:201], v150 offset:39936
	global_load_lds_dwordx4 v134, s[8:9]
	s_mov_b32 m0, s27
	s_nop 0
	global_load_lds_dwordx4 v130, s[8:9]
	s_waitcnt lgkmcnt(8)
	s_setprio 1
	s_barrier
	s_waitcnt lgkmcnt(7)
	v_mfma_f32_16x16x32_bf16 v[124:127], v[152:155], v[168:171], v[124:127]
	v_mfma_f32_16x16x32_bf16 v[120:123], v[160:163], v[168:171], v[120:123]
	s_waitcnt lgkmcnt(5)
	v_mfma_f32_16x16x32_bf16 v[108:111], v[152:155], v[176:179], v[108:111]
	v_mfma_f32_16x16x32_bf16 v[104:107], v[160:163], v[176:179], v[104:107]
	s_waitcnt lgkmcnt(3)
	v_mfma_f32_16x16x32_bf16 v[92:95], v[152:155], v[184:187], v[92:95]
	v_mfma_f32_16x16x32_bf16 v[88:91], v[160:163], v[184:187], v[88:91]
	s_waitcnt lgkmcnt(1)
	v_mfma_f32_16x16x32_bf16 v[76:79], v[152:155], v[192:195], v[76:79]
	v_mfma_f32_16x16x32_bf16 v[72:75], v[160:163], v[192:195], v[72:75]
	v_mfma_f32_16x16x32_bf16 v[124:127], v[156:159], v[172:175], v[124:127]
	s_add_i32 s14, 0, 0x1c000
	v_mfma_f32_16x16x32_bf16 v[120:123], v[164:167], v[172:175], v[120:123]
	s_add_i32 s8, s39, s22
	v_mfma_f32_16x16x32_bf16 v[108:111], v[156:159], v[180:183], v[108:111]
	v_add_u32_e32 v196, s14, v148
	v_mfma_f32_16x16x32_bf16 v[104:107], v[164:167], v[180:183], v[104:107]
	v_lshl_add_u64 v[144:145], v[144:145], 0, s[52:53]
	v_mfma_f32_16x16x32_bf16 v[92:95], v[156:159], v[188:191], v[92:95]
	v_mfma_f32_16x16x32_bf16 v[88:91], v[164:167], v[188:191], v[88:91]
	s_waitcnt lgkmcnt(0)
	v_mfma_f32_16x16x32_bf16 v[76:79], v[156:159], v[198:201], v[76:79]
	s_setprio 0
	v_mfma_f32_16x16x32_bf16 v[72:75], v[164:167], v[198:201], v[72:75]
	s_barrier
	s_mov_b32 m0, s8
	ds_read_b128 v[202:205], v196
	ds_read_b128 v[206:209], v196 offset:1024
	ds_read_b128 v[210:213], v196 offset:2048
	ds_read_b128 v[214:217], v196 offset:3072
	global_load_lds_dwordx4 v[144:145], off
	v_lshl_add_u64 v[144:145], v[218:219], 0, s[52:53]
	s_add_i32 m0, s8, 0x2000
	s_nop 0
	global_load_lds_dwordx4 v[144:145], off
	s_setprio 1
	s_barrier
	s_waitcnt lgkmcnt(3)
	v_mfma_f32_16x16x32_bf16 v[116:119], v[202:205], v[168:171], v[116:119]
	s_waitcnt lgkmcnt(1)
	v_mfma_f32_16x16x32_bf16 v[112:115], v[210:213], v[168:171], v[112:115]
	v_mfma_f32_16x16x32_bf16 v[100:103], v[202:205], v[176:179], v[100:103]
	v_mfma_f32_16x16x32_bf16 v[96:99], v[210:213], v[176:179], v[96:99]
	v_mfma_f32_16x16x32_bf16 v[84:87], v[202:205], v[184:187], v[84:87]
	v_mfma_f32_16x16x32_bf16 v[80:83], v[210:213], v[184:187], v[80:83]
	v_mfma_f32_16x16x32_bf16 v[68:71], v[202:205], v[192:195], v[68:71]
	v_mfma_f32_16x16x32_bf16 v[64:67], v[210:213], v[192:195], v[64:67]
	v_mfma_f32_16x16x32_bf16 v[116:119], v[206:209], v[172:175], v[116:119]
	s_mov_b32 m0, s30
	s_waitcnt lgkmcnt(0)
	v_mfma_f32_16x16x32_bf16 v[112:115], v[214:217], v[172:175], v[112:115]
	v_lshl_add_u64 v[144:145], v[220:221], 0, s[52:53]
	v_mfma_f32_16x16x32_bf16 v[100:103], v[206:209], v[180:183], v[100:103]
	v_mfma_f32_16x16x32_bf16 v[96:99], v[214:217], v[180:183], v[96:99]
	v_mfma_f32_16x16x32_bf16 v[84:87], v[206:209], v[188:191], v[84:87]
	v_mfma_f32_16x16x32_bf16 v[80:83], v[214:217], v[188:191], v[80:83]
	v_mfma_f32_16x16x32_bf16 v[68:71], v[206:209], v[198:201], v[68:71]
	s_setprio 0
	v_mfma_f32_16x16x32_bf16 v[64:67], v[214:217], v[198:201], v[64:67]
	s_barrier
	ds_read_b128 v[168:171], v150 offset:49152
	ds_read_b128 v[172:175], v150 offset:50176
	ds_read_b128 v[176:179], v150 offset:51200
	ds_read_b128 v[180:183], v150 offset:52224
	ds_read_b128 v[184:187], v150 offset:53248
	ds_read_b128 v[188:191], v150 offset:54272
	ds_read_b128 v[192:195], v150 offset:55296
	ds_read_b128 v[198:201], v150 offset:56320
	global_load_lds_dwordx4 v[144:145], off
	v_lshl_add_u64 v[144:145], v[222:223], 0, s[52:53]
	s_mov_b32 m0, s31
	s_nop 0
	global_load_lds_dwordx4 v[144:145], off
	s_waitcnt vmcnt(10)
	s_setprio 1
	s_barrier
; DI unsigned pack2(float a, float b) { f32x2 v = {a, b}; hwbf16x2 r = __builtin_convertvector(v, hwbf16x2); return __builtin_bit_cast(unsigned, r); }
; DI float bflo(unsigned w) { return __uint_as_float(w << 16); }
; DI float bfhi(unsigned w) { return __uint_as_float(w & 0xffff0000u); }
; #define PG8_WAIT_V(n) asm volatile("s_waitcnt vmcnt(" #n ")" ::: "memory")
; #define PG8_BAR __builtin_amdgcn_s_barrier()
;     DI void operator()(const f32x4 (&acc)[2][2][4][2], const Unit& u, int wr, int wc, int fr, int fq) const {
;     ...
;         for (int ai = 0; ai < 2; ++ai)
; #pragma unroll
;             for (int m = 0; m < 4; ++m) { const size_t ro = (size_t)(row0 + ai * HALF + m * 16) * D + col0;
; #pragma unroll
;                 for (int bj = 0; bj < 2; ++bj) {
;                     f32x4 x0, x1;
;                     if constexpr (IB) { const u32x4 w = *(const u32x4*)((const bf16_t*)Xin + ro + bj * HALF);
;                         x0 = (f32x4){bflo(w[0]), bfhi(w[0]), bflo(w[1]), bfhi(w[1])}; x1 = (f32x4){bflo(w[2]), bfhi(w[2]), bflo(w[3]), bfhi(w[3])}; }
;                     else { x0 = *(const f32x4*)((const float*)Xin + ro + bj * HALF); x1 = *(const f32x4*)((const float*)Xin + ro + bj * HALF + 4); }
;                     x0 += acc[ai][bj][m][0] * sc[bj][0]; x1 += acc[ai][bj][m][1] * sc[bj][1];
;                     if constexpr (OB) { u32x4 o; o[0] = pack2(x0[0], x0[1]); o[1] = pack2(x0[2], x0[3]); o[2] = pack2(x1[0], x1[1]); o[3] = pack2(x1[2], x1[3]);
;                         *(u32x4*)((bf16_t*)Xout + ro + bj * HALF) = o; }
;                     else { *(f32x4*)((float*)Xout + ro + bj * HALF) = x0; *(f32x4*)((float*)Xout + ro + bj * HALF + 4) = x1; } } }
; template <class Map, class Epi>
; DI void gemm_phase(LAS unsigned char* lds, const Map& MP, const Epi& E, const int nM, const int nN, const int K, const int lda, const int ldb) {
;     ...
;             PG8_WAIT_L(8); PG8_BAR; PG8_WAIT_L(0); PG8_MMA(0, 0, At, B0); PG8_BAR; PG8_SCHED;
;             PG8_LDB(B1, 1, 1); PG8_STAGE(PG8_SB(1, 0), b3, voffB);
;             PG8_BAR; PG8_WAIT_L(0); PG8_MMA(0, 1, At, B1); PG8_BAR;
;             PG8_LDA(At, 1, 1); PG8_STAGE(PG8_SA(1, 0), a3, voffA);
;             PG8_BAR; PG8_WAIT_L(0); PG8_MMA(1, 0, At, B0); PG8_BAR; PG8_SCHED;
;             PG8_STAGE(PG8_SB(1, 1), b3 + hstepB, voffB);
;             PG8_WAIT_V(6); PG8_BAR; PG8_MMA(1, 1, At, B1); PG8_BAR;
	s_waitcnt lgkmcnt(7)
	v_mfma_f32_16x16x32_bf16 v[60:63], v[152:155], v[168:171], v[60:63]
	v_mfma_f32_16x16x32_bf16 v[56:59], v[160:163], v[168:171], v[56:59]
	s_waitcnt lgkmcnt(5)
	v_mfma_f32_16x16x32_bf16 v[44:47], v[152:155], v[176:179], v[44:47]
	v_mfma_f32_16x16x32_bf16 v[40:43], v[160:163], v[176:179], v[40:43]
	s_waitcnt lgkmcnt(3)
	v_mfma_f32_16x16x32_bf16 v[28:31], v[152:155], v[184:187], v[28:31]
	v_mfma_f32_16x16x32_bf16 v[24:27], v[160:163], v[184:187], v[24:27]
	s_waitcnt lgkmcnt(1)
	v_mfma_f32_16x16x32_bf16 v[12:15], v[152:155], v[192:195], v[12:15]
	v_mfma_f32_16x16x32_bf16 v[8:11], v[160:163], v[192:195], v[8:11]
	v_mfma_f32_16x16x32_bf16 v[60:63], v[156:159], v[172:175], v[60:63]
	s_add_u32 s8, s12, 0x160080
	s_addc_u32 s9, s13, 0
	v_mfma_f32_16x16x32_bf16 v[56:59], v[164:167], v[172:175], v[56:59]
	s_add_i32 s12, s14, s22
	v_mfma_f32_16x16x32_bf16 v[44:47], v[156:159], v[180:183], v[44:47]
	v_mfma_f32_16x16x32_bf16 v[40:43], v[164:167], v[180:183], v[40:43]
	v_mfma_f32_16x16x32_bf16 v[28:31], v[156:159], v[188:191], v[28:31]
	v_mfma_f32_16x16x32_bf16 v[24:27], v[164:167], v[188:191], v[24:27]
	s_waitcnt lgkmcnt(0)
	v_mfma_f32_16x16x32_bf16 v[12:15], v[156:159], v[198:201], v[12:15]
	s_setprio 0
	v_mfma_f32_16x16x32_bf16 v[8:11], v[164:167], v[198:201], v[8:11]
	s_barrier
	s_mov_b32 m0, s12
	s_nop 0
	global_load_lds_dwordx4 v132, s[8:9]
	s_add_i32 m0, s12, 0x2000
	s_nop 0
	global_load_lds_dwordx4 v128, s[8:9]
	s_waitcnt vmcnt(6)
	s_setprio 1
	s_barrier
	v_mfma_f32_16x16x32_bf16 v[52:55], v[202:205], v[168:171], v[52:55]
	v_mfma_f32_16x16x32_bf16 v[48:51], v[210:213], v[168:171], v[48:51]
	ds_read_b128 v[152:155], v149
	v_mfma_f32_16x16x32_bf16 v[36:39], v[202:205], v[176:179], v[36:39]
	v_mfma_f32_16x16x32_bf16 v[32:35], v[210:213], v[176:179], v[32:35]
	ds_read_b128 v[156:159], v149 offset:1024
	v_mfma_f32_16x16x32_bf16 v[20:23], v[202:205], v[184:187], v[20:23]
	v_mfma_f32_16x16x32_bf16 v[16:19], v[210:213], v[184:187], v[16:19]
	ds_read_b128 v[160:163], v149 offset:2048
	v_mfma_f32_16x16x32_bf16 v[4:7], v[202:205], v[192:195], v[4:7]
	v_mfma_f32_16x16x32_bf16 v[0:3], v[210:213], v[192:195], v[0:3]
	ds_read_b128 v[164:167], v149 offset:3072
	v_mfma_f32_16x16x32_bf16 v[52:55], v[206:209], v[172:175], v[52:55]
	s_add_i32 s3, s3, 2
	v_mfma_f32_16x16x32_bf16 v[48:51], v[214:217], v[172:175], v[48:51]
	s_add_u32 s5, s5, 0x100
	s_addc_u32 s38, s38, 0
	v_mfma_f32_16x16x32_bf16 v[36:39], v[206:209], v[180:183], v[36:39]
	s_cmpk_gt_u32 s3, 0x55
	v_mfma_f32_16x16x32_bf16 v[32:35], v[214:217], v[180:183], v[32:35]
	s_mov_b64 s[8:9], s[10:11]
	v_mfma_f32_16x16x32_bf16 v[20:23], v[206:209], v[188:191], v[20:23]
	v_mfma_f32_16x16x32_bf16 v[16:19], v[214:217], v[188:191], v[16:19]
	v_mfma_f32_16x16x32_bf16 v[4:7], v[206:209], v[198:201], v[4:7]
	s_setprio 0
	v_mfma_f32_16x16x32_bf16 v[0:3], v[214:217], v[198:201], v[0:3]
	s_barrier
	s_cbranch_scc0 .LBB1_1239
	s_waitcnt lgkmcnt(0)
	v_mov_b32_e32 v152, v147
	v_mov_b32_e32 v144, v146
	s_lshl_b32 s2, s2, 8
	s_add_i32 s2, s2, s29
	s_lshl_b32 s3, s4, 8
	v_add_u32_e32 v152, s2, v152
	s_or_b32 s3, s3, s54
	v_ashrrev_i32_e32 v153, 31, v152
	v_lshl_add_u32 v144, v144, 3, s3
	v_lshlrev_b64 v[152:153], 12, v[152:153]
	v_ashrrev_i32_e32 v145, 31, v144
	v_lshl_add_u64 v[152:153], s[46:47], 0, v[152:153]
	v_lshl_add_u64 v[144:145], v[144:145], 1, v[152:153]
	global_load_dwordx4 v[160:163], v[144:145], off
	global_load_dwordx4 v[164:167], v[144:145], off offset:256
	s_mov_b64 s[98:99], 0x10000
	v_lshl_add_u64 v[154:155], v[144:145], 0, s[98:99]
	global_load_dwordx4 v[168:171], v[154:155], off
	global_load_dwordx4 v[172:175], v[154:155], off offset:256
	s_mov_b64 s[98:99], 0x20000
	v_lshl_add_u64 v[154:155], v[144:145], 0, s[98:99]
	global_load_dwordx4 v[176:179], v[154:155], off
	global_load_dwordx4 v[180:183], v[154:155], off offset:256
	s_mov_b64 s[98:99], 0x30000
	v_lshl_add_u64 v[154:155], v[144:145], 0, s[98:99]
	global_load_dwordx4 v[184:187], v[154:155], off
	global_load_dwordx4 v[188:191], v[154:155], off offset:256
	s_mov_b64 s[98:99], 0x80000
	v_lshl_add_u64 v[154:155], v[144:145], 0, s[98:99]
	global_load_dwordx4 v[192:195], v[154:155], off
	global_load_dwordx4 v[198:201], v[154:155], off offset:256
	s_mov_b64 s[98:99], 0x90000
	v_lshl_add_u64 v[154:155], v[144:145], 0, s[98:99]
	global_load_dwordx4 v[202:205], v[154:155], off
	global_load_dwordx4 v[206:209], v[154:155], off offset:256
	s_mov_b64 s[98:99], 0xa0000
	v_lshl_add_u64 v[154:155], v[144:145], 0, s[98:99]
	global_load_dwordx4 v[210:213], v[154:155], off
	global_load_dwordx4 v[214:217], v[154:155], off offset:256
	s_mov_b64 s[98:99], 0xb0000
	v_lshl_add_u64 v[154:155], v[144:145], 0, s[98:99]
	global_load_dwordx4 v[248:251], v[154:155], off
	global_load_dwordx4 v[252:255], v[154:155], off offset:256
	s_waitcnt vmcnt(15)
	s_nop 1
	v_mov_b32_e32 v152, v160
	v_mov_b32_e32 v153, v161
	v_mov_b32_e32 v154, v162
	v_mov_b32_e32 v155, v163
	s_mov_b64 s[2:3], 0x10000
	s_mov_b32 s4, s37
	s_mov_b64 s[10:11], s[6:7]
	s_mov_b64 s[8:9], s[42:43]
	s_waitcnt lgkmcnt(0)
	v_lshlrev_b32_e32 v156, 16, v152
	v_and_b32_e32 v157, 0xffff0000, v152
	v_lshlrev_b32_e32 v152, 16, v153
	v_and_b32_e32 v153, 0xffff0000, v153
	v_lshlrev_b32_e32 v158, 16, v154
	v_and_b32_e32 v159, 0xffff0000, v154
	v_lshlrev_b32_e32 v154, 16, v155
	v_and_b32_e32 v155, 0xffff0000, v155
	v_pk_add_f32 v[126:127], v[126:127], v[152:153]
	v_pk_add_f32 v[124:125], v[124:125], v[156:157]
	v_pk_add_f32 v[152:153], v[122:123], v[154:155]
	v_pk_add_f32 v[122:123], v[120:121], v[158:159]
	v_cvt_pk_bf16_f32 v120, v124, v125
	v_cvt_pk_bf16_f32 v121, v126, v127
	v_cvt_pk_bf16_f32 v122, v122, v123
	v_cvt_pk_bf16_f32 v123, v152, v153
	global_store_dwordx4 v[144:145], v[120:123], off
	s_waitcnt vmcnt(15)
; DI unsigned pack2(float a, float b) { f32x2 v = {a, b}; hwbf16x2 r = __builtin_convertvector(v, hwbf16x2); return __builtin_bit_cast(unsigned, r); }
; DI float bflo(unsigned w) { return __uint_as_float(w << 16); }
; DI float bfhi(unsigned w) { return __uint_as_float(w & 0xffff0000u); }
;     DI void operator()(const f32x4 (&acc)[2][2][4][2], const Unit& u, int wr, int wc, int fr, int fq) const {
;     ...
;         for (int ai = 0; ai < 2; ++ai)
; #pragma unroll
;             for (int m = 0; m < 4; ++m) { const size_t ro = (size_t)(row0 + ai * HALF + m * 16) * D + col0;
; #pragma unroll
;                 for (int bj = 0; bj < 2; ++bj) {
;                     f32x4 x0, x1;
;                     if constexpr (IB) { const u32x4 w = *(const u32x4*)((const bf16_t*)Xin + ro + bj * HALF);
;                         x0 = (f32x4){bflo(w[0]), bfhi(w[0]), bflo(w[1]), bfhi(w[1])}; x1 = (f32x4){bflo(w[2]), bfhi(w[2]), bflo(w[3]), bfhi(w[3])}; }
;                     else { x0 = *(const f32x4*)((const float*)Xin + ro + bj * HALF); x1 = *(const f32x4*)((const float*)Xin + ro + bj * HALF + 4); }
;                     x0 += acc[ai][bj][m][0] * sc[bj][0]; x1 += acc[ai][bj][m][1] * sc[bj][1];
;                     if constexpr (OB) { u32x4 o; o[0] = pack2(x0[0], x0[1]); o[1] = pack2(x0[2], x0[3]); o[2] = pack2(x1[0], x1[1]); o[3] = pack2(x1[2], x1[3]);
;                         *(u32x4*)((bf16_t*)Xout + ro + bj * HALF) = o; }
;                     else { *(f32x4*)((float*)Xout + ro + bj * HALF) = x0; *(f32x4*)((float*)Xout + ro + bj * HALF + 4) = x1; } } }
	s_nop 1
	v_mov_b32_e32 v120, v164
	v_mov_b32_e32 v121, v165
	v_mov_b32_e32 v122, v166
	v_mov_b32_e32 v123, v167
	s_waitcnt lgkmcnt(0)
	v_lshlrev_b32_e32 v124, 16, v120
	v_and_b32_e32 v125, 0xffff0000, v120
	v_lshlrev_b32_e32 v120, 16, v121
	v_and_b32_e32 v121, 0xffff0000, v121
	v_lshlrev_b32_e32 v126, 16, v122
	v_and_b32_e32 v127, 0xffff0000, v122
	v_lshlrev_b32_e32 v122, 16, v123
	v_and_b32_e32 v123, 0xffff0000, v123
	v_pk_add_f32 v[116:117], v[116:117], v[124:125]
	v_pk_add_f32 v[118:119], v[118:119], v[120:121]
	v_pk_add_f32 v[120:121], v[114:115], v[122:123]
	v_pk_add_f32 v[114:115], v[112:113], v[126:127]
	v_cvt_pk_bf16_f32 v112, v116, v117
	v_lshl_add_u64 v[116:117], v[144:145], 0, s[2:3]
	s_mov_b32 s2, 0x10000
	v_cvt_pk_bf16_f32 v113, v118, v119
	v_add_co_u32_e32 v118, vcc, s2, v144
	v_cvt_pk_bf16_f32 v114, v114, v115
	v_cvt_pk_bf16_f32 v115, v120, v121
	v_addc_co_u32_e32 v119, vcc, 0, v145, vcc
	global_store_dwordx4 v[144:145], v[112:115], off offset:256
	s_waitcnt vmcnt(15)
	s_nop 1
	v_mov_b32_e32 v112, v168
	v_mov_b32_e32 v113, v169
	v_mov_b32_e32 v114, v170
	v_mov_b32_e32 v115, v171
	s_mov_b64 s[2:3], 0x20000
	s_waitcnt lgkmcnt(0)
	v_lshlrev_b32_e32 v120, 16, v112
	v_and_b32_e32 v121, 0xffff0000, v112
	v_lshlrev_b32_e32 v112, 16, v113
	v_and_b32_e32 v113, 0xffff0000, v113
	v_lshlrev_b32_e32 v122, 16, v114
	v_and_b32_e32 v123, 0xffff0000, v114
	v_lshlrev_b32_e32 v114, 16, v115
	v_and_b32_e32 v115, 0xffff0000, v115
	v_pk_add_f32 v[110:111], v[110:111], v[112:113]
	v_pk_add_f32 v[108:109], v[108:109], v[120:121]
	v_pk_add_f32 v[112:113], v[106:107], v[114:115]
	v_pk_add_f32 v[106:107], v[104:105], v[122:123]
	v_cvt_pk_bf16_f32 v104, v108, v109
	v_cvt_pk_bf16_f32 v105, v110, v111
	v_cvt_pk_bf16_f32 v106, v106, v107
	v_cvt_pk_bf16_f32 v107, v112, v113
	global_store_dwordx4 v[118:119], v[104:107], off
	s_waitcnt vmcnt(15)
	s_nop 1
	v_mov_b32_e32 v104, v172
	v_mov_b32_e32 v105, v173
	v_mov_b32_e32 v106, v174
	v_mov_b32_e32 v107, v175
	s_waitcnt lgkmcnt(0)
	v_lshlrev_b32_e32 v108, 16, v104
	v_and_b32_e32 v109, 0xffff0000, v104
	v_lshlrev_b32_e32 v104, 16, v105
	v_and_b32_e32 v105, 0xffff0000, v105
	v_lshlrev_b32_e32 v110, 16, v106
	v_and_b32_e32 v111, 0xffff0000, v106
	v_lshlrev_b32_e32 v106, 16, v107
	v_and_b32_e32 v107, 0xffff0000, v107
	v_pk_add_f32 v[100:101], v[100:101], v[108:109]
	v_pk_add_f32 v[102:103], v[102:103], v[104:105]
	v_pk_add_f32 v[104:105], v[98:99], v[106:107]
	v_pk_add_f32 v[98:99], v[96:97], v[110:111]
	v_cvt_pk_bf16_f32 v96, v100, v101
	v_lshl_add_u64 v[100:101], v[144:145], 0, s[2:3]
	s_mov_b32 s2, 0x20000
	v_cvt_pk_bf16_f32 v97, v102, v103
	v_add_co_u32_e32 v102, vcc, s2, v144
	v_cvt_pk_bf16_f32 v98, v98, v99
	v_cvt_pk_bf16_f32 v99, v104, v105
	v_addc_co_u32_e32 v103, vcc, 0, v145, vcc
	global_store_dwordx4 v[116:117], v[96:99], off offset:256
	s_waitcnt vmcnt(15)
	s_nop 1
	v_mov_b32_e32 v96, v176
	v_mov_b32_e32 v97, v177
	v_mov_b32_e32 v98, v178
	v_mov_b32_e32 v99, v179
	s_mov_b64 s[2:3], 0x30000
	s_waitcnt lgkmcnt(0)
	v_lshlrev_b32_e32 v104, 16, v96
	v_and_b32_e32 v105, 0xffff0000, v96
	v_lshlrev_b32_e32 v96, 16, v97
	v_and_b32_e32 v97, 0xffff0000, v97
	v_lshlrev_b32_e32 v106, 16, v98
	v_and_b32_e32 v107, 0xffff0000, v98
	v_lshlrev_b32_e32 v98, 16, v99
	v_and_b32_e32 v99, 0xffff0000, v99
	v_pk_add_f32 v[94:95], v[94:95], v[96:97]
	v_pk_add_f32 v[92:93], v[92:93], v[104:105]
	v_pk_add_f32 v[96:97], v[90:91], v[98:99]
	v_pk_add_f32 v[90:91], v[88:89], v[106:107]
	v_cvt_pk_bf16_f32 v88, v92, v93
	v_cvt_pk_bf16_f32 v89, v94, v95
	v_cvt_pk_bf16_f32 v90, v90, v91
	v_cvt_pk_bf16_f32 v91, v96, v97
	global_store_dwordx4 v[102:103], v[88:91], off
	s_waitcnt vmcnt(15)
	s_nop 1
	v_mov_b32_e32 v88, v180
	v_mov_b32_e32 v89, v181
	v_mov_b32_e32 v90, v182
	v_mov_b32_e32 v91, v183
	s_waitcnt lgkmcnt(0)
	v_lshlrev_b32_e32 v92, 16, v88
	v_and_b32_e32 v93, 0xffff0000, v88
	v_lshlrev_b32_e32 v88, 16, v89
	v_and_b32_e32 v89, 0xffff0000, v89
	v_lshlrev_b32_e32 v94, 16, v90
	v_and_b32_e32 v95, 0xffff0000, v90
	v_lshlrev_b32_e32 v90, 16, v91
	v_and_b32_e32 v91, 0xffff0000, v91
	v_pk_add_f32 v[86:87], v[86:87], v[88:89]
	v_pk_add_f32 v[84:85], v[84:85], v[92:93]
	v_pk_add_f32 v[88:89], v[82:83], v[90:91]
	v_pk_add_f32 v[82:83], v[80:81], v[94:95]
	v_cvt_pk_bf16_f32 v80, v84, v85
	v_cvt_pk_bf16_f32 v81, v86, v87
	v_cvt_pk_bf16_f32 v82, v82, v83
	v_cvt_pk_bf16_f32 v83, v88, v89
	global_store_dwordx4 v[100:101], v[80:83], off offset:256
	s_nop 1
	v_lshl_add_u64 v[80:81], v[144:145], 0, s[2:3]
	s_mov_b32 s2, 0x30000
	v_add_co_u32_e32 v86, vcc, s2, v144
	s_mov_b64 s[2:3], 0x80000
	s_nop 0
	v_addc_co_u32_e32 v87, vcc, 0, v145, vcc
	s_waitcnt vmcnt(15)
	s_nop 1
	v_mov_b32_e32 v82, v184
	v_mov_b32_e32 v83, v185
	v_mov_b32_e32 v84, v186
	v_mov_b32_e32 v85, v187
	s_waitcnt lgkmcnt(0)
	v_lshlrev_b32_e32 v88, 16, v82
	v_and_b32_e32 v89, 0xffff0000, v82
	v_lshlrev_b32_e32 v82, 16, v83
	v_and_b32_e32 v83, 0xffff0000, v83
	v_lshlrev_b32_e32 v90, 16, v84
	v_and_b32_e32 v91, 0xffff0000, v84
	v_lshlrev_b32_e32 v84, 16, v85
	v_and_b32_e32 v85, 0xffff0000, v85
	v_pk_add_f32 v[78:79], v[78:79], v[82:83]
	v_pk_add_f32 v[76:77], v[76:77], v[88:89]
	v_pk_add_f32 v[82:83], v[74:75], v[84:85]
	v_pk_add_f32 v[74:75], v[72:73], v[90:91]
	v_cvt_pk_bf16_f32 v72, v76, v77
	v_cvt_pk_bf16_f32 v73, v78, v79
	v_cvt_pk_bf16_f32 v74, v74, v75
	v_cvt_pk_bf16_f32 v75, v82, v83
	global_store_dwordx4 v[86:87], v[72:75], off
	s_waitcnt vmcnt(15)
	s_nop 1
	v_mov_b32_e32 v72, v188
	v_mov_b32_e32 v73, v189
	v_mov_b32_e32 v74, v190
	v_mov_b32_e32 v75, v191
	s_waitcnt lgkmcnt(0)
; DI unsigned pack2(float a, float b) { f32x2 v = {a, b}; hwbf16x2 r = __builtin_convertvector(v, hwbf16x2); return __builtin_bit_cast(unsigned, r); }
; DI float bflo(unsigned w) { return __uint_as_float(w << 16); }
; DI float bfhi(unsigned w) { return __uint_as_float(w & 0xffff0000u); }
;     DI void operator()(const f32x4 (&acc)[2][2][4][2], const Unit& u, int wr, int wc, int fr, int fq) const {
;     ...
;         for (int ai = 0; ai < 2; ++ai)
; #pragma unroll
;             for (int m = 0; m < 4; ++m) { const size_t ro = (size_t)(row0 + ai * HALF + m * 16) * D + col0;
; #pragma unroll
;                 for (int bj = 0; bj < 2; ++bj) {
;                     f32x4 x0, x1;
;                     if constexpr (IB) { const u32x4 w = *(const u32x4*)((const bf16_t*)Xin + ro + bj * HALF);
;                         x0 = (f32x4){bflo(w[0]), bfhi(w[0]), bflo(w[1]), bfhi(w[1])}; x1 = (f32x4){bflo(w[2]), bfhi(w[2]), bflo(w[3]), bfhi(w[3])}; }
;                     else { x0 = *(const f32x4*)((const float*)Xin + ro + bj * HALF); x1 = *(const f32x4*)((const float*)Xin + ro + bj * HALF + 4); }
;                     x0 += acc[ai][bj][m][0] * sc[bj][0]; x1 += acc[ai][bj][m][1] * sc[bj][1];
;                     if constexpr (OB) { u32x4 o; o[0] = pack2(x0[0], x0[1]); o[1] = pack2(x0[2], x0[3]); o[2] = pack2(x1[0], x1[1]); o[3] = pack2(x1[2], x1[3]);
;                         *(u32x4*)((bf16_t*)Xout + ro + bj * HALF) = o; }
;                     else { *(f32x4*)((float*)Xout + ro + bj * HALF) = x0; *(f32x4*)((float*)Xout + ro + bj * HALF + 4) = x1; } } }
	v_lshlrev_b32_e32 v76, 16, v72
	v_and_b32_e32 v77, 0xffff0000, v72
	v_lshlrev_b32_e32 v72, 16, v73
	v_and_b32_e32 v73, 0xffff0000, v73
	v_lshlrev_b32_e32 v78, 16, v74
	v_and_b32_e32 v79, 0xffff0000, v74
	v_lshlrev_b32_e32 v74, 16, v75
	v_and_b32_e32 v75, 0xffff0000, v75
	v_pk_add_f32 v[70:71], v[70:71], v[72:73]
	v_pk_add_f32 v[68:69], v[68:69], v[76:77]
	v_pk_add_f32 v[72:73], v[66:67], v[74:75]
	v_pk_add_f32 v[66:67], v[64:65], v[78:79]
	v_cvt_pk_bf16_f32 v64, v68, v69
	v_cvt_pk_bf16_f32 v65, v70, v71
	v_cvt_pk_bf16_f32 v66, v66, v67
	v_cvt_pk_bf16_f32 v67, v72, v73
	global_store_dwordx4 v[80:81], v[64:67], off offset:256
	s_nop 1
	v_lshl_add_u64 v[64:65], v[144:145], 0, s[2:3]
	s_mov_b32 s2, 0x80000
	v_add_co_u32_e32 v70, vcc, s2, v144
	s_mov_b64 s[2:3], 0x90000
	s_nop 0
	v_addc_co_u32_e32 v71, vcc, 0, v145, vcc
	s_waitcnt vmcnt(15)
	s_nop 1
	v_mov_b32_e32 v66, v192
	v_mov_b32_e32 v67, v193
	v_mov_b32_e32 v68, v194
	v_mov_b32_e32 v69, v195
	s_waitcnt lgkmcnt(0)
	v_lshlrev_b32_e32 v72, 16, v66
	v_and_b32_e32 v73, 0xffff0000, v66
	v_lshlrev_b32_e32 v66, 16, v67
	v_and_b32_e32 v67, 0xffff0000, v67
	v_lshlrev_b32_e32 v74, 16, v68
	v_and_b32_e32 v75, 0xffff0000, v68
	v_lshlrev_b32_e32 v68, 16, v69
	v_and_b32_e32 v69, 0xffff0000, v69
	v_pk_add_f32 v[62:63], v[62:63], v[66:67]
	v_pk_add_f32 v[60:61], v[60:61], v[72:73]
	v_pk_add_f32 v[66:67], v[58:59], v[68:69]
	v_pk_add_f32 v[58:59], v[56:57], v[74:75]
	v_cvt_pk_bf16_f32 v56, v60, v61
	v_cvt_pk_bf16_f32 v57, v62, v63
	v_cvt_pk_bf16_f32 v58, v58, v59
	v_cvt_pk_bf16_f32 v59, v66, v67
	global_store_dwordx4 v[70:71], v[56:59], off
	s_waitcnt vmcnt(15)
	s_nop 1
	v_mov_b32_e32 v56, v198
	v_mov_b32_e32 v57, v199
	v_mov_b32_e32 v58, v200
	v_mov_b32_e32 v59, v201
	s_waitcnt lgkmcnt(0)
	v_lshlrev_b32_e32 v60, 16, v56
	v_and_b32_e32 v61, 0xffff0000, v56
	v_lshlrev_b32_e32 v56, 16, v57
	v_and_b32_e32 v57, 0xffff0000, v57
	v_lshlrev_b32_e32 v62, 16, v58
	v_and_b32_e32 v63, 0xffff0000, v58
	v_lshlrev_b32_e32 v58, 16, v59
	v_and_b32_e32 v59, 0xffff0000, v59
	v_pk_add_f32 v[54:55], v[54:55], v[56:57]
	v_pk_add_f32 v[52:53], v[52:53], v[60:61]
	v_pk_add_f32 v[56:57], v[50:51], v[58:59]
	v_pk_add_f32 v[50:51], v[48:49], v[62:63]
	v_cvt_pk_bf16_f32 v48, v52, v53
	v_cvt_pk_bf16_f32 v49, v54, v55
	v_cvt_pk_bf16_f32 v50, v50, v51
	v_cvt_pk_bf16_f32 v51, v56, v57
	global_store_dwordx4 v[64:65], v[48:51], off offset:256
	s_nop 1
	v_lshl_add_u64 v[48:49], v[144:145], 0, s[2:3]
	s_mov_b32 s2, 0x90000
	v_add_co_u32_e32 v54, vcc, s2, v144
	s_mov_b64 s[2:3], 0xa0000
	s_nop 0
	v_addc_co_u32_e32 v55, vcc, 0, v145, vcc
	s_waitcnt vmcnt(15)
	s_nop 1
	v_mov_b32_e32 v50, v202
	v_mov_b32_e32 v51, v203
	v_mov_b32_e32 v52, v204
	v_mov_b32_e32 v53, v205
	s_waitcnt lgkmcnt(0)
	v_lshlrev_b32_e32 v56, 16, v50
	v_and_b32_e32 v57, 0xffff0000, v50
	v_lshlrev_b32_e32 v50, 16, v51
	v_and_b32_e32 v51, 0xffff0000, v51
	v_lshlrev_b32_e32 v58, 16, v52
	v_and_b32_e32 v59, 0xffff0000, v52
	v_lshlrev_b32_e32 v52, 16, v53
	v_and_b32_e32 v53, 0xffff0000, v53
	v_pk_add_f32 v[46:47], v[46:47], v[50:51]
	v_pk_add_f32 v[44:45], v[44:45], v[56:57]
	v_pk_add_f32 v[50:51], v[42:43], v[52:53]
	v_pk_add_f32 v[42:43], v[40:41], v[58:59]
	v_cvt_pk_bf16_f32 v40, v44, v45
	v_cvt_pk_bf16_f32 v41, v46, v47
	v_cvt_pk_bf16_f32 v42, v42, v43
	v_cvt_pk_bf16_f32 v43, v50, v51
	global_store_dwordx4 v[54:55], v[40:43], off
	s_waitcnt vmcnt(15)
	s_nop 1
	v_mov_b32_e32 v40, v206
	v_mov_b32_e32 v41, v207
	v_mov_b32_e32 v42, v208
	v_mov_b32_e32 v43, v209
	s_waitcnt lgkmcnt(0)
; DI unsigned pack2(float a, float b) { f32x2 v = {a, b}; hwbf16x2 r = __builtin_convertvector(v, hwbf16x2); return __builtin_bit_cast(unsigned, r); }
; DI float bflo(unsigned w) { return __uint_as_float(w << 16); }
; DI float bfhi(unsigned w) { return __uint_as_float(w & 0xffff0000u); }
;     DI const char* a(const Unit& u) const { return (const char*)(A + (size_t)u.pm * BM * lda); }
;     DI const char* a(const Unit& u) const { return (const char*)(A + (size_t)u.pm * BM * 2048 + (u.pn >> 1) * 512); }
;     DI void operator()(const f32x4 (&acc)[2][2][4][2], const Unit& u, int wr, int wc, int fr, int fq) const {
;     ...
;         for (int ai = 0; ai < 2; ++ai)
; #pragma unroll
;             for (int m = 0; m < 4; ++m) { const size_t ro = (size_t)(row0 + ai * HALF + m * 16) * D + col0;
; #pragma unroll
;                 for (int bj = 0; bj < 2; ++bj) {
;                     f32x4 x0, x1;
;                     if constexpr (IB) { const u32x4 w = *(const u32x4*)((const bf16_t*)Xin + ro + bj * HALF);
;                         x0 = (f32x4){bflo(w[0]), bfhi(w[0]), bflo(w[1]), bfhi(w[1])}; x1 = (f32x4){bflo(w[2]), bfhi(w[2]), bflo(w[3]), bfhi(w[3])}; }
;                     else { x0 = *(const f32x4*)((const float*)Xin + ro + bj * HALF); x1 = *(const f32x4*)((const float*)Xin + ro + bj * HALF + 4); }
;                     x0 += acc[ai][bj][m][0] * sc[bj][0]; x1 += acc[ai][bj][m][1] * sc[bj][1];
;                     if constexpr (OB) { u32x4 o; o[0] = pack2(x0[0], x0[1]); o[1] = pack2(x0[2], x0[3]); o[2] = pack2(x1[0], x1[1]); o[3] = pack2(x1[2], x1[3]);
;                         *(u32x4*)((bf16_t*)Xout + ro + bj * HALF) = o; }
;                     else { *(f32x4*)((float*)Xout + ro + bj * HALF) = x0; *(f32x4*)((float*)Xout + ro + bj * HALF + 4) = x1; } } }
; template <class Map, class Epi>
; DI void gemm_phase(LAS unsigned char* lds, const Map& MP, const Epi& E, const int nM, const int nN, const int K, const int lda, const int ldb) {
;     ...
;         if (!has_next) break;
; #pragma unroll
;         for (int a = 0; a < 2; ++a)
; #pragma unroll
;             for (int b = 0; b < 2; ++b)
; #pragma unroll
;                 for (int m = 0; m < 4; ++m)
; #pragma unroll
;                     for (int n = 0; n < 2; ++n) acc[a][b][m][n] = (f32x4){0.f, 0.f, 0.f, 0.f};
;         cur = nxt; cA = nA; cB = nB; ++ui;
;     }
;     PG8_WAIT_V(0);
;     if (wr == 0) PG8_BAR;
;     PG8_BAR;
	v_lshlrev_b32_e32 v44, 16, v40
	v_and_b32_e32 v45, 0xffff0000, v40
	v_lshlrev_b32_e32 v40, 16, v41
	v_and_b32_e32 v41, 0xffff0000, v41
	v_lshlrev_b32_e32 v46, 16, v42
	v_and_b32_e32 v47, 0xffff0000, v42
	v_lshlrev_b32_e32 v42, 16, v43
	v_and_b32_e32 v43, 0xffff0000, v43
	v_pk_add_f32 v[38:39], v[38:39], v[40:41]
	v_pk_add_f32 v[36:37], v[36:37], v[44:45]
	v_pk_add_f32 v[40:41], v[34:35], v[42:43]
	v_pk_add_f32 v[34:35], v[32:33], v[46:47]
	v_cvt_pk_bf16_f32 v32, v36, v37
	v_cvt_pk_bf16_f32 v33, v38, v39
	v_cvt_pk_bf16_f32 v34, v34, v35
	v_cvt_pk_bf16_f32 v35, v40, v41
	global_store_dwordx4 v[48:49], v[32:35], off offset:256
	s_nop 1
	v_lshl_add_u64 v[32:33], v[144:145], 0, s[2:3]
	s_mov_b32 s2, 0xa0000
	v_add_co_u32_e32 v38, vcc, s2, v144
	s_mov_b64 s[2:3], 0xb0000
	s_nop 0
	v_addc_co_u32_e32 v39, vcc, 0, v145, vcc
	s_waitcnt vmcnt(15)
	s_nop 1
	v_mov_b32_e32 v34, v210
	v_mov_b32_e32 v35, v211
	v_mov_b32_e32 v36, v212
	v_mov_b32_e32 v37, v213
	s_waitcnt lgkmcnt(0)
	v_lshlrev_b32_e32 v40, 16, v34
	v_and_b32_e32 v41, 0xffff0000, v34
	v_lshlrev_b32_e32 v34, 16, v35
	v_and_b32_e32 v35, 0xffff0000, v35
	v_lshlrev_b32_e32 v42, 16, v36
	v_and_b32_e32 v43, 0xffff0000, v36
	v_lshlrev_b32_e32 v36, 16, v37
	v_and_b32_e32 v37, 0xffff0000, v37
	v_pk_add_f32 v[30:31], v[30:31], v[34:35]
	v_pk_add_f32 v[28:29], v[28:29], v[40:41]
	v_pk_add_f32 v[34:35], v[26:27], v[36:37]
	v_pk_add_f32 v[26:27], v[24:25], v[42:43]
	v_cvt_pk_bf16_f32 v24, v28, v29
	v_cvt_pk_bf16_f32 v25, v30, v31
	v_cvt_pk_bf16_f32 v26, v26, v27
	v_cvt_pk_bf16_f32 v27, v34, v35
	global_store_dwordx4 v[38:39], v[24:27], off
	s_waitcnt vmcnt(15)
	s_nop 1
	v_mov_b32_e32 v24, v214
	v_mov_b32_e32 v25, v215
	v_mov_b32_e32 v26, v216
	v_mov_b32_e32 v27, v217
	s_waitcnt lgkmcnt(0)
	v_lshlrev_b32_e32 v28, 16, v24
	v_and_b32_e32 v29, 0xffff0000, v24
	v_lshlrev_b32_e32 v24, 16, v25
	v_and_b32_e32 v25, 0xffff0000, v25
	v_lshlrev_b32_e32 v30, 16, v26
	v_and_b32_e32 v31, 0xffff0000, v26
	v_lshlrev_b32_e32 v26, 16, v27
	v_and_b32_e32 v27, 0xffff0000, v27
	v_pk_add_f32 v[22:23], v[22:23], v[24:25]
	v_pk_add_f32 v[20:21], v[20:21], v[28:29]
	v_pk_add_f32 v[24:25], v[18:19], v[26:27]
	v_pk_add_f32 v[18:19], v[16:17], v[30:31]
	v_cvt_pk_bf16_f32 v16, v20, v21
	v_cvt_pk_bf16_f32 v17, v22, v23
	v_cvt_pk_bf16_f32 v18, v18, v19
	v_cvt_pk_bf16_f32 v19, v24, v25
	global_store_dwordx4 v[32:33], v[16:19], off offset:256
	s_nop 1
	v_lshl_add_u64 v[16:17], v[144:145], 0, s[2:3]
	s_mov_b32 s2, 0xb0000
	v_add_co_u32_e32 v22, vcc, s2, v144
	s_mov_b32 s2, s55
	s_nop 0
	v_addc_co_u32_e32 v23, vcc, 0, v145, vcc
	s_waitcnt vmcnt(15)
	s_nop 1
	v_mov_b32_e32 v18, v248
	v_mov_b32_e32 v19, v249
	v_mov_b32_e32 v20, v250
	v_mov_b32_e32 v21, v251
	s_and_b64 vcc, exec, s[40:41]
	s_waitcnt lgkmcnt(0)
	v_lshlrev_b32_e32 v24, 16, v18
	v_and_b32_e32 v25, 0xffff0000, v18
	v_lshlrev_b32_e32 v18, 16, v19
	v_and_b32_e32 v19, 0xffff0000, v19
	v_lshlrev_b32_e32 v26, 16, v20
	v_and_b32_e32 v27, 0xffff0000, v20
	v_lshlrev_b32_e32 v20, 16, v21
	v_and_b32_e32 v21, 0xffff0000, v21
	v_pk_add_f32 v[14:15], v[14:15], v[18:19]
	v_pk_add_f32 v[12:13], v[12:13], v[24:25]
	v_pk_add_f32 v[18:19], v[10:11], v[20:21]
	v_pk_add_f32 v[10:11], v[8:9], v[26:27]
	v_cvt_pk_bf16_f32 v8, v12, v13
	v_cvt_pk_bf16_f32 v9, v14, v15
	v_cvt_pk_bf16_f32 v10, v10, v11
	v_cvt_pk_bf16_f32 v11, v18, v19
	global_store_dwordx4 v[22:23], v[8:11], off
	s_waitcnt vmcnt(15)
	s_nop 1
	v_mov_b32_e32 v8, v252
	v_mov_b32_e32 v9, v253
	v_mov_b32_e32 v10, v254
	v_mov_b32_e32 v11, v255
	s_waitcnt lgkmcnt(0)
	v_lshlrev_b32_e32 v12, 16, v8
	v_and_b32_e32 v13, 0xffff0000, v8
	v_lshlrev_b32_e32 v8, 16, v9
	v_and_b32_e32 v9, 0xffff0000, v9
	v_lshlrev_b32_e32 v14, 16, v10
	v_and_b32_e32 v15, 0xffff0000, v10
	v_lshlrev_b32_e32 v10, 16, v11
	v_and_b32_e32 v11, 0xffff0000, v11
	v_pk_add_f32 v[6:7], v[6:7], v[8:9]
	v_pk_add_f32 v[4:5], v[4:5], v[12:13]
	v_pk_add_f32 v[8:9], v[2:3], v[10:11]
	v_pk_add_f32 v[2:3], v[0:1], v[14:15]
	v_cvt_pk_bf16_f32 v0, v4, v5
	v_cvt_pk_bf16_f32 v1, v6, v7
	v_cvt_pk_bf16_f32 v2, v2, v3
	v_cvt_pk_bf16_f32 v3, v8, v9
	global_store_dwordx4 v[16:17], v[0:3], off offset:256
	s_cbranch_vccz .LBB1_1232
	s_waitcnt vmcnt(0)
	s_cmpk_gt_u32 s17, 0xff
	s_cbranch_scc1 .LBB1_1243
	s_barrier

; #define PG8_STAGE(bufoff, gbase, voff) do { _Pragma("unroll") for (int _i = 0; _i < 2; ++_i) \
;         __builtin_amdgcn_global_load_lds((const unsigned*)((const char*)(gbase) + (voff)[_i]), (LAS unsigned*)(lds + (bufoff) + ldsw + _i * 8192), 16, 0, 0); } while (0)
; #define PG8_LDA(dst, b, h) do { _Pragma("unroll") for (int m = 0; m < 4; ++m) _Pragma("unroll") for (int k = 0; k < 2; ++k) dst[m][k] = *(const LAS bf16x8*)(lds + PG8_SA(b, h) + aoff + m * 2048 + k * 1024); } while (0)
; #define PG8_LDB(dst, b, h) do { _Pragma("unroll") for (int n = 0; n < 2; ++n) _Pragma("unroll") for (int k = 0; k < 2; ++k) dst[n][k] = *(const LAS bf16x8*)(lds + PG8_SB(b, h) + boff + n * 2048 + k * 1024); } while (0)
; #define PG8_MMA(ai, bj, At, Bt) do { __builtin_amdgcn_s_setprio(1); _Pragma("unroll") for (int m = 0; m < 4; ++m) _Pragma("unroll") for (int n = 0; n < 2; ++n) _Pragma("unroll") for (int k = 0; k < 2; ++k) \
;         acc[ai][bj][m][n] = __builtin_amdgcn_mfma_f32_16x16x32_bf16(Bt[n][k], At[m][k], acc[ai][bj][m][n], 0, 0, 0); __builtin_amdgcn_s_setprio(0); } while (0)
; #define PG8_WAIT_V(n) asm volatile("s_waitcnt vmcnt(" #n ")" ::: "memory")
; #define PG8_WAIT_L(n) asm volatile("s_waitcnt lgkmcnt(" #n ")" ::: "memory")
; template <class Map, class Epi>
; DI void gemm_phase(LAS unsigned char* lds, const Map& MP, const Epi& E, const int nM, const int nN, const int K, const int lda, const int ldb) {
;     ...
;         for (int t = 0; t < nt; t += 2) {
;             const bool last = (t == nt - 2);
;             const char* a1 = cA + (size_t)(t + 1) * kstep;
;             const char* a2 = last ? nA : cA + (size_t)(t + 2) * kstep; const char* b2 = last ? nB : cB + (size_t)(t + 2) * kstep;
;             const char* a3 = a2 + kstep; const char* b3 = b2 + kstep;
;             PG8_LDB(B0, 0, 0); PG8_SCHED; PG8_LDA(At, 0, 0); PG8_STAGE(PG8_SA(1, 1), a1 + hstepA, voffA);
;             PG8_WAIT_L(8); PG8_BAR; PG8_WAIT_L(0); PG8_MMA(0, 0, At, B0); PG8_BAR; PG8_SCHED;
;             PG8_LDB(B1, 0, 1); PG8_STAGE(PG8_SB(0, 0), b2, voffB);
;             PG8_BAR; PG8_WAIT_L(0); PG8_MMA(0, 1, At, B1); PG8_BAR;
;             PG8_LDA(At, 0, 1); PG8_STAGE(PG8_SA(0, 0), a2, voffA);
;             PG8_BAR; PG8_WAIT_L(0); PG8_MMA(1, 0, At, B0); PG8_BAR; PG8_SCHED;
;             PG8_STAGE(PG8_SB(0, 1), b2 + hstepB, voffB);
;             PG8_WAIT_V(6); PG8_BAR; PG8_MMA(1, 1, At, B1); PG8_BAR;
.LBB1_1382:
	s_add_u32 s22, s20, 0xfff80080
	s_addc_u32 s23, s21, -1
	s_cmp_eq_u32 s3, 28
	s_cselect_b32 s25, s15, s23
	s_cselect_b32 s24, s48, s22
	s_cselect_b32 s23, s13, s53
	s_cselect_b32 s22, s49, s52
	s_add_i32 m0, s31, 0xc000
	ds_read_b128 v[166:169], v148
	ds_read_b128 v[170:173], v148 offset:1024
	ds_read_b128 v[174:177], v148 offset:2048
	ds_read_b128 v[178:181], v148 offset:3072
	ds_read_b128 v[182:185], v148 offset:4096
	ds_read_b128 v[186:189], v148 offset:5120
	ds_read_b128 v[190:193], v148 offset:6144
	ds_read_b128 v[198:201], v148 offset:7168
	global_load_lds_dwordx4 v138, s[20:21]
	s_add_i32 m0, s31, 0xe000
	s_nop 0
	global_load_lds_dwordx4 v136, s[20:21]
	s_waitcnt lgkmcnt(8)
	s_setprio 1
	s_barrier
	s_waitcnt lgkmcnt(7)
	v_mfma_f32_16x16x32_bf16 v[124:127], v[150:153], v[166:169], v[124:127]
	v_mfma_f32_16x16x32_bf16 v[120:123], v[158:161], v[166:169], v[120:123]
	s_waitcnt lgkmcnt(5)
	v_mfma_f32_16x16x32_bf16 v[116:119], v[150:153], v[174:177], v[116:119]
	v_mfma_f32_16x16x32_bf16 v[112:115], v[158:161], v[174:177], v[112:115]
	s_waitcnt lgkmcnt(3)
	v_mfma_f32_16x16x32_bf16 v[100:103], v[150:153], v[182:185], v[100:103]
	v_mfma_f32_16x16x32_bf16 v[96:99], v[158:161], v[182:185], v[96:99]
	s_waitcnt lgkmcnt(1)
	v_mfma_f32_16x16x32_bf16 v[84:87], v[150:153], v[190:193], v[84:87]
	v_mfma_f32_16x16x32_bf16 v[80:83], v[158:161], v[190:193], v[80:83]
	v_mfma_f32_16x16x32_bf16 v[124:127], v[154:157], v[170:173], v[124:127]
	s_add_i32 s54, s44, s29
	v_mfma_f32_16x16x32_bf16 v[120:123], v[162:165], v[170:173], v[120:123]
	v_lshl_add_u64 v[194:195], s[22:23], 0, v[132:133]
	v_mfma_f32_16x16x32_bf16 v[116:119], v[154:157], v[178:181], v[116:119]
	v_lshl_add_u64 v[218:219], s[22:23], 0, v[128:129]
	v_mfma_f32_16x16x32_bf16 v[112:115], v[162:165], v[178:181], v[112:115]
	v_mfma_f32_16x16x32_bf16 v[100:103], v[154:157], v[186:189], v[100:103]
	v_mfma_f32_16x16x32_bf16 v[96:99], v[162:165], v[186:189], v[96:99]
	s_waitcnt lgkmcnt(0)
	v_mfma_f32_16x16x32_bf16 v[84:87], v[154:157], v[198:201], v[84:87]
	s_setprio 0
	v_mfma_f32_16x16x32_bf16 v[80:83], v[162:165], v[198:201], v[80:83]
	s_barrier
	s_mov_b32 m0, s54
	ds_read_b128 v[202:205], v149
	ds_read_b128 v[206:209], v149 offset:1024
	ds_read_b128 v[210:213], v149 offset:2048
	ds_read_b128 v[214:217], v149 offset:3072
	global_load_lds_dwordx4 v[194:195], off
	s_add_i32 m0, s54, 0x2000
	s_nop 0
	global_load_lds_dwordx4 v[218:219], off
	s_setprio 1
	s_barrier
	s_waitcnt lgkmcnt(3)
	v_mfma_f32_16x16x32_bf16 v[108:111], v[202:205], v[166:169], v[108:111]
	s_waitcnt lgkmcnt(1)
	v_mfma_f32_16x16x32_bf16 v[104:107], v[210:213], v[166:169], v[104:107]
	v_mfma_f32_16x16x32_bf16 v[92:95], v[202:205], v[174:177], v[92:95]
	v_mfma_f32_16x16x32_bf16 v[88:91], v[210:213], v[174:177], v[88:91]
	v_mfma_f32_16x16x32_bf16 v[76:79], v[202:205], v[182:185], v[76:79]
	v_mfma_f32_16x16x32_bf16 v[72:75], v[210:213], v[182:185], v[72:75]
	v_mfma_f32_16x16x32_bf16 v[68:71], v[202:205], v[190:193], v[68:71]
	v_mfma_f32_16x16x32_bf16 v[64:67], v[210:213], v[190:193], v[64:67]
	v_mfma_f32_16x16x32_bf16 v[108:111], v[206:209], v[170:173], v[108:111]
	v_lshl_add_u64 v[222:223], s[24:25], 0, v[130:131]
	s_mov_b32 m0, s31
	s_waitcnt lgkmcnt(0)
	v_mfma_f32_16x16x32_bf16 v[104:107], v[214:217], v[170:173], v[104:107]
	v_lshl_add_u64 v[220:221], s[24:25], 0, v[134:135]
	v_mfma_f32_16x16x32_bf16 v[92:95], v[206:209], v[178:181], v[92:95]
	v_mfma_f32_16x16x32_bf16 v[88:91], v[214:217], v[178:181], v[88:91]
	v_mfma_f32_16x16x32_bf16 v[76:79], v[206:209], v[186:189], v[76:79]
	v_mfma_f32_16x16x32_bf16 v[72:75], v[214:217], v[186:189], v[72:75]
	v_mfma_f32_16x16x32_bf16 v[68:71], v[206:209], v[198:201], v[68:71]
	s_setprio 0
	v_mfma_f32_16x16x32_bf16 v[64:67], v[214:217], v[198:201], v[64:67]
	s_barrier
	ds_read_b128 v[166:169], v148 offset:16384
	ds_read_b128 v[170:173], v148 offset:17408
	ds_read_b128 v[174:177], v148 offset:18432
	ds_read_b128 v[178:181], v148 offset:19456
	ds_read_b128 v[182:185], v148 offset:20480
	ds_read_b128 v[186:189], v148 offset:21504
	ds_read_b128 v[190:193], v148 offset:22528
	ds_read_b128 v[198:201], v148 offset:23552
	global_load_lds_dwordx4 v[220:221], off
	s_mov_b32 m0, s11
	s_nop 0
	global_load_lds_dwordx4 v[222:223], off
	s_waitcnt vmcnt(10)
	s_setprio 1
	s_barrier
	s_waitcnt lgkmcnt(7)
	v_mfma_f32_16x16x32_bf16 v[60:63], v[150:153], v[166:169], v[60:63]
	v_mfma_f32_16x16x32_bf16 v[56:59], v[158:161], v[166:169], v[56:59]
	s_waitcnt lgkmcnt(5)
	v_mfma_f32_16x16x32_bf16 v[52:55], v[150:153], v[174:177], v[52:55]
	v_mfma_f32_16x16x32_bf16 v[48:51], v[158:161], v[174:177], v[48:51]
	s_waitcnt lgkmcnt(3)
	v_mfma_f32_16x16x32_bf16 v[36:39], v[150:153], v[182:185], v[36:39]
	v_mfma_f32_16x16x32_bf16 v[32:35], v[158:161], v[182:185], v[32:35]
	s_waitcnt lgkmcnt(1)
	v_mfma_f32_16x16x32_bf16 v[20:23], v[150:153], v[190:193], v[20:23]
	v_mfma_f32_16x16x32_bf16 v[16:19], v[158:161], v[190:193], v[16:19]
	v_mfma_f32_16x16x32_bf16 v[60:63], v[154:157], v[170:173], v[60:63]
	s_add_u32 s54, s22, 0x80000
	s_addc_u32 s55, s23, 0
	v_mfma_f32_16x16x32_bf16 v[56:59], v[162:165], v[170:173], v[56:59]
	s_add_i32 s56, s45, s29
	v_mfma_f32_16x16x32_bf16 v[52:55], v[154:157], v[178:181], v[52:55]
	v_mfma_f32_16x16x32_bf16 v[48:51], v[162:165], v[178:181], v[48:51]
	v_mfma_f32_16x16x32_bf16 v[36:39], v[154:157], v[186:189], v[36:39]
	v_mfma_f32_16x16x32_bf16 v[32:35], v[162:165], v[186:189], v[32:35]
	s_waitcnt lgkmcnt(0)
	v_mfma_f32_16x16x32_bf16 v[20:23], v[154:157], v[198:201], v[20:23]
	s_setprio 0
	v_mfma_f32_16x16x32_bf16 v[16:19], v[162:165], v[198:201], v[16:19]
	s_barrier
; #define PG8_STAGE(bufoff, gbase, voff) do { _Pragma("unroll") for (int _i = 0; _i < 2; ++_i) \
;         __builtin_amdgcn_global_load_lds((const unsigned*)((const char*)(gbase) + (voff)[_i]), (LAS unsigned*)(lds + (bufoff) + ldsw + _i * 8192), 16, 0, 0); } while (0)
; #define PG8_LDA(dst, b, h) do { _Pragma("unroll") for (int m = 0; m < 4; ++m) _Pragma("unroll") for (int k = 0; k < 2; ++k) dst[m][k] = *(const LAS bf16x8*)(lds + PG8_SA(b, h) + aoff + m * 2048 + k * 1024); } while (0)
; #define PG8_LDB(dst, b, h) do { _Pragma("unroll") for (int n = 0; n < 2; ++n) _Pragma("unroll") for (int k = 0; k < 2; ++k) dst[n][k] = *(const LAS bf16x8*)(lds + PG8_SB(b, h) + boff + n * 2048 + k * 1024); } while (0)
; #define PG8_MMA(ai, bj, At, Bt) do { __builtin_amdgcn_s_setprio(1); _Pragma("unroll") for (int m = 0; m < 4; ++m) _Pragma("unroll") for (int n = 0; n < 2; ++n) _Pragma("unroll") for (int k = 0; k < 2; ++k) \
;         acc[ai][bj][m][n] = __builtin_amdgcn_mfma_f32_16x16x32_bf16(Bt[n][k], At[m][k], acc[ai][bj][m][n], 0, 0, 0); __builtin_amdgcn_s_setprio(0); } while (0)
; #define PG8_WAIT_V(n) asm volatile("s_waitcnt vmcnt(" #n ")" ::: "memory")
; #define PG8_WAIT_L(n) asm volatile("s_waitcnt lgkmcnt(" #n ")" ::: "memory")
; #define PG8_BAR __builtin_amdgcn_s_barrier()
; #define PG8_SCHED __builtin_amdgcn_sched_barrier(0)
; template <class Map, class Epi>
; DI void gemm_phase(LAS unsigned char* lds, const Map& MP, const Epi& E, const int nM, const int nN, const int K, const int lda, const int ldb) {
;     ...
;             PG8_LDA(At, 0, 1); PG8_STAGE(PG8_SA(0, 0), a2, voffA);
;             PG8_BAR; PG8_WAIT_L(0); PG8_MMA(1, 0, At, B0); PG8_BAR; PG8_SCHED;
;             PG8_STAGE(PG8_SB(0, 1), b2 + hstepB, voffB);
;             PG8_WAIT_V(6); PG8_BAR; PG8_MMA(1, 1, At, B1); PG8_BAR;
;             PG8_LDB(B0, 1, 0); PG8_SCHED; PG8_LDA(At, 1, 0); PG8_STAGE(PG8_SA(0, 1), a2 + hstepA, voffA);
;             PG8_WAIT_L(8); PG8_BAR; PG8_WAIT_L(0); PG8_MMA(0, 0, At, B0); PG8_BAR; PG8_SCHED;
;             PG8_LDB(B1, 1, 1); PG8_STAGE(PG8_SB(1, 0), b3, voffB);
;             PG8_BAR; PG8_WAIT_L(0); PG8_MMA(0, 1, At, B1); PG8_BAR;
;             PG8_LDA(At, 1, 1); PG8_STAGE(PG8_SA(1, 0), a3, voffA);
	s_mov_b32 m0, s56
	s_nop 0
	global_load_lds_dwordx4 v132, s[54:55]
	s_add_i32 m0, s56, 0x2000
	s_nop 0
	global_load_lds_dwordx4 v128, s[54:55]
	s_waitcnt vmcnt(6)
	s_setprio 1
	s_barrier
	v_mfma_f32_16x16x32_bf16 v[44:47], v[202:205], v[166:169], v[44:47]
	v_mfma_f32_16x16x32_bf16 v[40:43], v[210:213], v[166:169], v[40:43]
	s_add_i32 s54, 0, 0x18000
	v_add_u32_e32 v162, s54, v146
	ds_read_b128 v[150:153], v162
	v_mfma_f32_16x16x32_bf16 v[28:31], v[202:205], v[174:177], v[28:31]
	v_mfma_f32_16x16x32_bf16 v[24:27], v[210:213], v[174:177], v[24:27]
	ds_read_b128 v[154:157], v162 offset:1024
	v_mfma_f32_16x16x32_bf16 v[12:15], v[202:205], v[182:185], v[12:15]
	v_mfma_f32_16x16x32_bf16 v[8:11], v[210:213], v[182:185], v[8:11]
	ds_read_b128 v[158:161], v162 offset:2048
	v_mfma_f32_16x16x32_bf16 v[4:7], v[202:205], v[190:193], v[4:7]
	v_mfma_f32_16x16x32_bf16 v[0:3], v[210:213], v[190:193], v[0:3]
	ds_read_b128 v[162:165], v162 offset:3072
	v_mfma_f32_16x16x32_bf16 v[44:47], v[206:209], v[170:173], v[44:47]
	s_add_u32 s24, s24, 0x80000
	s_addc_u32 s25, s25, 0
	v_mfma_f32_16x16x32_bf16 v[40:43], v[214:217], v[170:173], v[40:43]
	v_mfma_f32_16x16x32_bf16 v[28:31], v[206:209], v[178:181], v[28:31]
	v_mfma_f32_16x16x32_bf16 v[24:27], v[214:217], v[178:181], v[24:27]
	v_mfma_f32_16x16x32_bf16 v[12:15], v[206:209], v[186:189], v[12:15]
	v_mfma_f32_16x16x32_bf16 v[8:11], v[214:217], v[186:189], v[8:11]
	v_mfma_f32_16x16x32_bf16 v[4:7], v[206:209], v[198:201], v[4:7]
	s_setprio 0
	v_mfma_f32_16x16x32_bf16 v[0:3], v[214:217], v[198:201], v[0:3]
	s_barrier
	s_mov_b32 m0, s34
	ds_read_b128 v[166:169], v148 offset:32768
	ds_read_b128 v[170:173], v148 offset:33792
	ds_read_b128 v[174:177], v148 offset:34816
	ds_read_b128 v[178:181], v148 offset:35840
	ds_read_b128 v[182:185], v148 offset:36864
	ds_read_b128 v[186:189], v148 offset:37888
	ds_read_b128 v[190:193], v148 offset:38912
	ds_read_b128 v[198:201], v148 offset:39936
	global_load_lds_dwordx4 v134, s[24:25]
	s_mov_b32 m0, s35
	s_nop 0
	global_load_lds_dwordx4 v130, s[24:25]
	s_waitcnt lgkmcnt(8)
	s_setprio 1
	s_barrier
	s_waitcnt lgkmcnt(7)
	v_mfma_f32_16x16x32_bf16 v[124:127], v[150:153], v[166:169], v[124:127]
	v_mfma_f32_16x16x32_bf16 v[120:123], v[158:161], v[166:169], v[120:123]
	s_waitcnt lgkmcnt(5)
	v_mfma_f32_16x16x32_bf16 v[116:119], v[150:153], v[174:177], v[116:119]
	v_mfma_f32_16x16x32_bf16 v[112:115], v[158:161], v[174:177], v[112:115]
	s_waitcnt lgkmcnt(3)
	v_mfma_f32_16x16x32_bf16 v[100:103], v[150:153], v[182:185], v[100:103]
	v_mfma_f32_16x16x32_bf16 v[96:99], v[158:161], v[182:185], v[96:99]
	s_waitcnt lgkmcnt(1)
	v_mfma_f32_16x16x32_bf16 v[84:87], v[150:153], v[190:193], v[84:87]
	v_mfma_f32_16x16x32_bf16 v[80:83], v[158:161], v[190:193], v[80:83]
	v_mfma_f32_16x16x32_bf16 v[124:127], v[154:157], v[170:173], v[124:127]
	s_add_i32 s24, 0, 0x1c000
	v_mfma_f32_16x16x32_bf16 v[120:123], v[162:165], v[170:173], v[120:123]
	s_add_i32 s25, s54, s29
	v_mfma_f32_16x16x32_bf16 v[116:119], v[154:157], v[178:181], v[116:119]
	v_add_u32_e32 v196, s24, v146
	v_mfma_f32_16x16x32_bf16 v[112:115], v[162:165], v[178:181], v[112:115]
	v_lshl_add_u64 v[194:195], v[194:195], 0, s[8:9]
	v_mfma_f32_16x16x32_bf16 v[100:103], v[154:157], v[186:189], v[100:103]
	v_mfma_f32_16x16x32_bf16 v[96:99], v[162:165], v[186:189], v[96:99]
	s_waitcnt lgkmcnt(0)
	v_mfma_f32_16x16x32_bf16 v[84:87], v[154:157], v[198:201], v[84:87]
	s_setprio 0
	v_mfma_f32_16x16x32_bf16 v[80:83], v[162:165], v[198:201], v[80:83]
	s_barrier
	s_mov_b32 m0, s25
	ds_read_b128 v[202:205], v196
	ds_read_b128 v[206:209], v196 offset:1024
	ds_read_b128 v[210:213], v196 offset:2048
	ds_read_b128 v[214:217], v196 offset:3072
	global_load_lds_dwordx4 v[194:195], off
	v_lshl_add_u64 v[194:195], v[218:219], 0, s[8:9]
	s_add_i32 m0, s25, 0x2000
	s_nop 0
	global_load_lds_dwordx4 v[194:195], off
	s_setprio 1
	s_barrier
	s_waitcnt lgkmcnt(3)
	v_mfma_f32_16x16x32_bf16 v[108:111], v[202:205], v[166:169], v[108:111]
	s_waitcnt lgkmcnt(1)
	v_mfma_f32_16x16x32_bf16 v[104:107], v[210:213], v[166:169], v[104:107]
	v_mfma_f32_16x16x32_bf16 v[92:95], v[202:205], v[174:177], v[92:95]
	v_mfma_f32_16x16x32_bf16 v[88:91], v[210:213], v[174:177], v[88:91]
	v_mfma_f32_16x16x32_bf16 v[76:79], v[202:205], v[182:185], v[76:79]
	v_mfma_f32_16x16x32_bf16 v[72:75], v[210:213], v[182:185], v[72:75]
	v_mfma_f32_16x16x32_bf16 v[68:71], v[202:205], v[190:193], v[68:71]
	v_mfma_f32_16x16x32_bf16 v[64:67], v[210:213], v[190:193], v[64:67]
	v_mfma_f32_16x16x32_bf16 v[108:111], v[206:209], v[170:173], v[108:111]
	s_mov_b32 m0, s39
	s_waitcnt lgkmcnt(0)
	v_mfma_f32_16x16x32_bf16 v[104:107], v[214:217], v[170:173], v[104:107]
	v_lshl_add_u64 v[194:195], v[220:221], 0, s[8:9]
	v_mfma_f32_16x16x32_bf16 v[92:95], v[206:209], v[178:181], v[92:95]
	v_mfma_f32_16x16x32_bf16 v[88:91], v[214:217], v[178:181], v[88:91]
	v_mfma_f32_16x16x32_bf16 v[76:79], v[206:209], v[186:189], v[76:79]
	v_mfma_f32_16x16x32_bf16 v[72:75], v[214:217], v[186:189], v[72:75]
	v_mfma_f32_16x16x32_bf16 v[68:71], v[206:209], v[198:201], v[68:71]
	s_setprio 0
	v_mfma_f32_16x16x32_bf16 v[64:67], v[214:217], v[198:201], v[64:67]
	s_barrier
	ds_read_b128 v[166:169], v148 offset:49152
	ds_read_b128 v[170:173], v148 offset:50176
	ds_read_b128 v[174:177], v148 offset:51200
	ds_read_b128 v[178:181], v148 offset:52224
	ds_read_b128 v[182:185], v148 offset:53248
	ds_read_b128 v[186:189], v148 offset:54272
	ds_read_b128 v[190:193], v148 offset:55296
	ds_read_b128 v[198:201], v148 offset:56320
	global_load_lds_dwordx4 v[194:195], off
	v_lshl_add_u64 v[194:195], v[222:223], 0, s[8:9]
	s_mov_b32 m0, s42
	s_nop 0
	global_load_lds_dwordx4 v[194:195], off
	s_waitcnt vmcnt(10)
	s_setprio 1
	s_barrier
; #define PG8_STAGE(bufoff, gbase, voff) do { _Pragma("unroll") for (int _i = 0; _i < 2; ++_i) \
;         __builtin_amdgcn_global_load_lds((const unsigned*)((const char*)(gbase) + (voff)[_i]), (LAS unsigned*)(lds + (bufoff) + ldsw + _i * 8192), 16, 0, 0); } while (0)
; #define PG8_LDA(dst, b, h) do { _Pragma("unroll") for (int m = 0; m < 4; ++m) _Pragma("unroll") for (int k = 0; k < 2; ++k) dst[m][k] = *(const LAS bf16x8*)(lds + PG8_SA(b, h) + aoff + m * 2048 + k * 1024); } while (0)
; #define PG8_MMA(ai, bj, At, Bt) do { __builtin_amdgcn_s_setprio(1); _Pragma("unroll") for (int m = 0; m < 4; ++m) _Pragma("unroll") for (int n = 0; n < 2; ++n) _Pragma("unroll") for (int k = 0; k < 2; ++k) \
;         acc[ai][bj][m][n] = __builtin_amdgcn_mfma_f32_16x16x32_bf16(Bt[n][k], At[m][k], acc[ai][bj][m][n], 0, 0, 0); __builtin_amdgcn_s_setprio(0); } while (0)
; #define PG8_WAIT_V(n) asm volatile("s_waitcnt vmcnt(" #n ")" ::: "memory")
; #define PG8_WAIT_L(n) asm volatile("s_waitcnt lgkmcnt(" #n ")" ::: "memory")
; #define PG8_BAR __builtin_amdgcn_s_barrier()
; #define PG8_SCHED __builtin_amdgcn_sched_barrier(0)
; template <class Map, class Epi>
; DI void gemm_phase(LAS unsigned char* lds, const Map& MP, const Epi& E, const int nM, const int nN, const int K, const int lda, const int ldb) {
;     ...
;             PG8_LDA(At, 1, 1); PG8_STAGE(PG8_SA(1, 0), a3, voffA);
;             PG8_BAR; PG8_WAIT_L(0); PG8_MMA(1, 0, At, B0); PG8_BAR; PG8_SCHED;
;             PG8_STAGE(PG8_SB(1, 1), b3 + hstepB, voffB);
;             PG8_WAIT_V(6); PG8_BAR; PG8_MMA(1, 1, At, B1); PG8_BAR;
	s_waitcnt lgkmcnt(7)
	v_mfma_f32_16x16x32_bf16 v[60:63], v[150:153], v[166:169], v[60:63]
	v_mfma_f32_16x16x32_bf16 v[56:59], v[158:161], v[166:169], v[56:59]
	s_waitcnt lgkmcnt(5)
	v_mfma_f32_16x16x32_bf16 v[52:55], v[150:153], v[174:177], v[52:55]
	v_mfma_f32_16x16x32_bf16 v[48:51], v[158:161], v[174:177], v[48:51]
	s_waitcnt lgkmcnt(3)
	v_mfma_f32_16x16x32_bf16 v[36:39], v[150:153], v[182:185], v[36:39]
	v_mfma_f32_16x16x32_bf16 v[32:35], v[158:161], v[182:185], v[32:35]
	s_waitcnt lgkmcnt(1)
	v_mfma_f32_16x16x32_bf16 v[20:23], v[150:153], v[190:193], v[20:23]
	v_mfma_f32_16x16x32_bf16 v[16:19], v[158:161], v[190:193], v[16:19]
	v_mfma_f32_16x16x32_bf16 v[60:63], v[154:157], v[170:173], v[60:63]
	s_add_u32 s22, s22, 0x80080
	s_addc_u32 s23, s23, 0
	v_mfma_f32_16x16x32_bf16 v[56:59], v[162:165], v[170:173], v[56:59]
	s_add_i32 s24, s24, s29
	v_mfma_f32_16x16x32_bf16 v[52:55], v[154:157], v[178:181], v[52:55]
	v_mfma_f32_16x16x32_bf16 v[48:51], v[162:165], v[178:181], v[48:51]
	v_mfma_f32_16x16x32_bf16 v[36:39], v[154:157], v[186:189], v[36:39]
	v_mfma_f32_16x16x32_bf16 v[32:35], v[162:165], v[186:189], v[32:35]
	s_waitcnt lgkmcnt(0)
	v_mfma_f32_16x16x32_bf16 v[20:23], v[154:157], v[198:201], v[20:23]
	s_setprio 0
	v_mfma_f32_16x16x32_bf16 v[16:19], v[162:165], v[198:201], v[16:19]
	s_barrier
	s_mov_b32 m0, s24
	s_nop 0
	global_load_lds_dwordx4 v132, s[22:23]
	s_add_i32 m0, s24, 0x2000
	s_nop 0
	global_load_lds_dwordx4 v128, s[22:23]
	s_waitcnt vmcnt(6)
	s_setprio 1
	s_barrier
	v_mfma_f32_16x16x32_bf16 v[44:47], v[202:205], v[166:169], v[44:47]
	v_mfma_f32_16x16x32_bf16 v[40:43], v[210:213], v[166:169], v[40:43]
	ds_read_b128 v[150:153], v147
	v_mfma_f32_16x16x32_bf16 v[28:31], v[202:205], v[174:177], v[28:31]
	v_mfma_f32_16x16x32_bf16 v[24:27], v[210:213], v[174:177], v[24:27]
	ds_read_b128 v[154:157], v147 offset:1024
	v_mfma_f32_16x16x32_bf16 v[12:15], v[202:205], v[182:185], v[12:15]
	v_mfma_f32_16x16x32_bf16 v[8:11], v[210:213], v[182:185], v[8:11]
	ds_read_b128 v[158:161], v147 offset:2048
	v_mfma_f32_16x16x32_bf16 v[4:7], v[202:205], v[190:193], v[4:7]
	v_mfma_f32_16x16x32_bf16 v[0:3], v[210:213], v[190:193], v[0:3]
	ds_read_b128 v[162:165], v147 offset:3072
	v_mfma_f32_16x16x32_bf16 v[44:47], v[206:209], v[170:173], v[44:47]
	s_add_i32 s3, s3, 2
	v_mfma_f32_16x16x32_bf16 v[40:43], v[214:217], v[170:173], v[40:43]
	s_add_u32 s52, s52, 0x100
	s_addc_u32 s53, s53, 0
	v_mfma_f32_16x16x32_bf16 v[28:31], v[206:209], v[178:181], v[28:31]
	s_add_u32 s20, s20, 0x100
	s_addc_u32 s21, s21, 0
	v_mfma_f32_16x16x32_bf16 v[24:27], v[214:217], v[178:181], v[24:27]
	s_cmp_gt_u32 s3, 29
	v_mfma_f32_16x16x32_bf16 v[12:15], v[206:209], v[186:189], v[12:15]
	v_mfma_f32_16x16x32_bf16 v[8:11], v[214:217], v[186:189], v[8:11]
	v_mfma_f32_16x16x32_bf16 v[4:7], v[206:209], v[198:201], v[4:7]
	s_setprio 0
	v_mfma_f32_16x16x32_bf16 v[0:3], v[214:217], v[198:201], v[0:3]
	s_barrier
	s_cbranch_scc0 .LBB1_1382
; DI unsigned pack2(float a, float b) { f32x2 v = {a, b}; hwbf16x2 r = __builtin_convertvector(v, hwbf16x2); return __builtin_bit_cast(unsigned, r); }
;     DI void operator()(const f32x4 (&acc)[2][2][4][2], const Unit& u, int wr, int wc, int fr, int fq) const {
;         bf16_t* O = O1; int ldc = ldc1, pn = u.pn; if (pn >= split) { O = O2; ldc = ldc2; pn -= split; }
;         const int row0 = u.pm * BM + wr * 64 + fr, col0 = pn * BM + wc * 32 + 8 * fq;
; #pragma unroll
;         for (int ai = 0; ai < 2; ++ai)
; #pragma unroll
;             for (int m = 0; m < 4; ++m) { bf16_t* rowp = O + (size_t)(row0 + ai * HALF + m * 16) * ldc + col0;
; #pragma unroll
;                 for (int bj = 0; bj < 2; ++bj) { const f32x4 v0 = acc[ai][bj][m][0], v1 = acc[ai][bj][m][1];
;                     u32x4 o; o[0] = pack2(v0[0], v0[1]); o[1] = pack2(v0[2], v0[3]); o[2] = pack2(v1[0], v1[1]); o[3] = pack2(v1[2], v1[3]);
;                     *(u32x4*)(rowp + bj * HALF) = o; } }
;     }
	s_waitcnt lgkmcnt(0)
	s_lshl_b32 s3, s10, 8
	v_mov_b32_e32 v150, v144
	v_mov_b32_e32 v151, v145
	s_add_i32 s3, s3, s37
	v_cvt_pk_bf16_f32 v68, v68, v69
	v_add_u32_e32 v154, s3, v150
	s_lshl_b32 s3, s47, 8
	s_or_b32 s3, s3, s38
	v_lshl_add_u32 v150, v151, 3, s3
	v_ashrrev_i32_e32 v151, 31, v150
	v_lshl_add_u64 v[150:151], v[150:151], 1, s[6:7]
	v_cvt_pk_bf16_f32 v69, v70, v71
	v_cvt_pk_bf16_f32 v70, v64, v65
	v_add_u32_e32 v64, 0x80, v154
	v_mad_i64_i32 v[152:153], s[20:21], v154, s46, v[150:151]
	v_cvt_pk_bf16_f32 v108, v108, v109
	v_cvt_pk_bf16_f32 v109, v110, v111
	v_cvt_pk_bf16_f32 v110, v104, v105
	v_cvt_pk_bf16_f32 v111, v106, v107
	v_add_u32_e32 v104, 16, v154
	v_mad_i64_i32 v[64:65], s[20:21], v64, s46, v[150:151]
	v_cvt_pk_bf16_f32 v44, v44, v45
	v_cvt_pk_bf16_f32 v45, v46, v47
	v_cvt_pk_bf16_f32 v46, v40, v41
	v_cvt_pk_bf16_f32 v47, v42, v43
	v_add_u32_e32 v40, 0x90, v154
	global_store_dwordx4 v[152:153], v[108:111], off offset:256
	v_cvt_pk_bf16_f32 v92, v92, v93
	v_cvt_pk_bf16_f32 v93, v94, v95
	v_mad_i64_i32 v[108:109], s[20:21], v104, s46, v[150:151]
	v_cvt_pk_bf16_f32 v94, v88, v89
	v_cvt_pk_bf16_f32 v95, v90, v91
	v_add_u32_e32 v88, 32, v154
	global_store_dwordx4 v[64:65], v[44:47], off offset:256
	v_cvt_pk_bf16_f32 v28, v28, v29
	v_cvt_pk_bf16_f32 v29, v30, v31
	v_mad_i64_i32 v[44:45], s[20:21], v40, s46, v[150:151]
	v_cvt_pk_bf16_f32 v30, v24, v25
	v_cvt_pk_bf16_f32 v31, v26, v27
	v_add_u32_e32 v24, 0xa0, v154
	global_store_dwordx4 v[108:109], v[92:95], off offset:256
	v_cvt_pk_bf16_f32 v76, v76, v77
	v_cvt_pk_bf16_f32 v77, v78, v79
	v_mad_i64_i32 v[92:93], s[20:21], v88, s46, v[150:151]
	v_cvt_pk_bf16_f32 v78, v72, v73
	v_cvt_pk_bf16_f32 v79, v74, v75
	v_add_u32_e32 v72, 48, v154
	global_store_dwordx4 v[44:45], v[28:31], off offset:256
	v_cvt_pk_bf16_f32 v12, v12, v13
	v_cvt_pk_bf16_f32 v13, v14, v15
	v_mad_i64_i32 v[28:29], s[20:21], v24, s46, v[150:151]
	v_cvt_pk_bf16_f32 v14, v8, v9
	v_cvt_pk_bf16_f32 v15, v10, v11
	v_add_u32_e32 v8, 0xb0, v154
	global_store_dwordx4 v[92:93], v[76:79], off offset:256
	global_store_dwordx4 v[28:29], v[12:15], off offset:256
	v_cvt_pk_bf16_f32 v124, v124, v125
	v_mad_i64_i32 v[76:77], s[20:21], v72, s46, v[150:151]
	v_mad_i64_i32 v[12:13], s[20:21], v8, s46, v[150:151]
	v_cvt_pk_bf16_f32 v125, v126, v127
	v_cvt_pk_bf16_f32 v126, v120, v121
	v_cvt_pk_bf16_f32 v127, v122, v123
	v_cvt_pk_bf16_f32 v104, v116, v117
	v_cvt_pk_bf16_f32 v105, v118, v119
	v_cvt_pk_bf16_f32 v106, v112, v113
	v_cvt_pk_bf16_f32 v107, v114, v115
	v_cvt_pk_bf16_f32 v88, v100, v101
	v_cvt_pk_bf16_f32 v89, v102, v103
	v_cvt_pk_bf16_f32 v90, v96, v97
	v_cvt_pk_bf16_f32 v91, v98, v99
	v_cvt_pk_bf16_f32 v72, v84, v85
	v_cvt_pk_bf16_f32 v73, v86, v87
	v_cvt_pk_bf16_f32 v74, v80, v81
	v_cvt_pk_bf16_f32 v75, v82, v83
	v_cvt_pk_bf16_f32 v71, v66, v67
	v_cvt_pk_bf16_f32 v60, v60, v61
	v_cvt_pk_bf16_f32 v61, v62, v63
	v_cvt_pk_bf16_f32 v62, v56, v57
	v_cvt_pk_bf16_f32 v63, v58, v59
	v_cvt_pk_bf16_f32 v40, v52, v53
	v_cvt_pk_bf16_f32 v41, v54, v55
	v_cvt_pk_bf16_f32 v42, v48, v49
	v_cvt_pk_bf16_f32 v43, v50, v51
	v_cvt_pk_bf16_f32 v24, v36, v37
	v_cvt_pk_bf16_f32 v25, v38, v39
	v_cvt_pk_bf16_f32 v26, v32, v33
	v_cvt_pk_bf16_f32 v27, v34, v35
	v_cvt_pk_bf16_f32 v8, v20, v21
	v_cvt_pk_bf16_f32 v9, v22, v23
	v_cvt_pk_bf16_f32 v10, v16, v17
	v_cvt_pk_bf16_f32 v11, v18, v19
	v_cvt_pk_bf16_f32 v4, v4, v5
	v_cvt_pk_bf16_f32 v5, v6, v7
	v_cvt_pk_bf16_f32 v6, v0, v1
	v_cvt_pk_bf16_f32 v7, v2, v3
	s_and_b64 vcc, exec, s[40:41]
	s_mov_b32 s47, s12
	s_mov_b32 s10, s14
	s_mov_b64 s[20:21], s[18:19]
	s_mov_b64 s[22:23], s[16:17]
	global_store_dwordx4 v[152:153], v[124:127], off
	global_store_dwordx4 v[108:109], v[104:107], off
	global_store_dwordx4 v[92:93], v[88:91], off
	global_store_dwordx4 v[76:77], v[72:75], off
	global_store_dwordx4 v[76:77], v[68:71], off offset:256
	global_store_dwordx4 v[64:65], v[60:63], off
	global_store_dwordx4 v[44:45], v[40:43], off
	global_store_dwordx4 v[28:29], v[24:27], off
	global_store_dwordx4 v[12:13], v[8:11], off
	global_store_dwordx4 v[12:13], v[4:7], off offset:256
	s_cbranch_vccz .LBB1_1379
	s_waitcnt vmcnt(0)
	s_cmpk_gt_u32 s4, 0xff
	s_cbranch_scc1 .LBB1_1386
	s_barrier

;     DI const char* a(const Unit& u) const { return (const char*)(A + (size_t)u.pm * BM * lda); }
;     DI const char* a(const Unit& u) const { return (const char*)(A + (size_t)u.pm * BM * 2048 + (u.pn >> 1) * 512); }
;     DI const char* a(const Unit& u) const { return (const char*)((u.pn < 12 ? A1 : A2) + (size_t)u.pm * BM * 512); }
; #define PG8_STAGE(bufoff, gbase, voff) do { _Pragma("unroll") for (int _i = 0; _i < 2; ++_i) \
;         __builtin_amdgcn_global_load_lds((const unsigned*)((const char*)(gbase) + (voff)[_i]), (LAS unsigned*)(lds + (bufoff) + ldsw + _i * 8192), 16, 0, 0); } while (0)
; #define PG8_LDA(dst, b, h) do { _Pragma("unroll") for (int m = 0; m < 4; ++m) _Pragma("unroll") for (int k = 0; k < 2; ++k) dst[m][k] = *(const LAS bf16x8*)(lds + PG8_SA(b, h) + aoff + m * 2048 + k * 1024); } while (0)
; #define PG8_LDB(dst, b, h) do { _Pragma("unroll") for (int n = 0; n < 2; ++n) _Pragma("unroll") for (int k = 0; k < 2; ++k) dst[n][k] = *(const LAS bf16x8*)(lds + PG8_SB(b, h) + boff + n * 2048 + k * 1024); } while (0)
; template <class Map, class Epi>
; DI void gemm_phase(LAS unsigned char* lds, const Map& MP, const Epi& E, const int nM, const int nN, const int K, const int lda, const int ldb) {
;     ...
;         const bool has_next = sched_next(ui + 1, nM, nN, G, cblk, nxt);
;         const char* nA = has_next ? MP.a(nxt) : cA; const char* nB = has_next ? MP.b(nxt) : cB;
;         for (int t = 0; t < nt; t += 2) {
;             const bool last = (t == nt - 2);
;             const char* a1 = cA + (size_t)(t + 1) * kstep;
;             const char* a2 = last ? nA : cA + (size_t)(t + 2) * kstep; const char* b2 = last ? nB : cB + (size_t)(t + 2) * kstep;
;             const char* a3 = a2 + kstep; const char* b3 = b2 + kstep;
;             PG8_LDB(B0, 0, 0); PG8_SCHED; PG8_LDA(At, 0, 0); PG8_STAGE(PG8_SA(1, 1), a1 + hstepA, voffA);
;             PG8_WAIT_L(8); PG8_BAR; PG8_WAIT_L(0); PG8_MMA(0, 0, At, B0); PG8_BAR; PG8_SCHED;
;             PG8_LDB(B1, 0, 1); PG8_STAGE(PG8_SB(0, 0), b2, voffB);
;             PG8_BAR; PG8_WAIT_L(0); PG8_MMA(0, 1, At, B1); PG8_BAR;
;             PG8_LDA(At, 0, 1); PG8_STAGE(PG8_SA(0, 0), a2, voffA);
;             PG8_BAR; PG8_WAIT_L(0); PG8_MMA(1, 0, At, B0); PG8_BAR; PG8_SCHED;
;             PG8_STAGE(PG8_SB(0, 1), b2 + hstepB, voffB);
;             PG8_WAIT_V(6); PG8_BAR; PG8_MMA(1, 1, At, B1); PG8_BAR;
.LBB1_1529:
	s_add_u32 s20, s18, 0xfffe0080
	s_addc_u32 s21, s19, -1
	s_cmp_eq_u32 s3, 4
	s_cselect_b32 s23, s13, s21
	s_cselect_b32 s22, s52, s20
	s_cselect_b32 s21, s53, s56
	s_cselect_b32 s20, s54, s55
	s_add_i32 m0, s11, 0xc000
	ds_read_b128 v[166:169], v148
	ds_read_b128 v[170:173], v148 offset:1024
	ds_read_b128 v[174:177], v148 offset:2048
	ds_read_b128 v[178:181], v148 offset:3072
	ds_read_b128 v[182:185], v148 offset:4096
	ds_read_b128 v[186:189], v148 offset:5120
	ds_read_b128 v[190:193], v148 offset:6144
	ds_read_b128 v[198:201], v148 offset:7168
	global_load_lds_dwordx4 v138, s[18:19]
	s_add_i32 m0, s11, 0xe000
	s_nop 0
	global_load_lds_dwordx4 v136, s[18:19]
	s_waitcnt lgkmcnt(8)
	s_setprio 1
	s_barrier
	s_waitcnt lgkmcnt(7)
	v_mfma_f32_16x16x32_bf16 v[124:127], v[150:153], v[166:169], v[124:127]
	v_mfma_f32_16x16x32_bf16 v[120:123], v[158:161], v[166:169], v[120:123]
	s_waitcnt lgkmcnt(5)
	v_mfma_f32_16x16x32_bf16 v[116:119], v[150:153], v[174:177], v[116:119]
	v_mfma_f32_16x16x32_bf16 v[112:115], v[158:161], v[174:177], v[112:115]
	s_waitcnt lgkmcnt(3)
	v_mfma_f32_16x16x32_bf16 v[100:103], v[150:153], v[182:185], v[100:103]
	v_mfma_f32_16x16x32_bf16 v[96:99], v[158:161], v[182:185], v[96:99]
	s_waitcnt lgkmcnt(1)
	v_mfma_f32_16x16x32_bf16 v[84:87], v[150:153], v[190:193], v[84:87]
	v_mfma_f32_16x16x32_bf16 v[80:83], v[158:161], v[190:193], v[80:83]
	v_mfma_f32_16x16x32_bf16 v[124:127], v[154:157], v[170:173], v[124:127]
	s_add_i32 s57, s47, s31
	v_mfma_f32_16x16x32_bf16 v[120:123], v[162:165], v[170:173], v[120:123]
	v_lshl_add_u64 v[194:195], s[20:21], 0, v[132:133]
	v_mfma_f32_16x16x32_bf16 v[116:119], v[154:157], v[178:181], v[116:119]
	v_lshl_add_u64 v[218:219], s[20:21], 0, v[128:129]
	v_mfma_f32_16x16x32_bf16 v[112:115], v[162:165], v[178:181], v[112:115]
	v_mfma_f32_16x16x32_bf16 v[100:103], v[154:157], v[186:189], v[100:103]
	v_mfma_f32_16x16x32_bf16 v[96:99], v[162:165], v[186:189], v[96:99]
	s_waitcnt lgkmcnt(0)
	v_mfma_f32_16x16x32_bf16 v[84:87], v[154:157], v[198:201], v[84:87]
	s_setprio 0
	v_mfma_f32_16x16x32_bf16 v[80:83], v[162:165], v[198:201], v[80:83]
	s_barrier
	s_mov_b32 m0, s57
	ds_read_b128 v[202:205], v149
	ds_read_b128 v[206:209], v149 offset:1024
	ds_read_b128 v[210:213], v149 offset:2048
	ds_read_b128 v[214:217], v149 offset:3072
	global_load_lds_dwordx4 v[194:195], off
	s_add_i32 m0, s57, 0x2000
	s_nop 0
	global_load_lds_dwordx4 v[218:219], off
	s_setprio 1
	s_barrier
	s_waitcnt lgkmcnt(3)
	v_mfma_f32_16x16x32_bf16 v[108:111], v[202:205], v[166:169], v[108:111]
	s_waitcnt lgkmcnt(1)
	v_mfma_f32_16x16x32_bf16 v[104:107], v[210:213], v[166:169], v[104:107]
	v_mfma_f32_16x16x32_bf16 v[92:95], v[202:205], v[174:177], v[92:95]
	v_mfma_f32_16x16x32_bf16 v[88:91], v[210:213], v[174:177], v[88:91]
	v_mfma_f32_16x16x32_bf16 v[76:79], v[202:205], v[182:185], v[76:79]
	v_mfma_f32_16x16x32_bf16 v[72:75], v[210:213], v[182:185], v[72:75]
	v_mfma_f32_16x16x32_bf16 v[68:71], v[202:205], v[190:193], v[68:71]
	v_mfma_f32_16x16x32_bf16 v[64:67], v[210:213], v[190:193], v[64:67]
	v_mfma_f32_16x16x32_bf16 v[108:111], v[206:209], v[170:173], v[108:111]
	v_lshl_add_u64 v[222:223], s[22:23], 0, v[130:131]
	s_mov_b32 m0, s11
	s_waitcnt lgkmcnt(0)
	v_mfma_f32_16x16x32_bf16 v[104:107], v[214:217], v[170:173], v[104:107]
	v_lshl_add_u64 v[220:221], s[22:23], 0, v[134:135]
	v_mfma_f32_16x16x32_bf16 v[92:95], v[206:209], v[178:181], v[92:95]
	v_mfma_f32_16x16x32_bf16 v[88:91], v[214:217], v[178:181], v[88:91]
	v_mfma_f32_16x16x32_bf16 v[76:79], v[206:209], v[186:189], v[76:79]
	v_mfma_f32_16x16x32_bf16 v[72:75], v[214:217], v[186:189], v[72:75]
	v_mfma_f32_16x16x32_bf16 v[68:71], v[206:209], v[198:201], v[68:71]
	s_setprio 0
	v_mfma_f32_16x16x32_bf16 v[64:67], v[214:217], v[198:201], v[64:67]
	s_barrier
	ds_read_b128 v[166:169], v148 offset:16384
	ds_read_b128 v[170:173], v148 offset:17408
	ds_read_b128 v[174:177], v148 offset:18432
	ds_read_b128 v[178:181], v148 offset:19456
	ds_read_b128 v[182:185], v148 offset:20480
	ds_read_b128 v[186:189], v148 offset:21504
	ds_read_b128 v[190:193], v148 offset:22528
	ds_read_b128 v[198:201], v148 offset:23552
	global_load_lds_dwordx4 v[220:221], off
	s_mov_b32 m0, s35
	s_nop 0
	global_load_lds_dwordx4 v[222:223], off
	s_waitcnt vmcnt(10)
	s_setprio 1
	s_barrier
	s_waitcnt lgkmcnt(7)
	v_mfma_f32_16x16x32_bf16 v[60:63], v[150:153], v[166:169], v[60:63]
	v_mfma_f32_16x16x32_bf16 v[56:59], v[158:161], v[166:169], v[56:59]
	s_waitcnt lgkmcnt(5)
	v_mfma_f32_16x16x32_bf16 v[52:55], v[150:153], v[174:177], v[52:55]
	v_mfma_f32_16x16x32_bf16 v[48:51], v[158:161], v[174:177], v[48:51]
	s_waitcnt lgkmcnt(3)
	v_mfma_f32_16x16x32_bf16 v[36:39], v[150:153], v[182:185], v[36:39]
	v_mfma_f32_16x16x32_bf16 v[32:35], v[158:161], v[182:185], v[32:35]
	s_waitcnt lgkmcnt(1)
	v_mfma_f32_16x16x32_bf16 v[20:23], v[150:153], v[190:193], v[20:23]
	v_mfma_f32_16x16x32_bf16 v[16:19], v[158:161], v[190:193], v[16:19]
	v_mfma_f32_16x16x32_bf16 v[60:63], v[154:157], v[170:173], v[60:63]
	s_add_u32 s58, s20, 0x20000
	s_addc_u32 s59, s21, 0
	v_mfma_f32_16x16x32_bf16 v[56:59], v[162:165], v[170:173], v[56:59]
	s_add_i32 s57, s48, s31
	v_mfma_f32_16x16x32_bf16 v[52:55], v[154:157], v[178:181], v[52:55]
	v_mfma_f32_16x16x32_bf16 v[48:51], v[162:165], v[178:181], v[48:51]
	v_mfma_f32_16x16x32_bf16 v[36:39], v[154:157], v[186:189], v[36:39]
	v_mfma_f32_16x16x32_bf16 v[32:35], v[162:165], v[186:189], v[32:35]
	s_waitcnt lgkmcnt(0)
	v_mfma_f32_16x16x32_bf16 v[20:23], v[154:157], v[198:201], v[20:23]
	s_setprio 0
	v_mfma_f32_16x16x32_bf16 v[16:19], v[162:165], v[198:201], v[16:19]
	s_barrier
; #define PG8_STAGE(bufoff, gbase, voff) do { _Pragma("unroll") for (int _i = 0; _i < 2; ++_i) \
;         __builtin_amdgcn_global_load_lds((const unsigned*)((const char*)(gbase) + (voff)[_i]), (LAS unsigned*)(lds + (bufoff) + ldsw + _i * 8192), 16, 0, 0); } while (0)
; #define PG8_LDA(dst, b, h) do { _Pragma("unroll") for (int m = 0; m < 4; ++m) _Pragma("unroll") for (int k = 0; k < 2; ++k) dst[m][k] = *(const LAS bf16x8*)(lds + PG8_SA(b, h) + aoff + m * 2048 + k * 1024); } while (0)
; #define PG8_LDB(dst, b, h) do { _Pragma("unroll") for (int n = 0; n < 2; ++n) _Pragma("unroll") for (int k = 0; k < 2; ++k) dst[n][k] = *(const LAS bf16x8*)(lds + PG8_SB(b, h) + boff + n * 2048 + k * 1024); } while (0)
; #define PG8_MMA(ai, bj, At, Bt) do { __builtin_amdgcn_s_setprio(1); _Pragma("unroll") for (int m = 0; m < 4; ++m) _Pragma("unroll") for (int n = 0; n < 2; ++n) _Pragma("unroll") for (int k = 0; k < 2; ++k) \
;         acc[ai][bj][m][n] = __builtin_amdgcn_mfma_f32_16x16x32_bf16(Bt[n][k], At[m][k], acc[ai][bj][m][n], 0, 0, 0); __builtin_amdgcn_s_setprio(0); } while (0)
; #define PG8_WAIT_V(n) asm volatile("s_waitcnt vmcnt(" #n ")" ::: "memory")
; #define PG8_WAIT_L(n) asm volatile("s_waitcnt lgkmcnt(" #n ")" ::: "memory")
; #define PG8_BAR __builtin_amdgcn_s_barrier()
; #define PG8_SCHED __builtin_amdgcn_sched_barrier(0)
; template <class Map, class Epi>
; DI void gemm_phase(LAS unsigned char* lds, const Map& MP, const Epi& E, const int nM, const int nN, const int K, const int lda, const int ldb) {
;     ...
;             PG8_STAGE(PG8_SB(0, 1), b2 + hstepB, voffB);
;             PG8_WAIT_V(6); PG8_BAR; PG8_MMA(1, 1, At, B1); PG8_BAR;
;             PG8_LDB(B0, 1, 0); PG8_SCHED; PG8_LDA(At, 1, 0); PG8_STAGE(PG8_SA(0, 1), a2 + hstepA, voffA);
;             PG8_WAIT_L(8); PG8_BAR; PG8_WAIT_L(0); PG8_MMA(0, 0, At, B0); PG8_BAR; PG8_SCHED;
;             PG8_LDB(B1, 1, 1); PG8_STAGE(PG8_SB(1, 0), b3, voffB);
;             PG8_BAR; PG8_WAIT_L(0); PG8_MMA(0, 1, At, B1); PG8_BAR;
;             PG8_LDA(At, 1, 1); PG8_STAGE(PG8_SA(1, 0), a3, voffA);
	s_mov_b32 m0, s57
	s_nop 0
	global_load_lds_dwordx4 v132, s[58:59]
	s_add_i32 m0, s57, 0x2000
	s_nop 0
	global_load_lds_dwordx4 v128, s[58:59]
	s_waitcnt vmcnt(6)
	s_setprio 1
	s_barrier
	v_mfma_f32_16x16x32_bf16 v[44:47], v[202:205], v[166:169], v[44:47]
	v_mfma_f32_16x16x32_bf16 v[40:43], v[210:213], v[166:169], v[40:43]
	s_add_i32 s57, 0, 0x18000
	v_add_u32_e32 v162, s57, v146
	ds_read_b128 v[150:153], v162
	v_mfma_f32_16x16x32_bf16 v[28:31], v[202:205], v[174:177], v[28:31]
	v_mfma_f32_16x16x32_bf16 v[24:27], v[210:213], v[174:177], v[24:27]
	ds_read_b128 v[154:157], v162 offset:1024
	v_mfma_f32_16x16x32_bf16 v[12:15], v[202:205], v[182:185], v[12:15]
	v_mfma_f32_16x16x32_bf16 v[8:11], v[210:213], v[182:185], v[8:11]
	ds_read_b128 v[158:161], v162 offset:2048
	v_mfma_f32_16x16x32_bf16 v[4:7], v[202:205], v[190:193], v[4:7]
	v_mfma_f32_16x16x32_bf16 v[0:3], v[210:213], v[190:193], v[0:3]
	ds_read_b128 v[162:165], v162 offset:3072
	v_mfma_f32_16x16x32_bf16 v[44:47], v[206:209], v[170:173], v[44:47]
	s_add_u32 s22, s22, 0x20000
	s_addc_u32 s23, s23, 0
	v_mfma_f32_16x16x32_bf16 v[40:43], v[214:217], v[170:173], v[40:43]
	v_mfma_f32_16x16x32_bf16 v[28:31], v[206:209], v[178:181], v[28:31]
	v_mfma_f32_16x16x32_bf16 v[24:27], v[214:217], v[178:181], v[24:27]
	v_mfma_f32_16x16x32_bf16 v[12:15], v[206:209], v[186:189], v[12:15]
	v_mfma_f32_16x16x32_bf16 v[8:11], v[214:217], v[186:189], v[8:11]
	v_mfma_f32_16x16x32_bf16 v[4:7], v[206:209], v[198:201], v[4:7]
	s_setprio 0
	v_mfma_f32_16x16x32_bf16 v[0:3], v[214:217], v[198:201], v[0:3]
	s_barrier
	s_mov_b32 m0, s36
	ds_read_b128 v[166:169], v148 offset:32768
	ds_read_b128 v[170:173], v148 offset:33792
	ds_read_b128 v[174:177], v148 offset:34816
	ds_read_b128 v[178:181], v148 offset:35840
	ds_read_b128 v[182:185], v148 offset:36864
	ds_read_b128 v[186:189], v148 offset:37888
	ds_read_b128 v[190:193], v148 offset:38912
	ds_read_b128 v[198:201], v148 offset:39936
	global_load_lds_dwordx4 v134, s[22:23]
	s_mov_b32 m0, s37
	s_nop 0
	global_load_lds_dwordx4 v130, s[22:23]
	s_waitcnt lgkmcnt(8)
	s_setprio 1
	s_barrier
	s_waitcnt lgkmcnt(7)
	v_mfma_f32_16x16x32_bf16 v[124:127], v[150:153], v[166:169], v[124:127]
	v_mfma_f32_16x16x32_bf16 v[120:123], v[158:161], v[166:169], v[120:123]
	s_waitcnt lgkmcnt(5)
	v_mfma_f32_16x16x32_bf16 v[116:119], v[150:153], v[174:177], v[116:119]
	v_mfma_f32_16x16x32_bf16 v[112:115], v[158:161], v[174:177], v[112:115]
	s_waitcnt lgkmcnt(3)
	v_mfma_f32_16x16x32_bf16 v[100:103], v[150:153], v[182:185], v[100:103]
	v_mfma_f32_16x16x32_bf16 v[96:99], v[158:161], v[182:185], v[96:99]
	s_waitcnt lgkmcnt(1)
	v_mfma_f32_16x16x32_bf16 v[84:87], v[150:153], v[190:193], v[84:87]
	v_mfma_f32_16x16x32_bf16 v[80:83], v[158:161], v[190:193], v[80:83]
	v_mfma_f32_16x16x32_bf16 v[124:127], v[154:157], v[170:173], v[124:127]
	s_add_i32 s22, 0, 0x1c000
	v_mfma_f32_16x16x32_bf16 v[120:123], v[162:165], v[170:173], v[120:123]
	s_add_i32 s23, s57, s31
	v_mfma_f32_16x16x32_bf16 v[116:119], v[154:157], v[178:181], v[116:119]
	v_add_u32_e32 v196, s22, v146
	v_mfma_f32_16x16x32_bf16 v[112:115], v[162:165], v[178:181], v[112:115]
	v_lshl_add_u64 v[194:195], v[194:195], 0, s[8:9]
	v_mfma_f32_16x16x32_bf16 v[100:103], v[154:157], v[186:189], v[100:103]
	v_mfma_f32_16x16x32_bf16 v[96:99], v[162:165], v[186:189], v[96:99]
	s_waitcnt lgkmcnt(0)
	v_mfma_f32_16x16x32_bf16 v[84:87], v[154:157], v[198:201], v[84:87]
	s_setprio 0
	v_mfma_f32_16x16x32_bf16 v[80:83], v[162:165], v[198:201], v[80:83]
	s_barrier
	s_mov_b32 m0, s23
	ds_read_b128 v[202:205], v196
	ds_read_b128 v[206:209], v196 offset:1024
	ds_read_b128 v[210:213], v196 offset:2048
	ds_read_b128 v[214:217], v196 offset:3072
	global_load_lds_dwordx4 v[194:195], off
	v_lshl_add_u64 v[194:195], v[218:219], 0, s[8:9]
	s_add_i32 m0, s23, 0x2000
	s_nop 0
	global_load_lds_dwordx4 v[194:195], off
	s_setprio 1
	s_barrier
	s_waitcnt lgkmcnt(3)
	v_mfma_f32_16x16x32_bf16 v[108:111], v[202:205], v[166:169], v[108:111]
	s_waitcnt lgkmcnt(1)
	v_mfma_f32_16x16x32_bf16 v[104:107], v[210:213], v[166:169], v[104:107]
	v_mfma_f32_16x16x32_bf16 v[92:95], v[202:205], v[174:177], v[92:95]
	v_mfma_f32_16x16x32_bf16 v[88:91], v[210:213], v[174:177], v[88:91]
	v_mfma_f32_16x16x32_bf16 v[76:79], v[202:205], v[182:185], v[76:79]
	v_mfma_f32_16x16x32_bf16 v[72:75], v[210:213], v[182:185], v[72:75]
	v_mfma_f32_16x16x32_bf16 v[68:71], v[202:205], v[190:193], v[68:71]
	v_mfma_f32_16x16x32_bf16 v[64:67], v[210:213], v[190:193], v[64:67]
	v_mfma_f32_16x16x32_bf16 v[108:111], v[206:209], v[170:173], v[108:111]
	s_mov_b32 m0, s43
	s_waitcnt lgkmcnt(0)
	v_mfma_f32_16x16x32_bf16 v[104:107], v[214:217], v[170:173], v[104:107]
	v_lshl_add_u64 v[194:195], v[220:221], 0, s[8:9]
	v_mfma_f32_16x16x32_bf16 v[92:95], v[206:209], v[178:181], v[92:95]
	v_mfma_f32_16x16x32_bf16 v[88:91], v[214:217], v[178:181], v[88:91]
	v_mfma_f32_16x16x32_bf16 v[76:79], v[206:209], v[186:189], v[76:79]
	v_mfma_f32_16x16x32_bf16 v[72:75], v[214:217], v[186:189], v[72:75]
	v_mfma_f32_16x16x32_bf16 v[68:71], v[206:209], v[198:201], v[68:71]
	s_setprio 0
	v_mfma_f32_16x16x32_bf16 v[64:67], v[214:217], v[198:201], v[64:67]
	s_barrier
	ds_read_b128 v[166:169], v148 offset:49152
	ds_read_b128 v[170:173], v148 offset:50176
	ds_read_b128 v[174:177], v148 offset:51200
	ds_read_b128 v[178:181], v148 offset:52224
	ds_read_b128 v[182:185], v148 offset:53248
	ds_read_b128 v[186:189], v148 offset:54272
	ds_read_b128 v[190:193], v148 offset:55296
	ds_read_b128 v[198:201], v148 offset:56320
	global_load_lds_dwordx4 v[194:195], off
	v_lshl_add_u64 v[194:195], v[222:223], 0, s[8:9]
	s_mov_b32 m0, s44
	s_nop 0
	global_load_lds_dwordx4 v[194:195], off
	s_waitcnt vmcnt(10)
	s_setprio 1
	s_barrier
; #define PG8_STAGE(bufoff, gbase, voff) do { _Pragma("unroll") for (int _i = 0; _i < 2; ++_i) \
;         __builtin_amdgcn_global_load_lds((const unsigned*)((const char*)(gbase) + (voff)[_i]), (LAS unsigned*)(lds + (bufoff) + ldsw + _i * 8192), 16, 0, 0); } while (0)
; #define PG8_LDA(dst, b, h) do { _Pragma("unroll") for (int m = 0; m < 4; ++m) _Pragma("unroll") for (int k = 0; k < 2; ++k) dst[m][k] = *(const LAS bf16x8*)(lds + PG8_SA(b, h) + aoff + m * 2048 + k * 1024); } while (0)
; #define PG8_MMA(ai, bj, At, Bt) do { __builtin_amdgcn_s_setprio(1); _Pragma("unroll") for (int m = 0; m < 4; ++m) _Pragma("unroll") for (int n = 0; n < 2; ++n) _Pragma("unroll") for (int k = 0; k < 2; ++k) \
;         acc[ai][bj][m][n] = __builtin_amdgcn_mfma_f32_16x16x32_bf16(Bt[n][k], At[m][k], acc[ai][bj][m][n], 0, 0, 0); __builtin_amdgcn_s_setprio(0); } while (0)
; #define PG8_WAIT_V(n) asm volatile("s_waitcnt vmcnt(" #n ")" ::: "memory")
; #define PG8_WAIT_L(n) asm volatile("s_waitcnt lgkmcnt(" #n ")" ::: "memory")
; #define PG8_BAR __builtin_amdgcn_s_barrier()
; #define PG8_SCHED __builtin_amdgcn_sched_barrier(0)
; template <class Map, class Epi>
; DI void gemm_phase(LAS unsigned char* lds, const Map& MP, const Epi& E, const int nM, const int nN, const int K, const int lda, const int ldb) {
;     ...
;             PG8_LDA(At, 1, 1); PG8_STAGE(PG8_SA(1, 0), a3, voffA);
;             PG8_BAR; PG8_WAIT_L(0); PG8_MMA(1, 0, At, B0); PG8_BAR; PG8_SCHED;
;             PG8_STAGE(PG8_SB(1, 1), b3 + hstepB, voffB);
;             PG8_WAIT_V(6); PG8_BAR; PG8_MMA(1, 1, At, B1); PG8_BAR;
	s_waitcnt lgkmcnt(7)
	v_mfma_f32_16x16x32_bf16 v[60:63], v[150:153], v[166:169], v[60:63]
	v_mfma_f32_16x16x32_bf16 v[56:59], v[158:161], v[166:169], v[56:59]
	s_waitcnt lgkmcnt(5)
	v_mfma_f32_16x16x32_bf16 v[52:55], v[150:153], v[174:177], v[52:55]
	v_mfma_f32_16x16x32_bf16 v[48:51], v[158:161], v[174:177], v[48:51]
	s_waitcnt lgkmcnt(3)
	v_mfma_f32_16x16x32_bf16 v[36:39], v[150:153], v[182:185], v[36:39]
	v_mfma_f32_16x16x32_bf16 v[32:35], v[158:161], v[182:185], v[32:35]
	s_waitcnt lgkmcnt(1)
	v_mfma_f32_16x16x32_bf16 v[20:23], v[150:153], v[190:193], v[20:23]
	v_mfma_f32_16x16x32_bf16 v[16:19], v[158:161], v[190:193], v[16:19]
	v_mfma_f32_16x16x32_bf16 v[60:63], v[154:157], v[170:173], v[60:63]
	s_add_u32 s20, s20, 0x20080
	s_addc_u32 s21, s21, 0
	v_mfma_f32_16x16x32_bf16 v[56:59], v[162:165], v[170:173], v[56:59]
	s_add_i32 s22, s22, s31
	v_mfma_f32_16x16x32_bf16 v[52:55], v[154:157], v[178:181], v[52:55]
	v_mfma_f32_16x16x32_bf16 v[48:51], v[162:165], v[178:181], v[48:51]
	v_mfma_f32_16x16x32_bf16 v[36:39], v[154:157], v[186:189], v[36:39]
	v_mfma_f32_16x16x32_bf16 v[32:35], v[162:165], v[186:189], v[32:35]
	s_waitcnt lgkmcnt(0)
	v_mfma_f32_16x16x32_bf16 v[20:23], v[154:157], v[198:201], v[20:23]
	s_setprio 0
	v_mfma_f32_16x16x32_bf16 v[16:19], v[162:165], v[198:201], v[16:19]
	s_barrier
	s_mov_b32 m0, s22
	s_nop 0
	global_load_lds_dwordx4 v132, s[20:21]
	s_add_i32 m0, s22, 0x2000
	s_nop 0
	global_load_lds_dwordx4 v128, s[20:21]
	s_waitcnt vmcnt(6)
	s_setprio 1
	s_barrier
	v_mfma_f32_16x16x32_bf16 v[44:47], v[202:205], v[166:169], v[44:47]
	v_mfma_f32_16x16x32_bf16 v[40:43], v[210:213], v[166:169], v[40:43]
	ds_read_b128 v[150:153], v147
	v_mfma_f32_16x16x32_bf16 v[28:31], v[202:205], v[174:177], v[28:31]
	v_mfma_f32_16x16x32_bf16 v[24:27], v[210:213], v[174:177], v[24:27]
	ds_read_b128 v[154:157], v147 offset:1024
	v_mfma_f32_16x16x32_bf16 v[12:15], v[202:205], v[182:185], v[12:15]
	v_mfma_f32_16x16x32_bf16 v[8:11], v[210:213], v[182:185], v[8:11]
	ds_read_b128 v[158:161], v147 offset:2048
	v_mfma_f32_16x16x32_bf16 v[4:7], v[202:205], v[190:193], v[4:7]
	v_mfma_f32_16x16x32_bf16 v[0:3], v[210:213], v[190:193], v[0:3]
	ds_read_b128 v[162:165], v147 offset:3072
	v_mfma_f32_16x16x32_bf16 v[44:47], v[206:209], v[170:173], v[44:47]
	s_add_i32 s3, s3, 2
	v_mfma_f32_16x16x32_bf16 v[40:43], v[214:217], v[170:173], v[40:43]
	s_add_u32 s55, s55, 0x100
	s_addc_u32 s56, s56, 0
	v_mfma_f32_16x16x32_bf16 v[28:31], v[206:209], v[178:181], v[28:31]
	s_add_u32 s18, s18, 0x100
	s_addc_u32 s19, s19, 0
	v_mfma_f32_16x16x32_bf16 v[24:27], v[214:217], v[178:181], v[24:27]
	s_cmp_gt_u32 s3, 5
	v_mfma_f32_16x16x32_bf16 v[12:15], v[206:209], v[186:189], v[12:15]
	v_mfma_f32_16x16x32_bf16 v[8:11], v[214:217], v[186:189], v[8:11]
	v_mfma_f32_16x16x32_bf16 v[4:7], v[206:209], v[198:201], v[4:7]
	s_setprio 0
	v_mfma_f32_16x16x32_bf16 v[0:3], v[214:217], v[198:201], v[0:3]
	s_barrier
	s_cbranch_scc0 .LBB1_1529
; DI unsigned pack2(float a, float b) { f32x2 v = {a, b}; hwbf16x2 r = __builtin_convertvector(v, hwbf16x2); return __builtin_bit_cast(unsigned, r); }
;     DI const char* a(const Unit& u) const { return (const char*)(A + (size_t)u.pm * BM * lda); }
;     DI const char* a(const Unit& u) const { return (const char*)(A + (size_t)u.pm * BM * 2048 + (u.pn >> 1) * 512); }
;     DI void operator()(const f32x4 (&acc)[2][2][4][2], const Unit& u, int wr, int wc, int fr, int fq) const {
;         bf16_t* O = O1; int ldc = ldc1, pn = u.pn; if (pn >= split) { O = O2; ldc = ldc2; pn -= split; }
;         const int row0 = u.pm * BM + wr * 64 + fr, col0 = pn * BM + wc * 32 + 8 * fq;
; #pragma unroll
;         for (int ai = 0; ai < 2; ++ai)
; #pragma unroll
;             for (int m = 0; m < 4; ++m) { bf16_t* rowp = O + (size_t)(row0 + ai * HALF + m * 16) * ldc + col0;
; #pragma unroll
;                 for (int bj = 0; bj < 2; ++bj) { const f32x4 v0 = acc[ai][bj][m][0], v1 = acc[ai][bj][m][1];
;                     u32x4 o; o[0] = pack2(v0[0], v0[1]); o[1] = pack2(v0[2], v0[3]); o[2] = pack2(v1[0], v1[1]); o[3] = pack2(v1[2], v1[3]);
;                     *(u32x4*)(rowp + bj * HALF) = o; } }
;     }
;     DI const char* a(const Unit& u) const { return (const char*)((u.pn < 12 ? A1 : A2) + (size_t)u.pm * BM * 512); }
	s_waitcnt lgkmcnt(0)
	s_cmp_lt_i32 s45, 12
	s_cselect_b32 s3, 0, -12
	s_mov_b32 s13, 0x1e510000
	s_movk_i32 s18, 0xc00
	s_cselect_b32 s13, s13, 0x2a510000
	s_cselect_b32 s20, s18, 0x1000
	s_add_i32 s3, s3, s45
	s_add_u32 s18, s6, s13
	v_mov_b32_e32 v150, v144
	v_mov_b32_e32 v151, v145
	s_addc_u32 s19, s7, 0
	s_lshl_b32 s10, s10, 8
	s_lshl_b32 s3, s3, 8
	s_add_i32 s10, s10, s39
	s_or_b32 s3, s3, s42
	v_add_u32_e32 v154, s10, v150
	v_lshl_add_u32 v150, v151, 3, s3
	v_ashrrev_i32_e32 v151, 31, v150
	v_lshl_add_u64 v[150:151], v[150:151], 1, s[18:19]
	v_mad_i64_i32 v[152:153], s[18:19], s20, v154, 0
	v_cvt_pk_bf16_f32 v108, v108, v109
	v_cvt_pk_bf16_f32 v109, v110, v111
	v_cvt_pk_bf16_f32 v110, v104, v105
	v_add_u32_e32 v104, 16, v154
	v_lshl_add_u64 v[152:153], v[152:153], 1, v[150:151]
	v_cvt_pk_bf16_f32 v111, v106, v107
	v_mad_i64_i32 v[104:105], s[18:19], s20, v104, 0
	v_cvt_pk_bf16_f32 v92, v92, v93
	v_cvt_pk_bf16_f32 v93, v94, v95
	v_cvt_pk_bf16_f32 v94, v88, v89
	v_add_u32_e32 v88, 32, v154
	v_cvt_pk_bf16_f32 v124, v124, v125
	v_cvt_pk_bf16_f32 v125, v126, v127
	v_cvt_pk_bf16_f32 v126, v120, v121
	v_cvt_pk_bf16_f32 v127, v122, v123
	global_store_dwordx4 v[152:153], v[108:111], off offset:256
	v_cvt_pk_bf16_f32 v95, v90, v91
	v_mad_i64_i32 v[88:89], s[18:19], s20, v88, 0
	v_lshl_add_u64 v[108:109], v[104:105], 1, v[150:151]
	v_cvt_pk_bf16_f32 v76, v76, v77
	v_cvt_pk_bf16_f32 v77, v78, v79
	v_cvt_pk_bf16_f32 v78, v72, v73
	v_add_u32_e32 v72, 48, v154
	v_cvt_pk_bf16_f32 v68, v68, v69
	v_cvt_pk_bf16_f32 v69, v70, v71
	v_cvt_pk_bf16_f32 v70, v64, v65
	v_add_u32_e32 v64, 0x80, v154
	global_store_dwordx4 v[152:153], v[124:127], off
	v_cvt_pk_bf16_f32 v104, v116, v117
	v_cvt_pk_bf16_f32 v105, v118, v119
	v_cvt_pk_bf16_f32 v106, v112, v113
	v_cvt_pk_bf16_f32 v107, v114, v115
	global_store_dwordx4 v[108:109], v[92:95], off offset:256
	v_cvt_pk_bf16_f32 v79, v74, v75
	v_mad_i64_i32 v[72:73], s[18:19], s20, v72, 0
	v_lshl_add_u64 v[92:93], v[88:89], 1, v[150:151]
	v_mad_i64_i32 v[64:65], s[18:19], s20, v64, 0
	v_cvt_pk_bf16_f32 v44, v44, v45
	v_cvt_pk_bf16_f32 v45, v46, v47
	v_cvt_pk_bf16_f32 v46, v40, v41
	v_add_u32_e32 v40, 0x90, v154
	global_store_dwordx4 v[108:109], v[104:107], off
	v_cvt_pk_bf16_f32 v88, v100, v101
	v_cvt_pk_bf16_f32 v89, v102, v103
	v_cvt_pk_bf16_f32 v90, v96, v97
	v_cvt_pk_bf16_f32 v91, v98, v99
	global_store_dwordx4 v[92:93], v[76:79], off offset:256
	v_cvt_pk_bf16_f32 v74, v80, v81
	v_cvt_pk_bf16_f32 v75, v82, v83
	v_lshl_add_u64 v[76:77], v[72:73], 1, v[150:151]
	v_cvt_pk_bf16_f32 v72, v84, v85
	v_cvt_pk_bf16_f32 v73, v86, v87
	v_cvt_pk_bf16_f32 v71, v66, v67
	v_lshl_add_u64 v[64:65], v[64:65], 1, v[150:151]
	v_cvt_pk_bf16_f32 v47, v42, v43
	v_mad_i64_i32 v[40:41], s[18:19], s20, v40, 0
	v_cvt_pk_bf16_f32 v28, v28, v29
	v_cvt_pk_bf16_f32 v29, v30, v31
	v_cvt_pk_bf16_f32 v30, v24, v25
	v_add_u32_e32 v24, 0xa0, v154
	global_store_dwordx4 v[92:93], v[88:91], off
	global_store_dwordx4 v[76:77], v[72:75], off
	global_store_dwordx4 v[76:77], v[68:71], off offset:256
	v_cvt_pk_bf16_f32 v60, v60, v61
	v_cvt_pk_bf16_f32 v61, v62, v63
	v_cvt_pk_bf16_f32 v62, v56, v57
	v_cvt_pk_bf16_f32 v63, v58, v59
	global_store_dwordx4 v[64:65], v[44:47], off offset:256
	v_cvt_pk_bf16_f32 v31, v26, v27
	v_mad_i64_i32 v[24:25], s[18:19], s20, v24, 0
	v_lshl_add_u64 v[44:45], v[40:41], 1, v[150:151]
	v_cvt_pk_bf16_f32 v12, v12, v13
	v_cvt_pk_bf16_f32 v13, v14, v15
	v_cvt_pk_bf16_f32 v14, v8, v9
	v_add_u32_e32 v8, 0xb0, v154
	global_store_dwordx4 v[64:65], v[60:63], off
	v_cvt_pk_bf16_f32 v40, v52, v53
	v_cvt_pk_bf16_f32 v41, v54, v55
	v_cvt_pk_bf16_f32 v42, v48, v49
	v_cvt_pk_bf16_f32 v43, v50, v51
	global_store_dwordx4 v[44:45], v[28:31], off offset:256
	v_cvt_pk_bf16_f32 v15, v10, v11
	v_mad_i64_i32 v[8:9], s[18:19], s20, v8, 0
	v_lshl_add_u64 v[28:29], v[24:25], 1, v[150:151]
	global_store_dwordx4 v[44:45], v[40:43], off
	v_cvt_pk_bf16_f32 v24, v36, v37
	v_cvt_pk_bf16_f32 v25, v38, v39
	v_cvt_pk_bf16_f32 v26, v32, v33
	v_cvt_pk_bf16_f32 v27, v34, v35
	global_store_dwordx4 v[28:29], v[12:15], off offset:256
	v_cvt_pk_bf16_f32 v10, v16, v17
	v_cvt_pk_bf16_f32 v11, v18, v19
	v_lshl_add_u64 v[12:13], v[8:9], 1, v[150:151]
	v_cvt_pk_bf16_f32 v8, v20, v21
	v_cvt_pk_bf16_f32 v9, v22, v23
	v_cvt_pk_bf16_f32 v4, v4, v5
	v_cvt_pk_bf16_f32 v5, v6, v7
	v_cvt_pk_bf16_f32 v6, v0, v1
	v_cvt_pk_bf16_f32 v7, v2, v3
	s_and_b64 vcc, exec, s[40:41]
	s_mov_b32 s45, s49
	s_mov_b32 s10, s12
	s_mov_b64 s[18:19], s[16:17]
	s_mov_b64 s[20:21], s[14:15]
	global_store_dwordx4 v[28:29], v[24:27], off
	global_store_dwordx4 v[12:13], v[8:11], off
	global_store_dwordx4 v[12:13], v[4:7], off offset:256
	s_cbranch_vccz .LBB1_1526
	s_waitcnt vmcnt(0)
	s_cmpk_gt_u32 s4, 0xff
	s_cbranch_scc1 .LBB1_1533
	s_barrier

;     DI const char* a(const Unit& u) const { return (const char*)(A + (size_t)u.pm * BM * lda); }
;     DI const char* a(const Unit& u) const { return (const char*)(A + (size_t)u.pm * BM * 2048 + (u.pn >> 1) * 512); }
;     DI const char* a(const Unit& u) const { return (const char*)((u.pn < 12 ? A1 : A2) + (size_t)u.pm * BM * 512); }
; #define PG8_STAGE(bufoff, gbase, voff) do { _Pragma("unroll") for (int _i = 0; _i < 2; ++_i) \
;         __builtin_amdgcn_global_load_lds((const unsigned*)((const char*)(gbase) + (voff)[_i]), (LAS unsigned*)(lds + (bufoff) + ldsw + _i * 8192), 16, 0, 0); } while (0)
; #define PG8_LDA(dst, b, h) do { _Pragma("unroll") for (int m = 0; m < 4; ++m) _Pragma("unroll") for (int k = 0; k < 2; ++k) dst[m][k] = *(const LAS bf16x8*)(lds + PG8_SA(b, h) + aoff + m * 2048 + k * 1024); } while (0)
; #define PG8_LDB(dst, b, h) do { _Pragma("unroll") for (int n = 0; n < 2; ++n) _Pragma("unroll") for (int k = 0; k < 2; ++k) dst[n][k] = *(const LAS bf16x8*)(lds + PG8_SB(b, h) + boff + n * 2048 + k * 1024); } while (0)
; template <class Map, class Epi>
; DI void gemm_phase(LAS unsigned char* lds, const Map& MP, const Epi& E, const int nM, const int nN, const int K, const int lda, const int ldb) {
;     ...
;         const bool has_next = sched_next(ui + 1, nM, nN, G, cblk, nxt);
;         const char* nA = has_next ? MP.a(nxt) : cA; const char* nB = has_next ? MP.b(nxt) : cB;
;         for (int t = 0; t < nt; t += 2) {
;             const bool last = (t == nt - 2);
;             const char* a1 = cA + (size_t)(t + 1) * kstep;
;             const char* a2 = last ? nA : cA + (size_t)(t + 2) * kstep; const char* b2 = last ? nB : cB + (size_t)(t + 2) * kstep;
;             const char* a3 = a2 + kstep; const char* b3 = b2 + kstep;
;             PG8_LDB(B0, 0, 0); PG8_SCHED; PG8_LDA(At, 0, 0); PG8_STAGE(PG8_SA(1, 1), a1 + hstepA, voffA);
;             PG8_WAIT_L(8); PG8_BAR; PG8_WAIT_L(0); PG8_MMA(0, 0, At, B0); PG8_BAR; PG8_SCHED;
;             PG8_LDB(B1, 0, 1); PG8_STAGE(PG8_SB(0, 0), b2, voffB);
;             PG8_BAR; PG8_WAIT_L(0); PG8_MMA(0, 1, At, B1); PG8_BAR;
;             PG8_LDA(At, 0, 1); PG8_STAGE(PG8_SA(0, 0), a2, voffA);
;             PG8_BAR; PG8_WAIT_L(0); PG8_MMA(1, 0, At, B0); PG8_BAR; PG8_SCHED;
;             PG8_STAGE(PG8_SB(0, 1), b2 + hstepB, voffB);
;             PG8_WAIT_V(6); PG8_BAR; PG8_MMA(1, 1, At, B1); PG8_BAR;
.LBB1_1764:
	s_add_u32 s12, s10, 0xfff80080
	s_addc_u32 s13, s11, -1
	s_cmp_eq_u32 s3, 28
	s_cselect_b32 s15, s37, s13
	s_cselect_b32 s14, s38, s12
	s_cselect_b32 s13, s39, s48
	s_cselect_b32 s12, s45, s47
	s_add_i32 m0, s24, 0xc000
	ds_read_b128 v[168:171], v150
	ds_read_b128 v[172:175], v150 offset:1024
	ds_read_b128 v[176:179], v150 offset:2048
	ds_read_b128 v[180:183], v150 offset:3072
	ds_read_b128 v[184:187], v150 offset:4096
	ds_read_b128 v[188:191], v150 offset:5120
	ds_read_b128 v[192:195], v150 offset:6144
	ds_read_b128 v[198:201], v150 offset:7168
	global_load_lds_dwordx4 v138, s[10:11]
	s_add_i32 m0, s24, 0xe000
	s_nop 0
	global_load_lds_dwordx4 v136, s[10:11]
	s_waitcnt lgkmcnt(8)
	s_setprio 1
	s_barrier
	s_waitcnt lgkmcnt(7)
	v_mfma_f32_16x16x32_bf16 v[124:127], v[152:155], v[168:171], v[124:127]
	v_mfma_f32_16x16x32_bf16 v[120:123], v[160:163], v[168:171], v[120:123]
	s_waitcnt lgkmcnt(5)
	v_mfma_f32_16x16x32_bf16 v[108:111], v[152:155], v[176:179], v[108:111]
	v_mfma_f32_16x16x32_bf16 v[104:107], v[160:163], v[176:179], v[104:107]
	s_waitcnt lgkmcnt(3)
	v_mfma_f32_16x16x32_bf16 v[92:95], v[152:155], v[184:187], v[92:95]
	v_mfma_f32_16x16x32_bf16 v[88:91], v[160:163], v[184:187], v[88:91]
	s_waitcnt lgkmcnt(1)
	v_mfma_f32_16x16x32_bf16 v[76:79], v[152:155], v[192:195], v[76:79]
	v_mfma_f32_16x16x32_bf16 v[72:75], v[160:163], v[192:195], v[72:75]
	v_mfma_f32_16x16x32_bf16 v[124:127], v[156:159], v[172:175], v[124:127]
	s_add_i32 s49, s35, s22
	v_mfma_f32_16x16x32_bf16 v[120:123], v[164:167], v[172:175], v[120:123]
	v_lshl_add_u64 v[144:145], s[12:13], 0, v[132:133]
	v_mfma_f32_16x16x32_bf16 v[108:111], v[156:159], v[180:183], v[108:111]
	v_lshl_add_u64 v[218:219], s[12:13], 0, v[128:129]
	v_mfma_f32_16x16x32_bf16 v[104:107], v[164:167], v[180:183], v[104:107]
	v_mfma_f32_16x16x32_bf16 v[92:95], v[156:159], v[188:191], v[92:95]
	v_mfma_f32_16x16x32_bf16 v[88:91], v[164:167], v[188:191], v[88:91]
	s_waitcnt lgkmcnt(0)
	v_mfma_f32_16x16x32_bf16 v[76:79], v[156:159], v[198:201], v[76:79]
	s_setprio 0
	v_mfma_f32_16x16x32_bf16 v[72:75], v[164:167], v[198:201], v[72:75]
	s_barrier
	s_mov_b32 m0, s49
	ds_read_b128 v[202:205], v151
	ds_read_b128 v[206:209], v151 offset:1024
	ds_read_b128 v[210:213], v151 offset:2048
	ds_read_b128 v[214:217], v151 offset:3072
	global_load_lds_dwordx4 v[144:145], off
	s_add_i32 m0, s49, 0x2000
	s_nop 0
	global_load_lds_dwordx4 v[218:219], off
	s_setprio 1
	s_barrier
	s_waitcnt lgkmcnt(3)
	v_mfma_f32_16x16x32_bf16 v[116:119], v[202:205], v[168:171], v[116:119]
	s_waitcnt lgkmcnt(1)
	v_mfma_f32_16x16x32_bf16 v[112:115], v[210:213], v[168:171], v[112:115]
	v_mfma_f32_16x16x32_bf16 v[100:103], v[202:205], v[176:179], v[100:103]
	v_mfma_f32_16x16x32_bf16 v[96:99], v[210:213], v[176:179], v[96:99]
	v_mfma_f32_16x16x32_bf16 v[84:87], v[202:205], v[184:187], v[84:87]
	v_mfma_f32_16x16x32_bf16 v[80:83], v[210:213], v[184:187], v[80:83]
	v_mfma_f32_16x16x32_bf16 v[68:71], v[202:205], v[192:195], v[68:71]
	v_mfma_f32_16x16x32_bf16 v[64:67], v[210:213], v[192:195], v[64:67]
	v_mfma_f32_16x16x32_bf16 v[116:119], v[206:209], v[172:175], v[116:119]
	v_lshl_add_u64 v[222:223], s[14:15], 0, v[130:131]
	s_mov_b32 m0, s24
	s_waitcnt lgkmcnt(0)
	v_mfma_f32_16x16x32_bf16 v[112:115], v[214:217], v[172:175], v[112:115]
	v_lshl_add_u64 v[220:221], s[14:15], 0, v[134:135]
	v_mfma_f32_16x16x32_bf16 v[100:103], v[206:209], v[180:183], v[100:103]
	v_mfma_f32_16x16x32_bf16 v[96:99], v[214:217], v[180:183], v[96:99]
	v_mfma_f32_16x16x32_bf16 v[84:87], v[206:209], v[188:191], v[84:87]
	v_mfma_f32_16x16x32_bf16 v[80:83], v[214:217], v[188:191], v[80:83]
	v_mfma_f32_16x16x32_bf16 v[68:71], v[206:209], v[198:201], v[68:71]
	s_setprio 0
	v_mfma_f32_16x16x32_bf16 v[64:67], v[214:217], v[198:201], v[64:67]
	s_barrier
	ds_read_b128 v[168:171], v150 offset:16384
	ds_read_b128 v[172:175], v150 offset:17408
	ds_read_b128 v[176:179], v150 offset:18432
	ds_read_b128 v[180:183], v150 offset:19456
	ds_read_b128 v[184:187], v150 offset:20480
	ds_read_b128 v[188:191], v150 offset:21504
	ds_read_b128 v[192:195], v150 offset:22528
	ds_read_b128 v[198:201], v150 offset:23552
	global_load_lds_dwordx4 v[220:221], off
	s_mov_b32 m0, s9
	s_nop 0
	global_load_lds_dwordx4 v[222:223], off
	s_waitcnt vmcnt(10)
	s_setprio 1
	s_barrier
	s_waitcnt lgkmcnt(7)
	v_mfma_f32_16x16x32_bf16 v[60:63], v[152:155], v[168:171], v[60:63]
	v_mfma_f32_16x16x32_bf16 v[56:59], v[160:163], v[168:171], v[56:59]
	s_waitcnt lgkmcnt(5)
	v_mfma_f32_16x16x32_bf16 v[44:47], v[152:155], v[176:179], v[44:47]
	v_mfma_f32_16x16x32_bf16 v[40:43], v[160:163], v[176:179], v[40:43]
	s_waitcnt lgkmcnt(3)
	v_mfma_f32_16x16x32_bf16 v[28:31], v[152:155], v[184:187], v[28:31]
	v_mfma_f32_16x16x32_bf16 v[24:27], v[160:163], v[184:187], v[24:27]
	s_waitcnt lgkmcnt(1)
	v_mfma_f32_16x16x32_bf16 v[12:15], v[152:155], v[192:195], v[12:15]
	v_mfma_f32_16x16x32_bf16 v[8:11], v[160:163], v[192:195], v[8:11]
	v_mfma_f32_16x16x32_bf16 v[60:63], v[156:159], v[172:175], v[60:63]
	s_add_u32 s54, s12, 0x80000
	s_addc_u32 s55, s13, 0
	v_mfma_f32_16x16x32_bf16 v[56:59], v[164:167], v[172:175], v[56:59]
	s_add_i32 s49, s36, s22
	v_mfma_f32_16x16x32_bf16 v[44:47], v[156:159], v[180:183], v[44:47]
	v_mfma_f32_16x16x32_bf16 v[40:43], v[164:167], v[180:183], v[40:43]
	v_mfma_f32_16x16x32_bf16 v[28:31], v[156:159], v[188:191], v[28:31]
	v_mfma_f32_16x16x32_bf16 v[24:27], v[164:167], v[188:191], v[24:27]
	s_waitcnt lgkmcnt(0)
	v_mfma_f32_16x16x32_bf16 v[12:15], v[156:159], v[198:201], v[12:15]
	s_setprio 0
	v_mfma_f32_16x16x32_bf16 v[8:11], v[164:167], v[198:201], v[8:11]
	s_barrier
; #define PG8_STAGE(bufoff, gbase, voff) do { _Pragma("unroll") for (int _i = 0; _i < 2; ++_i) \
;         __builtin_amdgcn_global_load_lds((const unsigned*)((const char*)(gbase) + (voff)[_i]), (LAS unsigned*)(lds + (bufoff) + ldsw + _i * 8192), 16, 0, 0); } while (0)
; #define PG8_LDA(dst, b, h) do { _Pragma("unroll") for (int m = 0; m < 4; ++m) _Pragma("unroll") for (int k = 0; k < 2; ++k) dst[m][k] = *(const LAS bf16x8*)(lds + PG8_SA(b, h) + aoff + m * 2048 + k * 1024); } while (0)
; #define PG8_LDB(dst, b, h) do { _Pragma("unroll") for (int n = 0; n < 2; ++n) _Pragma("unroll") for (int k = 0; k < 2; ++k) dst[n][k] = *(const LAS bf16x8*)(lds + PG8_SB(b, h) + boff + n * 2048 + k * 1024); } while (0)
; #define PG8_MMA(ai, bj, At, Bt) do { __builtin_amdgcn_s_setprio(1); _Pragma("unroll") for (int m = 0; m < 4; ++m) _Pragma("unroll") for (int n = 0; n < 2; ++n) _Pragma("unroll") for (int k = 0; k < 2; ++k) \
;         acc[ai][bj][m][n] = __builtin_amdgcn_mfma_f32_16x16x32_bf16(Bt[n][k], At[m][k], acc[ai][bj][m][n], 0, 0, 0); __builtin_amdgcn_s_setprio(0); } while (0)
; #define PG8_WAIT_V(n) asm volatile("s_waitcnt vmcnt(" #n ")" ::: "memory")
; #define PG8_WAIT_L(n) asm volatile("s_waitcnt lgkmcnt(" #n ")" ::: "memory")
; #define PG8_BAR __builtin_amdgcn_s_barrier()
; #define PG8_SCHED __builtin_amdgcn_sched_barrier(0)
; template <class Map, class Epi>
; DI void gemm_phase(LAS unsigned char* lds, const Map& MP, const Epi& E, const int nM, const int nN, const int K, const int lda, const int ldb) {
;     ...
;             PG8_STAGE(PG8_SB(0, 1), b2 + hstepB, voffB);
;             PG8_WAIT_V(6); PG8_BAR; PG8_MMA(1, 1, At, B1); PG8_BAR;
;             PG8_LDB(B0, 1, 0); PG8_SCHED; PG8_LDA(At, 1, 0); PG8_STAGE(PG8_SA(0, 1), a2 + hstepA, voffA);
;             PG8_WAIT_L(8); PG8_BAR; PG8_WAIT_L(0); PG8_MMA(0, 0, At, B0); PG8_BAR; PG8_SCHED;
;             PG8_LDB(B1, 1, 1); PG8_STAGE(PG8_SB(1, 0), b3, voffB);
;             PG8_BAR; PG8_WAIT_L(0); PG8_MMA(0, 1, At, B1); PG8_BAR;
;             PG8_LDA(At, 1, 1); PG8_STAGE(PG8_SA(1, 0), a3, voffA);
	s_mov_b32 m0, s49
	s_nop 0
	global_load_lds_dwordx4 v132, s[54:55]
	s_add_i32 m0, s49, 0x2000
	s_nop 0
	global_load_lds_dwordx4 v128, s[54:55]
	s_waitcnt vmcnt(6)
	s_setprio 1
	s_barrier
	v_mfma_f32_16x16x32_bf16 v[52:55], v[202:205], v[168:171], v[52:55]
	v_mfma_f32_16x16x32_bf16 v[48:51], v[210:213], v[168:171], v[48:51]
	s_add_i32 s49, 0, 0x18000
	v_add_u32_e32 v164, s49, v148
	ds_read_b128 v[152:155], v164
	v_mfma_f32_16x16x32_bf16 v[36:39], v[202:205], v[176:179], v[36:39]
	v_mfma_f32_16x16x32_bf16 v[32:35], v[210:213], v[176:179], v[32:35]
	ds_read_b128 v[156:159], v164 offset:1024
	v_mfma_f32_16x16x32_bf16 v[20:23], v[202:205], v[184:187], v[20:23]
	v_mfma_f32_16x16x32_bf16 v[16:19], v[210:213], v[184:187], v[16:19]
	ds_read_b128 v[160:163], v164 offset:2048
	v_mfma_f32_16x16x32_bf16 v[4:7], v[202:205], v[192:195], v[4:7]
	v_mfma_f32_16x16x32_bf16 v[0:3], v[210:213], v[192:195], v[0:3]
	ds_read_b128 v[164:167], v164 offset:3072
	v_mfma_f32_16x16x32_bf16 v[52:55], v[206:209], v[172:175], v[52:55]
	s_add_u32 s14, s14, 0x80000
	s_addc_u32 s15, s15, 0
	v_mfma_f32_16x16x32_bf16 v[48:51], v[214:217], v[172:175], v[48:51]
	v_mfma_f32_16x16x32_bf16 v[36:39], v[206:209], v[180:183], v[36:39]
	v_mfma_f32_16x16x32_bf16 v[32:35], v[214:217], v[180:183], v[32:35]
	v_mfma_f32_16x16x32_bf16 v[20:23], v[206:209], v[188:191], v[20:23]
	v_mfma_f32_16x16x32_bf16 v[16:19], v[214:217], v[188:191], v[16:19]
	v_mfma_f32_16x16x32_bf16 v[4:7], v[206:209], v[198:201], v[4:7]
	s_setprio 0
	v_mfma_f32_16x16x32_bf16 v[0:3], v[214:217], v[198:201], v[0:3]
	s_barrier
	s_mov_b32 m0, s25
	ds_read_b128 v[168:171], v150 offset:32768
	ds_read_b128 v[172:175], v150 offset:33792
	ds_read_b128 v[176:179], v150 offset:34816
	ds_read_b128 v[180:183], v150 offset:35840
	ds_read_b128 v[184:187], v150 offset:36864
	ds_read_b128 v[188:191], v150 offset:37888
	ds_read_b128 v[192:195], v150 offset:38912
	ds_read_b128 v[198:201], v150 offset:39936
	global_load_lds_dwordx4 v134, s[14:15]
	s_mov_b32 m0, s26
	s_nop 0
	global_load_lds_dwordx4 v130, s[14:15]
	s_waitcnt lgkmcnt(8)
	s_setprio 1
	s_barrier
	s_waitcnt lgkmcnt(7)
	v_mfma_f32_16x16x32_bf16 v[124:127], v[152:155], v[168:171], v[124:127]
	v_mfma_f32_16x16x32_bf16 v[120:123], v[160:163], v[168:171], v[120:123]
	s_waitcnt lgkmcnt(5)
	v_mfma_f32_16x16x32_bf16 v[108:111], v[152:155], v[176:179], v[108:111]
	v_mfma_f32_16x16x32_bf16 v[104:107], v[160:163], v[176:179], v[104:107]
	s_waitcnt lgkmcnt(3)
	v_mfma_f32_16x16x32_bf16 v[92:95], v[152:155], v[184:187], v[92:95]
	v_mfma_f32_16x16x32_bf16 v[88:91], v[160:163], v[184:187], v[88:91]
	s_waitcnt lgkmcnt(1)
	v_mfma_f32_16x16x32_bf16 v[76:79], v[152:155], v[192:195], v[76:79]
	v_mfma_f32_16x16x32_bf16 v[72:75], v[160:163], v[192:195], v[72:75]
	v_mfma_f32_16x16x32_bf16 v[124:127], v[156:159], v[172:175], v[124:127]
	s_add_i32 s14, 0, 0x1c000
	v_mfma_f32_16x16x32_bf16 v[120:123], v[164:167], v[172:175], v[120:123]
	s_add_i32 s15, s49, s22
	v_mfma_f32_16x16x32_bf16 v[108:111], v[156:159], v[180:183], v[108:111]
	v_add_u32_e32 v196, s14, v148
	v_mfma_f32_16x16x32_bf16 v[104:107], v[164:167], v[180:183], v[104:107]
	v_lshl_add_u64 v[144:145], v[144:145], 0, s[42:43]
	v_mfma_f32_16x16x32_bf16 v[92:95], v[156:159], v[188:191], v[92:95]
	v_mfma_f32_16x16x32_bf16 v[88:91], v[164:167], v[188:191], v[88:91]
	s_waitcnt lgkmcnt(0)
	v_mfma_f32_16x16x32_bf16 v[76:79], v[156:159], v[198:201], v[76:79]
	s_setprio 0
	v_mfma_f32_16x16x32_bf16 v[72:75], v[164:167], v[198:201], v[72:75]
	s_barrier
	s_mov_b32 m0, s15
	ds_read_b128 v[202:205], v196
	ds_read_b128 v[206:209], v196 offset:1024
	ds_read_b128 v[210:213], v196 offset:2048
	ds_read_b128 v[214:217], v196 offset:3072
	global_load_lds_dwordx4 v[144:145], off
	v_lshl_add_u64 v[144:145], v[218:219], 0, s[42:43]
	s_add_i32 m0, s15, 0x2000
	s_nop 0
	global_load_lds_dwordx4 v[144:145], off
	s_setprio 1
	s_barrier
	s_waitcnt lgkmcnt(3)
	v_mfma_f32_16x16x32_bf16 v[116:119], v[202:205], v[168:171], v[116:119]
	s_waitcnt lgkmcnt(1)
	v_mfma_f32_16x16x32_bf16 v[112:115], v[210:213], v[168:171], v[112:115]
	v_mfma_f32_16x16x32_bf16 v[100:103], v[202:205], v[176:179], v[100:103]
	v_mfma_f32_16x16x32_bf16 v[96:99], v[210:213], v[176:179], v[96:99]
	v_mfma_f32_16x16x32_bf16 v[84:87], v[202:205], v[184:187], v[84:87]
	v_mfma_f32_16x16x32_bf16 v[80:83], v[210:213], v[184:187], v[80:83]
	v_mfma_f32_16x16x32_bf16 v[68:71], v[202:205], v[192:195], v[68:71]
	v_mfma_f32_16x16x32_bf16 v[64:67], v[210:213], v[192:195], v[64:67]
	v_mfma_f32_16x16x32_bf16 v[116:119], v[206:209], v[172:175], v[116:119]
	s_mov_b32 m0, s30
	s_waitcnt lgkmcnt(0)
	v_mfma_f32_16x16x32_bf16 v[112:115], v[214:217], v[172:175], v[112:115]
	v_lshl_add_u64 v[144:145], v[220:221], 0, s[42:43]
	v_mfma_f32_16x16x32_bf16 v[100:103], v[206:209], v[180:183], v[100:103]
	v_mfma_f32_16x16x32_bf16 v[96:99], v[214:217], v[180:183], v[96:99]
	v_mfma_f32_16x16x32_bf16 v[84:87], v[206:209], v[188:191], v[84:87]
	v_mfma_f32_16x16x32_bf16 v[80:83], v[214:217], v[188:191], v[80:83]
	v_mfma_f32_16x16x32_bf16 v[68:71], v[206:209], v[198:201], v[68:71]
	s_setprio 0
	v_mfma_f32_16x16x32_bf16 v[64:67], v[214:217], v[198:201], v[64:67]
	s_barrier
	ds_read_b128 v[168:171], v150 offset:49152
	ds_read_b128 v[172:175], v150 offset:50176
	ds_read_b128 v[176:179], v150 offset:51200
	ds_read_b128 v[180:183], v150 offset:52224
	ds_read_b128 v[184:187], v150 offset:53248
	ds_read_b128 v[188:191], v150 offset:54272
	ds_read_b128 v[192:195], v150 offset:55296
	ds_read_b128 v[198:201], v150 offset:56320
	global_load_lds_dwordx4 v[144:145], off
	v_lshl_add_u64 v[144:145], v[222:223], 0, s[42:43]
	s_mov_b32 m0, s31
	s_nop 0
	global_load_lds_dwordx4 v[144:145], off
	s_waitcnt vmcnt(10)
	s_setprio 1
	s_barrier
; DI unsigned pack2(float a, float b) { f32x2 v = {a, b}; hwbf16x2 r = __builtin_convertvector(v, hwbf16x2); return __builtin_bit_cast(unsigned, r); }
; DI float bflo(unsigned w) { return __uint_as_float(w << 16); }
; DI float bfhi(unsigned w) { return __uint_as_float(w & 0xffff0000u); }
; #define PG8_STAGE(bufoff, gbase, voff) do { _Pragma("unroll") for (int _i = 0; _i < 2; ++_i) \
;         __builtin_amdgcn_global_load_lds((const unsigned*)((const char*)(gbase) + (voff)[_i]), (LAS unsigned*)(lds + (bufoff) + ldsw + _i * 8192), 16, 0, 0); } while (0)
; #define PG8_WAIT_V(n) asm volatile("s_waitcnt vmcnt(" #n ")" ::: "memory")
; #define PG8_WAIT_L(n) asm volatile("s_waitcnt lgkmcnt(" #n ")" ::: "memory")
;     DI void operator()(const f32x4 (&acc)[2][2][4][2], const Unit& u, int wr, int wc, int fr, int fq) const {
;     ...
;             for (int m = 0; m < 4; ++m) { const size_t ro = (size_t)(row0 + ai * HALF + m * 16) * D + col0;
; #pragma unroll
;                 for (int bj = 0; bj < 2; ++bj) {
;                     f32x4 x0, x1;
;                     if constexpr (IB) { const u32x4 w = *(const u32x4*)((const bf16_t*)Xin + ro + bj * HALF);
;                         x0 = (f32x4){bflo(w[0]), bfhi(w[0]), bflo(w[1]), bfhi(w[1])}; x1 = (f32x4){bflo(w[2]), bfhi(w[2]), bflo(w[3]), bfhi(w[3])}; }
;                     else { x0 = *(const f32x4*)((const float*)Xin + ro + bj * HALF); x1 = *(const f32x4*)((const float*)Xin + ro + bj * HALF + 4); }
;                     x0 += acc[ai][bj][m][0] * sc[bj][0]; x1 += acc[ai][bj][m][1] * sc[bj][1];
;                     if constexpr (OB) { u32x4 o; o[0] = pack2(x0[0], x0[1]); o[1] = pack2(x0[2], x0[3]); o[2] = pack2(x1[0], x1[1]); o[3] = pack2(x1[2], x1[3]);
;                         *(u32x4*)((bf16_t*)Xout + ro + bj * HALF) = o; }
;                     else { *(f32x4*)((float*)Xout + ro + bj * HALF) = x0; *(f32x4*)((float*)Xout + ro + bj * HALF + 4) = x1; } } }
; template <class Map, class Epi>
; DI void gemm_phase(LAS unsigned char* lds, const Map& MP, const Epi& E, const int nM, const int nN, const int K, const int lda, const int ldb) {
;     ...
;             PG8_LDA(At, 1, 1); PG8_STAGE(PG8_SA(1, 0), a3, voffA);
;             PG8_BAR; PG8_WAIT_L(0); PG8_MMA(1, 0, At, B0); PG8_BAR; PG8_SCHED;
;             PG8_STAGE(PG8_SB(1, 1), b3 + hstepB, voffB);
;             PG8_WAIT_V(6); PG8_BAR; PG8_MMA(1, 1, At, B1); PG8_BAR;
	s_waitcnt lgkmcnt(7)
	v_mfma_f32_16x16x32_bf16 v[60:63], v[152:155], v[168:171], v[60:63]
	v_mfma_f32_16x16x32_bf16 v[56:59], v[160:163], v[168:171], v[56:59]
	s_waitcnt lgkmcnt(5)
	v_mfma_f32_16x16x32_bf16 v[44:47], v[152:155], v[176:179], v[44:47]
	v_mfma_f32_16x16x32_bf16 v[40:43], v[160:163], v[176:179], v[40:43]
	s_waitcnt lgkmcnt(3)
	v_mfma_f32_16x16x32_bf16 v[28:31], v[152:155], v[184:187], v[28:31]
	v_mfma_f32_16x16x32_bf16 v[24:27], v[160:163], v[184:187], v[24:27]
	s_waitcnt lgkmcnt(1)
	v_mfma_f32_16x16x32_bf16 v[12:15], v[152:155], v[192:195], v[12:15]
	v_mfma_f32_16x16x32_bf16 v[8:11], v[160:163], v[192:195], v[8:11]
	v_mfma_f32_16x16x32_bf16 v[60:63], v[156:159], v[172:175], v[60:63]
	s_add_u32 s12, s12, 0x80080
	s_addc_u32 s13, s13, 0
	v_mfma_f32_16x16x32_bf16 v[56:59], v[164:167], v[172:175], v[56:59]
	s_add_i32 s14, s14, s22
	v_mfma_f32_16x16x32_bf16 v[44:47], v[156:159], v[180:183], v[44:47]
	v_mfma_f32_16x16x32_bf16 v[40:43], v[164:167], v[180:183], v[40:43]
	v_mfma_f32_16x16x32_bf16 v[28:31], v[156:159], v[188:191], v[28:31]
	v_mfma_f32_16x16x32_bf16 v[24:27], v[164:167], v[188:191], v[24:27]
	s_waitcnt lgkmcnt(0)
	v_mfma_f32_16x16x32_bf16 v[12:15], v[156:159], v[198:201], v[12:15]
	s_setprio 0
	v_mfma_f32_16x16x32_bf16 v[8:11], v[164:167], v[198:201], v[8:11]
	s_barrier
	s_mov_b32 m0, s14
	s_nop 0
	global_load_lds_dwordx4 v132, s[12:13]
	s_add_i32 m0, s14, 0x2000
	s_nop 0
	global_load_lds_dwordx4 v128, s[12:13]
	s_waitcnt vmcnt(6)
	s_setprio 1
	s_barrier
	v_mfma_f32_16x16x32_bf16 v[52:55], v[202:205], v[168:171], v[52:55]
	v_mfma_f32_16x16x32_bf16 v[48:51], v[210:213], v[168:171], v[48:51]
	ds_read_b128 v[152:155], v149
	v_mfma_f32_16x16x32_bf16 v[36:39], v[202:205], v[176:179], v[36:39]
	v_mfma_f32_16x16x32_bf16 v[32:35], v[210:213], v[176:179], v[32:35]
	ds_read_b128 v[156:159], v149 offset:1024
	v_mfma_f32_16x16x32_bf16 v[20:23], v[202:205], v[184:187], v[20:23]
	v_mfma_f32_16x16x32_bf16 v[16:19], v[210:213], v[184:187], v[16:19]
	ds_read_b128 v[160:163], v149 offset:2048
	v_mfma_f32_16x16x32_bf16 v[4:7], v[202:205], v[192:195], v[4:7]
	v_mfma_f32_16x16x32_bf16 v[0:3], v[210:213], v[192:195], v[0:3]
	ds_read_b128 v[164:167], v149 offset:3072
	v_mfma_f32_16x16x32_bf16 v[52:55], v[206:209], v[172:175], v[52:55]
	s_add_i32 s3, s3, 2
	v_mfma_f32_16x16x32_bf16 v[48:51], v[214:217], v[172:175], v[48:51]
	s_add_u32 s47, s47, 0x100
	s_addc_u32 s48, s48, 0
	v_mfma_f32_16x16x32_bf16 v[36:39], v[206:209], v[180:183], v[36:39]
	s_add_u32 s10, s10, 0x100
	s_addc_u32 s11, s11, 0
	v_mfma_f32_16x16x32_bf16 v[32:35], v[214:217], v[180:183], v[32:35]
	s_cmp_gt_u32 s3, 29
	v_mfma_f32_16x16x32_bf16 v[20:23], v[206:209], v[188:191], v[20:23]
	v_mfma_f32_16x16x32_bf16 v[16:19], v[214:217], v[188:191], v[16:19]
	v_mfma_f32_16x16x32_bf16 v[4:7], v[206:209], v[198:201], v[4:7]
	s_setprio 0
	v_mfma_f32_16x16x32_bf16 v[0:3], v[214:217], v[198:201], v[0:3]
	s_barrier
	s_cbranch_scc0 .LBB1_1764
	s_waitcnt lgkmcnt(0)
	v_mov_b32_e32 v152, v147
	v_mov_b32_e32 v144, v146
	s_lshl_b32 s2, s2, 8
	s_or_b32 s2, s2, s29
	v_lshl_add_u32 v144, v144, 3, s2
	s_lshl_b32 s2, s8, 8
	s_add_i32 s2, s2, s28
	v_add_u32_e32 v152, s2, v152
	v_ashrrev_i32_e32 v153, 31, v152
	v_lshlrev_b64 v[152:153], 12, v[152:153]
	v_ashrrev_i32_e32 v145, 31, v144
	v_lshl_add_u64 v[152:153], s[4:5], 0, v[152:153]
	v_lshl_add_u64 v[144:145], v[144:145], 1, v[152:153]
	global_load_dwordx4 v[160:163], v[144:145], off
	global_load_dwordx4 v[164:167], v[144:145], off offset:256
	s_mov_b64 s[98:99], 0x10000
	v_lshl_add_u64 v[154:155], v[144:145], 0, s[98:99]
	global_load_dwordx4 v[168:171], v[154:155], off
	global_load_dwordx4 v[172:175], v[154:155], off offset:256
	s_mov_b64 s[98:99], 0x20000
	v_lshl_add_u64 v[154:155], v[144:145], 0, s[98:99]
	global_load_dwordx4 v[176:179], v[154:155], off
	global_load_dwordx4 v[180:183], v[154:155], off offset:256
	s_mov_b64 s[98:99], 0x30000
	v_lshl_add_u64 v[154:155], v[144:145], 0, s[98:99]
	global_load_dwordx4 v[184:187], v[154:155], off
	global_load_dwordx4 v[188:191], v[154:155], off offset:256
	s_mov_b64 s[98:99], 0x80000
	v_lshl_add_u64 v[154:155], v[144:145], 0, s[98:99]
	global_load_dwordx4 v[192:195], v[154:155], off
	global_load_dwordx4 v[198:201], v[154:155], off offset:256
	s_mov_b64 s[98:99], 0x90000
	v_lshl_add_u64 v[154:155], v[144:145], 0, s[98:99]
	global_load_dwordx4 v[202:205], v[154:155], off
	global_load_dwordx4 v[206:209], v[154:155], off offset:256
	s_mov_b64 s[98:99], 0xa0000
	v_lshl_add_u64 v[154:155], v[144:145], 0, s[98:99]
	global_load_dwordx4 v[210:213], v[154:155], off
	global_load_dwordx4 v[214:217], v[154:155], off offset:256
	s_mov_b64 s[98:99], 0xb0000
	v_lshl_add_u64 v[154:155], v[144:145], 0, s[98:99]
	global_load_dwordx4 v[248:251], v[154:155], off
	global_load_dwordx4 v[252:255], v[154:155], off offset:256
	s_waitcnt vmcnt(15)
	s_nop 1
	v_mov_b32_e32 v152, v160
	v_mov_b32_e32 v153, v161
	v_mov_b32_e32 v154, v162
	v_mov_b32_e32 v155, v163
	s_mov_b64 s[2:3], 0x10000
	s_mov_b32 s8, s46
	s_mov_b64 s[10:11], s[6:7]
	s_mov_b64 s[12:13], s[52:53]
	s_waitcnt lgkmcnt(0)
	v_lshlrev_b32_e32 v156, 16, v152
	v_and_b32_e32 v157, 0xffff0000, v152
	v_lshlrev_b32_e32 v152, 16, v153
	v_and_b32_e32 v153, 0xffff0000, v153
	v_lshlrev_b32_e32 v158, 16, v154
	v_and_b32_e32 v159, 0xffff0000, v154
	v_lshlrev_b32_e32 v154, 16, v155
	v_and_b32_e32 v155, 0xffff0000, v155
	v_pk_add_f32 v[126:127], v[126:127], v[152:153]
	v_pk_add_f32 v[124:125], v[124:125], v[156:157]
	v_pk_add_f32 v[152:153], v[122:123], v[154:155]
	v_pk_add_f32 v[122:123], v[120:121], v[158:159]
	v_cvt_pk_bf16_f32 v120, v124, v125
	v_cvt_pk_bf16_f32 v121, v126, v127
	v_cvt_pk_bf16_f32 v122, v122, v123
	v_cvt_pk_bf16_f32 v123, v152, v153
	global_store_dwordx4 v[144:145], v[120:123], off
	s_waitcnt vmcnt(15)
; DI unsigned pack2(float a, float b) { f32x2 v = {a, b}; hwbf16x2 r = __builtin_convertvector(v, hwbf16x2); return __builtin_bit_cast(unsigned, r); }
; DI float bflo(unsigned w) { return __uint_as_float(w << 16); }
; DI float bfhi(unsigned w) { return __uint_as_float(w & 0xffff0000u); }
;     DI void operator()(const f32x4 (&acc)[2][2][4][2], const Unit& u, int wr, int wc, int fr, int fq) const {
;     ...
;             for (int m = 0; m < 4; ++m) { const size_t ro = (size_t)(row0 + ai * HALF + m * 16) * D + col0;
; #pragma unroll
;                 for (int bj = 0; bj < 2; ++bj) {
;                     f32x4 x0, x1;
;                     if constexpr (IB) { const u32x4 w = *(const u32x4*)((const bf16_t*)Xin + ro + bj * HALF);
;                         x0 = (f32x4){bflo(w[0]), bfhi(w[0]), bflo(w[1]), bfhi(w[1])}; x1 = (f32x4){bflo(w[2]), bfhi(w[2]), bflo(w[3]), bfhi(w[3])}; }
;                     else { x0 = *(const f32x4*)((const float*)Xin + ro + bj * HALF); x1 = *(const f32x4*)((const float*)Xin + ro + bj * HALF + 4); }
;                     x0 += acc[ai][bj][m][0] * sc[bj][0]; x1 += acc[ai][bj][m][1] * sc[bj][1];
;                     if constexpr (OB) { u32x4 o; o[0] = pack2(x0[0], x0[1]); o[1] = pack2(x0[2], x0[3]); o[2] = pack2(x1[0], x1[1]); o[3] = pack2(x1[2], x1[3]);
;                         *(u32x4*)((bf16_t*)Xout + ro + bj * HALF) = o; }
;                     else { *(f32x4*)((float*)Xout + ro + bj * HALF) = x0; *(f32x4*)((float*)Xout + ro + bj * HALF + 4) = x1; } } }
	s_nop 1
	v_mov_b32_e32 v120, v164
	v_mov_b32_e32 v121, v165
	v_mov_b32_e32 v122, v166
	v_mov_b32_e32 v123, v167
	s_waitcnt lgkmcnt(0)
	v_lshlrev_b32_e32 v124, 16, v120
	v_and_b32_e32 v125, 0xffff0000, v120
	v_lshlrev_b32_e32 v120, 16, v121
	v_and_b32_e32 v121, 0xffff0000, v121
	v_lshlrev_b32_e32 v126, 16, v122
	v_and_b32_e32 v127, 0xffff0000, v122
	v_lshlrev_b32_e32 v122, 16, v123
	v_and_b32_e32 v123, 0xffff0000, v123
	v_pk_add_f32 v[116:117], v[116:117], v[124:125]
	v_pk_add_f32 v[118:119], v[118:119], v[120:121]
	v_pk_add_f32 v[120:121], v[114:115], v[122:123]
	v_pk_add_f32 v[114:115], v[112:113], v[126:127]
	v_cvt_pk_bf16_f32 v112, v116, v117
	v_lshl_add_u64 v[116:117], v[144:145], 0, s[2:3]
	s_mov_b32 s2, 0x10000
	v_cvt_pk_bf16_f32 v113, v118, v119
	v_add_co_u32_e32 v118, vcc, s2, v144
	v_cvt_pk_bf16_f32 v114, v114, v115
	v_cvt_pk_bf16_f32 v115, v120, v121
	v_addc_co_u32_e32 v119, vcc, 0, v145, vcc
	global_store_dwordx4 v[144:145], v[112:115], off offset:256
	s_waitcnt vmcnt(15)
	s_nop 1
	v_mov_b32_e32 v112, v168
	v_mov_b32_e32 v113, v169
	v_mov_b32_e32 v114, v170
	v_mov_b32_e32 v115, v171
	s_mov_b64 s[2:3], 0x20000
	s_waitcnt lgkmcnt(0)
	v_lshlrev_b32_e32 v120, 16, v112
	v_and_b32_e32 v121, 0xffff0000, v112
	v_lshlrev_b32_e32 v112, 16, v113
	v_and_b32_e32 v113, 0xffff0000, v113
	v_lshlrev_b32_e32 v122, 16, v114
	v_and_b32_e32 v123, 0xffff0000, v114
	v_lshlrev_b32_e32 v114, 16, v115
	v_and_b32_e32 v115, 0xffff0000, v115
	v_pk_add_f32 v[110:111], v[110:111], v[112:113]
	v_pk_add_f32 v[108:109], v[108:109], v[120:121]
	v_pk_add_f32 v[112:113], v[106:107], v[114:115]
	v_pk_add_f32 v[106:107], v[104:105], v[122:123]
	v_cvt_pk_bf16_f32 v104, v108, v109
	v_cvt_pk_bf16_f32 v105, v110, v111
	v_cvt_pk_bf16_f32 v106, v106, v107
	v_cvt_pk_bf16_f32 v107, v112, v113
	global_store_dwordx4 v[118:119], v[104:107], off
	s_waitcnt vmcnt(15)
	s_nop 1
	v_mov_b32_e32 v104, v172
	v_mov_b32_e32 v105, v173
	v_mov_b32_e32 v106, v174
	v_mov_b32_e32 v107, v175
	s_waitcnt lgkmcnt(0)
	v_lshlrev_b32_e32 v108, 16, v104
	v_and_b32_e32 v109, 0xffff0000, v104
	v_lshlrev_b32_e32 v104, 16, v105
	v_and_b32_e32 v105, 0xffff0000, v105
	v_lshlrev_b32_e32 v110, 16, v106
	v_and_b32_e32 v111, 0xffff0000, v106
	v_lshlrev_b32_e32 v106, 16, v107
	v_and_b32_e32 v107, 0xffff0000, v107
	v_pk_add_f32 v[100:101], v[100:101], v[108:109]
	v_pk_add_f32 v[102:103], v[102:103], v[104:105]
	v_pk_add_f32 v[104:105], v[98:99], v[106:107]
	v_pk_add_f32 v[98:99], v[96:97], v[110:111]
	v_cvt_pk_bf16_f32 v96, v100, v101
	v_lshl_add_u64 v[100:101], v[144:145], 0, s[2:3]
	s_mov_b32 s2, 0x20000
	v_cvt_pk_bf16_f32 v97, v102, v103
	v_add_co_u32_e32 v102, vcc, s2, v144
	v_cvt_pk_bf16_f32 v98, v98, v99
	v_cvt_pk_bf16_f32 v99, v104, v105
	v_addc_co_u32_e32 v103, vcc, 0, v145, vcc
	global_store_dwordx4 v[116:117], v[96:99], off offset:256
	s_waitcnt vmcnt(15)
	s_nop 1
	v_mov_b32_e32 v96, v176
	v_mov_b32_e32 v97, v177
	v_mov_b32_e32 v98, v178
	v_mov_b32_e32 v99, v179
	s_mov_b64 s[2:3], 0x30000
	s_waitcnt lgkmcnt(0)
	v_lshlrev_b32_e32 v104, 16, v96
	v_and_b32_e32 v105, 0xffff0000, v96
	v_lshlrev_b32_e32 v96, 16, v97
	v_and_b32_e32 v97, 0xffff0000, v97
	v_lshlrev_b32_e32 v106, 16, v98
	v_and_b32_e32 v107, 0xffff0000, v98
	v_lshlrev_b32_e32 v98, 16, v99
	v_and_b32_e32 v99, 0xffff0000, v99
	v_pk_add_f32 v[94:95], v[94:95], v[96:97]
	v_pk_add_f32 v[92:93], v[92:93], v[104:105]
	v_pk_add_f32 v[96:97], v[90:91], v[98:99]
	v_pk_add_f32 v[90:91], v[88:89], v[106:107]
	v_cvt_pk_bf16_f32 v88, v92, v93
	v_cvt_pk_bf16_f32 v89, v94, v95
	v_cvt_pk_bf16_f32 v90, v90, v91
	v_cvt_pk_bf16_f32 v91, v96, v97
	global_store_dwordx4 v[102:103], v[88:91], off
	s_waitcnt vmcnt(15)
	s_nop 1
	v_mov_b32_e32 v88, v180
	v_mov_b32_e32 v89, v181
	v_mov_b32_e32 v90, v182
	v_mov_b32_e32 v91, v183
	s_waitcnt lgkmcnt(0)
	v_lshlrev_b32_e32 v92, 16, v88
	v_and_b32_e32 v93, 0xffff0000, v88
	v_lshlrev_b32_e32 v88, 16, v89
	v_and_b32_e32 v89, 0xffff0000, v89
	v_lshlrev_b32_e32 v94, 16, v90
	v_and_b32_e32 v95, 0xffff0000, v90
	v_lshlrev_b32_e32 v90, 16, v91
	v_and_b32_e32 v91, 0xffff0000, v91
	v_pk_add_f32 v[86:87], v[86:87], v[88:89]
	v_pk_add_f32 v[84:85], v[84:85], v[92:93]
	v_pk_add_f32 v[88:89], v[82:83], v[90:91]
	v_pk_add_f32 v[82:83], v[80:81], v[94:95]
	v_cvt_pk_bf16_f32 v80, v84, v85
	v_cvt_pk_bf16_f32 v81, v86, v87
	v_cvt_pk_bf16_f32 v82, v82, v83
	v_cvt_pk_bf16_f32 v83, v88, v89
	global_store_dwordx4 v[100:101], v[80:83], off offset:256
	s_nop 1
	v_lshl_add_u64 v[80:81], v[144:145], 0, s[2:3]
	s_mov_b32 s2, 0x30000
	v_add_co_u32_e32 v86, vcc, s2, v144
	s_mov_b64 s[2:3], 0x80000
	s_nop 0
	v_addc_co_u32_e32 v87, vcc, 0, v145, vcc
	s_waitcnt vmcnt(15)
	s_nop 1
	v_mov_b32_e32 v82, v184
	v_mov_b32_e32 v83, v185
	v_mov_b32_e32 v84, v186
	v_mov_b32_e32 v85, v187
	s_waitcnt lgkmcnt(0)
	v_lshlrev_b32_e32 v88, 16, v82
	v_and_b32_e32 v89, 0xffff0000, v82
	v_lshlrev_b32_e32 v82, 16, v83
	v_and_b32_e32 v83, 0xffff0000, v83
	v_lshlrev_b32_e32 v90, 16, v84
	v_and_b32_e32 v91, 0xffff0000, v84
	v_lshlrev_b32_e32 v84, 16, v85
	v_and_b32_e32 v85, 0xffff0000, v85
	v_pk_add_f32 v[78:79], v[78:79], v[82:83]
	v_pk_add_f32 v[76:77], v[76:77], v[88:89]
	v_pk_add_f32 v[82:83], v[74:75], v[84:85]
	v_pk_add_f32 v[74:75], v[72:73], v[90:91]
	v_cvt_pk_bf16_f32 v72, v76, v77
	v_cvt_pk_bf16_f32 v73, v78, v79
	v_cvt_pk_bf16_f32 v74, v74, v75
	v_cvt_pk_bf16_f32 v75, v82, v83
	global_store_dwordx4 v[86:87], v[72:75], off
	s_waitcnt vmcnt(15)
	s_nop 1
	v_mov_b32_e32 v72, v188
	v_mov_b32_e32 v73, v189
	v_mov_b32_e32 v74, v190
	v_mov_b32_e32 v75, v191
	s_waitcnt lgkmcnt(0)
; DI unsigned pack2(float a, float b) { f32x2 v = {a, b}; hwbf16x2 r = __builtin_convertvector(v, hwbf16x2); return __builtin_bit_cast(unsigned, r); }
; DI float bflo(unsigned w) { return __uint_as_float(w << 16); }
; DI float bfhi(unsigned w) { return __uint_as_float(w & 0xffff0000u); }
;     DI void operator()(const f32x4 (&acc)[2][2][4][2], const Unit& u, int wr, int wc, int fr, int fq) const {
;     ...
;             for (int m = 0; m < 4; ++m) { const size_t ro = (size_t)(row0 + ai * HALF + m * 16) * D + col0;
; #pragma unroll
;                 for (int bj = 0; bj < 2; ++bj) {
;                     f32x4 x0, x1;
;                     if constexpr (IB) { const u32x4 w = *(const u32x4*)((const bf16_t*)Xin + ro + bj * HALF);
;                         x0 = (f32x4){bflo(w[0]), bfhi(w[0]), bflo(w[1]), bfhi(w[1])}; x1 = (f32x4){bflo(w[2]), bfhi(w[2]), bflo(w[3]), bfhi(w[3])}; }
;                     else { x0 = *(const f32x4*)((const float*)Xin + ro + bj * HALF); x1 = *(const f32x4*)((const float*)Xin + ro + bj * HALF + 4); }
;                     x0 += acc[ai][bj][m][0] * sc[bj][0]; x1 += acc[ai][bj][m][1] * sc[bj][1];
;                     if constexpr (OB) { u32x4 o; o[0] = pack2(x0[0], x0[1]); o[1] = pack2(x0[2], x0[3]); o[2] = pack2(x1[0], x1[1]); o[3] = pack2(x1[2], x1[3]);
;                         *(u32x4*)((bf16_t*)Xout + ro + bj * HALF) = o; }
;                     else { *(f32x4*)((float*)Xout + ro + bj * HALF) = x0; *(f32x4*)((float*)Xout + ro + bj * HALF + 4) = x1; } } }
	v_lshlrev_b32_e32 v76, 16, v72
	v_and_b32_e32 v77, 0xffff0000, v72
	v_lshlrev_b32_e32 v72, 16, v73
	v_and_b32_e32 v73, 0xffff0000, v73
	v_lshlrev_b32_e32 v78, 16, v74
	v_and_b32_e32 v79, 0xffff0000, v74
	v_lshlrev_b32_e32 v74, 16, v75
	v_and_b32_e32 v75, 0xffff0000, v75
	v_pk_add_f32 v[70:71], v[70:71], v[72:73]
	v_pk_add_f32 v[68:69], v[68:69], v[76:77]
	v_pk_add_f32 v[72:73], v[66:67], v[74:75]
	v_pk_add_f32 v[66:67], v[64:65], v[78:79]
	v_cvt_pk_bf16_f32 v64, v68, v69
	v_cvt_pk_bf16_f32 v65, v70, v71
	v_cvt_pk_bf16_f32 v66, v66, v67
	v_cvt_pk_bf16_f32 v67, v72, v73
	global_store_dwordx4 v[80:81], v[64:67], off offset:256
	s_nop 1
	v_lshl_add_u64 v[64:65], v[144:145], 0, s[2:3]
	s_mov_b32 s2, 0x80000
	v_add_co_u32_e32 v70, vcc, s2, v144
	s_mov_b64 s[2:3], 0x90000
	s_nop 0
	v_addc_co_u32_e32 v71, vcc, 0, v145, vcc
	s_waitcnt vmcnt(15)
	s_nop 1
	v_mov_b32_e32 v66, v192
	v_mov_b32_e32 v67, v193
	v_mov_b32_e32 v68, v194
	v_mov_b32_e32 v69, v195
	s_waitcnt lgkmcnt(0)
	v_lshlrev_b32_e32 v72, 16, v66
	v_and_b32_e32 v73, 0xffff0000, v66
	v_lshlrev_b32_e32 v66, 16, v67
	v_and_b32_e32 v67, 0xffff0000, v67
	v_lshlrev_b32_e32 v74, 16, v68
	v_and_b32_e32 v75, 0xffff0000, v68
	v_lshlrev_b32_e32 v68, 16, v69
	v_and_b32_e32 v69, 0xffff0000, v69
	v_pk_add_f32 v[62:63], v[62:63], v[66:67]
	v_pk_add_f32 v[60:61], v[60:61], v[72:73]
	v_pk_add_f32 v[66:67], v[58:59], v[68:69]
	v_pk_add_f32 v[58:59], v[56:57], v[74:75]
	v_cvt_pk_bf16_f32 v56, v60, v61
	v_cvt_pk_bf16_f32 v57, v62, v63
	v_cvt_pk_bf16_f32 v58, v58, v59
	v_cvt_pk_bf16_f32 v59, v66, v67
	global_store_dwordx4 v[70:71], v[56:59], off
	s_waitcnt vmcnt(15)
	s_nop 1
	v_mov_b32_e32 v56, v198
	v_mov_b32_e32 v57, v199
	v_mov_b32_e32 v58, v200
	v_mov_b32_e32 v59, v201
	s_waitcnt lgkmcnt(0)
	v_lshlrev_b32_e32 v60, 16, v56
	v_and_b32_e32 v61, 0xffff0000, v56
	v_lshlrev_b32_e32 v56, 16, v57
	v_and_b32_e32 v57, 0xffff0000, v57
	v_lshlrev_b32_e32 v62, 16, v58
	v_and_b32_e32 v63, 0xffff0000, v58
	v_lshlrev_b32_e32 v58, 16, v59
	v_and_b32_e32 v59, 0xffff0000, v59
	v_pk_add_f32 v[54:55], v[54:55], v[56:57]
	v_pk_add_f32 v[52:53], v[52:53], v[60:61]
	v_pk_add_f32 v[56:57], v[50:51], v[58:59]
	v_pk_add_f32 v[50:51], v[48:49], v[62:63]
	v_cvt_pk_bf16_f32 v48, v52, v53
	v_cvt_pk_bf16_f32 v49, v54, v55
	v_cvt_pk_bf16_f32 v50, v50, v51
	v_cvt_pk_bf16_f32 v51, v56, v57
	global_store_dwordx4 v[64:65], v[48:51], off offset:256
	s_nop 1
	v_lshl_add_u64 v[48:49], v[144:145], 0, s[2:3]
	s_mov_b32 s2, 0x90000
	v_add_co_u32_e32 v54, vcc, s2, v144
	s_mov_b64 s[2:3], 0xa0000
	s_nop 0
	v_addc_co_u32_e32 v55, vcc, 0, v145, vcc
	s_waitcnt vmcnt(15)
	s_nop 1
	v_mov_b32_e32 v50, v202
	v_mov_b32_e32 v51, v203
	v_mov_b32_e32 v52, v204
	v_mov_b32_e32 v53, v205
	s_waitcnt lgkmcnt(0)
	v_lshlrev_b32_e32 v56, 16, v50
	v_and_b32_e32 v57, 0xffff0000, v50
	v_lshlrev_b32_e32 v50, 16, v51
	v_and_b32_e32 v51, 0xffff0000, v51
	v_lshlrev_b32_e32 v58, 16, v52
	v_and_b32_e32 v59, 0xffff0000, v52
	v_lshlrev_b32_e32 v52, 16, v53
	v_and_b32_e32 v53, 0xffff0000, v53
	v_pk_add_f32 v[46:47], v[46:47], v[50:51]
	v_pk_add_f32 v[44:45], v[44:45], v[56:57]
	v_pk_add_f32 v[50:51], v[42:43], v[52:53]
	v_pk_add_f32 v[42:43], v[40:41], v[58:59]
	v_cvt_pk_bf16_f32 v40, v44, v45
	v_cvt_pk_bf16_f32 v41, v46, v47
	v_cvt_pk_bf16_f32 v42, v42, v43
	v_cvt_pk_bf16_f32 v43, v50, v51
	global_store_dwordx4 v[54:55], v[40:43], off
	s_waitcnt vmcnt(15)
	s_nop 1
	v_mov_b32_e32 v40, v206
	v_mov_b32_e32 v41, v207
	v_mov_b32_e32 v42, v208
	v_mov_b32_e32 v43, v209
	s_waitcnt lgkmcnt(0)
; DI unsigned pack2(float a, float b) { f32x2 v = {a, b}; hwbf16x2 r = __builtin_convertvector(v, hwbf16x2); return __builtin_bit_cast(unsigned, r); }
; DI float bflo(unsigned w) { return __uint_as_float(w << 16); }
; DI float bfhi(unsigned w) { return __uint_as_float(w & 0xffff0000u); }
;     DI void operator()(const f32x4 (&acc)[2][2][4][2], const Unit& u, int wr, int wc, int fr, int fq) const {
;     ...
;             for (int m = 0; m < 4; ++m) { const size_t ro = (size_t)(row0 + ai * HALF + m * 16) * D + col0;
; #pragma unroll
;                 for (int bj = 0; bj < 2; ++bj) {
;                     f32x4 x0, x1;
;                     if constexpr (IB) { const u32x4 w = *(const u32x4*)((const bf16_t*)Xin + ro + bj * HALF);
;                         x0 = (f32x4){bflo(w[0]), bfhi(w[0]), bflo(w[1]), bfhi(w[1])}; x1 = (f32x4){bflo(w[2]), bfhi(w[2]), bflo(w[3]), bfhi(w[3])}; }
;                     else { x0 = *(const f32x4*)((const float*)Xin + ro + bj * HALF); x1 = *(const f32x4*)((const float*)Xin + ro + bj * HALF + 4); }
;                     x0 += acc[ai][bj][m][0] * sc[bj][0]; x1 += acc[ai][bj][m][1] * sc[bj][1];
;                     if constexpr (OB) { u32x4 o; o[0] = pack2(x0[0], x0[1]); o[1] = pack2(x0[2], x0[3]); o[2] = pack2(x1[0], x1[1]); o[3] = pack2(x1[2], x1[3]);
;                         *(u32x4*)((bf16_t*)Xout + ro + bj * HALF) = o; }
;                     else { *(f32x4*)((float*)Xout + ro + bj * HALF) = x0; *(f32x4*)((float*)Xout + ro + bj * HALF + 4) = x1; } } }
; template <class Map, class Epi>
; DI void gemm_phase(LAS unsigned char* lds, const Map& MP, const Epi& E, const int nM, const int nN, const int K, const int lda, const int ldb) {
;     ...
;         { int frr = fr, fqq = fq; asm volatile("" : "+v"(frr), "+v"(fqq)); E(acc, cur, wr, wc, frr, fqq); }
;         if (!has_next) break;
	v_lshlrev_b32_e32 v44, 16, v40
	v_and_b32_e32 v45, 0xffff0000, v40
	v_lshlrev_b32_e32 v40, 16, v41
	v_and_b32_e32 v41, 0xffff0000, v41
	v_lshlrev_b32_e32 v46, 16, v42
	v_and_b32_e32 v47, 0xffff0000, v42
	v_lshlrev_b32_e32 v42, 16, v43
	v_and_b32_e32 v43, 0xffff0000, v43
	v_pk_add_f32 v[38:39], v[38:39], v[40:41]
	v_pk_add_f32 v[36:37], v[36:37], v[44:45]
	v_pk_add_f32 v[40:41], v[34:35], v[42:43]
	v_pk_add_f32 v[34:35], v[32:33], v[46:47]
	v_cvt_pk_bf16_f32 v32, v36, v37
	v_cvt_pk_bf16_f32 v33, v38, v39
	v_cvt_pk_bf16_f32 v34, v34, v35
	v_cvt_pk_bf16_f32 v35, v40, v41
	global_store_dwordx4 v[48:49], v[32:35], off offset:256
	s_nop 1
	v_lshl_add_u64 v[32:33], v[144:145], 0, s[2:3]
	s_mov_b32 s2, 0xa0000
	v_add_co_u32_e32 v38, vcc, s2, v144
	s_mov_b64 s[2:3], 0xb0000
	s_nop 0
	v_addc_co_u32_e32 v39, vcc, 0, v145, vcc
	s_waitcnt vmcnt(15)
	s_nop 1
	v_mov_b32_e32 v34, v210
	v_mov_b32_e32 v35, v211
	v_mov_b32_e32 v36, v212
	v_mov_b32_e32 v37, v213
	s_waitcnt lgkmcnt(0)
	v_lshlrev_b32_e32 v40, 16, v34
	v_and_b32_e32 v41, 0xffff0000, v34
	v_lshlrev_b32_e32 v34, 16, v35
	v_and_b32_e32 v35, 0xffff0000, v35
	v_lshlrev_b32_e32 v42, 16, v36
	v_and_b32_e32 v43, 0xffff0000, v36
	v_lshlrev_b32_e32 v36, 16, v37
	v_and_b32_e32 v37, 0xffff0000, v37
	v_pk_add_f32 v[30:31], v[30:31], v[34:35]
	v_pk_add_f32 v[28:29], v[28:29], v[40:41]
	v_pk_add_f32 v[34:35], v[26:27], v[36:37]
	v_pk_add_f32 v[26:27], v[24:25], v[42:43]
	v_cvt_pk_bf16_f32 v24, v28, v29
	v_cvt_pk_bf16_f32 v25, v30, v31
	v_cvt_pk_bf16_f32 v26, v26, v27
	v_cvt_pk_bf16_f32 v27, v34, v35
	global_store_dwordx4 v[38:39], v[24:27], off
	s_waitcnt vmcnt(15)
	s_nop 1
	v_mov_b32_e32 v24, v214
	v_mov_b32_e32 v25, v215
	v_mov_b32_e32 v26, v216
	v_mov_b32_e32 v27, v217
	s_waitcnt lgkmcnt(0)
	v_lshlrev_b32_e32 v28, 16, v24
	v_and_b32_e32 v29, 0xffff0000, v24
	v_lshlrev_b32_e32 v24, 16, v25
	v_and_b32_e32 v25, 0xffff0000, v25
	v_lshlrev_b32_e32 v30, 16, v26
	v_and_b32_e32 v31, 0xffff0000, v26
	v_lshlrev_b32_e32 v26, 16, v27
	v_and_b32_e32 v27, 0xffff0000, v27
	v_pk_add_f32 v[22:23], v[22:23], v[24:25]
	v_pk_add_f32 v[20:21], v[20:21], v[28:29]
	v_pk_add_f32 v[24:25], v[18:19], v[26:27]
	v_pk_add_f32 v[18:19], v[16:17], v[30:31]
	v_cvt_pk_bf16_f32 v16, v20, v21
	v_cvt_pk_bf16_f32 v17, v22, v23
	v_cvt_pk_bf16_f32 v18, v18, v19
	v_cvt_pk_bf16_f32 v19, v24, v25
	global_store_dwordx4 v[32:33], v[16:19], off offset:256
	s_nop 1
	v_lshl_add_u64 v[16:17], v[144:145], 0, s[2:3]
	s_mov_b32 s2, 0xb0000
	v_add_co_u32_e32 v22, vcc, s2, v144
	s_mov_b32 s2, s44
	s_nop 0
	v_addc_co_u32_e32 v23, vcc, 0, v145, vcc
	s_waitcnt vmcnt(15)
	s_nop 1
	v_mov_b32_e32 v18, v248
	v_mov_b32_e32 v19, v249
	v_mov_b32_e32 v20, v250
	v_mov_b32_e32 v21, v251
	s_and_b64 vcc, exec, s[40:41]
	s_waitcnt lgkmcnt(0)
	v_lshlrev_b32_e32 v24, 16, v18
	v_and_b32_e32 v25, 0xffff0000, v18
	v_lshlrev_b32_e32 v18, 16, v19
	v_and_b32_e32 v19, 0xffff0000, v19
	v_lshlrev_b32_e32 v26, 16, v20
	v_and_b32_e32 v27, 0xffff0000, v20
	v_lshlrev_b32_e32 v20, 16, v21
	v_and_b32_e32 v21, 0xffff0000, v21
	v_pk_add_f32 v[14:15], v[14:15], v[18:19]
	v_pk_add_f32 v[12:13], v[12:13], v[24:25]
	v_pk_add_f32 v[18:19], v[10:11], v[20:21]
	v_pk_add_f32 v[10:11], v[8:9], v[26:27]
	v_cvt_pk_bf16_f32 v8, v12, v13
	v_cvt_pk_bf16_f32 v9, v14, v15
	v_cvt_pk_bf16_f32 v10, v10, v11
	v_cvt_pk_bf16_f32 v11, v18, v19
	global_store_dwordx4 v[22:23], v[8:11], off
	s_waitcnt vmcnt(15)
	s_nop 1
	v_mov_b32_e32 v8, v252
	v_mov_b32_e32 v9, v253
	v_mov_b32_e32 v10, v254
	v_mov_b32_e32 v11, v255
	s_waitcnt lgkmcnt(0)
	v_lshlrev_b32_e32 v12, 16, v8
	v_and_b32_e32 v13, 0xffff0000, v8
	v_lshlrev_b32_e32 v8, 16, v9
	v_and_b32_e32 v9, 0xffff0000, v9
	v_lshlrev_b32_e32 v14, 16, v10
	v_and_b32_e32 v15, 0xffff0000, v10
	v_lshlrev_b32_e32 v10, 16, v11
	v_and_b32_e32 v11, 0xffff0000, v11
	v_pk_add_f32 v[6:7], v[6:7], v[8:9]
	v_pk_add_f32 v[4:5], v[4:5], v[12:13]
	v_pk_add_f32 v[8:9], v[2:3], v[10:11]
	v_pk_add_f32 v[2:3], v[0:1], v[14:15]
	v_cvt_pk_bf16_f32 v0, v4, v5
	v_cvt_pk_bf16_f32 v1, v6, v7
	v_cvt_pk_bf16_f32 v2, v2, v3
	v_cvt_pk_bf16_f32 v3, v8, v9
	global_store_dwordx4 v[16:17], v[0:3], off offset:256
	s_cbranch_vccz .LBB1_1761
	s_waitcnt vmcnt(0)
	s_cmpk_gt_u32 s17, 0xff
	s_cbranch_scc1 .LBB1_1768
	s_barrier

;     DI const char* a(const Unit& u) const { return (const char*)(A + (size_t)u.pm * BM * lda); }
;     DI const char* a(const Unit& u) const { return (const char*)(A + (size_t)u.pm * BM * 2048 + (u.pn >> 1) * 512); }
;     DI const char* a(const Unit& u) const { return (const char*)((u.pn < 12 ? A1 : A2) + (size_t)u.pm * BM * 512); }
; #define PG8_STAGE(bufoff, gbase, voff) do { _Pragma("unroll") for (int _i = 0; _i < 2; ++_i) \
;         __builtin_amdgcn_global_load_lds((const unsigned*)((const char*)(gbase) + (voff)[_i]), (LAS unsigned*)(lds + (bufoff) + ldsw + _i * 8192), 16, 0, 0); } while (0)
; #define PG8_LDA(dst, b, h) do { _Pragma("unroll") for (int m = 0; m < 4; ++m) _Pragma("unroll") for (int k = 0; k < 2; ++k) dst[m][k] = *(const LAS bf16x8*)(lds + PG8_SA(b, h) + aoff + m * 2048 + k * 1024); } while (0)
; #define PG8_LDB(dst, b, h) do { _Pragma("unroll") for (int n = 0; n < 2; ++n) _Pragma("unroll") for (int k = 0; k < 2; ++k) dst[n][k] = *(const LAS bf16x8*)(lds + PG8_SB(b, h) + boff + n * 2048 + k * 1024); } while (0)
; template <class Map, class Epi>
; DI void gemm_phase(LAS unsigned char* lds, const Map& MP, const Epi& E, const int nM, const int nN, const int K, const int lda, const int ldb) {
;     ...
;         const bool has_next = sched_next(ui + 1, nM, nN, G, cblk, nxt);
;         const char* nA = has_next ? MP.a(nxt) : cA; const char* nB = has_next ? MP.b(nxt) : cB;
;         for (int t = 0; t < nt; t += 2) {
;             const bool last = (t == nt - 2);
;             const char* a1 = cA + (size_t)(t + 1) * kstep;
;             const char* a2 = last ? nA : cA + (size_t)(t + 2) * kstep; const char* b2 = last ? nB : cB + (size_t)(t + 2) * kstep;
;             const char* a3 = a2 + kstep; const char* b3 = b2 + kstep;
;             PG8_LDB(B0, 0, 0); PG8_SCHED; PG8_LDA(At, 0, 0); PG8_STAGE(PG8_SA(1, 1), a1 + hstepA, voffA);
;             PG8_WAIT_L(8); PG8_BAR; PG8_WAIT_L(0); PG8_MMA(0, 0, At, B0); PG8_BAR; PG8_SCHED;
;             PG8_LDB(B1, 0, 1); PG8_STAGE(PG8_SB(0, 0), b2, voffB);
;             PG8_BAR; PG8_WAIT_L(0); PG8_MMA(0, 1, At, B1); PG8_BAR;
;             PG8_LDA(At, 0, 1); PG8_STAGE(PG8_SA(0, 0), a2, voffA);
;             PG8_BAR; PG8_WAIT_L(0); PG8_MMA(1, 0, At, B0); PG8_BAR; PG8_SCHED;
;             PG8_STAGE(PG8_SB(0, 1), b2 + hstepB, voffB);
;             PG8_WAIT_V(6); PG8_BAR; PG8_MMA(1, 1, At, B1); PG8_BAR;
.LBB1_1908:
	s_add_u32 s28, s42, 0xfff80080
	s_addc_u32 s29, s43, -1
	s_cmp_eq_u32 s3, 28
	s_cselect_b32 s47, s23, s29
	s_cselect_b32 s46, s58, s28
	s_cselect_b32 s29, s21, vcc_hi
	s_cselect_b32 s28, s59, vcc_lo
	s_add_i32 m0, s38, 0xc000
	ds_read_b128 v[96:99], v190
	ds_read_b128 v[100:103], v190 offset:1024
	ds_read_b128 v[108:111], v190 offset:2048
	ds_read_b128 v[112:115], v190 offset:3072
	ds_read_b128 v[160:163], v190 offset:4096
	ds_read_b128 v[164:167], v190 offset:5120
	ds_read_b128 v[198:201], v190 offset:6144
	ds_read_b128 v[202:205], v190 offset:7168
	global_load_lds_dwordx4 v178, s[42:43]
	s_add_i32 m0, s38, 0xe000
	s_nop 0
	global_load_lds_dwordx4 v176, s[42:43]
	s_waitcnt lgkmcnt(8)
	s_setprio 1
	s_barrier
	s_waitcnt lgkmcnt(7)
	v_mfma_f32_16x16x32_bf16 v[148:151], v[80:83], v[96:99], v[148:151]
	v_mfma_f32_16x16x32_bf16 v[144:147], v[88:91], v[96:99], v[144:147]
	s_waitcnt lgkmcnt(5)
	v_mfma_f32_16x16x32_bf16 v[136:139], v[80:83], v[108:111], v[136:139]
	v_mfma_f32_16x16x32_bf16 v[128:131], v[88:91], v[108:111], v[128:131]
	s_waitcnt lgkmcnt(3)
	v_mfma_f32_16x16x32_bf16 v[120:123], v[80:83], v[160:163], v[120:123]
	v_mfma_f32_16x16x32_bf16 v[104:107], v[88:91], v[160:163], v[104:107]
	s_waitcnt lgkmcnt(1)
	v_mfma_f32_16x16x32_bf16 v[76:79], v[80:83], v[198:201], v[76:79]
	v_mfma_f32_16x16x32_bf16 v[72:75], v[88:91], v[198:201], v[72:75]
	v_mfma_f32_16x16x32_bf16 v[148:151], v[84:87], v[100:103], v[148:151]
	s_add_i32 s68, s2, s54
	v_mfma_f32_16x16x32_bf16 v[144:147], v[92:95], v[100:103], v[144:147]
	v_lshl_add_u64 v[184:185], s[28:29], 0, v[172:173]
	v_mfma_f32_16x16x32_bf16 v[136:139], v[84:87], v[112:115], v[136:139]
	v_lshl_add_u64 v[194:195], s[28:29], 0, v[168:169]
	v_mfma_f32_16x16x32_bf16 v[128:131], v[92:95], v[112:115], v[128:131]
	v_mfma_f32_16x16x32_bf16 v[120:123], v[84:87], v[164:167], v[120:123]
	v_mfma_f32_16x16x32_bf16 v[104:107], v[92:95], v[164:167], v[104:107]
	s_waitcnt lgkmcnt(0)
	v_mfma_f32_16x16x32_bf16 v[76:79], v[84:87], v[202:205], v[76:79]
	s_setprio 0
	v_mfma_f32_16x16x32_bf16 v[72:75], v[92:95], v[202:205], v[72:75]
	s_barrier
	s_mov_b32 m0, s68
	ds_read_b128 v[206:209], v191
	ds_read_b128 v[210:213], v191 offset:1024
	ds_read_b128 v[214:217], v191 offset:2048
	ds_read_b128 v[218:221], v191 offset:3072
	global_load_lds_dwordx4 v[184:185], off
	s_add_i32 m0, s68, 0x2000
	s_nop 0
	global_load_lds_dwordx4 v[194:195], off
	s_setprio 1
	s_barrier
	s_waitcnt lgkmcnt(3)
	v_mfma_f32_16x16x32_bf16 v[156:159], v[206:209], v[96:99], v[156:159]
	s_waitcnt lgkmcnt(1)
	v_mfma_f32_16x16x32_bf16 v[96:99], v[214:217], v[96:99], v[152:155]
	v_mfma_f32_16x16x32_bf16 v[156:159], v[210:213], v[100:103], v[156:159]
	s_waitcnt lgkmcnt(0)
	v_mfma_f32_16x16x32_bf16 v[96:99], v[218:221], v[100:103], v[96:99]
	v_mfma_f32_16x16x32_bf16 v[100:103], v[206:209], v[108:111], v[140:143]
	v_mfma_f32_16x16x32_bf16 v[108:111], v[214:217], v[108:111], v[132:135]
	v_mfma_f32_16x16x32_bf16 v[116:119], v[214:217], v[160:163], v[116:119]
	v_mfma_f32_16x16x32_bf16 v[68:71], v[206:209], v[198:201], v[68:71]
	v_mfma_f32_16x16x32_bf16 v[64:67], v[214:217], v[198:201], v[64:67]
	v_lshl_add_u64 v[234:235], s[46:47], 0, v[170:171]
	s_mov_b32 m0, s38
	v_mfma_f32_16x16x32_bf16 v[100:103], v[210:213], v[112:115], v[100:103]
	v_lshl_add_u64 v[226:227], s[46:47], 0, v[174:175]
	v_mfma_f32_16x16x32_bf16 v[108:111], v[218:221], v[112:115], v[108:111]
	v_mfma_f32_16x16x32_bf16 v[112:115], v[206:209], v[160:163], v[124:127]
	v_mfma_f32_16x16x32_bf16 v[116:119], v[218:221], v[164:167], v[116:119]
	v_mfma_f32_16x16x32_bf16 v[68:71], v[210:213], v[202:205], v[68:71]
	v_mfma_f32_16x16x32_bf16 v[64:67], v[218:221], v[202:205], v[64:67]
	s_setprio 0
	v_mfma_f32_16x16x32_bf16 v[112:115], v[210:213], v[164:167], v[112:115]
	s_barrier
	ds_read_b128 v[124:127], v190 offset:16384
	ds_read_b128 v[132:135], v190 offset:17408
	ds_read_b128 v[140:143], v190 offset:18432
	ds_read_b128 v[152:155], v190 offset:19456
	ds_read_b128 v[160:163], v190 offset:20480
	ds_read_b128 v[164:167], v190 offset:21504
	ds_read_b128 v[198:201], v190 offset:22528
	ds_read_b128 v[202:205], v190 offset:23552
	global_load_lds_dwordx4 v[226:227], off
	s_mov_b32 m0, s39
	s_nop 0
	global_load_lds_dwordx4 v[234:235], off
	s_waitcnt vmcnt(10)
	s_setprio 1
	s_barrier
	s_waitcnt lgkmcnt(7)
	v_mfma_f32_16x16x32_bf16 v[60:63], v[80:83], v[124:127], v[60:63]
	v_mfma_f32_16x16x32_bf16 v[48:51], v[88:91], v[124:127], v[48:51]
	s_waitcnt lgkmcnt(5)
	v_mfma_f32_16x16x32_bf16 v[40:43], v[80:83], v[140:143], v[40:43]
	v_mfma_f32_16x16x32_bf16 v[32:35], v[88:91], v[140:143], v[32:35]
	s_waitcnt lgkmcnt(3)
	v_mfma_f32_16x16x32_bf16 v[24:27], v[80:83], v[160:163], v[24:27]
	v_mfma_f32_16x16x32_bf16 v[16:19], v[88:91], v[160:163], v[16:19]
	s_waitcnt lgkmcnt(1)
	v_mfma_f32_16x16x32_bf16 v[12:15], v[80:83], v[198:201], v[12:15]
	v_mfma_f32_16x16x32_bf16 v[8:11], v[88:91], v[198:201], v[8:11]
	v_mfma_f32_16x16x32_bf16 v[60:63], v[84:87], v[132:135], v[60:63]
	s_add_u32 s68, s28, 0x80000
	s_addc_u32 s69, s29, 0
	v_mfma_f32_16x16x32_bf16 v[48:51], v[92:95], v[132:135], v[48:51]
	s_add_i32 s70, s31, s54
	v_mfma_f32_16x16x32_bf16 v[40:43], v[84:87], v[152:155], v[40:43]
	v_mfma_f32_16x16x32_bf16 v[32:35], v[92:95], v[152:155], v[32:35]
	v_mfma_f32_16x16x32_bf16 v[24:27], v[84:87], v[164:167], v[24:27]
	v_mfma_f32_16x16x32_bf16 v[16:19], v[92:95], v[164:167], v[16:19]
	s_waitcnt lgkmcnt(0)
	v_mfma_f32_16x16x32_bf16 v[12:15], v[84:87], v[202:205], v[12:15]
	s_setprio 0
	v_mfma_f32_16x16x32_bf16 v[8:11], v[92:95], v[202:205], v[8:11]
	s_barrier
; #define PG8_STAGE(bufoff, gbase, voff) do { _Pragma("unroll") for (int _i = 0; _i < 2; ++_i) \
;         __builtin_amdgcn_global_load_lds((const unsigned*)((const char*)(gbase) + (voff)[_i]), (LAS unsigned*)(lds + (bufoff) + ldsw + _i * 8192), 16, 0, 0); } while (0)
; #define PG8_LDA(dst, b, h) do { _Pragma("unroll") for (int m = 0; m < 4; ++m) _Pragma("unroll") for (int k = 0; k < 2; ++k) dst[m][k] = *(const LAS bf16x8*)(lds + PG8_SA(b, h) + aoff + m * 2048 + k * 1024); } while (0)
; #define PG8_LDB(dst, b, h) do { _Pragma("unroll") for (int n = 0; n < 2; ++n) _Pragma("unroll") for (int k = 0; k < 2; ++k) dst[n][k] = *(const LAS bf16x8*)(lds + PG8_SB(b, h) + boff + n * 2048 + k * 1024); } while (0)
; #define PG8_MMA(ai, bj, At, Bt) do { __builtin_amdgcn_s_setprio(1); _Pragma("unroll") for (int m = 0; m < 4; ++m) _Pragma("unroll") for (int n = 0; n < 2; ++n) _Pragma("unroll") for (int k = 0; k < 2; ++k) \
;         acc[ai][bj][m][n] = __builtin_amdgcn_mfma_f32_16x16x32_bf16(Bt[n][k], At[m][k], acc[ai][bj][m][n], 0, 0, 0); __builtin_amdgcn_s_setprio(0); } while (0)
; #define PG8_WAIT_V(n) asm volatile("s_waitcnt vmcnt(" #n ")" ::: "memory")
; #define PG8_WAIT_L(n) asm volatile("s_waitcnt lgkmcnt(" #n ")" ::: "memory")
; #define PG8_BAR __builtin_amdgcn_s_barrier()
; #define PG8_SCHED __builtin_amdgcn_sched_barrier(0)
; template <class Map, class Epi>
; DI void gemm_phase(LAS unsigned char* lds, const Map& MP, const Epi& E, const int nM, const int nN, const int K, const int lda, const int ldb) {
;     ...
;             PG8_STAGE(PG8_SB(0, 1), b2 + hstepB, voffB);
;             PG8_WAIT_V(6); PG8_BAR; PG8_MMA(1, 1, At, B1); PG8_BAR;
;             PG8_LDB(B0, 1, 0); PG8_SCHED; PG8_LDA(At, 1, 0); PG8_STAGE(PG8_SA(0, 1), a2 + hstepA, voffA);
;             PG8_WAIT_L(8); PG8_BAR; PG8_WAIT_L(0); PG8_MMA(0, 0, At, B0); PG8_BAR; PG8_SCHED;
;             PG8_LDB(B1, 1, 1); PG8_STAGE(PG8_SB(1, 0), b3, voffB);
;             PG8_BAR; PG8_WAIT_L(0); PG8_MMA(0, 1, At, B1); PG8_BAR;
;             PG8_LDA(At, 1, 1); PG8_STAGE(PG8_SA(1, 0), a3, voffA);
	s_mov_b32 m0, s70
	s_nop 0
	global_load_lds_dwordx4 v172, s[68:69]
	s_add_i32 m0, s70, 0x2000
	s_nop 0
	global_load_lds_dwordx4 v168, s[68:69]
	s_waitcnt vmcnt(6)
	s_setprio 1
	s_barrier
	v_mfma_f32_16x16x32_bf16 v[56:59], v[206:209], v[124:127], v[56:59]
	v_mfma_f32_16x16x32_bf16 v[52:55], v[214:217], v[124:127], v[52:55]
	s_add_i32 s68, 0, 0x18000
	v_add_u32_e32 v92, s68, v188
	ds_read_b128 v[80:83], v92
	v_mfma_f32_16x16x32_bf16 v[44:47], v[206:209], v[140:143], v[44:47]
	v_mfma_f32_16x16x32_bf16 v[36:39], v[214:217], v[140:143], v[36:39]
	ds_read_b128 v[84:87], v92 offset:1024
	v_mfma_f32_16x16x32_bf16 v[28:31], v[206:209], v[160:163], v[28:31]
	v_mfma_f32_16x16x32_bf16 v[20:23], v[214:217], v[160:163], v[20:23]
	ds_read_b128 v[88:91], v92 offset:2048
	v_mfma_f32_16x16x32_bf16 v[4:7], v[206:209], v[198:201], v[4:7]
	v_mfma_f32_16x16x32_bf16 v[0:3], v[214:217], v[198:201], v[0:3]
	ds_read_b128 v[92:95], v92 offset:3072
	v_mfma_f32_16x16x32_bf16 v[56:59], v[210:213], v[132:135], v[56:59]
	s_add_u32 s46, s46, 0x80000
	s_addc_u32 s47, s47, 0
	v_mfma_f32_16x16x32_bf16 v[52:55], v[218:221], v[132:135], v[52:55]
	v_mfma_f32_16x16x32_bf16 v[44:47], v[210:213], v[152:155], v[44:47]
	v_mfma_f32_16x16x32_bf16 v[36:39], v[218:221], v[152:155], v[36:39]
	v_mfma_f32_16x16x32_bf16 v[28:31], v[210:213], v[164:167], v[28:31]
	v_mfma_f32_16x16x32_bf16 v[20:23], v[218:221], v[164:167], v[20:23]
	v_mfma_f32_16x16x32_bf16 v[4:7], v[210:213], v[202:205], v[4:7]
	s_setprio 0
	v_mfma_f32_16x16x32_bf16 v[0:3], v[218:221], v[202:205], v[0:3]
	s_barrier
	s_mov_b32 m0, s56
	ds_read_b128 v[124:127], v190 offset:32768
	ds_read_b128 v[132:135], v190 offset:33792
	ds_read_b128 v[160:163], v190 offset:34816
	ds_read_b128 v[164:167], v190 offset:35840
	ds_read_b128 v[198:201], v190 offset:36864
	ds_read_b128 v[202:205], v190 offset:37888
	ds_read_b128 v[206:209], v190 offset:38912
	ds_read_b128 v[210:213], v190 offset:39936
	global_load_lds_dwordx4 v174, s[46:47]
	s_mov_b32 m0, s57
	s_nop 0
	global_load_lds_dwordx4 v170, s[46:47]
	s_waitcnt lgkmcnt(8)
	s_setprio 1
	s_barrier
	s_waitcnt lgkmcnt(7)
	v_mfma_f32_16x16x32_bf16 v[140:143], v[80:83], v[124:127], v[148:151]
	s_waitcnt lgkmcnt(6)
	v_mfma_f32_16x16x32_bf16 v[148:151], v[84:87], v[132:135], v[140:143]
	v_mfma_f32_16x16x32_bf16 v[140:143], v[88:91], v[124:127], v[144:147]
	s_waitcnt lgkmcnt(5)
	v_mfma_f32_16x16x32_bf16 v[136:139], v[80:83], v[160:163], v[136:139]
	v_mfma_f32_16x16x32_bf16 v[128:131], v[88:91], v[160:163], v[128:131]
	s_waitcnt lgkmcnt(3)
	v_mfma_f32_16x16x32_bf16 v[120:123], v[80:83], v[198:201], v[120:123]
	v_mfma_f32_16x16x32_bf16 v[104:107], v[88:91], v[198:201], v[104:107]
	s_waitcnt lgkmcnt(1)
	v_mfma_f32_16x16x32_bf16 v[76:79], v[80:83], v[206:209], v[76:79]
	v_mfma_f32_16x16x32_bf16 v[72:75], v[88:91], v[206:209], v[72:75]
	s_add_i32 s46, 0, 0x1c000
	v_mfma_f32_16x16x32_bf16 v[144:147], v[92:95], v[132:135], v[140:143]
	v_add_u32_e32 v140, s46, v188
	v_mfma_f32_16x16x32_bf16 v[136:139], v[84:87], v[164:167], v[136:139]
	s_add_i32 s47, s68, s54
	v_mfma_f32_16x16x32_bf16 v[128:131], v[92:95], v[164:167], v[128:131]
	v_mfma_f32_16x16x32_bf16 v[120:123], v[84:87], v[202:205], v[120:123]
	v_mfma_f32_16x16x32_bf16 v[104:107], v[92:95], v[202:205], v[104:107]
	s_waitcnt lgkmcnt(0)
	v_mfma_f32_16x16x32_bf16 v[76:79], v[84:87], v[210:213], v[76:79]
	s_setprio 0
	v_mfma_f32_16x16x32_bf16 v[72:75], v[92:95], v[210:213], v[72:75]
	s_barrier
	ds_read_b128 v[214:217], v140
	ds_read_b128 v[218:221], v140 offset:1024
	ds_read_b128 v[222:225], v140 offset:2048
	ds_read_b128 v[230:233], v140 offset:3072
	v_lshl_add_u64 v[140:141], v[184:185], 0, s[14:15]
	s_mov_b32 m0, s47
	s_nop 0
	global_load_lds_dwordx4 v[140:141], off
	v_lshl_add_u64 v[140:141], v[194:195], 0, s[14:15]
	s_add_i32 m0, s47, 0x2000
	s_nop 0
	global_load_lds_dwordx4 v[140:141], off
	s_setprio 1
	s_barrier
	s_waitcnt lgkmcnt(1)
	v_mfma_f32_16x16x32_bf16 v[96:99], v[222:225], v[124:127], v[96:99]
	v_mfma_f32_16x16x32_bf16 v[140:143], v[214:217], v[124:127], v[156:159]
	s_waitcnt lgkmcnt(0)
	v_mfma_f32_16x16x32_bf16 v[152:155], v[230:233], v[132:135], v[96:99]
	v_mfma_f32_16x16x32_bf16 v[96:99], v[214:217], v[160:163], v[100:103]
	v_mfma_f32_16x16x32_bf16 v[156:159], v[218:221], v[132:135], v[140:143]
	v_mfma_f32_16x16x32_bf16 v[140:143], v[218:221], v[164:167], v[96:99]
	v_mfma_f32_16x16x32_bf16 v[96:99], v[222:225], v[160:163], v[108:111]
	v_mfma_f32_16x16x32_bf16 v[132:135], v[230:233], v[164:167], v[96:99]
	v_mfma_f32_16x16x32_bf16 v[96:99], v[214:217], v[198:201], v[112:115]
	s_mov_b32 m0, s63
	v_mfma_f32_16x16x32_bf16 v[124:127], v[218:221], v[202:205], v[96:99]
	v_lshl_add_u64 v[184:185], v[226:227], 0, s[14:15]
	v_mfma_f32_16x16x32_bf16 v[96:99], v[222:225], v[198:201], v[116:119]
	v_mfma_f32_16x16x32_bf16 v[68:71], v[214:217], v[206:209], v[68:71]
	v_mfma_f32_16x16x32_bf16 v[64:67], v[222:225], v[206:209], v[64:67]
	v_mfma_f32_16x16x32_bf16 v[116:119], v[230:233], v[202:205], v[96:99]
	v_mfma_f32_16x16x32_bf16 v[68:71], v[218:221], v[210:213], v[68:71]
	s_setprio 0
	v_mfma_f32_16x16x32_bf16 v[64:67], v[230:233], v[210:213], v[64:67]
	s_barrier
	ds_read_b128 v[96:99], v190 offset:49152
	ds_read_b128 v[100:103], v190 offset:50176
	ds_read_b128 v[108:111], v190 offset:51200
	ds_read_b128 v[112:115], v190 offset:52224
	ds_read_b128 v[160:163], v190 offset:53248
	ds_read_b128 v[164:167], v190 offset:54272
	ds_read_b128 v[198:201], v190 offset:55296
	ds_read_b128 v[202:205], v190 offset:56320
	global_load_lds_dwordx4 v[184:185], off
	v_lshl_add_u64 v[184:185], v[234:235], 0, s[14:15]
	s_mov_b32 m0, s66
	s_nop 0
	global_load_lds_dwordx4 v[184:185], off
	s_waitcnt vmcnt(10)
	s_setprio 1
	s_barrier
; #define PG8_STAGE(bufoff, gbase, voff) do { _Pragma("unroll") for (int _i = 0; _i < 2; ++_i) \
;         __builtin_amdgcn_global_load_lds((const unsigned*)((const char*)(gbase) + (voff)[_i]), (LAS unsigned*)(lds + (bufoff) + ldsw + _i * 8192), 16, 0, 0); } while (0)
; #define PG8_LDA(dst, b, h) do { _Pragma("unroll") for (int m = 0; m < 4; ++m) _Pragma("unroll") for (int k = 0; k < 2; ++k) dst[m][k] = *(const LAS bf16x8*)(lds + PG8_SA(b, h) + aoff + m * 2048 + k * 1024); } while (0)
; #define PG8_MMA(ai, bj, At, Bt) do { __builtin_amdgcn_s_setprio(1); _Pragma("unroll") for (int m = 0; m < 4; ++m) _Pragma("unroll") for (int n = 0; n < 2; ++n) _Pragma("unroll") for (int k = 0; k < 2; ++k) \
;         acc[ai][bj][m][n] = __builtin_amdgcn_mfma_f32_16x16x32_bf16(Bt[n][k], At[m][k], acc[ai][bj][m][n], 0, 0, 0); __builtin_amdgcn_s_setprio(0); } while (0)
; #define PG8_WAIT_V(n) asm volatile("s_waitcnt vmcnt(" #n ")" ::: "memory")
; #define PG8_WAIT_L(n) asm volatile("s_waitcnt lgkmcnt(" #n ")" ::: "memory")
; #define PG8_BAR __builtin_amdgcn_s_barrier()
; #define PG8_SCHED __builtin_amdgcn_sched_barrier(0)
; template <class Map, class Epi>
; DI void gemm_phase(LAS unsigned char* lds, const Map& MP, const Epi& E, const int nM, const int nN, const int K, const int lda, const int ldb) {
;     ...
;             PG8_LDA(At, 1, 1); PG8_STAGE(PG8_SA(1, 0), a3, voffA);
;             PG8_BAR; PG8_WAIT_L(0); PG8_MMA(1, 0, At, B0); PG8_BAR; PG8_SCHED;
;             PG8_STAGE(PG8_SB(1, 1), b3 + hstepB, voffB);
;             PG8_WAIT_V(6); PG8_BAR; PG8_MMA(1, 1, At, B1); PG8_BAR;
	s_waitcnt lgkmcnt(7)
	v_mfma_f32_16x16x32_bf16 v[60:63], v[80:83], v[96:99], v[60:63]
	v_mfma_f32_16x16x32_bf16 v[48:51], v[88:91], v[96:99], v[48:51]
	s_waitcnt lgkmcnt(5)
	v_mfma_f32_16x16x32_bf16 v[40:43], v[80:83], v[108:111], v[40:43]
	v_mfma_f32_16x16x32_bf16 v[32:35], v[88:91], v[108:111], v[32:35]
	s_waitcnt lgkmcnt(3)
	v_mfma_f32_16x16x32_bf16 v[24:27], v[80:83], v[160:163], v[24:27]
	v_mfma_f32_16x16x32_bf16 v[16:19], v[88:91], v[160:163], v[16:19]
	s_waitcnt lgkmcnt(1)
	v_mfma_f32_16x16x32_bf16 v[12:15], v[80:83], v[198:201], v[12:15]
	v_mfma_f32_16x16x32_bf16 v[8:11], v[88:91], v[198:201], v[8:11]
	v_mfma_f32_16x16x32_bf16 v[60:63], v[84:87], v[100:103], v[60:63]
	s_add_u32 s28, s28, 0x80080
	s_addc_u32 s29, s29, 0
	v_mfma_f32_16x16x32_bf16 v[48:51], v[92:95], v[100:103], v[48:51]
	s_add_i32 s46, s46, s54
	v_mfma_f32_16x16x32_bf16 v[40:43], v[84:87], v[112:115], v[40:43]
	v_mfma_f32_16x16x32_bf16 v[32:35], v[92:95], v[112:115], v[32:35]
	v_mfma_f32_16x16x32_bf16 v[24:27], v[84:87], v[164:167], v[24:27]
	v_mfma_f32_16x16x32_bf16 v[16:19], v[92:95], v[164:167], v[16:19]
	s_waitcnt lgkmcnt(0)
	v_mfma_f32_16x16x32_bf16 v[12:15], v[84:87], v[202:205], v[12:15]
	s_setprio 0
	v_mfma_f32_16x16x32_bf16 v[8:11], v[92:95], v[202:205], v[8:11]
	s_barrier
	s_mov_b32 m0, s46
	s_nop 0
	global_load_lds_dwordx4 v172, s[28:29]
	s_add_i32 m0, s46, 0x2000
	s_nop 0
	global_load_lds_dwordx4 v168, s[28:29]
	s_waitcnt vmcnt(6)
	s_setprio 1
	s_barrier
	v_mfma_f32_16x16x32_bf16 v[56:59], v[214:217], v[96:99], v[56:59]
	v_mfma_f32_16x16x32_bf16 v[52:55], v[222:225], v[96:99], v[52:55]
	ds_read_b128 v[80:83], v189
	v_mfma_f32_16x16x32_bf16 v[44:47], v[214:217], v[108:111], v[44:47]
	v_mfma_f32_16x16x32_bf16 v[36:39], v[222:225], v[108:111], v[36:39]
	ds_read_b128 v[84:87], v189 offset:1024
	v_mfma_f32_16x16x32_bf16 v[28:31], v[214:217], v[160:163], v[28:31]
	v_mfma_f32_16x16x32_bf16 v[20:23], v[222:225], v[160:163], v[20:23]
	ds_read_b128 v[88:91], v189 offset:2048
	v_mfma_f32_16x16x32_bf16 v[4:7], v[214:217], v[198:201], v[4:7]
	v_mfma_f32_16x16x32_bf16 v[0:3], v[222:225], v[198:201], v[0:3]
	ds_read_b128 v[92:95], v189 offset:3072
	v_mfma_f32_16x16x32_bf16 v[56:59], v[218:221], v[100:103], v[56:59]
	s_add_i32 s3, s3, 2
	v_mfma_f32_16x16x32_bf16 v[52:55], v[230:233], v[100:103], v[52:55]
	s_add_u32 vcc_lo, vcc_lo, 0x100
	s_addc_u32 vcc_hi, vcc_hi, 0
	v_mfma_f32_16x16x32_bf16 v[44:47], v[218:221], v[112:115], v[44:47]
	s_add_u32 s42, s42, 0x100
	s_addc_u32 s43, s43, 0
	v_mfma_f32_16x16x32_bf16 v[36:39], v[230:233], v[112:115], v[36:39]
	s_cmp_gt_u32 s3, 29
	v_mfma_f32_16x16x32_bf16 v[28:31], v[218:221], v[164:167], v[28:31]
	v_mfma_f32_16x16x32_bf16 v[20:23], v[230:233], v[164:167], v[20:23]
	v_mfma_f32_16x16x32_bf16 v[4:7], v[218:221], v[202:205], v[4:7]
	s_setprio 0
	v_mfma_f32_16x16x32_bf16 v[0:3], v[230:233], v[202:205], v[0:3]
	s_barrier
	s_cbranch_scc0 .LBB1_1908
; DI float silu_mul(float g, float v) { return g * v * __builtin_amdgcn_rcpf(1.0f + __builtin_amdgcn_exp2f(-LOG2E * g)); }
;     DI void operator()(const f32x4 (&acc)[2][2][4][2], const Unit& u, int wr, int wc, int fr, int fq) const {
;         const int row0 = u.pm * BM + wr * 64 + fr, ch0 = u.pn * 128 + wc * 32 + 8 * fq;
;         f32x4 w0[2], w1[2], w2[2], bb[2];
; #pragma unroll
;         for (int n = 0; n < 2; ++n) { w0[n] = *(const f32x4*)(cw + ch0 + 4 * n); w1[n] = *(const f32x4*)(cw + DFF + ch0 + 4 * n); w2[n] = *(const f32x4*)(cw + 2 * DFF + ch0 + 4 * n); bb[n] = *(const f32x4*)(cb + ch0 + 4 * n); }
; #pragma unroll
;         for (int ai = 0; ai < 2; ++ai)
; #pragma unroll
;             for (int m = 0; m < 4; ++m) {
;                 const bool efirst = (m == 0) && (fr == 0), elast = (m == 3) && (fr == 15);
;                 const int row = row0 + ai * HALF + m * 16;
;                 f32x4 gc[2];
; #pragma unroll
;                 for (int n = 0; n < 2; ++n) {
;                     const f32x4 g = acc[ai][0][m][n];
;                     const f32x4 gprev = acc[ai][0][m > 0 ? m - 1 : 0][n], gnext = acc[ai][0][m < 3 ? m + 1 : 3][n];
;                     f32x4 up, dn;
; #pragma unroll
;                     for (int e = 0; e < 4; ++e) {
;                         const float pu = (m > 0 && fr == 15) ? gprev[e] : g[e];
;                         const float pd = (m < 3 && fr == 0) ? gnext[e] : g[e];
;                         up[e] = dpp_ror1(pu); dn[e] = dpp_ror15(pd);
;                     }
;                     if (efirst) up = (f32x4){0.f, 0.f, 0.f, 0.f};
;                     if (elast) dn = (f32x4){0.f, 0.f, 0.f, 0.f};
;                     gc[n] = w0[n] * up + w1[n] * g + w2[n] * dn + bb[n];
;                 }
;                 if (efirst || elast) {
;                     const size_t eo = (size_t)((row >> 6) * 2 + (elast ? 1 : 0)) * DFF + ch0;
; #pragma unroll
;                     for (int n = 0; n < 2; ++n) { *(f32x4*)(EP + eo + 4 * n) = gc[n]; *(f32x4*)(ER + eo + 4 * n) = acc[ai][0][m][n]; *(f32x4*)(EV + eo + 4 * n) = acc[ai][1][m][n]; }
;                 } else {
;                     const f32x4 v0 = acc[ai][1][m][0], v1 = acc[ai][1][m][1];
;                     u32x4 o;
;                     o[0] = pack2(silu_mul(gc[0][0], v0[0]), silu_mul(gc[0][1], v0[1])); o[1] = pack2(silu_mul(gc[0][2], v0[2]), silu_mul(gc[0][3], v0[3]));
	s_waitcnt lgkmcnt(0)
	s_lshl_b32 s21, s45, 7
	v_mov_b32_e32 v194, v186
	v_mov_b32_e32 v80, v187
	s_or_b32 s21, s21, s62
	v_lshl_add_u32 v184, v80, 3, s21
	v_ashrrev_i32_e32 v185, 31, v184
	v_lshlrev_b64 v[80:81], 2, v[184:185]
	v_lshl_add_u64 v[84:85], s[4:5], 0, v[80:81]
	v_lshl_add_u64 v[88:89], s[16:17], 0, v[80:81]
	v_lshl_add_u64 v[92:93], s[18:19], 0, v[80:81]
	v_lshl_add_u64 v[112:113], s[6:7], 0, v[80:81]
	global_load_dwordx4 v[80:83], v[84:85], off offset:16
	global_load_dwordx4 v[96:99], v[84:85], off
	s_nop 0
	global_load_dwordx4 v[84:87], v[88:89], off offset:16
	global_load_dwordx4 v[100:103], v[88:89], off
	s_nop 0
	global_load_dwordx4 v[88:91], v[92:93], off offset:16
	global_load_dwordx4 v[108:111], v[92:93], off
	s_nop 0
	global_load_dwordx4 v[92:95], v[112:113], off offset:16
	s_nop 0
	global_load_dwordx4 v[112:115], v[112:113], off
	v_cmp_eq_u32_e32 vcc, 0, v194
	s_nop 0
	s_nop 0
	v_cndmask_b32_e32 v161, v148, v136, vcc
	v_cndmask_b32_e32 v162, v149, v137, vcc
	v_cndmask_b32_e32 v163, v150, v138, vcc
	v_mov_b32_dpp v160, v161 row_ror:15 row_mask:0xf bank_mask:0xf
	s_nop 0
	s_nop 0
	v_mov_b32_dpp v161, v162 row_ror:15 row_mask:0xf bank_mask:0xf
	v_mov_b32_dpp v164, v150 row_ror:1 row_mask:0xf bank_mask:0xf
	v_cndmask_b32_e32 v165, v151, v139, vcc
	v_mov_b32_dpp v162, v163 row_ror:15 row_mask:0xf bank_mask:0xf
	v_mov_b32_dpp v195, v151 row_ror:1 row_mask:0xf bank_mask:0xf
	v_mov_b32_dpp v166, v148 row_ror:1 row_mask:0xf bank_mask:0xf
	v_mov_b32_dpp v167, v149 row_ror:1 row_mask:0xf bank_mask:0xf
	v_mov_b32_dpp v163, v165 row_ror:15 row_mask:0xf bank_mask:0xf
	v_cndmask_b32_e64 v165, v195, 0, vcc
	v_cndmask_b32_e64 v164, v164, 0, vcc
	v_cndmask_b32_e64 v167, v167, 0, vcc
	v_cndmask_b32_e64 v166, v166, 0, vcc
	s_nop 0
	s_nop 0
	v_mov_b32_dpp v195, v144 row_ror:1 row_mask:0xf bank_mask:0xf
	v_mov_b32_dpp v196, v145 row_ror:1 row_mask:0xf bank_mask:0xf
	v_mov_b32_dpp v198, v146 row_ror:1 row_mask:0xf bank_mask:0xf
	v_cndmask_b32_e32 v199, v147, v131, vcc
	v_mov_b32_dpp v200, v147 row_ror:1 row_mask:0xf bank_mask:0xf
	v_cndmask_b32_e64 v198, v198, 0, vcc
	v_cndmask_b32_e64 v201, v196, 0, vcc
	s_lshl_b32 s3, s44, 8
	s_add_i32 s3, s3, s49
	v_add_u32_e32 v193, s3, v194
	v_cmp_ne_u32_e64 s[46:47], 0, v194
	s_waitcnt vmcnt(0)
	v_pk_mul_f32 v[164:165], v[98:99], v[164:165]
	v_pk_mul_f32 v[166:167], v[96:97], v[166:167]
	v_pk_fma_f32 v[164:165], v[150:151], v[102:103], v[164:165]
	v_pk_fma_f32 v[166:167], v[148:149], v[100:101], v[166:167]
	v_pk_fma_f32 v[162:163], v[110:111], v[162:163], v[164:165]
	v_cndmask_b32_e32 v165, v144, v128, vcc
	v_pk_fma_f32 v[160:161], v[108:109], v[160:161], v[166:167]
	v_cndmask_b32_e32 v166, v145, v129, vcc
	v_mov_b32_dpp v164, v165 row_ror:15 row_mask:0xf bank_mask:0xf
	v_cndmask_b32_e32 v167, v146, v130, vcc
	v_pk_add_f32 v[162:163], v[114:115], v[162:163]
	v_mov_b32_dpp v165, v166 row_ror:15 row_mask:0xf bank_mask:0xf
	v_pk_add_f32 v[160:161], v[112:113], v[160:161]
	s_nop 0
	v_mov_b32_dpp v166, v167 row_ror:15 row_mask:0xf bank_mask:0xf
	s_nop 1
	v_mov_b32_dpp v167, v199 row_ror:15 row_mask:0xf bank_mask:0xf
	v_cndmask_b32_e64 v199, v200, 0, vcc
	v_cndmask_b32_e64 v200, v195, 0, vcc
	v_pk_mul_f32 v[200:201], v[80:81], v[200:201]
	v_pk_mul_f32 v[198:199], v[82:83], v[198:199]
	v_pk_fma_f32 v[200:201], v[144:145], v[84:85], v[200:201]
	v_pk_fma_f32 v[198:199], v[146:147], v[86:87], v[198:199]
	v_pk_fma_f32 v[164:165], v[88:89], v[164:165], v[200:201]
	v_pk_fma_f32 v[166:167], v[90:91], v[166:167], v[198:199]
	v_pk_add_f32 v[164:165], v[92:93], v[164:165]
	v_pk_add_f32 v[166:167], v[94:95], v[166:167]
	s_and_saveexec_b64 s[28:29], s[46:47]
	s_xor_b64 s[28:29], exec, s[28:29]
	s_cbranch_execz .LBB1_1911
	v_mul_f32_e32 v195, 0xbfb8aa3b, v160
	v_exp_f32_e32 v195, v195
	v_mul_f32_e32 v196, 0xbfb8aa3b, v161
	v_exp_f32_e32 v196, v196
	v_pk_mul_f32 v[160:161], v[156:157], v[160:161]
	v_add_f32_e32 v195, 1.0, v195
	v_rcp_f32_e32 v198, v195
	v_add_f32_e32 v196, 1.0, v196
	v_mul_f32_e32 v195, 0xbfb8aa3b, v162
	v_rcp_f32_e32 v199, v196
	v_exp_f32_e32 v195, v195
	v_mul_f32_e32 v196, 0xbfb8aa3b, v163
	v_exp_f32_e32 v196, v196
	v_pk_mul_f32 v[160:161], v[160:161], v[198:199]
	v_add_f32_e32 v195, 1.0, v195
	v_rcp_f32_e32 v200, v195
	v_add_f32_e32 v195, 1.0, v196
	v_rcp_f32_e32 v201, v195
	v_cvt_pk_bf16_f32 v160, v160, v161
	v_mul_f32_e32 v161, 0xbfb8aa3b, v164
	v_exp_f32_e32 v195, v161
	v_mul_f32_e32 v161, 0xbfb8aa3b, v165
	v_exp_f32_e32 v196, v161
	v_pk_mul_f32 v[162:163], v[158:159], v[162:163]
	v_pk_mul_f32 v[164:165], v[152:153], v[164:165]
	v_pk_mul_f32 v[162:163], v[162:163], v[200:201]
	s_nop 0
	v_cvt_pk_bf16_f32 v161, v162, v163
	v_add_f32_e32 v162, 1.0, v195
	v_mul_f32_e32 v195, 0xbfb8aa3b, v166
	v_add_f32_e32 v163, 1.0, v196
	v_exp_f32_e32 v195, v195
	v_mul_f32_e32 v196, 0xbfb8aa3b, v167
	v_exp_f32_e32 v196, v196
	v_rcp_f32_e32 v162, v162
	v_add_f32_e32 v195, 1.0, v195
	v_rcp_f32_e32 v198, v195
	v_add_f32_e32 v195, 1.0, v196
	v_rcp_f32_e32 v163, v163
	v_rcp_f32_e32 v199, v195
	v_pk_mul_f32 v[166:167], v[154:155], v[166:167]
	v_pk_mul_f32 v[162:163], v[164:165], v[162:163]
	v_pk_mul_f32 v[164:165], v[166:167], v[198:199]
	v_cvt_pk_bf16_f32 v162, v162, v163
	v_cvt_pk_bf16_f32 v163, v164, v165
	v_mov_b64_e32 v[164:165], s[52:53]
	v_mad_i64_i32 v[164:165], s[42:43], v193, s60, v[164:165]
	v_lshl_add_u64 v[164:165], v[184:185], 1, v[164:165]
	global_store_dwordx4 v[164:165], v[160:163], off

;     DI const char* a(const Unit& u) const { return (const char*)(A + (size_t)u.pm * BM * lda); }
;     DI const char* a(const Unit& u) const { return (const char*)(A + (size_t)u.pm * BM * 2048 + (u.pn >> 1) * 512); }
;     DI const char* a(const Unit& u) const { return (const char*)((u.pn < 12 ? A1 : A2) + (size_t)u.pm * BM * 512); }
; #define PG8_STAGE(bufoff, gbase, voff) do { _Pragma("unroll") for (int _i = 0; _i < 2; ++_i) \
;         __builtin_amdgcn_global_load_lds((const unsigned*)((const char*)(gbase) + (voff)[_i]), (LAS unsigned*)(lds + (bufoff) + ldsw + _i * 8192), 16, 0, 0); } while (0)
; #define PG8_LDA(dst, b, h) do { _Pragma("unroll") for (int m = 0; m < 4; ++m) _Pragma("unroll") for (int k = 0; k < 2; ++k) dst[m][k] = *(const LAS bf16x8*)(lds + PG8_SA(b, h) + aoff + m * 2048 + k * 1024); } while (0)
; #define PG8_LDB(dst, b, h) do { _Pragma("unroll") for (int n = 0; n < 2; ++n) _Pragma("unroll") for (int k = 0; k < 2; ++k) dst[n][k] = *(const LAS bf16x8*)(lds + PG8_SB(b, h) + boff + n * 2048 + k * 1024); } while (0)
; template <class Map, class Epi>
; DI void gemm_phase(LAS unsigned char* lds, const Map& MP, const Epi& E, const int nM, const int nN, const int K, const int lda, const int ldb) {
;     ...
;         const bool has_next = sched_next(ui + 1, nM, nN, G, cblk, nxt);
;         const char* nA = has_next ? MP.a(nxt) : cA; const char* nB = has_next ? MP.b(nxt) : cB;
;         for (int t = 0; t < nt; t += 2) {
;             const bool last = (t == nt - 2);
;             const char* a1 = cA + (size_t)(t + 1) * kstep;
;             const char* a2 = last ? nA : cA + (size_t)(t + 2) * kstep; const char* b2 = last ? nB : cB + (size_t)(t + 2) * kstep;
;             const char* a3 = a2 + kstep; const char* b3 = b2 + kstep;
;             PG8_LDB(B0, 0, 0); PG8_SCHED; PG8_LDA(At, 0, 0); PG8_STAGE(PG8_SA(1, 1), a1 + hstepA, voffA);
;             PG8_WAIT_L(8); PG8_BAR; PG8_WAIT_L(0); PG8_MMA(0, 0, At, B0); PG8_BAR; PG8_SCHED;
;             PG8_LDB(B1, 0, 1); PG8_STAGE(PG8_SB(0, 0), b2, voffB);
;             PG8_BAR; PG8_WAIT_L(0); PG8_MMA(0, 1, At, B1); PG8_BAR;
;             PG8_LDA(At, 0, 1); PG8_STAGE(PG8_SA(0, 0), a2, voffA);
;             PG8_BAR; PG8_WAIT_L(0); PG8_MMA(1, 0, At, B0); PG8_BAR; PG8_SCHED;
;             PG8_STAGE(PG8_SB(0, 1), b2 + hstepB, voffB);
;             PG8_WAIT_V(6); PG8_BAR; PG8_MMA(1, 1, At, B1); PG8_BAR;
.LBB1_2078:
	s_add_u32 s10, s8, 0x100
	s_addc_u32 s11, s9, 0
	s_cmpk_eq_i32 s3, 0x54
	s_cselect_b32 s15, s43, s11
	s_cselect_b32 s14, s42, s10
	s_cselect_b32 s13, s7, s44
	s_cselect_b32 s12, s6, s39
	s_add_i32 m0, s24, 0xc000
	ds_read_b128 v[168:171], v150
	ds_read_b128 v[172:175], v150 offset:1024
	ds_read_b128 v[176:179], v150 offset:2048
	ds_read_b128 v[180:183], v150 offset:3072
	ds_read_b128 v[184:187], v150 offset:4096
	ds_read_b128 v[188:191], v150 offset:5120
	ds_read_b128 v[192:195], v150 offset:6144
	ds_read_b128 v[198:201], v150 offset:7168
	global_load_lds_dwordx4 v138, s[8:9]
	s_add_i32 m0, s24, 0xe000
	s_nop 0
	global_load_lds_dwordx4 v136, s[8:9]
	s_waitcnt lgkmcnt(8)
	s_setprio 1
	s_barrier
	s_waitcnt lgkmcnt(7)
	v_mfma_f32_16x16x32_bf16 v[124:127], v[152:155], v[168:171], v[124:127]
	v_mfma_f32_16x16x32_bf16 v[120:123], v[160:163], v[168:171], v[120:123]
	s_waitcnt lgkmcnt(5)
	v_mfma_f32_16x16x32_bf16 v[108:111], v[152:155], v[176:179], v[108:111]
	v_mfma_f32_16x16x32_bf16 v[104:107], v[160:163], v[176:179], v[104:107]
	s_waitcnt lgkmcnt(3)
	v_mfma_f32_16x16x32_bf16 v[92:95], v[152:155], v[184:187], v[92:95]
	v_mfma_f32_16x16x32_bf16 v[88:91], v[160:163], v[184:187], v[88:91]
	s_waitcnt lgkmcnt(1)
	v_mfma_f32_16x16x32_bf16 v[76:79], v[152:155], v[192:195], v[76:79]
	v_mfma_f32_16x16x32_bf16 v[72:75], v[160:163], v[192:195], v[72:75]
	v_mfma_f32_16x16x32_bf16 v[124:127], v[156:159], v[172:175], v[124:127]
	s_add_i32 s8, s35, s22
	v_mfma_f32_16x16x32_bf16 v[120:123], v[164:167], v[172:175], v[120:123]
	v_lshl_add_u64 v[144:145], s[12:13], 0, v[132:133]
	v_mfma_f32_16x16x32_bf16 v[108:111], v[156:159], v[180:183], v[108:111]
	v_lshl_add_u64 v[218:219], s[12:13], 0, v[128:129]
	v_mfma_f32_16x16x32_bf16 v[104:107], v[164:167], v[180:183], v[104:107]
	v_mfma_f32_16x16x32_bf16 v[92:95], v[156:159], v[188:191], v[92:95]
	v_mfma_f32_16x16x32_bf16 v[88:91], v[164:167], v[188:191], v[88:91]
	s_waitcnt lgkmcnt(0)
	v_mfma_f32_16x16x32_bf16 v[76:79], v[156:159], v[198:201], v[76:79]
	s_setprio 0
	v_mfma_f32_16x16x32_bf16 v[72:75], v[164:167], v[198:201], v[72:75]
	s_barrier
	s_mov_b32 m0, s8
	ds_read_b128 v[202:205], v151
	ds_read_b128 v[206:209], v151 offset:1024
	ds_read_b128 v[210:213], v151 offset:2048
	ds_read_b128 v[214:217], v151 offset:3072
	global_load_lds_dwordx4 v[144:145], off
	s_add_i32 m0, s8, 0x2000
	s_nop 0
	global_load_lds_dwordx4 v[218:219], off
	s_setprio 1
	s_barrier
	s_waitcnt lgkmcnt(3)
	v_mfma_f32_16x16x32_bf16 v[116:119], v[202:205], v[168:171], v[116:119]
	s_waitcnt lgkmcnt(1)
	v_mfma_f32_16x16x32_bf16 v[112:115], v[210:213], v[168:171], v[112:115]
	v_mfma_f32_16x16x32_bf16 v[100:103], v[202:205], v[176:179], v[100:103]
	v_mfma_f32_16x16x32_bf16 v[96:99], v[210:213], v[176:179], v[96:99]
	v_mfma_f32_16x16x32_bf16 v[84:87], v[202:205], v[184:187], v[84:87]
	v_mfma_f32_16x16x32_bf16 v[80:83], v[210:213], v[184:187], v[80:83]
	v_mfma_f32_16x16x32_bf16 v[68:71], v[202:205], v[192:195], v[68:71]
	v_mfma_f32_16x16x32_bf16 v[64:67], v[210:213], v[192:195], v[64:67]
	v_mfma_f32_16x16x32_bf16 v[116:119], v[206:209], v[172:175], v[116:119]
	v_lshl_add_u64 v[222:223], s[14:15], 0, v[130:131]
	s_mov_b32 m0, s24
	s_waitcnt lgkmcnt(0)
	v_mfma_f32_16x16x32_bf16 v[112:115], v[214:217], v[172:175], v[112:115]
	v_lshl_add_u64 v[220:221], s[14:15], 0, v[134:135]
	v_mfma_f32_16x16x32_bf16 v[100:103], v[206:209], v[180:183], v[100:103]
	v_mfma_f32_16x16x32_bf16 v[96:99], v[214:217], v[180:183], v[96:99]
	v_mfma_f32_16x16x32_bf16 v[84:87], v[206:209], v[188:191], v[84:87]
	v_mfma_f32_16x16x32_bf16 v[80:83], v[214:217], v[188:191], v[80:83]
	v_mfma_f32_16x16x32_bf16 v[68:71], v[206:209], v[198:201], v[68:71]
	s_setprio 0
	v_mfma_f32_16x16x32_bf16 v[64:67], v[214:217], v[198:201], v[64:67]
	s_barrier
	ds_read_b128 v[168:171], v150 offset:16384
	ds_read_b128 v[172:175], v150 offset:17408
	ds_read_b128 v[176:179], v150 offset:18432
	ds_read_b128 v[180:183], v150 offset:19456
	ds_read_b128 v[184:187], v150 offset:20480
	ds_read_b128 v[188:191], v150 offset:21504
	ds_read_b128 v[192:195], v150 offset:22528
	ds_read_b128 v[198:201], v150 offset:23552
	global_load_lds_dwordx4 v[220:221], off
	s_mov_b32 m0, s25
	s_nop 0
	global_load_lds_dwordx4 v[222:223], off
	s_waitcnt vmcnt(10)
	s_setprio 1
	s_barrier
	s_waitcnt lgkmcnt(7)
	v_mfma_f32_16x16x32_bf16 v[60:63], v[152:155], v[168:171], v[60:63]
	v_mfma_f32_16x16x32_bf16 v[56:59], v[160:163], v[168:171], v[56:59]
	s_waitcnt lgkmcnt(5)
	v_mfma_f32_16x16x32_bf16 v[44:47], v[152:155], v[176:179], v[44:47]
	v_mfma_f32_16x16x32_bf16 v[40:43], v[160:163], v[176:179], v[40:43]
	s_waitcnt lgkmcnt(3)
	v_mfma_f32_16x16x32_bf16 v[28:31], v[152:155], v[184:187], v[28:31]
	v_mfma_f32_16x16x32_bf16 v[24:27], v[160:163], v[184:187], v[24:27]
	s_waitcnt lgkmcnt(1)
	v_mfma_f32_16x16x32_bf16 v[12:15], v[152:155], v[192:195], v[12:15]
	v_mfma_f32_16x16x32_bf16 v[8:11], v[160:163], v[192:195], v[8:11]
	v_mfma_f32_16x16x32_bf16 v[60:63], v[156:159], v[172:175], v[60:63]
	s_add_u32 s8, s12, 0x160000
	s_addc_u32 s9, s13, 0
	v_mfma_f32_16x16x32_bf16 v[56:59], v[164:167], v[172:175], v[56:59]
	s_add_i32 s45, s36, s22
	v_mfma_f32_16x16x32_bf16 v[44:47], v[156:159], v[180:183], v[44:47]
	v_mfma_f32_16x16x32_bf16 v[40:43], v[164:167], v[180:183], v[40:43]
	v_mfma_f32_16x16x32_bf16 v[28:31], v[156:159], v[188:191], v[28:31]
	v_mfma_f32_16x16x32_bf16 v[24:27], v[164:167], v[188:191], v[24:27]
	s_waitcnt lgkmcnt(0)
	v_mfma_f32_16x16x32_bf16 v[12:15], v[156:159], v[198:201], v[12:15]
	s_setprio 0
	v_mfma_f32_16x16x32_bf16 v[8:11], v[164:167], v[198:201], v[8:11]
	s_barrier
; #define PG8_STAGE(bufoff, gbase, voff) do { _Pragma("unroll") for (int _i = 0; _i < 2; ++_i) \
;         __builtin_amdgcn_global_load_lds((const unsigned*)((const char*)(gbase) + (voff)[_i]), (LAS unsigned*)(lds + (bufoff) + ldsw + _i * 8192), 16, 0, 0); } while (0)
; #define PG8_LDA(dst, b, h) do { _Pragma("unroll") for (int m = 0; m < 4; ++m) _Pragma("unroll") for (int k = 0; k < 2; ++k) dst[m][k] = *(const LAS bf16x8*)(lds + PG8_SA(b, h) + aoff + m * 2048 + k * 1024); } while (0)
; #define PG8_LDB(dst, b, h) do { _Pragma("unroll") for (int n = 0; n < 2; ++n) _Pragma("unroll") for (int k = 0; k < 2; ++k) dst[n][k] = *(const LAS bf16x8*)(lds + PG8_SB(b, h) + boff + n * 2048 + k * 1024); } while (0)
; #define PG8_MMA(ai, bj, At, Bt) do { __builtin_amdgcn_s_setprio(1); _Pragma("unroll") for (int m = 0; m < 4; ++m) _Pragma("unroll") for (int n = 0; n < 2; ++n) _Pragma("unroll") for (int k = 0; k < 2; ++k) \
;         acc[ai][bj][m][n] = __builtin_amdgcn_mfma_f32_16x16x32_bf16(Bt[n][k], At[m][k], acc[ai][bj][m][n], 0, 0, 0); __builtin_amdgcn_s_setprio(0); } while (0)
; #define PG8_WAIT_V(n) asm volatile("s_waitcnt vmcnt(" #n ")" ::: "memory")
; #define PG8_WAIT_L(n) asm volatile("s_waitcnt lgkmcnt(" #n ")" ::: "memory")
; #define PG8_BAR __builtin_amdgcn_s_barrier()
; #define PG8_SCHED __builtin_amdgcn_sched_barrier(0)
; template <class Map, class Epi>
; DI void gemm_phase(LAS unsigned char* lds, const Map& MP, const Epi& E, const int nM, const int nN, const int K, const int lda, const int ldb) {
;     ...
;             PG8_STAGE(PG8_SB(0, 1), b2 + hstepB, voffB);
;             PG8_WAIT_V(6); PG8_BAR; PG8_MMA(1, 1, At, B1); PG8_BAR;
;             PG8_LDB(B0, 1, 0); PG8_SCHED; PG8_LDA(At, 1, 0); PG8_STAGE(PG8_SA(0, 1), a2 + hstepA, voffA);
;             PG8_WAIT_L(8); PG8_BAR; PG8_WAIT_L(0); PG8_MMA(0, 0, At, B0); PG8_BAR; PG8_SCHED;
;             PG8_LDB(B1, 1, 1); PG8_STAGE(PG8_SB(1, 0), b3, voffB);
;             PG8_BAR; PG8_WAIT_L(0); PG8_MMA(0, 1, At, B1); PG8_BAR;
;             PG8_LDA(At, 1, 1); PG8_STAGE(PG8_SA(1, 0), a3, voffA);
	s_mov_b32 m0, s45
	s_nop 0
	global_load_lds_dwordx4 v132, s[8:9]
	s_add_i32 m0, s45, 0x2000
	s_nop 0
	global_load_lds_dwordx4 v128, s[8:9]
	s_waitcnt vmcnt(6)
	s_setprio 1
	s_barrier
	v_mfma_f32_16x16x32_bf16 v[52:55], v[202:205], v[168:171], v[52:55]
	v_mfma_f32_16x16x32_bf16 v[48:51], v[210:213], v[168:171], v[48:51]
	s_add_i32 s45, 0, 0x18000
	v_add_u32_e32 v164, s45, v148
	ds_read_b128 v[152:155], v164
	v_mfma_f32_16x16x32_bf16 v[36:39], v[202:205], v[176:179], v[36:39]
	v_mfma_f32_16x16x32_bf16 v[32:35], v[210:213], v[176:179], v[32:35]
	ds_read_b128 v[156:159], v164 offset:1024
	v_mfma_f32_16x16x32_bf16 v[20:23], v[202:205], v[184:187], v[20:23]
	v_mfma_f32_16x16x32_bf16 v[16:19], v[210:213], v[184:187], v[16:19]
	ds_read_b128 v[160:163], v164 offset:2048
	v_mfma_f32_16x16x32_bf16 v[4:7], v[202:205], v[192:195], v[4:7]
	v_mfma_f32_16x16x32_bf16 v[0:3], v[210:213], v[192:195], v[0:3]
	ds_read_b128 v[164:167], v164 offset:3072
	v_mfma_f32_16x16x32_bf16 v[52:55], v[206:209], v[172:175], v[52:55]
	s_add_u32 s8, s14, 0x160000
	s_addc_u32 s9, s15, 0
	v_mfma_f32_16x16x32_bf16 v[48:51], v[214:217], v[172:175], v[48:51]
	v_mfma_f32_16x16x32_bf16 v[36:39], v[206:209], v[180:183], v[36:39]
	v_mfma_f32_16x16x32_bf16 v[32:35], v[214:217], v[180:183], v[32:35]
	v_mfma_f32_16x16x32_bf16 v[20:23], v[206:209], v[188:191], v[20:23]
	v_mfma_f32_16x16x32_bf16 v[16:19], v[214:217], v[188:191], v[16:19]
	v_mfma_f32_16x16x32_bf16 v[4:7], v[206:209], v[198:201], v[4:7]
	s_setprio 0
	v_mfma_f32_16x16x32_bf16 v[0:3], v[214:217], v[198:201], v[0:3]
	s_barrier
	s_mov_b32 m0, s26
	ds_read_b128 v[168:171], v150 offset:32768
	ds_read_b128 v[172:175], v150 offset:33792
	ds_read_b128 v[176:179], v150 offset:34816
	ds_read_b128 v[180:183], v150 offset:35840
	ds_read_b128 v[184:187], v150 offset:36864
	ds_read_b128 v[188:191], v150 offset:37888
	ds_read_b128 v[192:195], v150 offset:38912
	ds_read_b128 v[198:201], v150 offset:39936
	global_load_lds_dwordx4 v134, s[8:9]
	s_mov_b32 m0, s27
	s_nop 0
	global_load_lds_dwordx4 v130, s[8:9]
	s_waitcnt lgkmcnt(8)
	s_setprio 1
	s_barrier
	s_waitcnt lgkmcnt(7)
	v_mfma_f32_16x16x32_bf16 v[124:127], v[152:155], v[168:171], v[124:127]
	v_mfma_f32_16x16x32_bf16 v[120:123], v[160:163], v[168:171], v[120:123]
	s_waitcnt lgkmcnt(5)
	v_mfma_f32_16x16x32_bf16 v[108:111], v[152:155], v[176:179], v[108:111]
	v_mfma_f32_16x16x32_bf16 v[104:107], v[160:163], v[176:179], v[104:107]
	s_waitcnt lgkmcnt(3)
	v_mfma_f32_16x16x32_bf16 v[92:95], v[152:155], v[184:187], v[92:95]
	v_mfma_f32_16x16x32_bf16 v[88:91], v[160:163], v[184:187], v[88:91]
	s_waitcnt lgkmcnt(1)
	v_mfma_f32_16x16x32_bf16 v[76:79], v[152:155], v[192:195], v[76:79]
	v_mfma_f32_16x16x32_bf16 v[72:75], v[160:163], v[192:195], v[72:75]
	v_mfma_f32_16x16x32_bf16 v[124:127], v[156:159], v[172:175], v[124:127]
	s_add_i32 s14, 0, 0x1c000
	v_mfma_f32_16x16x32_bf16 v[120:123], v[164:167], v[172:175], v[120:123]
	s_add_i32 s8, s45, s22
	v_mfma_f32_16x16x32_bf16 v[108:111], v[156:159], v[180:183], v[108:111]
	v_add_u32_e32 v196, s14, v148
	v_mfma_f32_16x16x32_bf16 v[104:107], v[164:167], v[180:183], v[104:107]
	v_lshl_add_u64 v[144:145], v[144:145], 0, s[46:47]
	v_mfma_f32_16x16x32_bf16 v[92:95], v[156:159], v[188:191], v[92:95]
	v_mfma_f32_16x16x32_bf16 v[88:91], v[164:167], v[188:191], v[88:91]
	s_waitcnt lgkmcnt(0)
	v_mfma_f32_16x16x32_bf16 v[76:79], v[156:159], v[198:201], v[76:79]
	s_setprio 0
	v_mfma_f32_16x16x32_bf16 v[72:75], v[164:167], v[198:201], v[72:75]
	s_barrier
	s_mov_b32 m0, s8
	ds_read_b128 v[202:205], v196
	ds_read_b128 v[206:209], v196 offset:1024
	ds_read_b128 v[210:213], v196 offset:2048
	ds_read_b128 v[214:217], v196 offset:3072
	global_load_lds_dwordx4 v[144:145], off
	v_lshl_add_u64 v[144:145], v[218:219], 0, s[46:47]
	s_add_i32 m0, s8, 0x2000
	s_nop 0
	global_load_lds_dwordx4 v[144:145], off
	s_setprio 1
	s_barrier
	s_waitcnt lgkmcnt(3)
	v_mfma_f32_16x16x32_bf16 v[116:119], v[202:205], v[168:171], v[116:119]
	s_waitcnt lgkmcnt(1)
	v_mfma_f32_16x16x32_bf16 v[112:115], v[210:213], v[168:171], v[112:115]
	v_mfma_f32_16x16x32_bf16 v[100:103], v[202:205], v[176:179], v[100:103]
	v_mfma_f32_16x16x32_bf16 v[96:99], v[210:213], v[176:179], v[96:99]
	v_mfma_f32_16x16x32_bf16 v[84:87], v[202:205], v[184:187], v[84:87]
	v_mfma_f32_16x16x32_bf16 v[80:83], v[210:213], v[184:187], v[80:83]
	v_mfma_f32_16x16x32_bf16 v[68:71], v[202:205], v[192:195], v[68:71]
	v_mfma_f32_16x16x32_bf16 v[64:67], v[210:213], v[192:195], v[64:67]
	v_mfma_f32_16x16x32_bf16 v[116:119], v[206:209], v[172:175], v[116:119]
	s_mov_b32 m0, s30
	s_waitcnt lgkmcnt(0)
	v_mfma_f32_16x16x32_bf16 v[112:115], v[214:217], v[172:175], v[112:115]
	v_lshl_add_u64 v[144:145], v[220:221], 0, s[46:47]
	v_mfma_f32_16x16x32_bf16 v[100:103], v[206:209], v[180:183], v[100:103]
	v_mfma_f32_16x16x32_bf16 v[96:99], v[214:217], v[180:183], v[96:99]
	v_mfma_f32_16x16x32_bf16 v[84:87], v[206:209], v[188:191], v[84:87]
	v_mfma_f32_16x16x32_bf16 v[80:83], v[214:217], v[188:191], v[80:83]
	v_mfma_f32_16x16x32_bf16 v[68:71], v[206:209], v[198:201], v[68:71]
	s_setprio 0
	v_mfma_f32_16x16x32_bf16 v[64:67], v[214:217], v[198:201], v[64:67]
	s_barrier
	ds_read_b128 v[168:171], v150 offset:49152
	ds_read_b128 v[172:175], v150 offset:50176
	ds_read_b128 v[176:179], v150 offset:51200
	ds_read_b128 v[180:183], v150 offset:52224
	ds_read_b128 v[184:187], v150 offset:53248
	ds_read_b128 v[188:191], v150 offset:54272
	ds_read_b128 v[192:195], v150 offset:55296
	ds_read_b128 v[198:201], v150 offset:56320
	global_load_lds_dwordx4 v[144:145], off
	v_lshl_add_u64 v[144:145], v[222:223], 0, s[46:47]
	s_mov_b32 m0, s31
	s_nop 0
	global_load_lds_dwordx4 v[144:145], off
	s_waitcnt vmcnt(10)
	s_setprio 1
	s_barrier
; DI unsigned pack2(float a, float b) { f32x2 v = {a, b}; hwbf16x2 r = __builtin_convertvector(v, hwbf16x2); return __builtin_bit_cast(unsigned, r); }
; DI float bflo(unsigned w) { return __uint_as_float(w << 16); }
; DI float bfhi(unsigned w) { return __uint_as_float(w & 0xffff0000u); }
; #define PG8_STAGE(bufoff, gbase, voff) do { _Pragma("unroll") for (int _i = 0; _i < 2; ++_i) \
;         __builtin_amdgcn_global_load_lds((const unsigned*)((const char*)(gbase) + (voff)[_i]), (LAS unsigned*)(lds + (bufoff) + ldsw + _i * 8192), 16, 0, 0); } while (0)
; #define PG8_WAIT_V(n) asm volatile("s_waitcnt vmcnt(" #n ")" ::: "memory")
; #define PG8_WAIT_L(n) asm volatile("s_waitcnt lgkmcnt(" #n ")" ::: "memory")
;     DI void operator()(const f32x4 (&acc)[2][2][4][2], const Unit& u, int wr, int wc, int fr, int fq) const {
;     ...
;             for (int m = 0; m < 4; ++m) { const size_t ro = (size_t)(row0 + ai * HALF + m * 16) * D + col0;
; #pragma unroll
;                 for (int bj = 0; bj < 2; ++bj) {
;                     f32x4 x0, x1;
;                     if constexpr (IB) { const u32x4 w = *(const u32x4*)((const bf16_t*)Xin + ro + bj * HALF);
;                         x0 = (f32x4){bflo(w[0]), bfhi(w[0]), bflo(w[1]), bfhi(w[1])}; x1 = (f32x4){bflo(w[2]), bfhi(w[2]), bflo(w[3]), bfhi(w[3])}; }
;                     else { x0 = *(const f32x4*)((const float*)Xin + ro + bj * HALF); x1 = *(const f32x4*)((const float*)Xin + ro + bj * HALF + 4); }
;                     x0 += acc[ai][bj][m][0] * sc[bj][0]; x1 += acc[ai][bj][m][1] * sc[bj][1];
;                     if constexpr (OB) { u32x4 o; o[0] = pack2(x0[0], x0[1]); o[1] = pack2(x0[2], x0[3]); o[2] = pack2(x1[0], x1[1]); o[3] = pack2(x1[2], x1[3]);
;                         *(u32x4*)((bf16_t*)Xout + ro + bj * HALF) = o; }
;                     else { *(f32x4*)((float*)Xout + ro + bj * HALF) = x0; *(f32x4*)((float*)Xout + ro + bj * HALF + 4) = x1; } } }
; template <class Map, class Epi>
; DI void gemm_phase(LAS unsigned char* lds, const Map& MP, const Epi& E, const int nM, const int nN, const int K, const int lda, const int ldb) {
;     ...
;             PG8_LDA(At, 1, 1); PG8_STAGE(PG8_SA(1, 0), a3, voffA);
;             PG8_BAR; PG8_WAIT_L(0); PG8_MMA(1, 0, At, B0); PG8_BAR; PG8_SCHED;
;             PG8_STAGE(PG8_SB(1, 1), b3 + hstepB, voffB);
;             PG8_WAIT_V(6); PG8_BAR; PG8_MMA(1, 1, At, B1); PG8_BAR;
	s_waitcnt lgkmcnt(7)
	v_mfma_f32_16x16x32_bf16 v[60:63], v[152:155], v[168:171], v[60:63]
	v_mfma_f32_16x16x32_bf16 v[56:59], v[160:163], v[168:171], v[56:59]
	s_waitcnt lgkmcnt(5)
	v_mfma_f32_16x16x32_bf16 v[44:47], v[152:155], v[176:179], v[44:47]
	v_mfma_f32_16x16x32_bf16 v[40:43], v[160:163], v[176:179], v[40:43]
	s_waitcnt lgkmcnt(3)
	v_mfma_f32_16x16x32_bf16 v[28:31], v[152:155], v[184:187], v[28:31]
	v_mfma_f32_16x16x32_bf16 v[24:27], v[160:163], v[184:187], v[24:27]
	s_waitcnt lgkmcnt(1)
	v_mfma_f32_16x16x32_bf16 v[12:15], v[152:155], v[192:195], v[12:15]
	v_mfma_f32_16x16x32_bf16 v[8:11], v[160:163], v[192:195], v[8:11]
	v_mfma_f32_16x16x32_bf16 v[60:63], v[156:159], v[172:175], v[60:63]
	s_add_u32 s8, s12, 0x160080
	s_addc_u32 s9, s13, 0
	v_mfma_f32_16x16x32_bf16 v[56:59], v[164:167], v[172:175], v[56:59]
	s_add_i32 s12, s14, s22
	v_mfma_f32_16x16x32_bf16 v[44:47], v[156:159], v[180:183], v[44:47]
	v_mfma_f32_16x16x32_bf16 v[40:43], v[164:167], v[180:183], v[40:43]
	v_mfma_f32_16x16x32_bf16 v[28:31], v[156:159], v[188:191], v[28:31]
	v_mfma_f32_16x16x32_bf16 v[24:27], v[164:167], v[188:191], v[24:27]
	s_waitcnt lgkmcnt(0)
	v_mfma_f32_16x16x32_bf16 v[12:15], v[156:159], v[198:201], v[12:15]
	s_setprio 0
	v_mfma_f32_16x16x32_bf16 v[8:11], v[164:167], v[198:201], v[8:11]
	s_barrier
	s_mov_b32 m0, s12
	s_nop 0
	global_load_lds_dwordx4 v132, s[8:9]
	s_add_i32 m0, s12, 0x2000
	s_nop 0
	global_load_lds_dwordx4 v128, s[8:9]
	s_waitcnt vmcnt(6)
	s_setprio 1
	s_barrier
	v_mfma_f32_16x16x32_bf16 v[52:55], v[202:205], v[168:171], v[52:55]
	v_mfma_f32_16x16x32_bf16 v[48:51], v[210:213], v[168:171], v[48:51]
	ds_read_b128 v[152:155], v149
	v_mfma_f32_16x16x32_bf16 v[36:39], v[202:205], v[176:179], v[36:39]
	v_mfma_f32_16x16x32_bf16 v[32:35], v[210:213], v[176:179], v[32:35]
	ds_read_b128 v[156:159], v149 offset:1024
	v_mfma_f32_16x16x32_bf16 v[20:23], v[202:205], v[184:187], v[20:23]
	v_mfma_f32_16x16x32_bf16 v[16:19], v[210:213], v[184:187], v[16:19]
	ds_read_b128 v[160:163], v149 offset:2048
	v_mfma_f32_16x16x32_bf16 v[4:7], v[202:205], v[192:195], v[4:7]
	v_mfma_f32_16x16x32_bf16 v[0:3], v[210:213], v[192:195], v[0:3]
	ds_read_b128 v[164:167], v149 offset:3072
	v_mfma_f32_16x16x32_bf16 v[52:55], v[206:209], v[172:175], v[52:55]
	s_add_i32 s3, s3, 2
	v_mfma_f32_16x16x32_bf16 v[48:51], v[214:217], v[172:175], v[48:51]
	s_add_u32 s39, s39, 0x100
	s_addc_u32 s44, s44, 0
	v_mfma_f32_16x16x32_bf16 v[36:39], v[206:209], v[180:183], v[36:39]
	s_cmpk_gt_u32 s3, 0x55
	v_mfma_f32_16x16x32_bf16 v[32:35], v[214:217], v[180:183], v[32:35]
	s_mov_b64 s[8:9], s[10:11]
	v_mfma_f32_16x16x32_bf16 v[20:23], v[206:209], v[188:191], v[20:23]
	v_mfma_f32_16x16x32_bf16 v[16:19], v[214:217], v[188:191], v[16:19]
	v_mfma_f32_16x16x32_bf16 v[4:7], v[206:209], v[198:201], v[4:7]
	s_setprio 0
	v_mfma_f32_16x16x32_bf16 v[0:3], v[214:217], v[198:201], v[0:3]
	s_barrier
	s_cbranch_scc0 .LBB1_2078
	s_waitcnt lgkmcnt(0)
	v_mov_b32_e32 v152, v147
	v_mov_b32_e32 v144, v146
	s_lshl_b32 s2, s2, 8
	s_add_i32 s2, s2, s29
	s_lshl_b32 s3, s38, 8
	v_add_u32_e32 v152, s2, v152
	s_or_b32 s3, s3, s52
	v_ashrrev_i32_e32 v153, 31, v152
	v_lshl_add_u32 v144, v144, 3, s3
	v_lshlrev_b64 v[152:153], 12, v[152:153]
	v_ashrrev_i32_e32 v145, 31, v144
	v_lshl_add_u64 v[152:153], s[4:5], 0, v[152:153]
	v_lshl_add_u64 v[144:145], v[144:145], 1, v[152:153]
	global_load_dwordx4 v[160:163], v[144:145], off
	global_load_dwordx4 v[164:167], v[144:145], off offset:256
	s_mov_b64 s[98:99], 0x10000
	v_lshl_add_u64 v[154:155], v[144:145], 0, s[98:99]
	global_load_dwordx4 v[168:171], v[154:155], off
	global_load_dwordx4 v[172:175], v[154:155], off offset:256
	s_mov_b64 s[98:99], 0x20000
	v_lshl_add_u64 v[154:155], v[144:145], 0, s[98:99]
	global_load_dwordx4 v[176:179], v[154:155], off
	global_load_dwordx4 v[180:183], v[154:155], off offset:256
	s_mov_b64 s[98:99], 0x30000
	v_lshl_add_u64 v[154:155], v[144:145], 0, s[98:99]
	global_load_dwordx4 v[184:187], v[154:155], off
	global_load_dwordx4 v[188:191], v[154:155], off offset:256
	s_mov_b64 s[98:99], 0x80000
	v_lshl_add_u64 v[154:155], v[144:145], 0, s[98:99]
	global_load_dwordx4 v[192:195], v[154:155], off
	global_load_dwordx4 v[198:201], v[154:155], off offset:256
	s_mov_b64 s[98:99], 0x90000
	v_lshl_add_u64 v[154:155], v[144:145], 0, s[98:99]
	global_load_dwordx4 v[202:205], v[154:155], off
	global_load_dwordx4 v[206:209], v[154:155], off offset:256
	s_mov_b64 s[98:99], 0xa0000
	v_lshl_add_u64 v[154:155], v[144:145], 0, s[98:99]
	global_load_dwordx4 v[210:213], v[154:155], off
	global_load_dwordx4 v[214:217], v[154:155], off offset:256
	s_mov_b64 s[98:99], 0xb0000
	v_lshl_add_u64 v[154:155], v[144:145], 0, s[98:99]
	global_load_dwordx4 v[248:251], v[154:155], off
	global_load_dwordx4 v[252:255], v[154:155], off offset:256
	s_waitcnt vmcnt(15)
	s_nop 1
	v_mov_b32_e32 v152, v160
	v_mov_b32_e32 v153, v161
	v_mov_b32_e32 v154, v162
	v_mov_b32_e32 v155, v163
	s_mov_b64 s[2:3], 0x10000
	s_mov_b32 s38, s37
	s_mov_b64 s[10:11], s[6:7]
	s_mov_b64 s[8:9], s[42:43]
	s_waitcnt lgkmcnt(0)
	v_lshlrev_b32_e32 v156, 16, v152
	v_and_b32_e32 v157, 0xffff0000, v152
	v_lshlrev_b32_e32 v152, 16, v153
	v_and_b32_e32 v153, 0xffff0000, v153
	v_lshlrev_b32_e32 v158, 16, v154
	v_and_b32_e32 v159, 0xffff0000, v154
	v_lshlrev_b32_e32 v154, 16, v155
	v_and_b32_e32 v155, 0xffff0000, v155
	v_pk_add_f32 v[126:127], v[126:127], v[152:153]
	v_pk_add_f32 v[124:125], v[124:125], v[156:157]
	v_pk_add_f32 v[152:153], v[122:123], v[154:155]
	v_pk_add_f32 v[122:123], v[120:121], v[158:159]
	v_cvt_pk_bf16_f32 v120, v124, v125
	v_cvt_pk_bf16_f32 v121, v126, v127
	v_cvt_pk_bf16_f32 v122, v122, v123
	v_cvt_pk_bf16_f32 v123, v152, v153
	global_store_dwordx4 v[144:145], v[120:123], off
	s_waitcnt vmcnt(15)
; DI unsigned pack2(float a, float b) { f32x2 v = {a, b}; hwbf16x2 r = __builtin_convertvector(v, hwbf16x2); return __builtin_bit_cast(unsigned, r); }
; DI float bflo(unsigned w) { return __uint_as_float(w << 16); }
; DI float bfhi(unsigned w) { return __uint_as_float(w & 0xffff0000u); }
;     DI void operator()(const f32x4 (&acc)[2][2][4][2], const Unit& u, int wr, int wc, int fr, int fq) const {
;     ...
;             for (int m = 0; m < 4; ++m) { const size_t ro = (size_t)(row0 + ai * HALF + m * 16) * D + col0;
; #pragma unroll
;                 for (int bj = 0; bj < 2; ++bj) {
;                     f32x4 x0, x1;
;                     if constexpr (IB) { const u32x4 w = *(const u32x4*)((const bf16_t*)Xin + ro + bj * HALF);
;                         x0 = (f32x4){bflo(w[0]), bfhi(w[0]), bflo(w[1]), bfhi(w[1])}; x1 = (f32x4){bflo(w[2]), bfhi(w[2]), bflo(w[3]), bfhi(w[3])}; }
;                     else { x0 = *(const f32x4*)((const float*)Xin + ro + bj * HALF); x1 = *(const f32x4*)((const float*)Xin + ro + bj * HALF + 4); }
;                     x0 += acc[ai][bj][m][0] * sc[bj][0]; x1 += acc[ai][bj][m][1] * sc[bj][1];
;                     if constexpr (OB) { u32x4 o; o[0] = pack2(x0[0], x0[1]); o[1] = pack2(x0[2], x0[3]); o[2] = pack2(x1[0], x1[1]); o[3] = pack2(x1[2], x1[3]);
;                         *(u32x4*)((bf16_t*)Xout + ro + bj * HALF) = o; }
;                     else { *(f32x4*)((float*)Xout + ro + bj * HALF) = x0; *(f32x4*)((float*)Xout + ro + bj * HALF + 4) = x1; } } }
	s_nop 1
	v_mov_b32_e32 v120, v164
	v_mov_b32_e32 v121, v165
	v_mov_b32_e32 v122, v166
	v_mov_b32_e32 v123, v167
	s_waitcnt lgkmcnt(0)
	v_lshlrev_b32_e32 v124, 16, v120
	v_and_b32_e32 v125, 0xffff0000, v120
	v_lshlrev_b32_e32 v120, 16, v121
	v_and_b32_e32 v121, 0xffff0000, v121
	v_lshlrev_b32_e32 v126, 16, v122
	v_and_b32_e32 v127, 0xffff0000, v122
	v_lshlrev_b32_e32 v122, 16, v123
	v_and_b32_e32 v123, 0xffff0000, v123
	v_pk_add_f32 v[116:117], v[116:117], v[124:125]
	v_pk_add_f32 v[118:119], v[118:119], v[120:121]
	v_pk_add_f32 v[120:121], v[114:115], v[122:123]
	v_pk_add_f32 v[114:115], v[112:113], v[126:127]
	v_cvt_pk_bf16_f32 v112, v116, v117
	v_lshl_add_u64 v[116:117], v[144:145], 0, s[2:3]
	s_mov_b32 s2, 0x10000
	v_cvt_pk_bf16_f32 v113, v118, v119
	v_add_co_u32_e32 v118, vcc, s2, v144
	v_cvt_pk_bf16_f32 v114, v114, v115
	v_cvt_pk_bf16_f32 v115, v120, v121
	v_addc_co_u32_e32 v119, vcc, 0, v145, vcc
	global_store_dwordx4 v[144:145], v[112:115], off offset:256
	s_waitcnt vmcnt(15)
	s_nop 1
	v_mov_b32_e32 v112, v168
	v_mov_b32_e32 v113, v169
	v_mov_b32_e32 v114, v170
	v_mov_b32_e32 v115, v171
	s_mov_b64 s[2:3], 0x20000
	s_waitcnt lgkmcnt(0)
	v_lshlrev_b32_e32 v120, 16, v112
	v_and_b32_e32 v121, 0xffff0000, v112
	v_lshlrev_b32_e32 v112, 16, v113
	v_and_b32_e32 v113, 0xffff0000, v113
	v_lshlrev_b32_e32 v122, 16, v114
	v_and_b32_e32 v123, 0xffff0000, v114
	v_lshlrev_b32_e32 v114, 16, v115
	v_and_b32_e32 v115, 0xffff0000, v115
	v_pk_add_f32 v[110:111], v[110:111], v[112:113]
	v_pk_add_f32 v[108:109], v[108:109], v[120:121]
	v_pk_add_f32 v[112:113], v[106:107], v[114:115]
	v_pk_add_f32 v[106:107], v[104:105], v[122:123]
	v_cvt_pk_bf16_f32 v104, v108, v109
	v_cvt_pk_bf16_f32 v105, v110, v111
	v_cvt_pk_bf16_f32 v106, v106, v107
	v_cvt_pk_bf16_f32 v107, v112, v113
	global_store_dwordx4 v[118:119], v[104:107], off
	s_waitcnt vmcnt(15)
	s_nop 1
	v_mov_b32_e32 v104, v172
	v_mov_b32_e32 v105, v173
	v_mov_b32_e32 v106, v174
	v_mov_b32_e32 v107, v175
	s_waitcnt lgkmcnt(0)
	v_lshlrev_b32_e32 v108, 16, v104
	v_and_b32_e32 v109, 0xffff0000, v104
	v_lshlrev_b32_e32 v104, 16, v105
	v_and_b32_e32 v105, 0xffff0000, v105
	v_lshlrev_b32_e32 v110, 16, v106
	v_and_b32_e32 v111, 0xffff0000, v106
	v_lshlrev_b32_e32 v106, 16, v107
	v_and_b32_e32 v107, 0xffff0000, v107
	v_pk_add_f32 v[100:101], v[100:101], v[108:109]
	v_pk_add_f32 v[102:103], v[102:103], v[104:105]
	v_pk_add_f32 v[104:105], v[98:99], v[106:107]
	v_pk_add_f32 v[98:99], v[96:97], v[110:111]
	v_cvt_pk_bf16_f32 v96, v100, v101
	v_lshl_add_u64 v[100:101], v[144:145], 0, s[2:3]
	s_mov_b32 s2, 0x20000
	v_cvt_pk_bf16_f32 v97, v102, v103
	v_add_co_u32_e32 v102, vcc, s2, v144
	v_cvt_pk_bf16_f32 v98, v98, v99
	v_cvt_pk_bf16_f32 v99, v104, v105
	v_addc_co_u32_e32 v103, vcc, 0, v145, vcc
	global_store_dwordx4 v[116:117], v[96:99], off offset:256
	s_waitcnt vmcnt(15)
	s_nop 1
	v_mov_b32_e32 v96, v176
	v_mov_b32_e32 v97, v177
	v_mov_b32_e32 v98, v178
	v_mov_b32_e32 v99, v179
	s_mov_b64 s[2:3], 0x30000
	s_waitcnt lgkmcnt(0)
	v_lshlrev_b32_e32 v104, 16, v96
	v_and_b32_e32 v105, 0xffff0000, v96
	v_lshlrev_b32_e32 v96, 16, v97
	v_and_b32_e32 v97, 0xffff0000, v97
	v_lshlrev_b32_e32 v106, 16, v98
	v_and_b32_e32 v107, 0xffff0000, v98
	v_lshlrev_b32_e32 v98, 16, v99
	v_and_b32_e32 v99, 0xffff0000, v99
	v_pk_add_f32 v[94:95], v[94:95], v[96:97]
	v_pk_add_f32 v[92:93], v[92:93], v[104:105]
	v_pk_add_f32 v[96:97], v[90:91], v[98:99]
	v_pk_add_f32 v[90:91], v[88:89], v[106:107]
	v_cvt_pk_bf16_f32 v88, v92, v93
	v_cvt_pk_bf16_f32 v89, v94, v95
	v_cvt_pk_bf16_f32 v90, v90, v91
	v_cvt_pk_bf16_f32 v91, v96, v97
	global_store_dwordx4 v[102:103], v[88:91], off
	s_waitcnt vmcnt(15)
	s_nop 1
	v_mov_b32_e32 v88, v180
	v_mov_b32_e32 v89, v181
	v_mov_b32_e32 v90, v182
	v_mov_b32_e32 v91, v183
	s_waitcnt lgkmcnt(0)
	v_lshlrev_b32_e32 v92, 16, v88
	v_and_b32_e32 v93, 0xffff0000, v88
	v_lshlrev_b32_e32 v88, 16, v89
	v_and_b32_e32 v89, 0xffff0000, v89
	v_lshlrev_b32_e32 v94, 16, v90
	v_and_b32_e32 v95, 0xffff0000, v90
	v_lshlrev_b32_e32 v90, 16, v91
	v_and_b32_e32 v91, 0xffff0000, v91
	v_pk_add_f32 v[86:87], v[86:87], v[88:89]
	v_pk_add_f32 v[84:85], v[84:85], v[92:93]
	v_pk_add_f32 v[88:89], v[82:83], v[90:91]
	v_pk_add_f32 v[82:83], v[80:81], v[94:95]
	v_cvt_pk_bf16_f32 v80, v84, v85
	v_cvt_pk_bf16_f32 v81, v86, v87
	v_cvt_pk_bf16_f32 v82, v82, v83
	v_cvt_pk_bf16_f32 v83, v88, v89
	global_store_dwordx4 v[100:101], v[80:83], off offset:256
	s_nop 1
	v_lshl_add_u64 v[80:81], v[144:145], 0, s[2:3]
	s_mov_b32 s2, 0x30000
	v_add_co_u32_e32 v86, vcc, s2, v144
	s_mov_b64 s[2:3], 0x80000
	s_nop 0
	v_addc_co_u32_e32 v87, vcc, 0, v145, vcc
	s_waitcnt vmcnt(15)
	s_nop 1
	v_mov_b32_e32 v82, v184
	v_mov_b32_e32 v83, v185
	v_mov_b32_e32 v84, v186
	v_mov_b32_e32 v85, v187
	s_waitcnt lgkmcnt(0)
	v_lshlrev_b32_e32 v88, 16, v82
	v_and_b32_e32 v89, 0xffff0000, v82
	v_lshlrev_b32_e32 v82, 16, v83
	v_and_b32_e32 v83, 0xffff0000, v83
	v_lshlrev_b32_e32 v90, 16, v84
	v_and_b32_e32 v91, 0xffff0000, v84
	v_lshlrev_b32_e32 v84, 16, v85
	v_and_b32_e32 v85, 0xffff0000, v85
	v_pk_add_f32 v[78:79], v[78:79], v[82:83]
	v_pk_add_f32 v[76:77], v[76:77], v[88:89]
	v_pk_add_f32 v[82:83], v[74:75], v[84:85]
	v_pk_add_f32 v[74:75], v[72:73], v[90:91]
	v_cvt_pk_bf16_f32 v72, v76, v77
	v_cvt_pk_bf16_f32 v73, v78, v79
	v_cvt_pk_bf16_f32 v74, v74, v75
	v_cvt_pk_bf16_f32 v75, v82, v83
	global_store_dwordx4 v[86:87], v[72:75], off
	s_waitcnt vmcnt(15)
	s_nop 1
	v_mov_b32_e32 v72, v188
	v_mov_b32_e32 v73, v189
	v_mov_b32_e32 v74, v190
	v_mov_b32_e32 v75, v191
	s_waitcnt lgkmcnt(0)
; DI unsigned pack2(float a, float b) { f32x2 v = {a, b}; hwbf16x2 r = __builtin_convertvector(v, hwbf16x2); return __builtin_bit_cast(unsigned, r); }
; DI float bflo(unsigned w) { return __uint_as_float(w << 16); }
; DI float bfhi(unsigned w) { return __uint_as_float(w & 0xffff0000u); }
;     DI void operator()(const f32x4 (&acc)[2][2][4][2], const Unit& u, int wr, int wc, int fr, int fq) const {
;     ...
;             for (int m = 0; m < 4; ++m) { const size_t ro = (size_t)(row0 + ai * HALF + m * 16) * D + col0;
; #pragma unroll
;                 for (int bj = 0; bj < 2; ++bj) {
;                     f32x4 x0, x1;
;                     if constexpr (IB) { const u32x4 w = *(const u32x4*)((const bf16_t*)Xin + ro + bj * HALF);
;                         x0 = (f32x4){bflo(w[0]), bfhi(w[0]), bflo(w[1]), bfhi(w[1])}; x1 = (f32x4){bflo(w[2]), bfhi(w[2]), bflo(w[3]), bfhi(w[3])}; }
;                     else { x0 = *(const f32x4*)((const float*)Xin + ro + bj * HALF); x1 = *(const f32x4*)((const float*)Xin + ro + bj * HALF + 4); }
;                     x0 += acc[ai][bj][m][0] * sc[bj][0]; x1 += acc[ai][bj][m][1] * sc[bj][1];
;                     if constexpr (OB) { u32x4 o; o[0] = pack2(x0[0], x0[1]); o[1] = pack2(x0[2], x0[3]); o[2] = pack2(x1[0], x1[1]); o[3] = pack2(x1[2], x1[3]);
;                         *(u32x4*)((bf16_t*)Xout + ro + bj * HALF) = o; }
;                     else { *(f32x4*)((float*)Xout + ro + bj * HALF) = x0; *(f32x4*)((float*)Xout + ro + bj * HALF + 4) = x1; } } }
	v_lshlrev_b32_e32 v76, 16, v72
	v_and_b32_e32 v77, 0xffff0000, v72
	v_lshlrev_b32_e32 v72, 16, v73
	v_and_b32_e32 v73, 0xffff0000, v73
	v_lshlrev_b32_e32 v78, 16, v74
	v_and_b32_e32 v79, 0xffff0000, v74
	v_lshlrev_b32_e32 v74, 16, v75
	v_and_b32_e32 v75, 0xffff0000, v75
	v_pk_add_f32 v[70:71], v[70:71], v[72:73]
	v_pk_add_f32 v[68:69], v[68:69], v[76:77]
	v_pk_add_f32 v[72:73], v[66:67], v[74:75]
	v_pk_add_f32 v[66:67], v[64:65], v[78:79]
	v_cvt_pk_bf16_f32 v64, v68, v69
	v_cvt_pk_bf16_f32 v65, v70, v71
	v_cvt_pk_bf16_f32 v66, v66, v67
	v_cvt_pk_bf16_f32 v67, v72, v73
	global_store_dwordx4 v[80:81], v[64:67], off offset:256
	s_nop 1
	v_lshl_add_u64 v[64:65], v[144:145], 0, s[2:3]
	s_mov_b32 s2, 0x80000
	v_add_co_u32_e32 v70, vcc, s2, v144
	s_mov_b64 s[2:3], 0x90000
	s_nop 0
	v_addc_co_u32_e32 v71, vcc, 0, v145, vcc
	s_waitcnt vmcnt(15)
	s_nop 1
	v_mov_b32_e32 v66, v192
	v_mov_b32_e32 v67, v193
	v_mov_b32_e32 v68, v194
	v_mov_b32_e32 v69, v195
	s_waitcnt lgkmcnt(0)
	v_lshlrev_b32_e32 v72, 16, v66
	v_and_b32_e32 v73, 0xffff0000, v66
	v_lshlrev_b32_e32 v66, 16, v67
	v_and_b32_e32 v67, 0xffff0000, v67
	v_lshlrev_b32_e32 v74, 16, v68
	v_and_b32_e32 v75, 0xffff0000, v68
	v_lshlrev_b32_e32 v68, 16, v69
	v_and_b32_e32 v69, 0xffff0000, v69
	v_pk_add_f32 v[62:63], v[62:63], v[66:67]
	v_pk_add_f32 v[60:61], v[60:61], v[72:73]
	v_pk_add_f32 v[66:67], v[58:59], v[68:69]
	v_pk_add_f32 v[58:59], v[56:57], v[74:75]
	v_cvt_pk_bf16_f32 v56, v60, v61
	v_cvt_pk_bf16_f32 v57, v62, v63
	v_cvt_pk_bf16_f32 v58, v58, v59
	v_cvt_pk_bf16_f32 v59, v66, v67
	global_store_dwordx4 v[70:71], v[56:59], off
	s_waitcnt vmcnt(15)
	s_nop 1
	v_mov_b32_e32 v56, v198
	v_mov_b32_e32 v57, v199
	v_mov_b32_e32 v58, v200
	v_mov_b32_e32 v59, v201
	s_waitcnt lgkmcnt(0)
	v_lshlrev_b32_e32 v60, 16, v56
	v_and_b32_e32 v61, 0xffff0000, v56
	v_lshlrev_b32_e32 v56, 16, v57
	v_and_b32_e32 v57, 0xffff0000, v57
	v_lshlrev_b32_e32 v62, 16, v58
	v_and_b32_e32 v63, 0xffff0000, v58
	v_lshlrev_b32_e32 v58, 16, v59
	v_and_b32_e32 v59, 0xffff0000, v59
	v_pk_add_f32 v[54:55], v[54:55], v[56:57]
	v_pk_add_f32 v[52:53], v[52:53], v[60:61]
	v_pk_add_f32 v[56:57], v[50:51], v[58:59]
	v_pk_add_f32 v[50:51], v[48:49], v[62:63]
	v_cvt_pk_bf16_f32 v48, v52, v53
	v_cvt_pk_bf16_f32 v49, v54, v55
	v_cvt_pk_bf16_f32 v50, v50, v51
	v_cvt_pk_bf16_f32 v51, v56, v57
	global_store_dwordx4 v[64:65], v[48:51], off offset:256
	s_nop 1
	v_lshl_add_u64 v[48:49], v[144:145], 0, s[2:3]
	s_mov_b32 s2, 0x90000
	v_add_co_u32_e32 v54, vcc, s2, v144
	s_mov_b64 s[2:3], 0xa0000
	s_nop 0
	v_addc_co_u32_e32 v55, vcc, 0, v145, vcc
	s_waitcnt vmcnt(15)
	s_nop 1
	v_mov_b32_e32 v50, v202
	v_mov_b32_e32 v51, v203
	v_mov_b32_e32 v52, v204
	v_mov_b32_e32 v53, v205
	s_waitcnt lgkmcnt(0)
	v_lshlrev_b32_e32 v56, 16, v50
	v_and_b32_e32 v57, 0xffff0000, v50
	v_lshlrev_b32_e32 v50, 16, v51
	v_and_b32_e32 v51, 0xffff0000, v51
	v_lshlrev_b32_e32 v58, 16, v52
	v_and_b32_e32 v59, 0xffff0000, v52
	v_lshlrev_b32_e32 v52, 16, v53
	v_and_b32_e32 v53, 0xffff0000, v53
	v_pk_add_f32 v[46:47], v[46:47], v[50:51]
	v_pk_add_f32 v[44:45], v[44:45], v[56:57]
	v_pk_add_f32 v[50:51], v[42:43], v[52:53]
	v_pk_add_f32 v[42:43], v[40:41], v[58:59]
	v_cvt_pk_bf16_f32 v40, v44, v45
	v_cvt_pk_bf16_f32 v41, v46, v47
	v_cvt_pk_bf16_f32 v42, v42, v43
	v_cvt_pk_bf16_f32 v43, v50, v51
	global_store_dwordx4 v[54:55], v[40:43], off
	s_waitcnt vmcnt(15)
	s_nop 1
	v_mov_b32_e32 v40, v206
	v_mov_b32_e32 v41, v207
	v_mov_b32_e32 v42, v208
	v_mov_b32_e32 v43, v209
	s_waitcnt lgkmcnt(0)
; DI unsigned pack2(float a, float b) { f32x2 v = {a, b}; hwbf16x2 r = __builtin_convertvector(v, hwbf16x2); return __builtin_bit_cast(unsigned, r); }
; DI float bflo(unsigned w) { return __uint_as_float(w << 16); }
; DI float bfhi(unsigned w) { return __uint_as_float(w & 0xffff0000u); }
;     DI void operator()(const f32x4 (&acc)[2][2][4][2], const Unit& u, int wr, int wc, int fr, int fq) const {
;     ...
;             for (int m = 0; m < 4; ++m) { const size_t ro = (size_t)(row0 + ai * HALF + m * 16) * D + col0;
; #pragma unroll
;                 for (int bj = 0; bj < 2; ++bj) {
;                     f32x4 x0, x1;
;                     if constexpr (IB) { const u32x4 w = *(const u32x4*)((const bf16_t*)Xin + ro + bj * HALF);
;                         x0 = (f32x4){bflo(w[0]), bfhi(w[0]), bflo(w[1]), bfhi(w[1])}; x1 = (f32x4){bflo(w[2]), bfhi(w[2]), bflo(w[3]), bfhi(w[3])}; }
;                     else { x0 = *(const f32x4*)((const float*)Xin + ro + bj * HALF); x1 = *(const f32x4*)((const float*)Xin + ro + bj * HALF + 4); }
;                     x0 += acc[ai][bj][m][0] * sc[bj][0]; x1 += acc[ai][bj][m][1] * sc[bj][1];
;                     if constexpr (OB) { u32x4 o; o[0] = pack2(x0[0], x0[1]); o[1] = pack2(x0[2], x0[3]); o[2] = pack2(x1[0], x1[1]); o[3] = pack2(x1[2], x1[3]);
;                         *(u32x4*)((bf16_t*)Xout + ro + bj * HALF) = o; }
;                     else { *(f32x4*)((float*)Xout + ro + bj * HALF) = x0; *(f32x4*)((float*)Xout + ro + bj * HALF + 4) = x1; } } }
; template <class Map, class Epi>
; DI void gemm_phase(LAS unsigned char* lds, const Map& MP, const Epi& E, const int nM, const int nN, const int K, const int lda, const int ldb) {
;     ...
;         { int frr = fr, fqq = fq; asm volatile("" : "+v"(frr), "+v"(fqq)); E(acc, cur, wr, wc, frr, fqq); }
;         if (!has_next) break;
	v_lshlrev_b32_e32 v44, 16, v40
	v_and_b32_e32 v45, 0xffff0000, v40
	v_lshlrev_b32_e32 v40, 16, v41
	v_and_b32_e32 v41, 0xffff0000, v41
	v_lshlrev_b32_e32 v46, 16, v42
	v_and_b32_e32 v47, 0xffff0000, v42
	v_lshlrev_b32_e32 v42, 16, v43
	v_and_b32_e32 v43, 0xffff0000, v43
	v_pk_add_f32 v[38:39], v[38:39], v[40:41]
	v_pk_add_f32 v[36:37], v[36:37], v[44:45]
	v_pk_add_f32 v[40:41], v[34:35], v[42:43]
	v_pk_add_f32 v[34:35], v[32:33], v[46:47]
	v_cvt_pk_bf16_f32 v32, v36, v37
	v_cvt_pk_bf16_f32 v33, v38, v39
	v_cvt_pk_bf16_f32 v34, v34, v35
	v_cvt_pk_bf16_f32 v35, v40, v41
	global_store_dwordx4 v[48:49], v[32:35], off offset:256
	s_nop 1
	v_lshl_add_u64 v[32:33], v[144:145], 0, s[2:3]
	s_mov_b32 s2, 0xa0000
	v_add_co_u32_e32 v38, vcc, s2, v144
	s_mov_b64 s[2:3], 0xb0000
	s_nop 0
	v_addc_co_u32_e32 v39, vcc, 0, v145, vcc
	s_waitcnt vmcnt(15)
	s_nop 1
	v_mov_b32_e32 v34, v210
	v_mov_b32_e32 v35, v211
	v_mov_b32_e32 v36, v212
	v_mov_b32_e32 v37, v213
	s_waitcnt lgkmcnt(0)
	v_lshlrev_b32_e32 v40, 16, v34
	v_and_b32_e32 v41, 0xffff0000, v34
	v_lshlrev_b32_e32 v34, 16, v35
	v_and_b32_e32 v35, 0xffff0000, v35
	v_lshlrev_b32_e32 v42, 16, v36
	v_and_b32_e32 v43, 0xffff0000, v36
	v_lshlrev_b32_e32 v36, 16, v37
	v_and_b32_e32 v37, 0xffff0000, v37
	v_pk_add_f32 v[30:31], v[30:31], v[34:35]
	v_pk_add_f32 v[28:29], v[28:29], v[40:41]
	v_pk_add_f32 v[34:35], v[26:27], v[36:37]
	v_pk_add_f32 v[26:27], v[24:25], v[42:43]
	v_cvt_pk_bf16_f32 v24, v28, v29
	v_cvt_pk_bf16_f32 v25, v30, v31
	v_cvt_pk_bf16_f32 v26, v26, v27
	v_cvt_pk_bf16_f32 v27, v34, v35
	global_store_dwordx4 v[38:39], v[24:27], off
	s_waitcnt vmcnt(15)
	s_nop 1
	v_mov_b32_e32 v24, v214
	v_mov_b32_e32 v25, v215
	v_mov_b32_e32 v26, v216
	v_mov_b32_e32 v27, v217
	s_waitcnt lgkmcnt(0)
	v_lshlrev_b32_e32 v28, 16, v24
	v_and_b32_e32 v29, 0xffff0000, v24
	v_lshlrev_b32_e32 v24, 16, v25
	v_and_b32_e32 v25, 0xffff0000, v25
	v_lshlrev_b32_e32 v30, 16, v26
	v_and_b32_e32 v31, 0xffff0000, v26
	v_lshlrev_b32_e32 v26, 16, v27
	v_and_b32_e32 v27, 0xffff0000, v27
	v_pk_add_f32 v[22:23], v[22:23], v[24:25]
	v_pk_add_f32 v[20:21], v[20:21], v[28:29]
	v_pk_add_f32 v[24:25], v[18:19], v[26:27]
	v_pk_add_f32 v[18:19], v[16:17], v[30:31]
	v_cvt_pk_bf16_f32 v16, v20, v21
	v_cvt_pk_bf16_f32 v17, v22, v23
	v_cvt_pk_bf16_f32 v18, v18, v19
	v_cvt_pk_bf16_f32 v19, v24, v25
	global_store_dwordx4 v[32:33], v[16:19], off offset:256
	s_nop 1
	v_lshl_add_u64 v[16:17], v[144:145], 0, s[2:3]
	s_mov_b32 s2, 0xb0000
	v_add_co_u32_e32 v22, vcc, s2, v144
	s_mov_b32 s2, s53
	s_nop 0
	v_addc_co_u32_e32 v23, vcc, 0, v145, vcc
	s_waitcnt vmcnt(15)
	s_nop 1
	v_mov_b32_e32 v18, v248
	v_mov_b32_e32 v19, v249
	v_mov_b32_e32 v20, v250
	v_mov_b32_e32 v21, v251
	s_and_b64 vcc, exec, s[40:41]
	s_waitcnt lgkmcnt(0)
	v_lshlrev_b32_e32 v24, 16, v18
	v_and_b32_e32 v25, 0xffff0000, v18
	v_lshlrev_b32_e32 v18, 16, v19
	v_and_b32_e32 v19, 0xffff0000, v19
	v_lshlrev_b32_e32 v26, 16, v20
	v_and_b32_e32 v27, 0xffff0000, v20
	v_lshlrev_b32_e32 v20, 16, v21
	v_and_b32_e32 v21, 0xffff0000, v21
	v_pk_add_f32 v[14:15], v[14:15], v[18:19]
	v_pk_add_f32 v[12:13], v[12:13], v[24:25]
	v_pk_add_f32 v[18:19], v[10:11], v[20:21]
	v_pk_add_f32 v[10:11], v[8:9], v[26:27]
	v_cvt_pk_bf16_f32 v8, v12, v13
	v_cvt_pk_bf16_f32 v9, v14, v15
	v_cvt_pk_bf16_f32 v10, v10, v11
	v_cvt_pk_bf16_f32 v11, v18, v19
	global_store_dwordx4 v[22:23], v[8:11], off
	s_waitcnt vmcnt(15)
	s_nop 1
	v_mov_b32_e32 v8, v252
	v_mov_b32_e32 v9, v253
	v_mov_b32_e32 v10, v254
	v_mov_b32_e32 v11, v255
	s_waitcnt lgkmcnt(0)
	v_lshlrev_b32_e32 v12, 16, v8
	v_and_b32_e32 v13, 0xffff0000, v8
	v_lshlrev_b32_e32 v8, 16, v9
	v_and_b32_e32 v9, 0xffff0000, v9
	v_lshlrev_b32_e32 v14, 16, v10
	v_and_b32_e32 v15, 0xffff0000, v10
	v_lshlrev_b32_e32 v10, 16, v11
	v_and_b32_e32 v11, 0xffff0000, v11
	v_pk_add_f32 v[6:7], v[6:7], v[8:9]
	v_pk_add_f32 v[4:5], v[4:5], v[12:13]
	v_pk_add_f32 v[8:9], v[2:3], v[10:11]
	v_pk_add_f32 v[2:3], v[0:1], v[14:15]
	v_cvt_pk_bf16_f32 v0, v4, v5
	v_cvt_pk_bf16_f32 v1, v6, v7
	v_cvt_pk_bf16_f32 v2, v2, v3
	v_cvt_pk_bf16_f32 v3, v8, v9
	global_store_dwordx4 v[16:17], v[0:3], off offset:256
	s_cbranch_vccz .LBB1_2071
	s_waitcnt vmcnt(0)
	s_cmpk_gt_u32 s17, 0xff
	s_cbranch_scc1 .LBB1_2082
	s_barrier

;     DI const char* a(const Unit& u) const { return (const char*)(A + (size_t)u.pm * BM * lda); }
;     DI const char* a(const Unit& u) const { return (const char*)(A + (size_t)u.pm * BM * 2048 + (u.pn >> 1) * 512); }
;     DI const char* a(const Unit& u) const { return (const char*)((u.pn < 12 ? A1 : A2) + (size_t)u.pm * BM * 512); }
; #define PG8_STAGE(bufoff, gbase, voff) do { _Pragma("unroll") for (int _i = 0; _i < 2; ++_i) \
;         __builtin_amdgcn_global_load_lds((const unsigned*)((const char*)(gbase) + (voff)[_i]), (LAS unsigned*)(lds + (bufoff) + ldsw + _i * 8192), 16, 0, 0); } while (0)
; #define PG8_LDA(dst, b, h) do { _Pragma("unroll") for (int m = 0; m < 4; ++m) _Pragma("unroll") for (int k = 0; k < 2; ++k) dst[m][k] = *(const LAS bf16x8*)(lds + PG8_SA(b, h) + aoff + m * 2048 + k * 1024); } while (0)
; #define PG8_LDB(dst, b, h) do { _Pragma("unroll") for (int n = 0; n < 2; ++n) _Pragma("unroll") for (int k = 0; k < 2; ++k) dst[n][k] = *(const LAS bf16x8*)(lds + PG8_SB(b, h) + boff + n * 2048 + k * 1024); } while (0)
; template <class Map, class Epi>
; DI void gemm_phase(LAS unsigned char* lds, const Map& MP, const Epi& E, const int nM, const int nN, const int K, const int lda, const int ldb) {
;     ...
;         const bool has_next = sched_next(ui + 1, nM, nN, G, cblk, nxt);
;         const char* nA = has_next ? MP.a(nxt) : cA; const char* nB = has_next ? MP.b(nxt) : cB;
;         for (int t = 0; t < nt; t += 2) {
;             const bool last = (t == nt - 2);
;             const char* a1 = cA + (size_t)(t + 1) * kstep;
;             const char* a2 = last ? nA : cA + (size_t)(t + 2) * kstep; const char* b2 = last ? nB : cB + (size_t)(t + 2) * kstep;
;             const char* a3 = a2 + kstep; const char* b3 = b2 + kstep;
;             PG8_LDB(B0, 0, 0); PG8_SCHED; PG8_LDA(At, 0, 0); PG8_STAGE(PG8_SA(1, 1), a1 + hstepA, voffA);
;             PG8_WAIT_L(8); PG8_BAR; PG8_WAIT_L(0); PG8_MMA(0, 0, At, B0); PG8_BAR; PG8_SCHED;
;             PG8_LDB(B1, 0, 1); PG8_STAGE(PG8_SB(0, 0), b2, voffB);
;             PG8_BAR; PG8_WAIT_L(0); PG8_MMA(0, 1, At, B1); PG8_BAR;
;             PG8_LDA(At, 0, 1); PG8_STAGE(PG8_SA(0, 0), a2, voffA);
;             PG8_BAR; PG8_WAIT_L(0); PG8_MMA(1, 0, At, B0); PG8_BAR; PG8_SCHED;
;             PG8_STAGE(PG8_SB(0, 1), b2 + hstepB, voffB);
;             PG8_WAIT_V(6); PG8_BAR; PG8_MMA(1, 1, At, B1); PG8_BAR;
.LBB1_2339:
	s_add_u32 s12, s10, 0xfff80080
	s_addc_u32 s13, s11, -1
	s_cmp_eq_u32 s3, 4
	s_cselect_b32 s15, s38, s13
	s_cselect_b32 s14, s39, s12
	s_cselect_b32 s13, s48, s56
	s_cselect_b32 s12, s49, s53
	s_add_i32 m0, s9, 0xc000
	ds_read_b128 v[168:171], v166
	ds_read_b128 v[172:175], v166 offset:1024
	ds_read_b128 v[176:179], v166 offset:2048
	ds_read_b128 v[180:183], v166 offset:3072
	ds_read_b128 v[184:187], v166 offset:4096
	ds_read_b128 v[188:191], v166 offset:5120
	ds_read_b128 v[192:195], v166 offset:6144
	ds_read_b128 v[198:201], v166 offset:7168
	global_load_lds_dwordx4 v154, s[10:11]
	s_add_i32 m0, s9, 0xe000
	s_nop 0
	global_load_lds_dwordx4 v152, s[10:11]
	s_waitcnt lgkmcnt(8)
	s_setprio 1
	s_barrier
	s_waitcnt lgkmcnt(7)
	v_mfma_f32_16x16x32_bf16 v[140:143], v[40:43], v[168:171], v[140:143]
	v_mfma_f32_16x16x32_bf16 v[136:139], v[56:59], v[168:171], v[136:139]
	s_waitcnt lgkmcnt(5)
	v_mfma_f32_16x16x32_bf16 v[124:127], v[40:43], v[176:179], v[124:127]
	v_mfma_f32_16x16x32_bf16 v[120:123], v[56:59], v[176:179], v[120:123]
	s_waitcnt lgkmcnt(3)
	v_mfma_f32_16x16x32_bf16 v[108:111], v[40:43], v[184:187], v[108:111]
	v_mfma_f32_16x16x32_bf16 v[104:107], v[56:59], v[184:187], v[104:107]
	s_waitcnt lgkmcnt(1)
	v_mfma_f32_16x16x32_bf16 v[92:95], v[40:43], v[192:195], v[92:95]
	v_mfma_f32_16x16x32_bf16 v[88:91], v[56:59], v[192:195], v[88:91]
	v_mfma_f32_16x16x32_bf16 v[140:143], v[44:47], v[172:175], v[140:143]
	s_add_i32 s57, s35, s22
	v_mfma_f32_16x16x32_bf16 v[136:139], v[60:63], v[172:175], v[136:139]
	v_lshl_add_u64 v[160:161], s[12:13], 0, v[148:149]
	v_mfma_f32_16x16x32_bf16 v[124:127], v[44:47], v[180:183], v[124:127]
	v_lshl_add_u64 v[218:219], s[12:13], 0, v[144:145]
	v_mfma_f32_16x16x32_bf16 v[120:123], v[60:63], v[180:183], v[120:123]
	v_mfma_f32_16x16x32_bf16 v[108:111], v[44:47], v[188:191], v[108:111]
	v_mfma_f32_16x16x32_bf16 v[104:107], v[60:63], v[188:191], v[104:107]
	s_waitcnt lgkmcnt(0)
	v_mfma_f32_16x16x32_bf16 v[92:95], v[44:47], v[198:201], v[92:95]
	s_setprio 0
	v_mfma_f32_16x16x32_bf16 v[88:91], v[60:63], v[198:201], v[88:91]
	s_barrier
	s_mov_b32 m0, s57
	ds_read_b128 v[202:205], v167
	ds_read_b128 v[206:209], v167 offset:1024
	ds_read_b128 v[210:213], v167 offset:2048
	ds_read_b128 v[214:217], v167 offset:3072
	global_load_lds_dwordx4 v[160:161], off
	s_add_i32 m0, s57, 0x2000
	s_nop 0
	global_load_lds_dwordx4 v[218:219], off
	s_setprio 1
	s_barrier
	s_waitcnt lgkmcnt(3)
	v_mfma_f32_16x16x32_bf16 v[132:135], v[202:205], v[168:171], v[132:135]
	s_waitcnt lgkmcnt(1)
	v_mfma_f32_16x16x32_bf16 v[128:131], v[210:213], v[168:171], v[128:131]
	v_mfma_f32_16x16x32_bf16 v[116:119], v[202:205], v[176:179], v[116:119]
	v_mfma_f32_16x16x32_bf16 v[112:115], v[210:213], v[176:179], v[112:115]
	v_mfma_f32_16x16x32_bf16 v[100:103], v[202:205], v[184:187], v[100:103]
	v_mfma_f32_16x16x32_bf16 v[96:99], v[210:213], v[184:187], v[96:99]
	v_mfma_f32_16x16x32_bf16 v[84:87], v[202:205], v[192:195], v[84:87]
	v_mfma_f32_16x16x32_bf16 v[80:83], v[210:213], v[192:195], v[80:83]
	v_mfma_f32_16x16x32_bf16 v[132:135], v[206:209], v[172:175], v[132:135]
	v_lshl_add_u64 v[222:223], s[14:15], 0, v[146:147]
	s_mov_b32 m0, s9
	s_waitcnt lgkmcnt(0)
	v_mfma_f32_16x16x32_bf16 v[128:131], v[214:217], v[172:175], v[128:131]
	v_lshl_add_u64 v[220:221], s[14:15], 0, v[150:151]
	v_mfma_f32_16x16x32_bf16 v[116:119], v[206:209], v[180:183], v[116:119]
	v_mfma_f32_16x16x32_bf16 v[112:115], v[214:217], v[180:183], v[112:115]
	v_mfma_f32_16x16x32_bf16 v[100:103], v[206:209], v[188:191], v[100:103]
	v_mfma_f32_16x16x32_bf16 v[96:99], v[214:217], v[188:191], v[96:99]
	v_mfma_f32_16x16x32_bf16 v[84:87], v[206:209], v[198:201], v[84:87]
	s_setprio 0
	v_mfma_f32_16x16x32_bf16 v[80:83], v[214:217], v[198:201], v[80:83]
	s_barrier
	ds_read_b128 v[168:171], v166 offset:16384
	ds_read_b128 v[172:175], v166 offset:17408
	ds_read_b128 v[176:179], v166 offset:18432
	ds_read_b128 v[180:183], v166 offset:19456
	ds_read_b128 v[184:187], v166 offset:20480
	ds_read_b128 v[188:191], v166 offset:21504
	ds_read_b128 v[192:195], v166 offset:22528
	ds_read_b128 v[198:201], v166 offset:23552
	global_load_lds_dwordx4 v[220:221], off
	s_mov_b32 m0, s24
	s_nop 0
	global_load_lds_dwordx4 v[222:223], off
	s_waitcnt vmcnt(10)
	s_setprio 1
	s_barrier
	s_waitcnt lgkmcnt(7)
	v_mfma_f32_16x16x32_bf16 v[76:79], v[40:43], v[168:171], v[76:79]
	v_mfma_f32_16x16x32_bf16 v[72:75], v[56:59], v[168:171], v[72:75]
	s_waitcnt lgkmcnt(5)
	v_mfma_f32_16x16x32_bf16 v[52:55], v[40:43], v[176:179], v[52:55]
	v_mfma_f32_16x16x32_bf16 v[48:51], v[56:59], v[176:179], v[48:51]
	s_waitcnt lgkmcnt(3)
	v_mfma_f32_16x16x32_bf16 v[28:31], v[40:43], v[184:187], v[28:31]
	v_mfma_f32_16x16x32_bf16 v[24:27], v[56:59], v[184:187], v[24:27]
	s_waitcnt lgkmcnt(1)
	v_mfma_f32_16x16x32_bf16 v[12:15], v[40:43], v[192:195], v[12:15]
	v_mfma_f32_16x16x32_bf16 v[8:11], v[56:59], v[192:195], v[8:11]
	v_mfma_f32_16x16x32_bf16 v[76:79], v[44:47], v[172:175], v[76:79]
	s_add_u32 s58, s12, 0x20000
	s_addc_u32 s59, s13, 0
	v_mfma_f32_16x16x32_bf16 v[72:75], v[60:63], v[172:175], v[72:75]
	s_add_i32 s57, s36, s22
	v_mfma_f32_16x16x32_bf16 v[52:55], v[44:47], v[180:183], v[52:55]
	v_mfma_f32_16x16x32_bf16 v[48:51], v[60:63], v[180:183], v[48:51]
	v_mfma_f32_16x16x32_bf16 v[28:31], v[44:47], v[188:191], v[28:31]
	v_mfma_f32_16x16x32_bf16 v[24:27], v[60:63], v[188:191], v[24:27]
	s_waitcnt lgkmcnt(0)
	v_mfma_f32_16x16x32_bf16 v[12:15], v[44:47], v[198:201], v[12:15]
	s_setprio 0
	v_mfma_f32_16x16x32_bf16 v[8:11], v[60:63], v[198:201], v[8:11]
	s_barrier
; #define PG8_STAGE(bufoff, gbase, voff) do { _Pragma("unroll") for (int _i = 0; _i < 2; ++_i) \
;         __builtin_amdgcn_global_load_lds((const unsigned*)((const char*)(gbase) + (voff)[_i]), (LAS unsigned*)(lds + (bufoff) + ldsw + _i * 8192), 16, 0, 0); } while (0)
; #define PG8_LDA(dst, b, h) do { _Pragma("unroll") for (int m = 0; m < 4; ++m) _Pragma("unroll") for (int k = 0; k < 2; ++k) dst[m][k] = *(const LAS bf16x8*)(lds + PG8_SA(b, h) + aoff + m * 2048 + k * 1024); } while (0)
; #define PG8_LDB(dst, b, h) do { _Pragma("unroll") for (int n = 0; n < 2; ++n) _Pragma("unroll") for (int k = 0; k < 2; ++k) dst[n][k] = *(const LAS bf16x8*)(lds + PG8_SB(b, h) + boff + n * 2048 + k * 1024); } while (0)
; #define PG8_WAIT_V(n) asm volatile("s_waitcnt vmcnt(" #n ")" ::: "memory")
; #define PG8_WAIT_L(n) asm volatile("s_waitcnt lgkmcnt(" #n ")" ::: "memory")
; #define PG8_BAR __builtin_amdgcn_s_barrier()
; #define PG8_SCHED __builtin_amdgcn_sched_barrier(0)
; template <class Map, class Epi>
; DI void gemm_phase(LAS unsigned char* lds, const Map& MP, const Epi& E, const int nM, const int nN, const int K, const int lda, const int ldb) {
;     ...
;             PG8_LDB(B0, 0, 0); PG8_SCHED; PG8_LDA(At, 0, 0); PG8_STAGE(PG8_SA(1, 1), a1 + hstepA, voffA);
;             PG8_WAIT_L(8); PG8_BAR; PG8_WAIT_L(0); PG8_MMA(0, 0, At, B0); PG8_BAR; PG8_SCHED;
;             PG8_LDB(B1, 0, 1); PG8_STAGE(PG8_SB(0, 0), b2, voffB);
;             PG8_BAR; PG8_WAIT_L(0); PG8_MMA(0, 1, At, B1); PG8_BAR;
;             PG8_LDA(At, 0, 1); PG8_STAGE(PG8_SA(0, 0), a2, voffA);
;             PG8_BAR; PG8_WAIT_L(0); PG8_MMA(1, 0, At, B0); PG8_BAR; PG8_SCHED;
;             PG8_STAGE(PG8_SB(0, 1), b2 + hstepB, voffB);
;             PG8_WAIT_V(6); PG8_BAR; PG8_MMA(1, 1, At, B1); PG8_BAR;
;             PG8_LDB(B0, 1, 0); PG8_SCHED; PG8_LDA(At, 1, 0); PG8_STAGE(PG8_SA(0, 1), a2 + hstepA, voffA);
;             PG8_WAIT_L(8); PG8_BAR; PG8_WAIT_L(0); PG8_MMA(0, 0, At, B0); PG8_BAR; PG8_SCHED;
;             PG8_LDB(B1, 1, 1); PG8_STAGE(PG8_SB(1, 0), b3, voffB);
;             PG8_BAR; PG8_WAIT_L(0); PG8_MMA(0, 1, At, B1); PG8_BAR;
;             PG8_LDA(At, 1, 1); PG8_STAGE(PG8_SA(1, 0), a3, voffA);
;             PG8_BAR; PG8_WAIT_L(0); PG8_MMA(1, 0, At, B0); PG8_BAR; PG8_SCHED;
;             PG8_STAGE(PG8_SB(1, 1), b3 + hstepB, voffB);
;             PG8_WAIT_V(6); PG8_BAR; PG8_MMA(1, 1, At, B1); PG8_BAR;
	s_mov_b32 m0, s57
	s_nop 0
	global_load_lds_dwordx4 v148, s[58:59]
	s_add_i32 m0, s57, 0x2000
	s_nop 0
	global_load_lds_dwordx4 v144, s[58:59]
	s_waitcnt vmcnt(6)
	s_setprio 1
	s_barrier
	v_mfma_f32_16x16x32_bf16 v[36:39], v[202:205], v[176:179], v[36:39]
	v_mfma_f32_16x16x32_bf16 v[32:35], v[210:213], v[176:179], v[32:35]
	v_mfma_f32_16x16x32_bf16 v[20:23], v[202:205], v[184:187], v[20:23]
	v_mfma_f32_16x16x32_bf16 v[16:19], v[210:213], v[184:187], v[16:19]
	v_mfma_f32_16x16x32_bf16 v[4:7], v[202:205], v[192:195], v[4:7]
	v_mfma_f32_16x16x32_bf16 v[0:3], v[210:213], v[192:195], v[0:3]
	v_mfma_f32_16x16x32_bf16 v[40:43], v[202:205], v[168:171], v[68:71]
	s_add_i32 s57, 0, 0x18000
	v_add_u32_e32 v68, s57, v164
	ds_read_b128 v[56:59], v68
	ds_read_b128 v[60:63], v68 offset:1024
	v_mfma_f32_16x16x32_bf16 v[44:47], v[210:213], v[168:171], v[64:67]
	ds_read_b128 v[64:67], v68 offset:2048
	ds_read_b128 v[68:71], v68 offset:3072
	v_mfma_f32_16x16x32_bf16 v[36:39], v[206:209], v[180:183], v[36:39]
	s_add_u32 s14, s14, 0x80000
	s_addc_u32 s15, s15, 0
	v_mfma_f32_16x16x32_bf16 v[32:35], v[214:217], v[180:183], v[32:35]
	v_mfma_f32_16x16x32_bf16 v[20:23], v[206:209], v[188:191], v[20:23]
	v_mfma_f32_16x16x32_bf16 v[16:19], v[214:217], v[188:191], v[16:19]
	v_mfma_f32_16x16x32_bf16 v[4:7], v[206:209], v[198:201], v[4:7]
	v_mfma_f32_16x16x32_bf16 v[0:3], v[214:217], v[198:201], v[0:3]
	v_mfma_f32_16x16x32_bf16 v[40:43], v[206:209], v[172:175], v[40:43]
	s_setprio 0
	v_mfma_f32_16x16x32_bf16 v[44:47], v[214:217], v[172:175], v[44:47]
	s_barrier
	s_mov_b32 m0, s25
	ds_read_b128 v[168:171], v166 offset:32768
	ds_read_b128 v[172:175], v166 offset:33792
	ds_read_b128 v[176:179], v166 offset:34816
	ds_read_b128 v[180:183], v166 offset:35840
	ds_read_b128 v[184:187], v166 offset:36864
	ds_read_b128 v[188:191], v166 offset:37888
	ds_read_b128 v[192:195], v166 offset:38912
	ds_read_b128 v[198:201], v166 offset:39936
	global_load_lds_dwordx4 v150, s[14:15]
	s_mov_b32 m0, s26
	s_nop 0
	global_load_lds_dwordx4 v146, s[14:15]
	s_waitcnt lgkmcnt(8)
	s_setprio 1
	s_barrier
	s_waitcnt lgkmcnt(7)
	v_mfma_f32_16x16x32_bf16 v[140:143], v[56:59], v[168:171], v[140:143]
	v_mfma_f32_16x16x32_bf16 v[136:139], v[64:67], v[168:171], v[136:139]
	s_waitcnt lgkmcnt(5)
	v_mfma_f32_16x16x32_bf16 v[124:127], v[56:59], v[176:179], v[124:127]
	v_mfma_f32_16x16x32_bf16 v[120:123], v[64:67], v[176:179], v[120:123]
	s_waitcnt lgkmcnt(3)
	v_mfma_f32_16x16x32_bf16 v[108:111], v[56:59], v[184:187], v[108:111]
	v_mfma_f32_16x16x32_bf16 v[104:107], v[64:67], v[184:187], v[104:107]
	s_waitcnt lgkmcnt(1)
	v_mfma_f32_16x16x32_bf16 v[92:95], v[56:59], v[192:195], v[92:95]
	v_mfma_f32_16x16x32_bf16 v[88:91], v[64:67], v[192:195], v[88:91]
	v_mfma_f32_16x16x32_bf16 v[140:143], v[60:63], v[172:175], v[140:143]
	s_add_i32 s14, 0, 0x1c000
	v_mfma_f32_16x16x32_bf16 v[136:139], v[68:71], v[172:175], v[136:139]
	s_add_i32 s15, s57, s22
	v_mfma_f32_16x16x32_bf16 v[124:127], v[60:63], v[180:183], v[124:127]
	v_add_u32_e32 v196, s14, v164
	v_mfma_f32_16x16x32_bf16 v[120:123], v[68:71], v[180:183], v[120:123]
	v_lshl_add_u64 v[160:161], v[160:161], 0, s[46:47]
	v_mfma_f32_16x16x32_bf16 v[108:111], v[60:63], v[188:191], v[108:111]
	v_mfma_f32_16x16x32_bf16 v[104:107], v[68:71], v[188:191], v[104:107]
	s_waitcnt lgkmcnt(0)
	v_mfma_f32_16x16x32_bf16 v[92:95], v[60:63], v[198:201], v[92:95]
	s_setprio 0
	v_mfma_f32_16x16x32_bf16 v[88:91], v[68:71], v[198:201], v[88:91]
	s_barrier
	s_mov_b32 m0, s15
	ds_read_b128 v[202:205], v196
	ds_read_b128 v[206:209], v196 offset:1024
	ds_read_b128 v[210:213], v196 offset:2048
	ds_read_b128 v[214:217], v196 offset:3072
	global_load_lds_dwordx4 v[160:161], off
	v_lshl_add_u64 v[160:161], v[218:219], 0, s[46:47]
	s_add_i32 m0, s15, 0x2000
	s_nop 0
	global_load_lds_dwordx4 v[160:161], off
	s_setprio 1
	s_barrier
	s_waitcnt lgkmcnt(3)
	v_mfma_f32_16x16x32_bf16 v[132:135], v[202:205], v[168:171], v[132:135]
	s_waitcnt lgkmcnt(1)
	v_mfma_f32_16x16x32_bf16 v[128:131], v[210:213], v[168:171], v[128:131]
	v_mfma_f32_16x16x32_bf16 v[116:119], v[202:205], v[176:179], v[116:119]
	v_mfma_f32_16x16x32_bf16 v[112:115], v[210:213], v[176:179], v[112:115]
	v_mfma_f32_16x16x32_bf16 v[100:103], v[202:205], v[184:187], v[100:103]
	v_mfma_f32_16x16x32_bf16 v[96:99], v[210:213], v[184:187], v[96:99]
	v_mfma_f32_16x16x32_bf16 v[84:87], v[202:205], v[192:195], v[84:87]
	v_mfma_f32_16x16x32_bf16 v[80:83], v[210:213], v[192:195], v[80:83]
	v_mfma_f32_16x16x32_bf16 v[132:135], v[206:209], v[172:175], v[132:135]
	s_mov_b32 m0, s30
	s_waitcnt lgkmcnt(0)
	v_mfma_f32_16x16x32_bf16 v[128:131], v[214:217], v[172:175], v[128:131]
	v_lshl_add_u64 v[160:161], v[220:221], 0, s[46:47]
	v_mfma_f32_16x16x32_bf16 v[116:119], v[206:209], v[180:183], v[116:119]
	v_mfma_f32_16x16x32_bf16 v[112:115], v[214:217], v[180:183], v[112:115]
	v_mfma_f32_16x16x32_bf16 v[100:103], v[206:209], v[188:191], v[100:103]
	v_mfma_f32_16x16x32_bf16 v[96:99], v[214:217], v[188:191], v[96:99]
	v_mfma_f32_16x16x32_bf16 v[84:87], v[206:209], v[198:201], v[84:87]
	s_setprio 0
	v_mfma_f32_16x16x32_bf16 v[80:83], v[214:217], v[198:201], v[80:83]
	s_barrier
	ds_read_b128 v[168:171], v166 offset:49152
	ds_read_b128 v[172:175], v166 offset:50176
	ds_read_b128 v[176:179], v166 offset:51200
	ds_read_b128 v[180:183], v166 offset:52224
	ds_read_b128 v[184:187], v166 offset:53248
	ds_read_b128 v[188:191], v166 offset:54272
	ds_read_b128 v[192:195], v166 offset:55296
	ds_read_b128 v[198:201], v166 offset:56320
	global_load_lds_dwordx4 v[160:161], off
	v_lshl_add_u64 v[160:161], v[222:223], 0, s[46:47]
	s_mov_b32 m0, s31
	s_nop 0
	global_load_lds_dwordx4 v[160:161], off
	s_waitcnt vmcnt(10)
	s_setprio 1
	s_barrier
; DI unsigned pack2(float a, float b) { f32x2 v = {a, b}; hwbf16x2 r = __builtin_convertvector(v, hwbf16x2); return __builtin_bit_cast(unsigned, r); }
; #define PG8_BAR __builtin_amdgcn_s_barrier()
;     DI void operator()(const f32x4 (&acc)[2][2][4][2], const Unit& u, int wr, int wc, int fr, int fq) const {
;         const int row0 = u.pm * BM + wr * 64 + fr, col0 = u.pn * BM + wc * 32 + 8 * fq;
;         f32x4 sc[2][2];
; #pragma unroll
;         for (int bj = 0; bj < 2; ++bj)
; #pragma unroll
;             for (int n = 0; n < 2; ++n) sc[bj][n] = scale ? *(const f32x4*)(scale + col0 + bj * HALF + 4 * n) : (f32x4){1.f, 1.f, 1.f, 1.f};
; #pragma unroll
;         for (int ai = 0; ai < 2; ++ai)
; #pragma unroll
;             for (int m = 0; m < 4; ++m) { const size_t ro = (size_t)(row0 + ai * HALF + m * 16) * D + col0;
; #pragma unroll
;                 for (int bj = 0; bj < 2; ++bj) {
;                     f32x4 x0, x1;
;                     if constexpr (IB) { const u32x4 w = *(const u32x4*)((const bf16_t*)Xin + ro + bj * HALF);
;                         x0 = (f32x4){bflo(w[0]), bfhi(w[0]), bflo(w[1]), bfhi(w[1])}; x1 = (f32x4){bflo(w[2]), bfhi(w[2]), bflo(w[3]), bfhi(w[3])}; }
;                     else { x0 = *(const f32x4*)((const float*)Xin + ro + bj * HALF); x1 = *(const f32x4*)((const float*)Xin + ro + bj * HALF + 4); }
;                     x0 += acc[ai][bj][m][0] * sc[bj][0]; x1 += acc[ai][bj][m][1] * sc[bj][1];
;                     if constexpr (OB) { u32x4 o; o[0] = pack2(x0[0], x0[1]); o[1] = pack2(x0[2], x0[3]); o[2] = pack2(x1[0], x1[1]); o[3] = pack2(x1[2], x1[3]);
;                         *(u32x4*)((bf16_t*)Xout + ro + bj * HALF) = o; }
;                     else { *(f32x4*)((float*)Xout + ro + bj * HALF) = x0; *(f32x4*)((float*)Xout + ro + bj * HALF + 4) = x1; } } }
; template <class Map, class Epi>
; DI void gemm_phase(LAS unsigned char* lds, const Map& MP, const Epi& E, const int nM, const int nN, const int K, const int lda, const int ldb) {
;     ...
;             PG8_LDA(At, 1, 1); PG8_STAGE(PG8_SA(1, 0), a3, voffA);
;             PG8_BAR; PG8_WAIT_L(0); PG8_MMA(1, 0, At, B0); PG8_BAR; PG8_SCHED;
;             PG8_STAGE(PG8_SB(1, 1), b3 + hstepB, voffB);
;             PG8_WAIT_V(6); PG8_BAR; PG8_MMA(1, 1, At, B1); PG8_BAR;
;         }
;         { int frr = fr, fqq = fq; asm volatile("" : "+v"(frr), "+v"(fqq)); E(acc, cur, wr, wc, frr, fqq); }
	s_waitcnt lgkmcnt(7)
	v_mfma_f32_16x16x32_bf16 v[76:79], v[56:59], v[168:171], v[76:79]
	v_mfma_f32_16x16x32_bf16 v[72:75], v[64:67], v[168:171], v[72:75]
	s_waitcnt lgkmcnt(5)
	v_mfma_f32_16x16x32_bf16 v[52:55], v[56:59], v[176:179], v[52:55]
	v_mfma_f32_16x16x32_bf16 v[48:51], v[64:67], v[176:179], v[48:51]
	s_waitcnt lgkmcnt(3)
	v_mfma_f32_16x16x32_bf16 v[28:31], v[56:59], v[184:187], v[28:31]
	v_mfma_f32_16x16x32_bf16 v[24:27], v[64:67], v[184:187], v[24:27]
	s_waitcnt lgkmcnt(1)
	v_mfma_f32_16x16x32_bf16 v[12:15], v[56:59], v[192:195], v[12:15]
	v_mfma_f32_16x16x32_bf16 v[8:11], v[64:67], v[192:195], v[8:11]
	v_mfma_f32_16x16x32_bf16 v[76:79], v[60:63], v[172:175], v[76:79]
	s_add_u32 s12, s12, 0x20080
	s_addc_u32 s13, s13, 0
	v_mfma_f32_16x16x32_bf16 v[72:75], v[68:71], v[172:175], v[72:75]
	s_add_i32 s14, s14, s22
	v_mfma_f32_16x16x32_bf16 v[52:55], v[60:63], v[180:183], v[52:55]
	v_mfma_f32_16x16x32_bf16 v[48:51], v[68:71], v[180:183], v[48:51]
	v_mfma_f32_16x16x32_bf16 v[28:31], v[60:63], v[188:191], v[28:31]
	v_mfma_f32_16x16x32_bf16 v[24:27], v[68:71], v[188:191], v[24:27]
	s_waitcnt lgkmcnt(0)
	v_mfma_f32_16x16x32_bf16 v[12:15], v[60:63], v[198:201], v[12:15]
	s_setprio 0
	v_mfma_f32_16x16x32_bf16 v[8:11], v[68:71], v[198:201], v[8:11]
	s_barrier
	s_mov_b32 m0, s14
	s_nop 0
	global_load_lds_dwordx4 v148, s[12:13]
	s_add_i32 m0, s14, 0x2000
	s_nop 0
	global_load_lds_dwordx4 v144, s[12:13]
	s_waitcnt vmcnt(6)
	s_setprio 1
	s_barrier
	v_mfma_f32_16x16x32_bf16 v[40:43], v[202:205], v[168:171], v[40:43]
	v_mfma_f32_16x16x32_bf16 v[68:71], v[206:209], v[172:175], v[40:43]
	v_mfma_f32_16x16x32_bf16 v[40:43], v[210:213], v[168:171], v[44:47]
	v_mfma_f32_16x16x32_bf16 v[36:39], v[202:205], v[176:179], v[36:39]
	v_mfma_f32_16x16x32_bf16 v[32:35], v[210:213], v[176:179], v[32:35]
	v_mfma_f32_16x16x32_bf16 v[20:23], v[202:205], v[184:187], v[20:23]
	v_mfma_f32_16x16x32_bf16 v[16:19], v[210:213], v[184:187], v[16:19]
	v_mfma_f32_16x16x32_bf16 v[4:7], v[202:205], v[192:195], v[4:7]
	v_mfma_f32_16x16x32_bf16 v[0:3], v[210:213], v[192:195], v[0:3]
	s_add_i32 s3, s3, 2
	v_mfma_f32_16x16x32_bf16 v[64:67], v[214:217], v[172:175], v[40:43]
	s_add_u32 s53, s53, 0x100
	s_addc_u32 s56, s56, 0
	ds_read_b128 v[40:43], v165
	ds_read_b128 v[44:47], v165 offset:1024
	ds_read_b128 v[56:59], v165 offset:2048
	ds_read_b128 v[60:63], v165 offset:3072
	v_mfma_f32_16x16x32_bf16 v[36:39], v[206:209], v[180:183], v[36:39]
	s_add_u32 s10, s10, 0x100
	s_addc_u32 s11, s11, 0
	v_mfma_f32_16x16x32_bf16 v[32:35], v[214:217], v[180:183], v[32:35]
	s_cmp_gt_u32 s3, 5
	v_mfma_f32_16x16x32_bf16 v[20:23], v[206:209], v[188:191], v[20:23]
	v_mfma_f32_16x16x32_bf16 v[16:19], v[214:217], v[188:191], v[16:19]
	v_mfma_f32_16x16x32_bf16 v[4:7], v[206:209], v[198:201], v[4:7]
	s_setprio 0
	v_mfma_f32_16x16x32_bf16 v[0:3], v[214:217], v[198:201], v[0:3]
	s_barrier
	s_cbranch_scc0 .LBB1_2339
	s_waitcnt lgkmcnt(0)
	s_lshl_b32 s2, s2, 8
	v_mov_b32_e32 v40, v163
	v_mov_b32_e32 v168, v162
	s_or_b32 s2, s2, s29
	s_and_b64 vcc, exec, s[40:41]
	v_lshl_add_u32 v160, v40, 3, s2
	s_lshl_b32 s2, s8, 8
	s_add_i32 s2, s2, s28
	v_add_u32_e32 v168, s2, v168
	v_ashrrev_i32_e32 v169, 31, v168
	v_ashrrev_i32_e32 v161, 31, v160
	v_lshlrev_b64 v[168:169], 11, v[168:169]
	v_lshl_add_u64 v[44:45], v[160:161], 2, s[44:45]
	v_lshl_add_u64 v[160:161], v[168:169], 0, v[160:161]
	v_lshlrev_b64 v[160:161], 1, v[160:161]
	v_lshl_add_u64 v[172:173], s[4:5], 0, v[160:161]
	global_load_dwordx4 v[56:59], v[44:45], off offset:16
	global_load_dwordx4 v[60:63], v[44:45], off
	global_load_dwordx4 v[40:43], v[44:45], off offset:528
	s_nop 0
	global_load_dwordx4 v[44:47], v[44:45], off offset:512
	s_mov_b64 s[2:3], 0x10000
	global_load_dwordx4 v[178:181], v[172:173], off
	global_load_dwordx4 v[182:185], v[172:173], off offset:256
	s_mov_b64 s[98:99], 0x10000
	v_lshl_add_u64 v[170:171], v[172:173], 0, s[98:99]
	global_load_dwordx4 v[186:189], v[170:171], off
	global_load_dwordx4 v[190:193], v[170:171], off offset:256
	s_mov_b64 s[98:99], 0x20000
	v_lshl_add_u64 v[170:171], v[172:173], 0, s[98:99]
	global_load_dwordx4 v[198:201], v[170:171], off
	global_load_dwordx4 v[202:205], v[170:171], off offset:256
	s_mov_b64 s[98:99], 0x30000
	v_lshl_add_u64 v[170:171], v[172:173], 0, s[98:99]
	global_load_dwordx4 v[206:209], v[170:171], off
	global_load_dwordx4 v[210:213], v[170:171], off offset:256
	s_mov_b64 s[98:99], 0x80000
	v_lshl_add_u64 v[170:171], v[172:173], 0, s[98:99]
	global_load_dwordx4 v[214:217], v[170:171], off
	global_load_dwordx4 v[248:251], v[170:171], off offset:256
	s_mov_b64 s[98:99], 0x90000
	v_lshl_add_u64 v[170:171], v[172:173], 0, s[98:99]
	global_load_dwordx4 v[252:255], v[170:171], off
	s_waitcnt vmcnt(10)
	s_nop 1
	v_mov_b32_e32 v168, v178
	v_mov_b32_e32 v169, v179
	v_mov_b32_e32 v170, v180
	v_mov_b32_e32 v171, v181
	s_mov_b32 s8, s52
	s_mov_b64 s[10:11], s[54:55]
	s_mov_b64 s[12:13], s[6:7]
	s_waitcnt lgkmcnt(0)
	v_lshlrev_b32_e32 v174, 16, v168
	v_and_b32_e32 v175, 0xffff0000, v168
	v_lshlrev_b32_e32 v168, 16, v169
	v_and_b32_e32 v169, 0xffff0000, v169
	v_lshlrev_b32_e32 v176, 16, v170
	v_and_b32_e32 v177, 0xffff0000, v170
	v_lshlrev_b32_e32 v170, 16, v171
	v_and_b32_e32 v171, 0xffff0000, v171
	v_pk_fma_f32 v[142:143], v[142:143], v[62:63], v[168:169]
	v_pk_fma_f32 v[140:141], v[140:141], v[60:61], v[174:175]
	v_pk_fma_f32 v[168:169], v[138:139], v[58:59], v[170:171]
	v_pk_fma_f32 v[138:139], v[136:137], v[56:57], v[176:177]
	v_cvt_pk_bf16_f32 v136, v140, v141
	v_cvt_pk_bf16_f32 v137, v142, v143
	v_cvt_pk_bf16_f32 v138, v138, v139
	v_cvt_pk_bf16_f32 v139, v168, v169
	v_lshl_add_u64 v[140:141], s[42:43], 0, v[160:161]
	global_store_dwordx4 v[140:141], v[136:139], off
	s_waitcnt vmcnt(10)
; DI unsigned pack2(float a, float b) { f32x2 v = {a, b}; hwbf16x2 r = __builtin_convertvector(v, hwbf16x2); return __builtin_bit_cast(unsigned, r); }
; DI float bflo(unsigned w) { return __uint_as_float(w << 16); }
; DI float bfhi(unsigned w) { return __uint_as_float(w & 0xffff0000u); }
;     DI void operator()(const f32x4 (&acc)[2][2][4][2], const Unit& u, int wr, int wc, int fr, int fq) const {
;     ...
;         for (int ai = 0; ai < 2; ++ai)
; #pragma unroll
;             for (int m = 0; m < 4; ++m) { const size_t ro = (size_t)(row0 + ai * HALF + m * 16) * D + col0;
; #pragma unroll
;                 for (int bj = 0; bj < 2; ++bj) {
;                     f32x4 x0, x1;
;                     if constexpr (IB) { const u32x4 w = *(const u32x4*)((const bf16_t*)Xin + ro + bj * HALF);
;                         x0 = (f32x4){bflo(w[0]), bfhi(w[0]), bflo(w[1]), bfhi(w[1])}; x1 = (f32x4){bflo(w[2]), bfhi(w[2]), bflo(w[3]), bfhi(w[3])}; }
;                     else { x0 = *(const f32x4*)((const float*)Xin + ro + bj * HALF); x1 = *(const f32x4*)((const float*)Xin + ro + bj * HALF + 4); }
;                     x0 += acc[ai][bj][m][0] * sc[bj][0]; x1 += acc[ai][bj][m][1] * sc[bj][1];
;                     if constexpr (OB) { u32x4 o; o[0] = pack2(x0[0], x0[1]); o[1] = pack2(x0[2], x0[3]); o[2] = pack2(x1[0], x1[1]); o[3] = pack2(x1[2], x1[3]);
;                         *(u32x4*)((bf16_t*)Xout + ro + bj * HALF) = o; }
;                     else { *(f32x4*)((float*)Xout + ro + bj * HALF) = x0; *(f32x4*)((float*)Xout + ro + bj * HALF + 4) = x1; } } }
	s_nop 1
	v_mov_b32_e32 v136, v182
	v_mov_b32_e32 v137, v183
	v_mov_b32_e32 v138, v184
	v_mov_b32_e32 v139, v185
	s_waitcnt lgkmcnt(0)
	v_lshlrev_b32_e32 v142, 16, v136
	v_and_b32_e32 v143, 0xffff0000, v136
	v_lshlrev_b32_e32 v136, 16, v137
	v_and_b32_e32 v137, 0xffff0000, v137
	v_lshlrev_b32_e32 v168, 16, v138
	v_and_b32_e32 v169, 0xffff0000, v138
	v_lshlrev_b32_e32 v138, 16, v139
	v_and_b32_e32 v139, 0xffff0000, v139
	v_pk_fma_f32 v[134:135], v[134:135], v[46:47], v[136:137]
	v_pk_fma_f32 v[132:133], v[132:133], v[44:45], v[142:143]
	v_pk_fma_f32 v[136:137], v[130:131], v[42:43], v[138:139]
	v_pk_fma_f32 v[130:131], v[128:129], v[40:41], v[168:169]
	v_cvt_pk_bf16_f32 v128, v132, v133
	v_cvt_pk_bf16_f32 v129, v134, v135
	v_cvt_pk_bf16_f32 v130, v130, v131
	v_cvt_pk_bf16_f32 v131, v136, v137
	v_lshl_add_u64 v[132:133], v[160:161], 0, s[2:3]
	global_store_dwordx4 v[140:141], v[128:131], off offset:256
	v_lshl_add_u64 v[134:135], s[4:5], 0, v[132:133]
	s_waitcnt vmcnt(10)
	s_nop 1
	v_mov_b32_e32 v128, v186
	v_mov_b32_e32 v129, v187
	v_mov_b32_e32 v130, v188
	v_mov_b32_e32 v131, v189
	s_mov_b64 s[2:3], 0x20000
	s_waitcnt lgkmcnt(0)
	v_lshlrev_b32_e32 v136, 16, v128
	v_and_b32_e32 v137, 0xffff0000, v128
	v_lshlrev_b32_e32 v128, 16, v129
	v_and_b32_e32 v129, 0xffff0000, v129
	v_lshlrev_b32_e32 v138, 16, v130
	v_and_b32_e32 v139, 0xffff0000, v130
	v_lshlrev_b32_e32 v130, 16, v131
	v_and_b32_e32 v131, 0xffff0000, v131
	v_pk_fma_f32 v[126:127], v[126:127], v[62:63], v[128:129]
	v_pk_fma_f32 v[124:125], v[124:125], v[60:61], v[136:137]
	v_pk_fma_f32 v[128:129], v[122:123], v[58:59], v[130:131]
	v_pk_fma_f32 v[122:123], v[120:121], v[56:57], v[138:139]
	v_cvt_pk_bf16_f32 v120, v124, v125
	v_cvt_pk_bf16_f32 v121, v126, v127
	v_cvt_pk_bf16_f32 v122, v122, v123
	v_cvt_pk_bf16_f32 v123, v128, v129
	v_lshl_add_u64 v[124:125], s[42:43], 0, v[132:133]
	global_store_dwordx4 v[124:125], v[120:123], off
	s_waitcnt vmcnt(10)
	s_nop 1
	v_mov_b32_e32 v120, v190
	v_mov_b32_e32 v121, v191
	v_mov_b32_e32 v122, v192
	v_mov_b32_e32 v123, v193
	s_waitcnt lgkmcnt(0)
	v_lshlrev_b32_e32 v126, 16, v120
	v_and_b32_e32 v127, 0xffff0000, v120
	v_lshlrev_b32_e32 v120, 16, v121
	v_and_b32_e32 v121, 0xffff0000, v121
	v_lshlrev_b32_e32 v128, 16, v122
	v_and_b32_e32 v129, 0xffff0000, v122
	v_lshlrev_b32_e32 v122, 16, v123
	v_and_b32_e32 v123, 0xffff0000, v123
	v_pk_fma_f32 v[118:119], v[118:119], v[46:47], v[120:121]
	v_pk_fma_f32 v[116:117], v[116:117], v[44:45], v[126:127]
	v_pk_fma_f32 v[120:121], v[114:115], v[42:43], v[122:123]
	v_pk_fma_f32 v[114:115], v[112:113], v[40:41], v[128:129]
	v_cvt_pk_bf16_f32 v112, v116, v117
	v_cvt_pk_bf16_f32 v113, v118, v119
	v_cvt_pk_bf16_f32 v114, v114, v115
	v_cvt_pk_bf16_f32 v115, v120, v121
	v_lshl_add_u64 v[116:117], v[160:161], 0, s[2:3]
	global_store_dwordx4 v[124:125], v[112:115], off offset:256
	v_lshl_add_u64 v[118:119], s[4:5], 0, v[116:117]
	s_waitcnt vmcnt(10)
	s_nop 1
	v_mov_b32_e32 v112, v198
	v_mov_b32_e32 v113, v199
	v_mov_b32_e32 v114, v200
	v_mov_b32_e32 v115, v201
	s_mov_b64 s[2:3], 0x30000
	s_waitcnt lgkmcnt(0)
	v_lshlrev_b32_e32 v120, 16, v112
	v_and_b32_e32 v121, 0xffff0000, v112
	v_lshlrev_b32_e32 v112, 16, v113
	v_and_b32_e32 v113, 0xffff0000, v113
	v_lshlrev_b32_e32 v122, 16, v114
	v_and_b32_e32 v123, 0xffff0000, v114
	v_lshlrev_b32_e32 v114, 16, v115
	v_and_b32_e32 v115, 0xffff0000, v115
	v_pk_fma_f32 v[110:111], v[110:111], v[62:63], v[112:113]
	v_pk_fma_f32 v[108:109], v[108:109], v[60:61], v[120:121]
	v_pk_fma_f32 v[112:113], v[106:107], v[58:59], v[114:115]
	v_pk_fma_f32 v[106:107], v[104:105], v[56:57], v[122:123]
	v_cvt_pk_bf16_f32 v104, v108, v109
	v_cvt_pk_bf16_f32 v105, v110, v111
	v_cvt_pk_bf16_f32 v106, v106, v107
	v_cvt_pk_bf16_f32 v107, v112, v113
	v_lshl_add_u64 v[108:109], s[42:43], 0, v[116:117]
	global_store_dwordx4 v[108:109], v[104:107], off
	s_waitcnt vmcnt(10)
	s_nop 1
	v_mov_b32_e32 v104, v202
	v_mov_b32_e32 v105, v203
	v_mov_b32_e32 v106, v204
	v_mov_b32_e32 v107, v205
	s_waitcnt lgkmcnt(0)
	v_lshlrev_b32_e32 v110, 16, v104
	v_and_b32_e32 v111, 0xffff0000, v104
	v_lshlrev_b32_e32 v104, 16, v105
	v_and_b32_e32 v105, 0xffff0000, v105
	v_lshlrev_b32_e32 v112, 16, v106
	v_and_b32_e32 v113, 0xffff0000, v106
	v_lshlrev_b32_e32 v106, 16, v107
	v_and_b32_e32 v107, 0xffff0000, v107
	v_pk_fma_f32 v[102:103], v[102:103], v[46:47], v[104:105]
	v_pk_fma_f32 v[100:101], v[100:101], v[44:45], v[110:111]
	v_pk_fma_f32 v[104:105], v[98:99], v[42:43], v[106:107]
	v_pk_fma_f32 v[98:99], v[96:97], v[40:41], v[112:113]
	v_cvt_pk_bf16_f32 v96, v100, v101
	v_cvt_pk_bf16_f32 v97, v102, v103
	v_cvt_pk_bf16_f32 v98, v98, v99
	v_cvt_pk_bf16_f32 v99, v104, v105
	v_lshl_add_u64 v[100:101], v[160:161], 0, s[2:3]
	global_store_dwordx4 v[108:109], v[96:99], off offset:256
	v_lshl_add_u64 v[102:103], s[4:5], 0, v[100:101]
	s_waitcnt vmcnt(10)
	s_nop 1
	v_mov_b32_e32 v96, v206
	v_mov_b32_e32 v97, v207
	v_mov_b32_e32 v98, v208
	v_mov_b32_e32 v99, v209
	s_mov_b64 s[2:3], 0x80000
	s_waitcnt lgkmcnt(0)
	v_lshlrev_b32_e32 v104, 16, v96
	v_and_b32_e32 v105, 0xffff0000, v96
	v_lshlrev_b32_e32 v96, 16, v97
	v_and_b32_e32 v97, 0xffff0000, v97
	v_lshlrev_b32_e32 v106, 16, v98
	v_and_b32_e32 v107, 0xffff0000, v98
	v_lshlrev_b32_e32 v98, 16, v99
	v_and_b32_e32 v99, 0xffff0000, v99
	v_pk_fma_f32 v[94:95], v[94:95], v[62:63], v[96:97]
	v_pk_fma_f32 v[92:93], v[92:93], v[60:61], v[104:105]
	v_pk_fma_f32 v[96:97], v[90:91], v[58:59], v[98:99]
	v_pk_fma_f32 v[90:91], v[88:89], v[56:57], v[106:107]
	v_cvt_pk_bf16_f32 v88, v92, v93
	v_cvt_pk_bf16_f32 v89, v94, v95
	v_cvt_pk_bf16_f32 v90, v90, v91
	v_cvt_pk_bf16_f32 v91, v96, v97
	v_lshl_add_u64 v[92:93], s[42:43], 0, v[100:101]
	global_store_dwordx4 v[92:93], v[88:91], off
	s_waitcnt vmcnt(10)
; DI unsigned pack2(float a, float b) { f32x2 v = {a, b}; hwbf16x2 r = __builtin_convertvector(v, hwbf16x2); return __builtin_bit_cast(unsigned, r); }
; DI float bflo(unsigned w) { return __uint_as_float(w << 16); }
; DI float bfhi(unsigned w) { return __uint_as_float(w & 0xffff0000u); }
;     DI void operator()(const f32x4 (&acc)[2][2][4][2], const Unit& u, int wr, int wc, int fr, int fq) const {
;     ...
;         for (int ai = 0; ai < 2; ++ai)
; #pragma unroll
;             for (int m = 0; m < 4; ++m) { const size_t ro = (size_t)(row0 + ai * HALF + m * 16) * D + col0;
; #pragma unroll
;                 for (int bj = 0; bj < 2; ++bj) {
;                     f32x4 x0, x1;
;                     if constexpr (IB) { const u32x4 w = *(const u32x4*)((const bf16_t*)Xin + ro + bj * HALF);
;                         x0 = (f32x4){bflo(w[0]), bfhi(w[0]), bflo(w[1]), bfhi(w[1])}; x1 = (f32x4){bflo(w[2]), bfhi(w[2]), bflo(w[3]), bfhi(w[3])}; }
;                     else { x0 = *(const f32x4*)((const float*)Xin + ro + bj * HALF); x1 = *(const f32x4*)((const float*)Xin + ro + bj * HALF + 4); }
;                     x0 += acc[ai][bj][m][0] * sc[bj][0]; x1 += acc[ai][bj][m][1] * sc[bj][1];
;                     if constexpr (OB) { u32x4 o; o[0] = pack2(x0[0], x0[1]); o[1] = pack2(x0[2], x0[3]); o[2] = pack2(x1[0], x1[1]); o[3] = pack2(x1[2], x1[3]);
;                         *(u32x4*)((bf16_t*)Xout + ro + bj * HALF) = o; }
;                     else { *(f32x4*)((float*)Xout + ro + bj * HALF) = x0; *(f32x4*)((float*)Xout + ro + bj * HALF + 4) = x1; } } }
	s_nop 1
	v_mov_b32_e32 v88, v210
	v_mov_b32_e32 v89, v211
	v_mov_b32_e32 v90, v212
	v_mov_b32_e32 v91, v213
	s_waitcnt lgkmcnt(0)
	v_lshlrev_b32_e32 v94, 16, v88
	v_and_b32_e32 v95, 0xffff0000, v88
	v_lshlrev_b32_e32 v88, 16, v89
	v_and_b32_e32 v89, 0xffff0000, v89
	v_lshlrev_b32_e32 v96, 16, v90
	v_and_b32_e32 v97, 0xffff0000, v90
	v_lshlrev_b32_e32 v90, 16, v91
	v_and_b32_e32 v91, 0xffff0000, v91
	v_pk_fma_f32 v[86:87], v[86:87], v[46:47], v[88:89]
	v_pk_fma_f32 v[84:85], v[84:85], v[44:45], v[94:95]
	v_pk_fma_f32 v[88:89], v[82:83], v[42:43], v[90:91]
	v_pk_fma_f32 v[82:83], v[80:81], v[40:41], v[96:97]
	v_cvt_pk_bf16_f32 v80, v84, v85
	v_cvt_pk_bf16_f32 v81, v86, v87
	v_cvt_pk_bf16_f32 v82, v82, v83
	v_cvt_pk_bf16_f32 v83, v88, v89
	v_lshl_add_u64 v[84:85], v[160:161], 0, s[2:3]
	global_store_dwordx4 v[92:93], v[80:83], off offset:256
	v_lshl_add_u64 v[86:87], s[4:5], 0, v[84:85]
	s_waitcnt vmcnt(10)
	s_nop 1
	v_mov_b32_e32 v80, v214
	v_mov_b32_e32 v81, v215
	v_mov_b32_e32 v82, v216
	v_mov_b32_e32 v83, v217
	s_mov_b64 s[2:3], 0x90000
	s_waitcnt lgkmcnt(0)
	v_lshlrev_b32_e32 v88, 16, v80
	v_and_b32_e32 v89, 0xffff0000, v80
	v_lshlrev_b32_e32 v80, 16, v81
	v_and_b32_e32 v81, 0xffff0000, v81
	v_lshlrev_b32_e32 v90, 16, v82
	v_and_b32_e32 v91, 0xffff0000, v82
	v_lshlrev_b32_e32 v82, 16, v83
	v_and_b32_e32 v83, 0xffff0000, v83
	v_pk_fma_f32 v[78:79], v[78:79], v[62:63], v[80:81]
	v_pk_fma_f32 v[76:77], v[76:77], v[60:61], v[88:89]
	v_pk_fma_f32 v[80:81], v[74:75], v[58:59], v[82:83]
	v_pk_fma_f32 v[74:75], v[72:73], v[56:57], v[90:91]
	v_cvt_pk_bf16_f32 v72, v76, v77
	v_cvt_pk_bf16_f32 v73, v78, v79
	v_cvt_pk_bf16_f32 v74, v74, v75
	v_cvt_pk_bf16_f32 v75, v80, v81
	v_lshl_add_u64 v[76:77], s[42:43], 0, v[84:85]
	global_store_dwordx4 v[76:77], v[72:75], off
	s_waitcnt vmcnt(10)
	s_nop 1
	v_mov_b32_e32 v72, v248
	v_mov_b32_e32 v73, v249
	v_mov_b32_e32 v74, v250
	v_mov_b32_e32 v75, v251
	s_waitcnt lgkmcnt(0)
	v_lshlrev_b32_e32 v78, 16, v72
	v_and_b32_e32 v79, 0xffff0000, v72
	v_lshlrev_b32_e32 v72, 16, v73
	v_and_b32_e32 v73, 0xffff0000, v73
	v_lshlrev_b32_e32 v80, 16, v74
	v_and_b32_e32 v81, 0xffff0000, v74
	v_lshlrev_b32_e32 v74, 16, v75
	v_and_b32_e32 v75, 0xffff0000, v75
	v_pk_fma_f32 v[70:71], v[70:71], v[46:47], v[72:73]
	v_pk_fma_f32 v[68:69], v[68:69], v[44:45], v[78:79]
	v_pk_fma_f32 v[72:73], v[66:67], v[42:43], v[74:75]
	v_pk_fma_f32 v[66:67], v[64:65], v[40:41], v[80:81]
	v_cvt_pk_bf16_f32 v64, v68, v69
	v_cvt_pk_bf16_f32 v65, v70, v71
	v_cvt_pk_bf16_f32 v66, v66, v67
	v_cvt_pk_bf16_f32 v67, v72, v73
	v_lshl_add_u64 v[68:69], v[160:161], 0, s[2:3]
	global_store_dwordx4 v[76:77], v[64:67], off offset:256
	v_lshl_add_u64 v[70:71], s[4:5], 0, v[68:69]
	s_waitcnt vmcnt(10)
	s_nop 1
	v_mov_b32_e32 v64, v252
	v_mov_b32_e32 v65, v253
	v_mov_b32_e32 v66, v254
	v_mov_b32_e32 v67, v255
	s_mov_b64 s[2:3], 0xa0000
	s_waitcnt lgkmcnt(0)
	v_lshlrev_b32_e32 v72, 16, v64
	v_and_b32_e32 v73, 0xffff0000, v64
	v_lshlrev_b32_e32 v64, 16, v65
	v_and_b32_e32 v65, 0xffff0000, v65
	v_lshlrev_b32_e32 v74, 16, v66
	v_and_b32_e32 v75, 0xffff0000, v66
	v_lshlrev_b32_e32 v66, 16, v67
	v_and_b32_e32 v67, 0xffff0000, v67
	v_pk_fma_f32 v[54:55], v[54:55], v[62:63], v[64:65]
	v_pk_fma_f32 v[52:53], v[52:53], v[60:61], v[72:73]
	v_pk_fma_f32 v[64:65], v[50:51], v[58:59], v[66:67]
	v_pk_fma_f32 v[50:51], v[48:49], v[56:57], v[74:75]
	v_cvt_pk_bf16_f32 v48, v52, v53
	v_cvt_pk_bf16_f32 v49, v54, v55
	v_cvt_pk_bf16_f32 v50, v50, v51
	v_cvt_pk_bf16_f32 v51, v64, v65
	v_lshl_add_u64 v[52:53], s[42:43], 0, v[68:69]
	global_store_dwordx4 v[52:53], v[48:51], off
	global_load_dwordx4 v[48:51], v[70:71], off offset:256
	s_waitcnt vmcnt(0) lgkmcnt(0)
; DI unsigned pack2(float a, float b) { f32x2 v = {a, b}; hwbf16x2 r = __builtin_convertvector(v, hwbf16x2); return __builtin_bit_cast(unsigned, r); }
; DI float bflo(unsigned w) { return __uint_as_float(w << 16); }
; DI float bfhi(unsigned w) { return __uint_as_float(w & 0xffff0000u); }
;     DI const char* a(const Unit& u) const { return (const char*)(A + (size_t)u.pm * BM * lda); }
;     DI const char* a(const Unit& u) const { return (const char*)(A + (size_t)u.pm * BM * 2048 + (u.pn >> 1) * 512); }
;     DI void operator()(const f32x4 (&acc)[2][2][4][2], const Unit& u, int wr, int wc, int fr, int fq) const {
;     ...
;         for (int ai = 0; ai < 2; ++ai)
; #pragma unroll
;             for (int m = 0; m < 4; ++m) { const size_t ro = (size_t)(row0 + ai * HALF + m * 16) * D + col0;
; #pragma unroll
;                 for (int bj = 0; bj < 2; ++bj) {
;                     f32x4 x0, x1;
;                     if constexpr (IB) { const u32x4 w = *(const u32x4*)((const bf16_t*)Xin + ro + bj * HALF);
;                         x0 = (f32x4){bflo(w[0]), bfhi(w[0]), bflo(w[1]), bfhi(w[1])}; x1 = (f32x4){bflo(w[2]), bfhi(w[2]), bflo(w[3]), bfhi(w[3])}; }
;                     else { x0 = *(const f32x4*)((const float*)Xin + ro + bj * HALF); x1 = *(const f32x4*)((const float*)Xin + ro + bj * HALF + 4); }
;                     x0 += acc[ai][bj][m][0] * sc[bj][0]; x1 += acc[ai][bj][m][1] * sc[bj][1];
;                     if constexpr (OB) { u32x4 o; o[0] = pack2(x0[0], x0[1]); o[1] = pack2(x0[2], x0[3]); o[2] = pack2(x1[0], x1[1]); o[3] = pack2(x1[2], x1[3]);
;                         *(u32x4*)((bf16_t*)Xout + ro + bj * HALF) = o; }
;                     else { *(f32x4*)((float*)Xout + ro + bj * HALF) = x0; *(f32x4*)((float*)Xout + ro + bj * HALF + 4) = x1; } } }
; template <class Map, class Epi>
; DI void gemm_phase(LAS unsigned char* lds, const Map& MP, const Epi& E, const int nM, const int nN, const int K, const int lda, const int ldb) {
;     ...
;         if (!has_next) break;
; #pragma unroll
;         for (int a = 0; a < 2; ++a)
; #pragma unroll
;             for (int b = 0; b < 2; ++b)
; #pragma unroll
;                 for (int m = 0; m < 4; ++m)
; #pragma unroll
;                     for (int n = 0; n < 2; ++n) acc[a][b][m][n] = (f32x4){0.f, 0.f, 0.f, 0.f};
;         cur = nxt; cA = nA; cB = nB; ++ui;
;     }
;     PG8_WAIT_V(0);
;     if (wr == 0) PG8_BAR;
;     PG8_BAR;
	v_lshlrev_b32_e32 v54, 16, v48
	v_and_b32_e32 v55, 0xffff0000, v48
	v_lshlrev_b32_e32 v48, 16, v49
	v_and_b32_e32 v49, 0xffff0000, v49
	v_lshlrev_b32_e32 v64, 16, v50
	v_and_b32_e32 v65, 0xffff0000, v50
	v_lshlrev_b32_e32 v50, 16, v51
	v_and_b32_e32 v51, 0xffff0000, v51
	v_pk_fma_f32 v[38:39], v[38:39], v[46:47], v[48:49]
	v_pk_fma_f32 v[36:37], v[36:37], v[44:45], v[54:55]
	v_pk_fma_f32 v[48:49], v[34:35], v[42:43], v[50:51]
	v_pk_fma_f32 v[34:35], v[32:33], v[40:41], v[64:65]
	v_cvt_pk_bf16_f32 v32, v36, v37
	v_cvt_pk_bf16_f32 v33, v38, v39
	v_cvt_pk_bf16_f32 v34, v34, v35
	v_cvt_pk_bf16_f32 v35, v48, v49
	v_lshl_add_u64 v[36:37], v[160:161], 0, s[2:3]
	global_store_dwordx4 v[52:53], v[32:35], off offset:256
	v_lshl_add_u64 v[38:39], s[4:5], 0, v[36:37]
	global_load_dwordx4 v[32:35], v[38:39], off
	s_mov_b64 s[2:3], 0xb0000
	s_waitcnt vmcnt(0) lgkmcnt(0)
	v_lshlrev_b32_e32 v48, 16, v32
	v_and_b32_e32 v49, 0xffff0000, v32
	v_lshlrev_b32_e32 v32, 16, v33
	v_and_b32_e32 v33, 0xffff0000, v33
	v_lshlrev_b32_e32 v50, 16, v34
	v_and_b32_e32 v51, 0xffff0000, v34
	v_lshlrev_b32_e32 v34, 16, v35
	v_and_b32_e32 v35, 0xffff0000, v35
	v_pk_fma_f32 v[30:31], v[30:31], v[62:63], v[32:33]
	v_pk_fma_f32 v[28:29], v[28:29], v[60:61], v[48:49]
	v_pk_fma_f32 v[32:33], v[26:27], v[58:59], v[34:35]
	v_pk_fma_f32 v[26:27], v[24:25], v[56:57], v[50:51]
	v_cvt_pk_bf16_f32 v24, v28, v29
	v_cvt_pk_bf16_f32 v25, v30, v31
	v_cvt_pk_bf16_f32 v26, v26, v27
	v_cvt_pk_bf16_f32 v27, v32, v33
	v_lshl_add_u64 v[28:29], s[42:43], 0, v[36:37]
	global_store_dwordx4 v[28:29], v[24:27], off
	global_load_dwordx4 v[24:27], v[38:39], off offset:256
	s_waitcnt vmcnt(0) lgkmcnt(0)
	v_lshlrev_b32_e32 v30, 16, v24
	v_and_b32_e32 v31, 0xffff0000, v24
	v_lshlrev_b32_e32 v24, 16, v25
	v_and_b32_e32 v25, 0xffff0000, v25
	v_lshlrev_b32_e32 v32, 16, v26
	v_and_b32_e32 v33, 0xffff0000, v26
	v_lshlrev_b32_e32 v26, 16, v27
	v_and_b32_e32 v27, 0xffff0000, v27
	v_pk_fma_f32 v[22:23], v[22:23], v[46:47], v[24:25]
	v_pk_fma_f32 v[20:21], v[20:21], v[44:45], v[30:31]
	v_pk_fma_f32 v[24:25], v[18:19], v[42:43], v[26:27]
	v_pk_fma_f32 v[18:19], v[16:17], v[40:41], v[32:33]
	v_cvt_pk_bf16_f32 v16, v20, v21
	v_cvt_pk_bf16_f32 v17, v22, v23
	v_cvt_pk_bf16_f32 v18, v18, v19
	v_cvt_pk_bf16_f32 v19, v24, v25
	v_lshl_add_u64 v[20:21], v[160:161], 0, s[2:3]
	global_store_dwordx4 v[28:29], v[16:19], off offset:256
	v_lshl_add_u64 v[22:23], s[4:5], 0, v[20:21]
	global_load_dwordx4 v[16:19], v[22:23], off
	s_mov_b32 s2, s37
	s_waitcnt vmcnt(0) lgkmcnt(0)
	v_lshlrev_b32_e32 v24, 16, v16
	v_and_b32_e32 v25, 0xffff0000, v16
	v_lshlrev_b32_e32 v16, 16, v17
	v_and_b32_e32 v17, 0xffff0000, v17
	v_lshlrev_b32_e32 v26, 16, v18
	v_and_b32_e32 v27, 0xffff0000, v18
	v_lshlrev_b32_e32 v18, 16, v19
	v_and_b32_e32 v19, 0xffff0000, v19
	v_pk_fma_f32 v[14:15], v[14:15], v[62:63], v[16:17]
	v_pk_fma_f32 v[12:13], v[12:13], v[60:61], v[24:25]
	v_pk_fma_f32 v[16:17], v[10:11], v[58:59], v[18:19]
	v_pk_fma_f32 v[10:11], v[8:9], v[56:57], v[26:27]
	v_cvt_pk_bf16_f32 v8, v12, v13
	v_cvt_pk_bf16_f32 v9, v14, v15
	v_cvt_pk_bf16_f32 v10, v10, v11
	v_cvt_pk_bf16_f32 v11, v16, v17
	v_lshl_add_u64 v[12:13], s[42:43], 0, v[20:21]
	global_store_dwordx4 v[12:13], v[8:11], off
	global_load_dwordx4 v[8:11], v[22:23], off offset:256
	s_waitcnt vmcnt(0) lgkmcnt(0)
	v_lshlrev_b32_e32 v14, 16, v8
	v_and_b32_e32 v15, 0xffff0000, v8
	v_lshlrev_b32_e32 v8, 16, v9
	v_and_b32_e32 v9, 0xffff0000, v9
	v_lshlrev_b32_e32 v16, 16, v10
	v_and_b32_e32 v17, 0xffff0000, v10
	v_lshlrev_b32_e32 v10, 16, v11
	v_and_b32_e32 v11, 0xffff0000, v11
	v_pk_fma_f32 v[6:7], v[6:7], v[46:47], v[8:9]
	v_pk_fma_f32 v[4:5], v[4:5], v[44:45], v[14:15]
	v_pk_fma_f32 v[8:9], v[2:3], v[42:43], v[10:11]
	v_pk_fma_f32 v[2:3], v[0:1], v[40:41], v[16:17]
	v_cvt_pk_bf16_f32 v0, v4, v5
	v_cvt_pk_bf16_f32 v1, v6, v7
	v_cvt_pk_bf16_f32 v2, v2, v3
	v_cvt_pk_bf16_f32 v3, v8, v9
	global_store_dwordx4 v[12:13], v[0:3], off offset:256
	s_cbranch_vccz .LBB1_2336
	s_waitcnt vmcnt(0)
	s_cmpk_gt_u32 s17, 0xff
	s_cbranch_scc1 .LBB1_2343
	s_barrier

; #define PG8_STAGE(bufoff, gbase, voff) do { _Pragma("unroll") for (int _i = 0; _i < 2; ++_i) \
;         __builtin_amdgcn_global_load_lds((const unsigned*)((const char*)(gbase) + (voff)[_i]), (LAS unsigned*)(lds + (bufoff) + ldsw + _i * 8192), 16, 0, 0); } while (0)
; #define PG8_LDA(dst, b, h) do { _Pragma("unroll") for (int m = 0; m < 4; ++m) _Pragma("unroll") for (int k = 0; k < 2; ++k) dst[m][k] = *(const LAS bf16x8*)(lds + PG8_SA(b, h) + aoff + m * 2048 + k * 1024); } while (0)
; #define PG8_WAIT_V(n) asm volatile("s_waitcnt vmcnt(" #n ")" ::: "memory")
; #define PG8_WAIT_L(n) asm volatile("s_waitcnt lgkmcnt(" #n ")" ::: "memory")
; #define PG8_BAR __builtin_amdgcn_s_barrier()
; template <class Map, class Epi>
; DI void gemm_phase(LAS unsigned char* lds, const Map& MP, const Epi& E, const int nM, const int nN, const int K, const int lda, const int ldb) {
;     ...
;             const char* a1 = cA + (size_t)(t + 1) * kstep;
;             const char* a2 = last ? nA : cA + (size_t)(t + 2) * kstep; const char* b2 = last ? nB : cB + (size_t)(t + 2) * kstep;
;             const char* a3 = a2 + kstep; const char* b3 = b2 + kstep;
;             PG8_LDB(B0, 0, 0); PG8_SCHED; PG8_LDA(At, 0, 0); PG8_STAGE(PG8_SA(1, 1), a1 + hstepA, voffA);
;             PG8_WAIT_L(8); PG8_BAR; PG8_WAIT_L(0); PG8_MMA(0, 0, At, B0); PG8_BAR; PG8_SCHED;
;             PG8_LDB(B1, 0, 1); PG8_STAGE(PG8_SB(0, 0), b2, voffB);
;             PG8_BAR; PG8_WAIT_L(0); PG8_MMA(0, 1, At, B1); PG8_BAR;
;             PG8_LDA(At, 0, 1); PG8_STAGE(PG8_SA(0, 0), a2, voffA);
;             PG8_BAR; PG8_WAIT_L(0); PG8_MMA(1, 0, At, B0); PG8_BAR; PG8_SCHED;
;             PG8_STAGE(PG8_SB(0, 1), b2 + hstepB, voffB);
;             PG8_WAIT_V(6); PG8_BAR; PG8_MMA(1, 1, At, B1); PG8_BAR;
;             PG8_LDB(B0, 1, 0); PG8_SCHED; PG8_LDA(At, 1, 0); PG8_STAGE(PG8_SA(0, 1), a2 + hstepA, voffA);
;             PG8_WAIT_L(8); PG8_BAR; PG8_WAIT_L(0); PG8_MMA(0, 0, At, B0); PG8_BAR; PG8_SCHED;
;             PG8_LDB(B1, 1, 1); PG8_STAGE(PG8_SB(1, 0), b3, voffB);
;             PG8_BAR; PG8_WAIT_L(0); PG8_MMA(0, 1, At, B1); PG8_BAR;
;             PG8_LDA(At, 1, 1); PG8_STAGE(PG8_SA(1, 0), a3, voffA);
;             PG8_BAR; PG8_WAIT_L(0); PG8_MMA(1, 0, At, B0); PG8_BAR; PG8_SCHED;
;             PG8_STAGE(PG8_SB(1, 1), b3 + hstepB, voffB);
;             PG8_WAIT_V(6); PG8_BAR; PG8_MMA(1, 1, At, B1); PG8_BAR;
.LBB1_2483:
	s_add_u32 s28, s42, 0xfff80080
	s_addc_u32 s29, s43, -1
	s_cmp_eq_u32 s3, 28
	s_cselect_b32 s47, s23, s29
	s_cselect_b32 s46, s58, s28
	s_cselect_b32 s29, s21, vcc_hi
	s_cselect_b32 s28, s59, vcc_lo
	s_add_i32 m0, s38, 0xc000
	ds_read_b128 v[96:99], v190
	ds_read_b128 v[100:103], v190 offset:1024
	ds_read_b128 v[108:111], v190 offset:2048
	ds_read_b128 v[112:115], v190 offset:3072
	ds_read_b128 v[160:163], v190 offset:4096
	ds_read_b128 v[164:167], v190 offset:5120
	ds_read_b128 v[198:201], v190 offset:6144
	ds_read_b128 v[202:205], v190 offset:7168
	global_load_lds_dwordx4 v178, s[42:43]
	s_add_i32 m0, s38, 0xe000
	s_nop 0
	global_load_lds_dwordx4 v176, s[42:43]
	s_waitcnt lgkmcnt(8)
	s_setprio 1
	s_barrier
	s_waitcnt lgkmcnt(7)
	v_mfma_f32_16x16x32_bf16 v[148:151], v[80:83], v[96:99], v[148:151]
	v_mfma_f32_16x16x32_bf16 v[144:147], v[88:91], v[96:99], v[144:147]
	s_waitcnt lgkmcnt(5)
	v_mfma_f32_16x16x32_bf16 v[136:139], v[80:83], v[108:111], v[136:139]
	v_mfma_f32_16x16x32_bf16 v[128:131], v[88:91], v[108:111], v[128:131]
	s_waitcnt lgkmcnt(3)
	v_mfma_f32_16x16x32_bf16 v[120:123], v[80:83], v[160:163], v[120:123]
	v_mfma_f32_16x16x32_bf16 v[104:107], v[88:91], v[160:163], v[104:107]
	s_waitcnt lgkmcnt(1)
	v_mfma_f32_16x16x32_bf16 v[76:79], v[80:83], v[198:201], v[76:79]
	v_mfma_f32_16x16x32_bf16 v[72:75], v[88:91], v[198:201], v[72:75]
	v_mfma_f32_16x16x32_bf16 v[148:151], v[84:87], v[100:103], v[148:151]
	s_add_i32 s68, s2, s37
	v_mfma_f32_16x16x32_bf16 v[144:147], v[92:95], v[100:103], v[144:147]
	v_lshl_add_u64 v[184:185], s[28:29], 0, v[172:173]
	v_mfma_f32_16x16x32_bf16 v[136:139], v[84:87], v[112:115], v[136:139]
	v_lshl_add_u64 v[194:195], s[28:29], 0, v[168:169]
	v_mfma_f32_16x16x32_bf16 v[128:131], v[92:95], v[112:115], v[128:131]
	v_mfma_f32_16x16x32_bf16 v[120:123], v[84:87], v[164:167], v[120:123]
	v_mfma_f32_16x16x32_bf16 v[104:107], v[92:95], v[164:167], v[104:107]
	s_waitcnt lgkmcnt(0)
	v_mfma_f32_16x16x32_bf16 v[76:79], v[84:87], v[202:205], v[76:79]
	s_setprio 0
	v_mfma_f32_16x16x32_bf16 v[72:75], v[92:95], v[202:205], v[72:75]
	s_barrier
	s_mov_b32 m0, s68
	ds_read_b128 v[206:209], v191
	ds_read_b128 v[210:213], v191 offset:1024
	ds_read_b128 v[214:217], v191 offset:2048
	ds_read_b128 v[218:221], v191 offset:3072
	global_load_lds_dwordx4 v[184:185], off
	s_add_i32 m0, s68, 0x2000
	s_nop 0
	global_load_lds_dwordx4 v[194:195], off
	s_setprio 1
	s_barrier
	s_waitcnt lgkmcnt(3)
	v_mfma_f32_16x16x32_bf16 v[156:159], v[206:209], v[96:99], v[156:159]
	s_waitcnt lgkmcnt(1)
	v_mfma_f32_16x16x32_bf16 v[96:99], v[214:217], v[96:99], v[152:155]
	v_mfma_f32_16x16x32_bf16 v[156:159], v[210:213], v[100:103], v[156:159]
	s_waitcnt lgkmcnt(0)
	v_mfma_f32_16x16x32_bf16 v[96:99], v[218:221], v[100:103], v[96:99]
	v_mfma_f32_16x16x32_bf16 v[100:103], v[206:209], v[108:111], v[140:143]
	v_mfma_f32_16x16x32_bf16 v[108:111], v[214:217], v[108:111], v[132:135]
	v_mfma_f32_16x16x32_bf16 v[116:119], v[214:217], v[160:163], v[116:119]
	v_mfma_f32_16x16x32_bf16 v[68:71], v[206:209], v[198:201], v[68:71]
	v_mfma_f32_16x16x32_bf16 v[64:67], v[214:217], v[198:201], v[64:67]
	v_lshl_add_u64 v[232:233], s[46:47], 0, v[170:171]
	s_mov_b32 m0, s38
	v_mfma_f32_16x16x32_bf16 v[100:103], v[210:213], v[112:115], v[100:103]
	v_lshl_add_u64 v[230:231], s[46:47], 0, v[174:175]
	v_mfma_f32_16x16x32_bf16 v[108:111], v[218:221], v[112:115], v[108:111]
	v_mfma_f32_16x16x32_bf16 v[112:115], v[206:209], v[160:163], v[124:127]
	v_mfma_f32_16x16x32_bf16 v[116:119], v[218:221], v[164:167], v[116:119]
	v_mfma_f32_16x16x32_bf16 v[68:71], v[210:213], v[202:205], v[68:71]
	v_mfma_f32_16x16x32_bf16 v[64:67], v[218:221], v[202:205], v[64:67]
	s_setprio 0
	v_mfma_f32_16x16x32_bf16 v[112:115], v[210:213], v[164:167], v[112:115]
	s_barrier
	ds_read_b128 v[124:127], v190 offset:16384
	ds_read_b128 v[132:135], v190 offset:17408
	ds_read_b128 v[140:143], v190 offset:18432
	ds_read_b128 v[152:155], v190 offset:19456
	ds_read_b128 v[160:163], v190 offset:20480
	ds_read_b128 v[164:167], v190 offset:21504
	ds_read_b128 v[198:201], v190 offset:22528
	ds_read_b128 v[202:205], v190 offset:23552
	global_load_lds_dwordx4 v[230:231], off
	s_mov_b32 m0, s39
	s_nop 0
	global_load_lds_dwordx4 v[232:233], off
	s_waitcnt vmcnt(10)
	s_setprio 1
	s_barrier
	s_waitcnt lgkmcnt(7)
	v_mfma_f32_16x16x32_bf16 v[60:63], v[80:83], v[124:127], v[60:63]
	v_mfma_f32_16x16x32_bf16 v[48:51], v[88:91], v[124:127], v[48:51]
	s_waitcnt lgkmcnt(5)
	v_mfma_f32_16x16x32_bf16 v[40:43], v[80:83], v[140:143], v[40:43]
	v_mfma_f32_16x16x32_bf16 v[32:35], v[88:91], v[140:143], v[32:35]
	s_waitcnt lgkmcnt(3)
	v_mfma_f32_16x16x32_bf16 v[24:27], v[80:83], v[160:163], v[24:27]
	v_mfma_f32_16x16x32_bf16 v[16:19], v[88:91], v[160:163], v[16:19]
	s_waitcnt lgkmcnt(1)
	v_mfma_f32_16x16x32_bf16 v[12:15], v[80:83], v[198:201], v[12:15]
	v_mfma_f32_16x16x32_bf16 v[8:11], v[88:91], v[198:201], v[8:11]
	v_mfma_f32_16x16x32_bf16 v[60:63], v[84:87], v[132:135], v[60:63]
	s_add_u32 s68, s28, 0x80000
	s_addc_u32 s69, s29, 0
	v_mfma_f32_16x16x32_bf16 v[48:51], v[92:95], v[132:135], v[48:51]
	s_add_i32 s70, s67, s37
	v_mfma_f32_16x16x32_bf16 v[40:43], v[84:87], v[152:155], v[40:43]
	v_mfma_f32_16x16x32_bf16 v[32:35], v[92:95], v[152:155], v[32:35]
	v_mfma_f32_16x16x32_bf16 v[24:27], v[84:87], v[164:167], v[24:27]
	v_mfma_f32_16x16x32_bf16 v[16:19], v[92:95], v[164:167], v[16:19]
	s_waitcnt lgkmcnt(0)
	v_mfma_f32_16x16x32_bf16 v[12:15], v[84:87], v[202:205], v[12:15]
	s_setprio 0
	v_mfma_f32_16x16x32_bf16 v[8:11], v[92:95], v[202:205], v[8:11]
	s_barrier
; #define PG8_STAGE(bufoff, gbase, voff) do { _Pragma("unroll") for (int _i = 0; _i < 2; ++_i) \
;         __builtin_amdgcn_global_load_lds((const unsigned*)((const char*)(gbase) + (voff)[_i]), (LAS unsigned*)(lds + (bufoff) + ldsw + _i * 8192), 16, 0, 0); } while (0)
; #define PG8_LDA(dst, b, h) do { _Pragma("unroll") for (int m = 0; m < 4; ++m) _Pragma("unroll") for (int k = 0; k < 2; ++k) dst[m][k] = *(const LAS bf16x8*)(lds + PG8_SA(b, h) + aoff + m * 2048 + k * 1024); } while (0)
; #define PG8_LDB(dst, b, h) do { _Pragma("unroll") for (int n = 0; n < 2; ++n) _Pragma("unroll") for (int k = 0; k < 2; ++k) dst[n][k] = *(const LAS bf16x8*)(lds + PG8_SB(b, h) + boff + n * 2048 + k * 1024); } while (0)
; #define PG8_WAIT_V(n) asm volatile("s_waitcnt vmcnt(" #n ")" ::: "memory")
; #define PG8_WAIT_L(n) asm volatile("s_waitcnt lgkmcnt(" #n ")" ::: "memory")
; #define PG8_BAR __builtin_amdgcn_s_barrier()
; #define PG8_SCHED __builtin_amdgcn_sched_barrier(0)
; template <class Map, class Epi>
; DI void gemm_phase(LAS unsigned char* lds, const Map& MP, const Epi& E, const int nM, const int nN, const int K, const int lda, const int ldb) {
;     ...
;             PG8_LDB(B0, 0, 0); PG8_SCHED; PG8_LDA(At, 0, 0); PG8_STAGE(PG8_SA(1, 1), a1 + hstepA, voffA);
;             PG8_WAIT_L(8); PG8_BAR; PG8_WAIT_L(0); PG8_MMA(0, 0, At, B0); PG8_BAR; PG8_SCHED;
;             PG8_LDB(B1, 0, 1); PG8_STAGE(PG8_SB(0, 0), b2, voffB);
;             PG8_BAR; PG8_WAIT_L(0); PG8_MMA(0, 1, At, B1); PG8_BAR;
;             PG8_LDA(At, 0, 1); PG8_STAGE(PG8_SA(0, 0), a2, voffA);
;             PG8_BAR; PG8_WAIT_L(0); PG8_MMA(1, 0, At, B0); PG8_BAR; PG8_SCHED;
;             PG8_STAGE(PG8_SB(0, 1), b2 + hstepB, voffB);
;             PG8_WAIT_V(6); PG8_BAR; PG8_MMA(1, 1, At, B1); PG8_BAR;
;             PG8_LDB(B0, 1, 0); PG8_SCHED; PG8_LDA(At, 1, 0); PG8_STAGE(PG8_SA(0, 1), a2 + hstepA, voffA);
;             PG8_WAIT_L(8); PG8_BAR; PG8_WAIT_L(0); PG8_MMA(0, 0, At, B0); PG8_BAR; PG8_SCHED;
;             PG8_LDB(B1, 1, 1); PG8_STAGE(PG8_SB(1, 0), b3, voffB);
;             PG8_BAR; PG8_WAIT_L(0); PG8_MMA(0, 1, At, B1); PG8_BAR;
;             PG8_LDA(At, 1, 1); PG8_STAGE(PG8_SA(1, 0), a3, voffA);
;             PG8_BAR; PG8_WAIT_L(0); PG8_MMA(1, 0, At, B0); PG8_BAR; PG8_SCHED;
;             PG8_STAGE(PG8_SB(1, 1), b3 + hstepB, voffB);
;             PG8_WAIT_V(6); PG8_BAR; PG8_MMA(1, 1, At, B1); PG8_BAR;
	s_mov_b32 m0, s70
	s_nop 0
	global_load_lds_dwordx4 v172, s[68:69]
	s_add_i32 m0, s70, 0x2000
	s_nop 0
	global_load_lds_dwordx4 v168, s[68:69]
	s_waitcnt vmcnt(6)
	s_setprio 1
	s_barrier
	v_mfma_f32_16x16x32_bf16 v[56:59], v[206:209], v[124:127], v[56:59]
	v_mfma_f32_16x16x32_bf16 v[52:55], v[214:217], v[124:127], v[52:55]
	s_add_i32 s68, 0, 0x18000
	v_add_u32_e32 v92, s68, v188
	ds_read_b128 v[80:83], v92
	v_mfma_f32_16x16x32_bf16 v[44:47], v[206:209], v[140:143], v[44:47]
	v_mfma_f32_16x16x32_bf16 v[36:39], v[214:217], v[140:143], v[36:39]
	ds_read_b128 v[84:87], v92 offset:1024
	v_mfma_f32_16x16x32_bf16 v[28:31], v[206:209], v[160:163], v[28:31]
	v_mfma_f32_16x16x32_bf16 v[20:23], v[214:217], v[160:163], v[20:23]
	ds_read_b128 v[88:91], v92 offset:2048
	v_mfma_f32_16x16x32_bf16 v[4:7], v[206:209], v[198:201], v[4:7]
	v_mfma_f32_16x16x32_bf16 v[0:3], v[214:217], v[198:201], v[0:3]
	ds_read_b128 v[92:95], v92 offset:3072
	v_mfma_f32_16x16x32_bf16 v[56:59], v[210:213], v[132:135], v[56:59]
	s_add_u32 s46, s46, 0x80000
	s_addc_u32 s47, s47, 0
	v_mfma_f32_16x16x32_bf16 v[52:55], v[218:221], v[132:135], v[52:55]
	v_mfma_f32_16x16x32_bf16 v[44:47], v[210:213], v[152:155], v[44:47]
	v_mfma_f32_16x16x32_bf16 v[36:39], v[218:221], v[152:155], v[36:39]
	v_mfma_f32_16x16x32_bf16 v[28:31], v[210:213], v[164:167], v[28:31]
	v_mfma_f32_16x16x32_bf16 v[20:23], v[218:221], v[164:167], v[20:23]
	v_mfma_f32_16x16x32_bf16 v[4:7], v[210:213], v[202:205], v[4:7]
	s_setprio 0
	v_mfma_f32_16x16x32_bf16 v[0:3], v[218:221], v[202:205], v[0:3]
	s_barrier
	s_mov_b32 m0, s55
	ds_read_b128 v[124:127], v190 offset:32768
	ds_read_b128 v[132:135], v190 offset:33792
	ds_read_b128 v[160:163], v190 offset:34816
	ds_read_b128 v[164:167], v190 offset:35840
	ds_read_b128 v[198:201], v190 offset:36864
	ds_read_b128 v[202:205], v190 offset:37888
	ds_read_b128 v[206:209], v190 offset:38912
	ds_read_b128 v[210:213], v190 offset:39936
	global_load_lds_dwordx4 v174, s[46:47]
	s_mov_b32 m0, s56
	s_nop 0
	global_load_lds_dwordx4 v170, s[46:47]
	s_waitcnt lgkmcnt(8)
	s_setprio 1
	s_barrier
	s_waitcnt lgkmcnt(7)
	v_mfma_f32_16x16x32_bf16 v[140:143], v[80:83], v[124:127], v[148:151]
	s_waitcnt lgkmcnt(6)
	v_mfma_f32_16x16x32_bf16 v[148:151], v[84:87], v[132:135], v[140:143]
	v_mfma_f32_16x16x32_bf16 v[140:143], v[88:91], v[124:127], v[144:147]
	s_waitcnt lgkmcnt(5)
	v_mfma_f32_16x16x32_bf16 v[136:139], v[80:83], v[160:163], v[136:139]
	v_mfma_f32_16x16x32_bf16 v[128:131], v[88:91], v[160:163], v[128:131]
	s_waitcnt lgkmcnt(3)
	v_mfma_f32_16x16x32_bf16 v[120:123], v[80:83], v[198:201], v[120:123]
	v_mfma_f32_16x16x32_bf16 v[104:107], v[88:91], v[198:201], v[104:107]
	s_waitcnt lgkmcnt(1)
	v_mfma_f32_16x16x32_bf16 v[76:79], v[80:83], v[206:209], v[76:79]
	v_mfma_f32_16x16x32_bf16 v[72:75], v[88:91], v[206:209], v[72:75]
	s_add_i32 s46, 0, 0x1c000
	v_mfma_f32_16x16x32_bf16 v[144:147], v[92:95], v[132:135], v[140:143]
	v_add_u32_e32 v140, s46, v188
	v_mfma_f32_16x16x32_bf16 v[136:139], v[84:87], v[164:167], v[136:139]
	s_add_i32 s47, s68, s37
	v_mfma_f32_16x16x32_bf16 v[128:131], v[92:95], v[164:167], v[128:131]
	v_mfma_f32_16x16x32_bf16 v[120:123], v[84:87], v[202:205], v[120:123]
	v_mfma_f32_16x16x32_bf16 v[104:107], v[92:95], v[202:205], v[104:107]
	s_waitcnt lgkmcnt(0)
	v_mfma_f32_16x16x32_bf16 v[76:79], v[84:87], v[210:213], v[76:79]
	s_setprio 0
	v_mfma_f32_16x16x32_bf16 v[72:75], v[92:95], v[210:213], v[72:75]
	s_barrier
	ds_read_b128 v[214:217], v140
	ds_read_b128 v[218:221], v140 offset:1024
	ds_read_b128 v[222:225], v140 offset:2048
	ds_read_b128 v[226:229], v140 offset:3072
	v_lshl_add_u64 v[140:141], v[184:185], 0, s[14:15]
	s_mov_b32 m0, s47
	s_nop 0
	global_load_lds_dwordx4 v[140:141], off
	v_lshl_add_u64 v[140:141], v[194:195], 0, s[14:15]
	s_add_i32 m0, s47, 0x2000
	s_nop 0
	global_load_lds_dwordx4 v[140:141], off
	s_setprio 1
	s_barrier
	s_waitcnt lgkmcnt(1)
	v_mfma_f32_16x16x32_bf16 v[96:99], v[222:225], v[124:127], v[96:99]
	v_mfma_f32_16x16x32_bf16 v[140:143], v[214:217], v[124:127], v[156:159]
	s_waitcnt lgkmcnt(0)
	v_mfma_f32_16x16x32_bf16 v[152:155], v[226:229], v[132:135], v[96:99]
	v_mfma_f32_16x16x32_bf16 v[96:99], v[214:217], v[160:163], v[100:103]
	v_mfma_f32_16x16x32_bf16 v[156:159], v[218:221], v[132:135], v[140:143]
	v_mfma_f32_16x16x32_bf16 v[140:143], v[218:221], v[164:167], v[96:99]
	v_mfma_f32_16x16x32_bf16 v[96:99], v[222:225], v[160:163], v[108:111]
	v_mfma_f32_16x16x32_bf16 v[132:135], v[226:229], v[164:167], v[96:99]
	v_mfma_f32_16x16x32_bf16 v[96:99], v[214:217], v[198:201], v[112:115]
	s_mov_b32 m0, s62
	v_mfma_f32_16x16x32_bf16 v[124:127], v[218:221], v[202:205], v[96:99]
	v_lshl_add_u64 v[184:185], v[230:231], 0, s[14:15]
	v_mfma_f32_16x16x32_bf16 v[96:99], v[222:225], v[198:201], v[116:119]
	v_mfma_f32_16x16x32_bf16 v[68:71], v[214:217], v[206:209], v[68:71]
	v_mfma_f32_16x16x32_bf16 v[64:67], v[222:225], v[206:209], v[64:67]
	v_mfma_f32_16x16x32_bf16 v[116:119], v[226:229], v[202:205], v[96:99]
	v_mfma_f32_16x16x32_bf16 v[68:71], v[218:221], v[210:213], v[68:71]
	s_setprio 0
	v_mfma_f32_16x16x32_bf16 v[64:67], v[226:229], v[210:213], v[64:67]
	s_barrier
	ds_read_b128 v[96:99], v190 offset:49152
	ds_read_b128 v[100:103], v190 offset:50176
	ds_read_b128 v[108:111], v190 offset:51200
	ds_read_b128 v[112:115], v190 offset:52224
	ds_read_b128 v[160:163], v190 offset:53248
	ds_read_b128 v[164:167], v190 offset:54272
	ds_read_b128 v[198:201], v190 offset:55296
	ds_read_b128 v[202:205], v190 offset:56320
	global_load_lds_dwordx4 v[184:185], off
	v_lshl_add_u64 v[184:185], v[232:233], 0, s[14:15]
	s_mov_b32 m0, s63
	s_nop 0
	global_load_lds_dwordx4 v[184:185], off
	s_waitcnt vmcnt(10)
	s_setprio 1
	s_barrier
; #define PG8_STAGE(bufoff, gbase, voff) do { _Pragma("unroll") for (int _i = 0; _i < 2; ++_i) \
;         __builtin_amdgcn_global_load_lds((const unsigned*)((const char*)(gbase) + (voff)[_i]), (LAS unsigned*)(lds + (bufoff) + ldsw + _i * 8192), 16, 0, 0); } while (0)
; #define PG8_LDA(dst, b, h) do { _Pragma("unroll") for (int m = 0; m < 4; ++m) _Pragma("unroll") for (int k = 0; k < 2; ++k) dst[m][k] = *(const LAS bf16x8*)(lds + PG8_SA(b, h) + aoff + m * 2048 + k * 1024); } while (0)
; #define PG8_LDB(dst, b, h) do { _Pragma("unroll") for (int n = 0; n < 2; ++n) _Pragma("unroll") for (int k = 0; k < 2; ++k) dst[n][k] = *(const LAS bf16x8*)(lds + PG8_SB(b, h) + boff + n * 2048 + k * 1024); } while (0)
; #define PG8_MMA(ai, bj, At, Bt) do { __builtin_amdgcn_s_setprio(1); _Pragma("unroll") for (int m = 0; m < 4; ++m) _Pragma("unroll") for (int n = 0; n < 2; ++n) _Pragma("unroll") for (int k = 0; k < 2; ++k) \
;         acc[ai][bj][m][n] = __builtin_amdgcn_mfma_f32_16x16x32_bf16(Bt[n][k], At[m][k], acc[ai][bj][m][n], 0, 0, 0); __builtin_amdgcn_s_setprio(0); } while (0)
; #define PG8_WAIT_V(n) asm volatile("s_waitcnt vmcnt(" #n ")" ::: "memory")
; #define PG8_WAIT_L(n) asm volatile("s_waitcnt lgkmcnt(" #n ")" ::: "memory")
; #define PG8_BAR __builtin_amdgcn_s_barrier()
; #define PG8_SCHED __builtin_amdgcn_sched_barrier(0)
; template <class Map, class Epi>
; DI void gemm_phase(LAS unsigned char* lds, const Map& MP, const Epi& E, const int nM, const int nN, const int K, const int lda, const int ldb) {
;     ...
;             PG8_WAIT_L(8); PG8_BAR; PG8_WAIT_L(0); PG8_MMA(0, 0, At, B0); PG8_BAR; PG8_SCHED;
;             PG8_LDB(B1, 1, 1); PG8_STAGE(PG8_SB(1, 0), b3, voffB);
;             PG8_BAR; PG8_WAIT_L(0); PG8_MMA(0, 1, At, B1); PG8_BAR;
;             PG8_LDA(At, 1, 1); PG8_STAGE(PG8_SA(1, 0), a3, voffA);
;             PG8_BAR; PG8_WAIT_L(0); PG8_MMA(1, 0, At, B0); PG8_BAR; PG8_SCHED;
;             PG8_STAGE(PG8_SB(1, 1), b3 + hstepB, voffB);
;             PG8_WAIT_V(6); PG8_BAR; PG8_MMA(1, 1, At, B1); PG8_BAR;
	s_waitcnt lgkmcnt(7)
	v_mfma_f32_16x16x32_bf16 v[60:63], v[80:83], v[96:99], v[60:63]
	v_mfma_f32_16x16x32_bf16 v[48:51], v[88:91], v[96:99], v[48:51]
	s_waitcnt lgkmcnt(5)
	v_mfma_f32_16x16x32_bf16 v[40:43], v[80:83], v[108:111], v[40:43]
	v_mfma_f32_16x16x32_bf16 v[32:35], v[88:91], v[108:111], v[32:35]
	s_waitcnt lgkmcnt(3)
	v_mfma_f32_16x16x32_bf16 v[24:27], v[80:83], v[160:163], v[24:27]
	v_mfma_f32_16x16x32_bf16 v[16:19], v[88:91], v[160:163], v[16:19]
	s_waitcnt lgkmcnt(1)
	v_mfma_f32_16x16x32_bf16 v[12:15], v[80:83], v[198:201], v[12:15]
	v_mfma_f32_16x16x32_bf16 v[8:11], v[88:91], v[198:201], v[8:11]
	v_mfma_f32_16x16x32_bf16 v[60:63], v[84:87], v[100:103], v[60:63]
	s_add_u32 s28, s28, 0x80080
	s_addc_u32 s29, s29, 0
	v_mfma_f32_16x16x32_bf16 v[48:51], v[92:95], v[100:103], v[48:51]
	s_add_i32 s46, s46, s37
	v_mfma_f32_16x16x32_bf16 v[40:43], v[84:87], v[112:115], v[40:43]
	v_mfma_f32_16x16x32_bf16 v[32:35], v[92:95], v[112:115], v[32:35]
	v_mfma_f32_16x16x32_bf16 v[24:27], v[84:87], v[164:167], v[24:27]
	v_mfma_f32_16x16x32_bf16 v[16:19], v[92:95], v[164:167], v[16:19]
	s_waitcnt lgkmcnt(0)
	v_mfma_f32_16x16x32_bf16 v[12:15], v[84:87], v[202:205], v[12:15]
	s_setprio 0
	v_mfma_f32_16x16x32_bf16 v[8:11], v[92:95], v[202:205], v[8:11]
	s_barrier
	s_mov_b32 m0, s46
	s_nop 0
	global_load_lds_dwordx4 v172, s[28:29]
	s_add_i32 m0, s46, 0x2000
	s_nop 0
	global_load_lds_dwordx4 v168, s[28:29]
	s_waitcnt vmcnt(6)
	s_setprio 1
	s_barrier
	v_mfma_f32_16x16x32_bf16 v[56:59], v[214:217], v[96:99], v[56:59]
	v_mfma_f32_16x16x32_bf16 v[52:55], v[222:225], v[96:99], v[52:55]
	ds_read_b128 v[80:83], v189
	v_mfma_f32_16x16x32_bf16 v[44:47], v[214:217], v[108:111], v[44:47]
	v_mfma_f32_16x16x32_bf16 v[36:39], v[222:225], v[108:111], v[36:39]
	ds_read_b128 v[84:87], v189 offset:1024
	v_mfma_f32_16x16x32_bf16 v[28:31], v[214:217], v[160:163], v[28:31]
	v_mfma_f32_16x16x32_bf16 v[20:23], v[222:225], v[160:163], v[20:23]
	ds_read_b128 v[88:91], v189 offset:2048
	v_mfma_f32_16x16x32_bf16 v[4:7], v[214:217], v[198:201], v[4:7]
	v_mfma_f32_16x16x32_bf16 v[0:3], v[222:225], v[198:201], v[0:3]
	ds_read_b128 v[92:95], v189 offset:3072
	v_mfma_f32_16x16x32_bf16 v[56:59], v[218:221], v[100:103], v[56:59]
	s_add_i32 s3, s3, 2
	v_mfma_f32_16x16x32_bf16 v[52:55], v[226:229], v[100:103], v[52:55]
	s_add_u32 vcc_lo, vcc_lo, 0x100
	s_addc_u32 vcc_hi, vcc_hi, 0
	v_mfma_f32_16x16x32_bf16 v[44:47], v[218:221], v[112:115], v[44:47]
	s_add_u32 s42, s42, 0x100
	s_addc_u32 s43, s43, 0
	v_mfma_f32_16x16x32_bf16 v[36:39], v[226:229], v[112:115], v[36:39]
	s_cmp_gt_u32 s3, 29
	v_mfma_f32_16x16x32_bf16 v[28:31], v[218:221], v[164:167], v[28:31]
	v_mfma_f32_16x16x32_bf16 v[20:23], v[226:229], v[164:167], v[20:23]
	v_mfma_f32_16x16x32_bf16 v[4:7], v[218:221], v[202:205], v[4:7]
	s_setprio 0
	v_mfma_f32_16x16x32_bf16 v[0:3], v[226:229], v[202:205], v[0:3]
	s_barrier
	s_cbranch_scc0 .LBB1_2483
; DI float silu_mul(float g, float v) { return g * v * __builtin_amdgcn_rcpf(1.0f + __builtin_amdgcn_exp2f(-LOG2E * g)); }
;     DI void operator()(const f32x4 (&acc)[2][2][4][2], const Unit& u, int wr, int wc, int fr, int fq) const {
;         const int row0 = u.pm * BM + wr * 64 + fr, ch0 = u.pn * 128 + wc * 32 + 8 * fq;
;         f32x4 w0[2], w1[2], w2[2], bb[2];
; #pragma unroll
;         for (int n = 0; n < 2; ++n) { w0[n] = *(const f32x4*)(cw + ch0 + 4 * n); w1[n] = *(const f32x4*)(cw + DFF + ch0 + 4 * n); w2[n] = *(const f32x4*)(cw + 2 * DFF + ch0 + 4 * n); bb[n] = *(const f32x4*)(cb + ch0 + 4 * n); }
; #pragma unroll
;         for (int ai = 0; ai < 2; ++ai)
; #pragma unroll
;             for (int m = 0; m < 4; ++m) {
;                 const bool efirst = (m == 0) && (fr == 0), elast = (m == 3) && (fr == 15);
;                 const int row = row0 + ai * HALF + m * 16;
;                 f32x4 gc[2];
; #pragma unroll
;                 for (int n = 0; n < 2; ++n) {
;                     const f32x4 g = acc[ai][0][m][n];
;                     const f32x4 gprev = acc[ai][0][m > 0 ? m - 1 : 0][n], gnext = acc[ai][0][m < 3 ? m + 1 : 3][n];
;                     f32x4 up, dn;
; #pragma unroll
;                     for (int e = 0; e < 4; ++e) {
;                         const float pu = (m > 0 && fr == 15) ? gprev[e] : g[e];
;                         const float pd = (m < 3 && fr == 0) ? gnext[e] : g[e];
;                         up[e] = dpp_ror1(pu); dn[e] = dpp_ror15(pd);
;                     }
;                     if (efirst) up = (f32x4){0.f, 0.f, 0.f, 0.f};
;                     if (elast) dn = (f32x4){0.f, 0.f, 0.f, 0.f};
;                     gc[n] = w0[n] * up + w1[n] * g + w2[n] * dn + bb[n];
;                 }
;                 if (efirst || elast) {
;                     const size_t eo = (size_t)((row >> 6) * 2 + (elast ? 1 : 0)) * DFF + ch0;
; #pragma unroll
;                     for (int n = 0; n < 2; ++n) { *(f32x4*)(EP + eo + 4 * n) = gc[n]; *(f32x4*)(ER + eo + 4 * n) = acc[ai][0][m][n]; *(f32x4*)(EV + eo + 4 * n) = acc[ai][1][m][n]; }
;                 } else {
;                     const f32x4 v0 = acc[ai][1][m][0], v1 = acc[ai][1][m][1];
;                     u32x4 o;
;                     o[0] = pack2(silu_mul(gc[0][0], v0[0]), silu_mul(gc[0][1], v0[1])); o[1] = pack2(silu_mul(gc[0][2], v0[2]), silu_mul(gc[0][3], v0[3]));
	s_waitcnt lgkmcnt(0)
	s_lshl_b32 s21, s45, 7
	v_mov_b32_e32 v80, v187
	v_mov_b32_e32 v194, v186
	s_or_b32 s21, s21, s57
	v_lshl_add_u32 v184, v80, 3, s21
	v_ashrrev_i32_e32 v185, 31, v184
	v_lshlrev_b64 v[80:81], 2, v[184:185]
	v_lshl_add_u64 v[84:85], s[4:5], 0, v[80:81]
	v_lshl_add_u64 v[88:89], s[16:17], 0, v[80:81]
	v_lshl_add_u64 v[92:93], s[18:19], 0, v[80:81]
	v_lshl_add_u64 v[112:113], s[6:7], 0, v[80:81]
	global_load_dwordx4 v[80:83], v[84:85], off offset:16
	global_load_dwordx4 v[96:99], v[84:85], off
	s_nop 0
	global_load_dwordx4 v[84:87], v[88:89], off offset:16
	global_load_dwordx4 v[100:103], v[88:89], off
	s_nop 0
	global_load_dwordx4 v[88:91], v[92:93], off offset:16
	global_load_dwordx4 v[108:111], v[92:93], off
	s_nop 0
	global_load_dwordx4 v[92:95], v[112:113], off offset:16
	s_nop 0
	global_load_dwordx4 v[112:115], v[112:113], off
	v_cmp_eq_u32_e32 vcc, 0, v194
	s_nop 0
	s_nop 0
	v_cndmask_b32_e32 v161, v148, v136, vcc
	v_cndmask_b32_e32 v162, v149, v137, vcc
	v_cndmask_b32_e32 v163, v150, v138, vcc
	v_mov_b32_dpp v160, v161 row_ror:15 row_mask:0xf bank_mask:0xf
	s_nop 0
	s_nop 0
	v_mov_b32_dpp v161, v162 row_ror:15 row_mask:0xf bank_mask:0xf
	v_mov_b32_dpp v164, v150 row_ror:1 row_mask:0xf bank_mask:0xf
	v_cndmask_b32_e32 v165, v151, v139, vcc
	v_mov_b32_dpp v162, v163 row_ror:15 row_mask:0xf bank_mask:0xf
	v_mov_b32_dpp v195, v151 row_ror:1 row_mask:0xf bank_mask:0xf
	v_mov_b32_dpp v166, v148 row_ror:1 row_mask:0xf bank_mask:0xf
	v_mov_b32_dpp v167, v149 row_ror:1 row_mask:0xf bank_mask:0xf
	v_mov_b32_dpp v163, v165 row_ror:15 row_mask:0xf bank_mask:0xf
	v_cndmask_b32_e64 v165, v195, 0, vcc
	v_cndmask_b32_e64 v164, v164, 0, vcc
	v_cndmask_b32_e64 v167, v167, 0, vcc
	v_cndmask_b32_e64 v166, v166, 0, vcc
	s_nop 0
	s_nop 0
	v_mov_b32_dpp v195, v144 row_ror:1 row_mask:0xf bank_mask:0xf
	v_mov_b32_dpp v196, v145 row_ror:1 row_mask:0xf bank_mask:0xf
	v_mov_b32_dpp v198, v146 row_ror:1 row_mask:0xf bank_mask:0xf
	v_cndmask_b32_e32 v199, v147, v131, vcc
	v_mov_b32_dpp v200, v147 row_ror:1 row_mask:0xf bank_mask:0xf
	v_cndmask_b32_e64 v198, v198, 0, vcc
	v_cndmask_b32_e64 v201, v196, 0, vcc
	s_lshl_b32 s3, s44, 8
	s_add_i32 s3, s3, s49
	v_add_u32_e32 v193, s3, v194
	v_cmp_ne_u32_e64 s[46:47], 0, v194
	s_waitcnt vmcnt(0)
	v_pk_mul_f32 v[164:165], v[98:99], v[164:165]
	v_pk_mul_f32 v[166:167], v[96:97], v[166:167]
	v_pk_fma_f32 v[164:165], v[150:151], v[102:103], v[164:165]
	v_pk_fma_f32 v[166:167], v[148:149], v[100:101], v[166:167]
	v_pk_fma_f32 v[162:163], v[110:111], v[162:163], v[164:165]
	v_cndmask_b32_e32 v165, v144, v128, vcc
	v_pk_fma_f32 v[160:161], v[108:109], v[160:161], v[166:167]
	v_cndmask_b32_e32 v166, v145, v129, vcc
	v_mov_b32_dpp v164, v165 row_ror:15 row_mask:0xf bank_mask:0xf
	v_cndmask_b32_e32 v167, v146, v130, vcc
	v_pk_add_f32 v[162:163], v[114:115], v[162:163]
	v_mov_b32_dpp v165, v166 row_ror:15 row_mask:0xf bank_mask:0xf
	v_pk_add_f32 v[160:161], v[112:113], v[160:161]
	s_nop 0
	v_mov_b32_dpp v166, v167 row_ror:15 row_mask:0xf bank_mask:0xf
	s_nop 1
	v_mov_b32_dpp v167, v199 row_ror:15 row_mask:0xf bank_mask:0xf
	v_cndmask_b32_e64 v199, v200, 0, vcc
	v_cndmask_b32_e64 v200, v195, 0, vcc
	v_pk_mul_f32 v[200:201], v[80:81], v[200:201]
	v_pk_mul_f32 v[198:199], v[82:83], v[198:199]
	v_pk_fma_f32 v[200:201], v[144:145], v[84:85], v[200:201]
	v_pk_fma_f32 v[198:199], v[146:147], v[86:87], v[198:199]
	v_pk_fma_f32 v[164:165], v[88:89], v[164:165], v[200:201]
	v_pk_fma_f32 v[166:167], v[90:91], v[166:167], v[198:199]
	v_pk_add_f32 v[164:165], v[92:93], v[164:165]
	v_pk_add_f32 v[166:167], v[94:95], v[166:167]
	s_and_saveexec_b64 s[28:29], s[46:47]
	s_xor_b64 s[28:29], exec, s[28:29]
	s_cbranch_execz .LBB1_2486
	v_mul_f32_e32 v195, 0xbfb8aa3b, v160
	v_exp_f32_e32 v195, v195
	v_mul_f32_e32 v196, 0xbfb8aa3b, v161
	v_exp_f32_e32 v196, v196
	v_pk_mul_f32 v[160:161], v[156:157], v[160:161]
	v_add_f32_e32 v195, 1.0, v195
	v_rcp_f32_e32 v198, v195
	v_add_f32_e32 v196, 1.0, v196
	v_mul_f32_e32 v195, 0xbfb8aa3b, v162
	v_rcp_f32_e32 v199, v196
	v_exp_f32_e32 v195, v195
	v_mul_f32_e32 v196, 0xbfb8aa3b, v163
	v_exp_f32_e32 v196, v196
	v_pk_mul_f32 v[160:161], v[160:161], v[198:199]
	v_add_f32_e32 v195, 1.0, v195
	v_rcp_f32_e32 v200, v195
	v_add_f32_e32 v195, 1.0, v196
	v_rcp_f32_e32 v201, v195
	v_cvt_pk_bf16_f32 v160, v160, v161
	v_mul_f32_e32 v161, 0xbfb8aa3b, v164
	v_exp_f32_e32 v195, v161
	v_mul_f32_e32 v161, 0xbfb8aa3b, v165
	v_exp_f32_e32 v196, v161
	v_pk_mul_f32 v[162:163], v[158:159], v[162:163]
	v_pk_mul_f32 v[164:165], v[152:153], v[164:165]
	v_pk_mul_f32 v[162:163], v[162:163], v[200:201]
	s_nop 0
	v_cvt_pk_bf16_f32 v161, v162, v163
	v_add_f32_e32 v162, 1.0, v195
	v_mul_f32_e32 v195, 0xbfb8aa3b, v166
	v_add_f32_e32 v163, 1.0, v196
	v_exp_f32_e32 v195, v195
	v_mul_f32_e32 v196, 0xbfb8aa3b, v167
	v_exp_f32_e32 v196, v196
	v_rcp_f32_e32 v162, v162
	v_add_f32_e32 v195, 1.0, v195
	v_rcp_f32_e32 v198, v195
	v_add_f32_e32 v195, 1.0, v196
	v_rcp_f32_e32 v163, v163
	v_rcp_f32_e32 v199, v195
	v_pk_mul_f32 v[166:167], v[154:155], v[166:167]
	v_pk_mul_f32 v[162:163], v[164:165], v[162:163]
	v_pk_mul_f32 v[164:165], v[166:167], v[198:199]
	v_cvt_pk_bf16_f32 v162, v162, v163
	v_cvt_pk_bf16_f32 v163, v164, v165
	v_mov_b64_e32 v[164:165], s[52:53]
	v_mad_i64_i32 v[164:165], s[42:43], v193, s60, v[164:165]
	v_lshl_add_u64 v[164:165], v[184:185], 1, v[164:165]
	global_store_dwordx4 v[164:165], v[160:163], off

; #define PG8_STAGE(bufoff, gbase, voff) do { _Pragma("unroll") for (int _i = 0; _i < 2; ++_i) \
;         __builtin_amdgcn_global_load_lds((const unsigned*)((const char*)(gbase) + (voff)[_i]), (LAS unsigned*)(lds + (bufoff) + ldsw + _i * 8192), 16, 0, 0); } while (0)
; #define PG8_LDA(dst, b, h) do { _Pragma("unroll") for (int m = 0; m < 4; ++m) _Pragma("unroll") for (int k = 0; k < 2; ++k) dst[m][k] = *(const LAS bf16x8*)(lds + PG8_SA(b, h) + aoff + m * 2048 + k * 1024); } while (0)
; #define PG8_WAIT_V(n) asm volatile("s_waitcnt vmcnt(" #n ")" ::: "memory")
; #define PG8_WAIT_L(n) asm volatile("s_waitcnt lgkmcnt(" #n ")" ::: "memory")
; #define PG8_BAR __builtin_amdgcn_s_barrier()
; template <class Map, class Epi>
; DI void gemm_phase(LAS unsigned char* lds, const Map& MP, const Epi& E, const int nM, const int nN, const int K, const int lda, const int ldb) {
;     ...
;             const char* a1 = cA + (size_t)(t + 1) * kstep;
;             const char* a2 = last ? nA : cA + (size_t)(t + 2) * kstep; const char* b2 = last ? nB : cB + (size_t)(t + 2) * kstep;
;             const char* a3 = a2 + kstep; const char* b3 = b2 + kstep;
;             PG8_LDB(B0, 0, 0); PG8_SCHED; PG8_LDA(At, 0, 0); PG8_STAGE(PG8_SA(1, 1), a1 + hstepA, voffA);
;             PG8_WAIT_L(8); PG8_BAR; PG8_WAIT_L(0); PG8_MMA(0, 0, At, B0); PG8_BAR; PG8_SCHED;
;             PG8_LDB(B1, 0, 1); PG8_STAGE(PG8_SB(0, 0), b2, voffB);
;             PG8_BAR; PG8_WAIT_L(0); PG8_MMA(0, 1, At, B1); PG8_BAR;
;             PG8_LDA(At, 0, 1); PG8_STAGE(PG8_SA(0, 0), a2, voffA);
;             PG8_BAR; PG8_WAIT_L(0); PG8_MMA(1, 0, At, B0); PG8_BAR; PG8_SCHED;
;             PG8_STAGE(PG8_SB(0, 1), b2 + hstepB, voffB);
;             PG8_WAIT_V(6); PG8_BAR; PG8_MMA(1, 1, At, B1); PG8_BAR;
;             PG8_LDB(B0, 1, 0); PG8_SCHED; PG8_LDA(At, 1, 0); PG8_STAGE(PG8_SA(0, 1), a2 + hstepA, voffA);
;             PG8_WAIT_L(8); PG8_BAR; PG8_WAIT_L(0); PG8_MMA(0, 0, At, B0); PG8_BAR; PG8_SCHED;
;             PG8_LDB(B1, 1, 1); PG8_STAGE(PG8_SB(1, 0), b3, voffB);
;             PG8_BAR; PG8_WAIT_L(0); PG8_MMA(0, 1, At, B1); PG8_BAR;
;             PG8_LDA(At, 1, 1); PG8_STAGE(PG8_SA(1, 0), a3, voffA);
;             PG8_BAR; PG8_WAIT_L(0); PG8_MMA(1, 0, At, B0); PG8_BAR; PG8_SCHED;
;             PG8_STAGE(PG8_SB(1, 1), b3 + hstepB, voffB);
;             PG8_WAIT_V(6); PG8_BAR; PG8_MMA(1, 1, At, B1); PG8_BAR;
.LBB1_2653:
	s_add_u32 s10, s8, 0x100
	s_addc_u32 s11, s9, 0
	s_cmpk_eq_i32 s48, 0x54
	s_cselect_b32 s15, s43, s11
	s_cselect_b32 s14, s42, s10
	s_cselect_b32 s13, s45, s39
	s_cselect_b32 s12, s44, s38
	s_add_i32 m0, s22, 0xc000
	ds_read_b128 v[168:171], v150
	ds_read_b128 v[172:175], v150 offset:1024
	ds_read_b128 v[176:179], v150 offset:2048
	ds_read_b128 v[180:183], v150 offset:3072
	ds_read_b128 v[184:187], v150 offset:4096
	ds_read_b128 v[188:191], v150 offset:5120
	ds_read_b128 v[192:195], v150 offset:6144
	ds_read_b128 v[196:199], v150 offset:7168
	global_load_lds_dwordx4 v138, s[8:9]
	s_add_i32 m0, s22, 0xe000
	s_nop 0
	global_load_lds_dwordx4 v136, s[8:9]
	s_waitcnt lgkmcnt(8)
	s_setprio 1
	s_barrier
	s_waitcnt lgkmcnt(7)
	v_mfma_f32_16x16x32_bf16 v[124:127], v[152:155], v[168:171], v[124:127]
	v_mfma_f32_16x16x32_bf16 v[120:123], v[160:163], v[168:171], v[120:123]
	s_waitcnt lgkmcnt(5)
	v_mfma_f32_16x16x32_bf16 v[108:111], v[152:155], v[176:179], v[108:111]
	v_mfma_f32_16x16x32_bf16 v[104:107], v[160:163], v[176:179], v[104:107]
	s_waitcnt lgkmcnt(3)
	v_mfma_f32_16x16x32_bf16 v[92:95], v[152:155], v[184:187], v[92:95]
	v_mfma_f32_16x16x32_bf16 v[88:91], v[160:163], v[184:187], v[88:91]
	s_waitcnt lgkmcnt(1)
	v_mfma_f32_16x16x32_bf16 v[76:79], v[152:155], v[192:195], v[76:79]
	v_mfma_f32_16x16x32_bf16 v[72:75], v[160:163], v[192:195], v[72:75]
	v_mfma_f32_16x16x32_bf16 v[124:127], v[156:159], v[172:175], v[124:127]
	s_add_i32 s8, s33, s20
	v_mfma_f32_16x16x32_bf16 v[120:123], v[164:167], v[172:175], v[120:123]
	v_lshl_add_u64 v[144:145], s[12:13], 0, v[132:133]
	v_mfma_f32_16x16x32_bf16 v[108:111], v[156:159], v[180:183], v[108:111]
	v_lshl_add_u64 v[216:217], s[12:13], 0, v[128:129]
	v_mfma_f32_16x16x32_bf16 v[104:107], v[164:167], v[180:183], v[104:107]
	v_mfma_f32_16x16x32_bf16 v[92:95], v[156:159], v[188:191], v[92:95]
	v_mfma_f32_16x16x32_bf16 v[88:91], v[164:167], v[188:191], v[88:91]
	s_waitcnt lgkmcnt(0)
	v_mfma_f32_16x16x32_bf16 v[76:79], v[156:159], v[196:199], v[76:79]
	s_setprio 0
	v_mfma_f32_16x16x32_bf16 v[72:75], v[164:167], v[196:199], v[72:75]
	s_barrier
	s_mov_b32 m0, s8
	ds_read_b128 v[200:203], v151
	ds_read_b128 v[204:207], v151 offset:1024
	ds_read_b128 v[208:211], v151 offset:2048
	ds_read_b128 v[212:215], v151 offset:3072
	global_load_lds_dwordx4 v[144:145], off
	s_add_i32 m0, s8, 0x2000
	s_nop 0
	global_load_lds_dwordx4 v[216:217], off
	s_setprio 1
	s_barrier
	s_waitcnt lgkmcnt(3)
	v_mfma_f32_16x16x32_bf16 v[116:119], v[200:203], v[168:171], v[116:119]
	s_waitcnt lgkmcnt(1)
	v_mfma_f32_16x16x32_bf16 v[112:115], v[208:211], v[168:171], v[112:115]
	v_mfma_f32_16x16x32_bf16 v[100:103], v[200:203], v[176:179], v[100:103]
	v_mfma_f32_16x16x32_bf16 v[96:99], v[208:211], v[176:179], v[96:99]
	v_mfma_f32_16x16x32_bf16 v[84:87], v[200:203], v[184:187], v[84:87]
	v_mfma_f32_16x16x32_bf16 v[80:83], v[208:211], v[184:187], v[80:83]
	v_mfma_f32_16x16x32_bf16 v[68:71], v[200:203], v[192:195], v[68:71]
	v_mfma_f32_16x16x32_bf16 v[64:67], v[208:211], v[192:195], v[64:67]
	v_mfma_f32_16x16x32_bf16 v[116:119], v[204:207], v[172:175], v[116:119]
	v_lshl_add_u64 v[220:221], s[14:15], 0, v[130:131]
	s_mov_b32 m0, s22
	s_waitcnt lgkmcnt(0)
	v_mfma_f32_16x16x32_bf16 v[112:115], v[212:215], v[172:175], v[112:115]
	v_lshl_add_u64 v[218:219], s[14:15], 0, v[134:135]
	v_mfma_f32_16x16x32_bf16 v[100:103], v[204:207], v[180:183], v[100:103]
	v_mfma_f32_16x16x32_bf16 v[96:99], v[212:215], v[180:183], v[96:99]
	v_mfma_f32_16x16x32_bf16 v[84:87], v[204:207], v[188:191], v[84:87]
	v_mfma_f32_16x16x32_bf16 v[80:83], v[212:215], v[188:191], v[80:83]
	v_mfma_f32_16x16x32_bf16 v[68:71], v[204:207], v[196:199], v[68:71]
	s_setprio 0
	v_mfma_f32_16x16x32_bf16 v[64:67], v[212:215], v[196:199], v[64:67]
	s_barrier
	ds_read_b128 v[168:171], v150 offset:16384
	ds_read_b128 v[172:175], v150 offset:17408
	ds_read_b128 v[176:179], v150 offset:18432
	ds_read_b128 v[180:183], v150 offset:19456
	ds_read_b128 v[184:187], v150 offset:20480
	ds_read_b128 v[188:191], v150 offset:21504
	ds_read_b128 v[192:195], v150 offset:22528
	ds_read_b128 v[196:199], v150 offset:23552
	global_load_lds_dwordx4 v[218:219], off
	s_mov_b32 m0, s23
	s_nop 0
	global_load_lds_dwordx4 v[220:221], off
	s_waitcnt vmcnt(10)
	s_setprio 1
	s_barrier
	s_waitcnt lgkmcnt(7)
	v_mfma_f32_16x16x32_bf16 v[60:63], v[152:155], v[168:171], v[60:63]
	v_mfma_f32_16x16x32_bf16 v[56:59], v[160:163], v[168:171], v[56:59]
	s_waitcnt lgkmcnt(5)
	v_mfma_f32_16x16x32_bf16 v[44:47], v[152:155], v[176:179], v[44:47]
	v_mfma_f32_16x16x32_bf16 v[40:43], v[160:163], v[176:179], v[40:43]
	s_waitcnt lgkmcnt(3)
	v_mfma_f32_16x16x32_bf16 v[28:31], v[152:155], v[184:187], v[28:31]
	v_mfma_f32_16x16x32_bf16 v[24:27], v[160:163], v[184:187], v[24:27]
	s_waitcnt lgkmcnt(1)
	v_mfma_f32_16x16x32_bf16 v[12:15], v[152:155], v[192:195], v[12:15]
	v_mfma_f32_16x16x32_bf16 v[8:11], v[160:163], v[192:195], v[8:11]
	v_mfma_f32_16x16x32_bf16 v[60:63], v[156:159], v[172:175], v[60:63]
	s_add_u32 s8, s12, 0x160000
	s_addc_u32 s9, s13, 0
	v_mfma_f32_16x16x32_bf16 v[56:59], v[164:167], v[172:175], v[56:59]
	s_add_i32 s49, s34, s20
	v_mfma_f32_16x16x32_bf16 v[44:47], v[156:159], v[180:183], v[44:47]
	v_mfma_f32_16x16x32_bf16 v[40:43], v[164:167], v[180:183], v[40:43]
	v_mfma_f32_16x16x32_bf16 v[28:31], v[156:159], v[188:191], v[28:31]
	v_mfma_f32_16x16x32_bf16 v[24:27], v[164:167], v[188:191], v[24:27]
	s_waitcnt lgkmcnt(0)
	v_mfma_f32_16x16x32_bf16 v[12:15], v[156:159], v[196:199], v[12:15]
	s_setprio 0
	v_mfma_f32_16x16x32_bf16 v[8:11], v[164:167], v[196:199], v[8:11]
	s_barrier
; #define PG8_STAGE(bufoff, gbase, voff) do { _Pragma("unroll") for (int _i = 0; _i < 2; ++_i) \
;         __builtin_amdgcn_global_load_lds((const unsigned*)((const char*)(gbase) + (voff)[_i]), (LAS unsigned*)(lds + (bufoff) + ldsw + _i * 8192), 16, 0, 0); } while (0)
; #define PG8_LDA(dst, b, h) do { _Pragma("unroll") for (int m = 0; m < 4; ++m) _Pragma("unroll") for (int k = 0; k < 2; ++k) dst[m][k] = *(const LAS bf16x8*)(lds + PG8_SA(b, h) + aoff + m * 2048 + k * 1024); } while (0)
; #define PG8_LDB(dst, b, h) do { _Pragma("unroll") for (int n = 0; n < 2; ++n) _Pragma("unroll") for (int k = 0; k < 2; ++k) dst[n][k] = *(const LAS bf16x8*)(lds + PG8_SB(b, h) + boff + n * 2048 + k * 1024); } while (0)
; #define PG8_WAIT_V(n) asm volatile("s_waitcnt vmcnt(" #n ")" ::: "memory")
; #define PG8_WAIT_L(n) asm volatile("s_waitcnt lgkmcnt(" #n ")" ::: "memory")
; #define PG8_BAR __builtin_amdgcn_s_barrier()
; #define PG8_SCHED __builtin_amdgcn_sched_barrier(0)
; template <class Map, class Epi>
; DI void gemm_phase(LAS unsigned char* lds, const Map& MP, const Epi& E, const int nM, const int nN, const int K, const int lda, const int ldb) {
;     ...
;             PG8_LDB(B0, 0, 0); PG8_SCHED; PG8_LDA(At, 0, 0); PG8_STAGE(PG8_SA(1, 1), a1 + hstepA, voffA);
;             PG8_WAIT_L(8); PG8_BAR; PG8_WAIT_L(0); PG8_MMA(0, 0, At, B0); PG8_BAR; PG8_SCHED;
;             PG8_LDB(B1, 0, 1); PG8_STAGE(PG8_SB(0, 0), b2, voffB);
;             PG8_BAR; PG8_WAIT_L(0); PG8_MMA(0, 1, At, B1); PG8_BAR;
;             PG8_LDA(At, 0, 1); PG8_STAGE(PG8_SA(0, 0), a2, voffA);
;             PG8_BAR; PG8_WAIT_L(0); PG8_MMA(1, 0, At, B0); PG8_BAR; PG8_SCHED;
;             PG8_STAGE(PG8_SB(0, 1), b2 + hstepB, voffB);
;             PG8_WAIT_V(6); PG8_BAR; PG8_MMA(1, 1, At, B1); PG8_BAR;
;             PG8_LDB(B0, 1, 0); PG8_SCHED; PG8_LDA(At, 1, 0); PG8_STAGE(PG8_SA(0, 1), a2 + hstepA, voffA);
;             PG8_WAIT_L(8); PG8_BAR; PG8_WAIT_L(0); PG8_MMA(0, 0, At, B0); PG8_BAR; PG8_SCHED;
;             PG8_LDB(B1, 1, 1); PG8_STAGE(PG8_SB(1, 0), b3, voffB);
;             PG8_BAR; PG8_WAIT_L(0); PG8_MMA(0, 1, At, B1); PG8_BAR;
;             PG8_LDA(At, 1, 1); PG8_STAGE(PG8_SA(1, 0), a3, voffA);
;             PG8_BAR; PG8_WAIT_L(0); PG8_MMA(1, 0, At, B0); PG8_BAR; PG8_SCHED;
;             PG8_STAGE(PG8_SB(1, 1), b3 + hstepB, voffB);
;             PG8_WAIT_V(6); PG8_BAR; PG8_MMA(1, 1, At, B1); PG8_BAR;
	s_mov_b32 m0, s49
	s_nop 0
	global_load_lds_dwordx4 v132, s[8:9]
	s_add_i32 m0, s49, 0x2000
	s_nop 0
	global_load_lds_dwordx4 v128, s[8:9]
	s_waitcnt vmcnt(6)
	s_setprio 1
	s_barrier
	v_mfma_f32_16x16x32_bf16 v[52:55], v[200:203], v[168:171], v[52:55]
	v_mfma_f32_16x16x32_bf16 v[48:51], v[208:211], v[168:171], v[48:51]
	s_add_i32 s49, 0, 0x18000
	v_add_u32_e32 v164, s49, v148
	ds_read_b128 v[152:155], v164
	v_mfma_f32_16x16x32_bf16 v[36:39], v[200:203], v[176:179], v[36:39]
	v_mfma_f32_16x16x32_bf16 v[32:35], v[208:211], v[176:179], v[32:35]
	ds_read_b128 v[156:159], v164 offset:1024
	v_mfma_f32_16x16x32_bf16 v[20:23], v[200:203], v[184:187], v[20:23]
	v_mfma_f32_16x16x32_bf16 v[16:19], v[208:211], v[184:187], v[16:19]
	ds_read_b128 v[160:163], v164 offset:2048
	v_mfma_f32_16x16x32_bf16 v[4:7], v[200:203], v[192:195], v[4:7]
	v_mfma_f32_16x16x32_bf16 v[0:3], v[208:211], v[192:195], v[0:3]
	ds_read_b128 v[164:167], v164 offset:3072
	v_mfma_f32_16x16x32_bf16 v[52:55], v[204:207], v[172:175], v[52:55]
	s_add_u32 s8, s14, 0x160000
	s_addc_u32 s9, s15, 0
	v_mfma_f32_16x16x32_bf16 v[48:51], v[212:215], v[172:175], v[48:51]
	v_mfma_f32_16x16x32_bf16 v[36:39], v[204:207], v[180:183], v[36:39]
	v_mfma_f32_16x16x32_bf16 v[32:35], v[212:215], v[180:183], v[32:35]
	v_mfma_f32_16x16x32_bf16 v[20:23], v[204:207], v[188:191], v[20:23]
	v_mfma_f32_16x16x32_bf16 v[16:19], v[212:215], v[188:191], v[16:19]
	v_mfma_f32_16x16x32_bf16 v[4:7], v[204:207], v[196:199], v[4:7]
	s_setprio 0
	v_mfma_f32_16x16x32_bf16 v[0:3], v[212:215], v[196:199], v[0:3]
	s_barrier
	s_mov_b32 m0, s24
	ds_read_b128 v[168:171], v150 offset:32768
	ds_read_b128 v[172:175], v150 offset:33792
	ds_read_b128 v[176:179], v150 offset:34816
	ds_read_b128 v[180:183], v150 offset:35840
	ds_read_b128 v[184:187], v150 offset:36864
	ds_read_b128 v[188:191], v150 offset:37888
	ds_read_b128 v[192:195], v150 offset:38912
	ds_read_b128 v[196:199], v150 offset:39936
	global_load_lds_dwordx4 v134, s[8:9]
	s_mov_b32 m0, s25
	s_nop 0
	global_load_lds_dwordx4 v130, s[8:9]
	s_waitcnt lgkmcnt(8)
	s_setprio 1
	s_barrier
	s_waitcnt lgkmcnt(7)
	v_mfma_f32_16x16x32_bf16 v[124:127], v[152:155], v[168:171], v[124:127]
	v_mfma_f32_16x16x32_bf16 v[120:123], v[160:163], v[168:171], v[120:123]
	s_waitcnt lgkmcnt(5)
	v_mfma_f32_16x16x32_bf16 v[108:111], v[152:155], v[176:179], v[108:111]
	v_mfma_f32_16x16x32_bf16 v[104:107], v[160:163], v[176:179], v[104:107]
	s_waitcnt lgkmcnt(3)
	v_mfma_f32_16x16x32_bf16 v[92:95], v[152:155], v[184:187], v[92:95]
	v_mfma_f32_16x16x32_bf16 v[88:91], v[160:163], v[184:187], v[88:91]
	s_waitcnt lgkmcnt(1)
	v_mfma_f32_16x16x32_bf16 v[76:79], v[152:155], v[192:195], v[76:79]
	v_mfma_f32_16x16x32_bf16 v[72:75], v[160:163], v[192:195], v[72:75]
	v_mfma_f32_16x16x32_bf16 v[124:127], v[156:159], v[172:175], v[124:127]
	s_add_i32 s14, 0, 0x1c000
	v_mfma_f32_16x16x32_bf16 v[120:123], v[164:167], v[172:175], v[120:123]
	s_add_i32 s8, s49, s20
	v_mfma_f32_16x16x32_bf16 v[108:111], v[156:159], v[180:183], v[108:111]
	v_add_u32_e32 v212, s14, v148
	v_mfma_f32_16x16x32_bf16 v[104:107], v[164:167], v[180:183], v[104:107]
	v_lshl_add_u64 v[144:145], v[144:145], 0, s[46:47]
	v_mfma_f32_16x16x32_bf16 v[92:95], v[156:159], v[188:191], v[92:95]
	v_mfma_f32_16x16x32_bf16 v[88:91], v[164:167], v[188:191], v[88:91]
	s_waitcnt lgkmcnt(0)
	v_mfma_f32_16x16x32_bf16 v[76:79], v[156:159], v[196:199], v[76:79]
	s_setprio 0
	v_mfma_f32_16x16x32_bf16 v[72:75], v[164:167], v[196:199], v[72:75]
	s_barrier
	s_mov_b32 m0, s8
	ds_read_b128 v[200:203], v212
	ds_read_b128 v[204:207], v212 offset:1024
	ds_read_b128 v[208:211], v212 offset:2048
	ds_read_b128 v[212:215], v212 offset:3072
	global_load_lds_dwordx4 v[144:145], off
	v_lshl_add_u64 v[144:145], v[216:217], 0, s[46:47]
	s_add_i32 m0, s8, 0x2000
	s_nop 0
	global_load_lds_dwordx4 v[144:145], off
	s_setprio 1
	s_barrier
	s_waitcnt lgkmcnt(3)
	v_mfma_f32_16x16x32_bf16 v[116:119], v[200:203], v[168:171], v[116:119]
	s_waitcnt lgkmcnt(1)
	v_mfma_f32_16x16x32_bf16 v[112:115], v[208:211], v[168:171], v[112:115]
	v_mfma_f32_16x16x32_bf16 v[100:103], v[200:203], v[176:179], v[100:103]
	v_mfma_f32_16x16x32_bf16 v[96:99], v[208:211], v[176:179], v[96:99]
	v_mfma_f32_16x16x32_bf16 v[84:87], v[200:203], v[184:187], v[84:87]
	v_mfma_f32_16x16x32_bf16 v[80:83], v[208:211], v[184:187], v[80:83]
	v_mfma_f32_16x16x32_bf16 v[68:71], v[200:203], v[192:195], v[68:71]
	v_mfma_f32_16x16x32_bf16 v[64:67], v[208:211], v[192:195], v[64:67]
	v_mfma_f32_16x16x32_bf16 v[116:119], v[204:207], v[172:175], v[116:119]
	s_mov_b32 m0, s29
	s_waitcnt lgkmcnt(0)
	v_mfma_f32_16x16x32_bf16 v[112:115], v[212:215], v[172:175], v[112:115]
	v_lshl_add_u64 v[144:145], v[218:219], 0, s[46:47]
	v_mfma_f32_16x16x32_bf16 v[100:103], v[204:207], v[180:183], v[100:103]
	v_mfma_f32_16x16x32_bf16 v[96:99], v[212:215], v[180:183], v[96:99]
	v_mfma_f32_16x16x32_bf16 v[84:87], v[204:207], v[188:191], v[84:87]
	v_mfma_f32_16x16x32_bf16 v[80:83], v[212:215], v[188:191], v[80:83]
	v_mfma_f32_16x16x32_bf16 v[68:71], v[204:207], v[196:199], v[68:71]
	s_setprio 0
	v_mfma_f32_16x16x32_bf16 v[64:67], v[212:215], v[196:199], v[64:67]
	s_barrier
	ds_read_b128 v[168:171], v150 offset:49152
	ds_read_b128 v[172:175], v150 offset:50176
	ds_read_b128 v[176:179], v150 offset:51200
	ds_read_b128 v[180:183], v150 offset:52224
	ds_read_b128 v[184:187], v150 offset:53248
	ds_read_b128 v[188:191], v150 offset:54272
	ds_read_b128 v[192:195], v150 offset:55296
	ds_read_b128 v[196:199], v150 offset:56320
	global_load_lds_dwordx4 v[144:145], off
	v_lshl_add_u64 v[144:145], v[220:221], 0, s[46:47]
	s_mov_b32 m0, s30
	s_nop 0
	global_load_lds_dwordx4 v[144:145], off
	s_waitcnt vmcnt(10)
	s_setprio 1
	s_barrier
; DI float bflo(unsigned w) { return __uint_as_float(w << 16); }
;     DI void operator()(const f32x4 (&acc)[2][2][4][2], const Unit& u, int wr, int wc, int fr, int fq) const {
;         const int row0 = u.pm * BM + wr * 64 + fr, col0 = u.pn * BM + wc * 32 + 8 * fq;
;         f32x4 sc[2][2];
; #pragma unroll
;         for (int bj = 0; bj < 2; ++bj)
; #pragma unroll
;             for (int n = 0; n < 2; ++n) sc[bj][n] = scale ? *(const f32x4*)(scale + col0 + bj * HALF + 4 * n) : (f32x4){1.f, 1.f, 1.f, 1.f};
; #pragma unroll
;         for (int ai = 0; ai < 2; ++ai)
; #pragma unroll
;             for (int m = 0; m < 4; ++m) { const size_t ro = (size_t)(row0 + ai * HALF + m * 16) * D + col0;
; #pragma unroll
;                 for (int bj = 0; bj < 2; ++bj) {
;                     f32x4 x0, x1;
;                     if constexpr (IB) { const u32x4 w = *(const u32x4*)((const bf16_t*)Xin + ro + bj * HALF);
;                         x0 = (f32x4){bflo(w[0]), bfhi(w[0]), bflo(w[1]), bfhi(w[1])}; x1 = (f32x4){bflo(w[2]), bfhi(w[2]), bflo(w[3]), bfhi(w[3])}; }
;                     else { x0 = *(const f32x4*)((const float*)Xin + ro + bj * HALF); x1 = *(const f32x4*)((const float*)Xin + ro + bj * HALF + 4); }
;                     x0 += acc[ai][bj][m][0] * sc[bj][0]; x1 += acc[ai][bj][m][1] * sc[bj][1];
;                     if constexpr (OB) { u32x4 o; o[0] = pack2(x0[0], x0[1]); o[1] = pack2(x0[2], x0[3]); o[2] = pack2(x1[0], x1[1]); o[3] = pack2(x1[2], x1[3]);
;                         *(u32x4*)((bf16_t*)Xout + ro + bj * HALF) = o; }
; template <class Map, class Epi>
; DI void gemm_phase(LAS unsigned char* lds, const Map& MP, const Epi& E, const int nM, const int nN, const int K, const int lda, const int ldb) {
;     ...
;             PG8_WAIT_L(8); PG8_BAR; PG8_WAIT_L(0); PG8_MMA(0, 0, At, B0); PG8_BAR; PG8_SCHED;
;             PG8_LDB(B1, 1, 1); PG8_STAGE(PG8_SB(1, 0), b3, voffB);
;             PG8_BAR; PG8_WAIT_L(0); PG8_MMA(0, 1, At, B1); PG8_BAR;
;             PG8_LDA(At, 1, 1); PG8_STAGE(PG8_SA(1, 0), a3, voffA);
;             PG8_BAR; PG8_WAIT_L(0); PG8_MMA(1, 0, At, B0); PG8_BAR; PG8_SCHED;
;             PG8_STAGE(PG8_SB(1, 1), b3 + hstepB, voffB);
;             PG8_WAIT_V(6); PG8_BAR; PG8_MMA(1, 1, At, B1); PG8_BAR;
;         }
;         { int frr = fr, fqq = fq; asm volatile("" : "+v"(frr), "+v"(fqq)); E(acc, cur, wr, wc, frr, fqq); }
	s_waitcnt lgkmcnt(7)
	v_mfma_f32_16x16x32_bf16 v[60:63], v[152:155], v[168:171], v[60:63]
	v_mfma_f32_16x16x32_bf16 v[56:59], v[160:163], v[168:171], v[56:59]
	s_waitcnt lgkmcnt(5)
	v_mfma_f32_16x16x32_bf16 v[44:47], v[152:155], v[176:179], v[44:47]
	v_mfma_f32_16x16x32_bf16 v[40:43], v[160:163], v[176:179], v[40:43]
	s_waitcnt lgkmcnt(3)
	v_mfma_f32_16x16x32_bf16 v[28:31], v[152:155], v[184:187], v[28:31]
	v_mfma_f32_16x16x32_bf16 v[24:27], v[160:163], v[184:187], v[24:27]
	s_waitcnt lgkmcnt(1)
	v_mfma_f32_16x16x32_bf16 v[12:15], v[152:155], v[192:195], v[12:15]
	v_mfma_f32_16x16x32_bf16 v[8:11], v[160:163], v[192:195], v[8:11]
	v_mfma_f32_16x16x32_bf16 v[60:63], v[156:159], v[172:175], v[60:63]
	s_add_u32 s8, s12, 0x160080
	s_addc_u32 s9, s13, 0
	v_mfma_f32_16x16x32_bf16 v[56:59], v[164:167], v[172:175], v[56:59]
	s_add_i32 s12, s14, s20
	v_mfma_f32_16x16x32_bf16 v[44:47], v[156:159], v[180:183], v[44:47]
	v_mfma_f32_16x16x32_bf16 v[40:43], v[164:167], v[180:183], v[40:43]
	v_mfma_f32_16x16x32_bf16 v[28:31], v[156:159], v[188:191], v[28:31]
	v_mfma_f32_16x16x32_bf16 v[24:27], v[164:167], v[188:191], v[24:27]
	s_waitcnt lgkmcnt(0)
	v_mfma_f32_16x16x32_bf16 v[12:15], v[156:159], v[196:199], v[12:15]
	s_setprio 0
	v_mfma_f32_16x16x32_bf16 v[8:11], v[164:167], v[196:199], v[8:11]
	s_barrier
	s_mov_b32 m0, s12
	s_nop 0
	global_load_lds_dwordx4 v132, s[8:9]
	s_add_i32 m0, s12, 0x2000
	s_nop 0
	global_load_lds_dwordx4 v128, s[8:9]
	s_waitcnt vmcnt(6)
	s_setprio 1
	s_barrier
	v_mfma_f32_16x16x32_bf16 v[52:55], v[200:203], v[168:171], v[52:55]
	v_mfma_f32_16x16x32_bf16 v[48:51], v[208:211], v[168:171], v[48:51]
	ds_read_b128 v[152:155], v149
	v_mfma_f32_16x16x32_bf16 v[36:39], v[200:203], v[176:179], v[36:39]
	v_mfma_f32_16x16x32_bf16 v[32:35], v[208:211], v[176:179], v[32:35]
	ds_read_b128 v[156:159], v149 offset:1024
	v_mfma_f32_16x16x32_bf16 v[20:23], v[200:203], v[184:187], v[20:23]
	v_mfma_f32_16x16x32_bf16 v[16:19], v[208:211], v[184:187], v[16:19]
	ds_read_b128 v[160:163], v149 offset:2048
	v_mfma_f32_16x16x32_bf16 v[4:7], v[200:203], v[192:195], v[4:7]
	v_mfma_f32_16x16x32_bf16 v[0:3], v[208:211], v[192:195], v[0:3]
	ds_read_b128 v[164:167], v149 offset:3072
	v_mfma_f32_16x16x32_bf16 v[52:55], v[204:207], v[172:175], v[52:55]
	s_add_i32 s48, s48, 2
	v_mfma_f32_16x16x32_bf16 v[48:51], v[212:215], v[172:175], v[48:51]
	s_add_u32 s38, s38, 0x100
	s_addc_u32 s39, s39, 0
	v_mfma_f32_16x16x32_bf16 v[36:39], v[204:207], v[180:183], v[36:39]
	s_cmpk_gt_u32 s48, 0x55
	v_mfma_f32_16x16x32_bf16 v[32:35], v[212:215], v[180:183], v[32:35]
	s_mov_b64 s[8:9], s[10:11]
	v_mfma_f32_16x16x32_bf16 v[20:23], v[204:207], v[188:191], v[20:23]
	v_mfma_f32_16x16x32_bf16 v[16:19], v[212:215], v[188:191], v[16:19]
	v_mfma_f32_16x16x32_bf16 v[4:7], v[204:207], v[196:199], v[4:7]
	s_setprio 0
	v_mfma_f32_16x16x32_bf16 v[0:3], v[212:215], v[196:199], v[0:3]
	s_barrier
	s_cbranch_scc0 .LBB1_2653
	s_waitcnt lgkmcnt(0)
	v_mov_b32_e32 v144, v147
	v_mov_b32_e32 v152, v146
	s_lshl_b32 s2, s2, 8
	s_lshl_b32 s8, s37, 8
	s_add_i32 s2, s2, s27
	s_or_b32 s8, s8, s28
	v_add_u32_e32 v152, s2, v152
	v_lshl_add_u32 v144, v144, 3, s8
	v_ashrrev_i32_e32 v153, 31, v152
	v_ashrrev_i32_e32 v145, 31, v144
	v_lshlrev_b64 v[152:153], 11, v[152:153]
	v_lshl_add_u64 v[144:145], v[152:153], 0, v[144:145]
	v_lshl_add_u64 v[156:157], v[144:145], 1, s[6:7]
	global_load_dwordx4 v[162:165], v[156:157], off
	global_load_dwordx4 v[166:169], v[156:157], off offset:256
	s_mov_b64 s[98:99], 0x10000
	v_lshl_add_u64 v[154:155], v[156:157], 0, s[98:99]
	global_load_dwordx4 v[170:173], v[154:155], off
	global_load_dwordx4 v[174:177], v[154:155], off offset:256
	s_mov_b64 s[98:99], 0x20000
	v_lshl_add_u64 v[154:155], v[156:157], 0, s[98:99]
	global_load_dwordx4 v[178:181], v[154:155], off
	global_load_dwordx4 v[182:185], v[154:155], off offset:256
	s_mov_b64 s[98:99], 0x30000
	v_lshl_add_u64 v[154:155], v[156:157], 0, s[98:99]
	global_load_dwordx4 v[186:189], v[154:155], off
	global_load_dwordx4 v[190:193], v[154:155], off offset:256
	s_mov_b64 s[98:99], 0x80000
	v_lshl_add_u64 v[154:155], v[156:157], 0, s[98:99]
	global_load_dwordx4 v[194:197], v[154:155], off
	global_load_dwordx4 v[198:201], v[154:155], off offset:256
	s_mov_b64 s[98:99], 0x90000
	v_lshl_add_u64 v[154:155], v[156:157], 0, s[98:99]
	global_load_dwordx4 v[202:205], v[154:155], off
	global_load_dwordx4 v[206:209], v[154:155], off offset:256
	s_mov_b64 s[98:99], 0xa0000
	v_lshl_add_u64 v[154:155], v[156:157], 0, s[98:99]
	global_load_dwordx4 v[210:213], v[154:155], off
	global_load_dwordx4 v[248:251], v[154:155], off offset:256
	s_mov_b64 s[98:99], 0xb0000
	v_lshl_add_u64 v[154:155], v[156:157], 0, s[98:99]
	global_load_dwordx4 v[252:255], v[154:155], off
	s_waitcnt vmcnt(14)
	s_nop 1
	v_mov_b32_e32 v152, v162
	v_mov_b32_e32 v153, v163
	v_mov_b32_e32 v154, v164
	v_mov_b32_e32 v155, v165
	s_mov_b64 s[8:9], 0x8000
	s_and_b64 vcc, exec, s[40:41]
	s_mov_b32 s37, s35
	s_mov_b32 s2, s36
	s_mov_b64 s[10:11], s[44:45]
	s_waitcnt lgkmcnt(0)
	v_lshlrev_b32_e32 v158, 16, v152
	v_and_b32_e32 v159, 0xffff0000, v152
	v_lshlrev_b32_e32 v152, 16, v153
	v_and_b32_e32 v153, 0xffff0000, v153
	v_lshlrev_b32_e32 v160, 16, v154
	v_and_b32_e32 v161, 0xffff0000, v154
	v_lshlrev_b32_e32 v154, 16, v155
	v_and_b32_e32 v155, 0xffff0000, v155
	v_pk_add_f32 v[126:127], v[126:127], v[152:153]
	v_pk_add_f32 v[124:125], v[124:125], v[158:159]
	v_lshl_add_u64 v[152:153], v[144:145], 2, s[4:5]
	v_pk_add_f32 v[122:123], v[122:123], v[154:155]
	v_pk_add_f32 v[120:121], v[120:121], v[160:161]
	global_store_dwordx4 v[152:153], v[124:127], off
	global_store_dwordx4 v[152:153], v[120:123], off offset:16
	s_waitcnt vmcnt(15)
; DI unsigned pack2(float a, float b) { f32x2 v = {a, b}; hwbf16x2 r = __builtin_convertvector(v, hwbf16x2); return __builtin_bit_cast(unsigned, r); }
; DI float bflo(unsigned w) { return __uint_as_float(w << 16); }
; DI float bfhi(unsigned w) { return __uint_as_float(w & 0xffff0000u); }
;     DI void operator()(const f32x4 (&acc)[2][2][4][2], const Unit& u, int wr, int wc, int fr, int fq) const {
;     ...
;         for (int ai = 0; ai < 2; ++ai)
; #pragma unroll
;             for (int m = 0; m < 4; ++m) { const size_t ro = (size_t)(row0 + ai * HALF + m * 16) * D + col0;
; #pragma unroll
;                 for (int bj = 0; bj < 2; ++bj) {
;                     f32x4 x0, x1;
;                     if constexpr (IB) { const u32x4 w = *(const u32x4*)((const bf16_t*)Xin + ro + bj * HALF);
;                         x0 = (f32x4){bflo(w[0]), bfhi(w[0]), bflo(w[1]), bfhi(w[1])}; x1 = (f32x4){bflo(w[2]), bfhi(w[2]), bflo(w[3]), bfhi(w[3])}; }
;                     else { x0 = *(const f32x4*)((const float*)Xin + ro + bj * HALF); x1 = *(const f32x4*)((const float*)Xin + ro + bj * HALF + 4); }
;                     x0 += acc[ai][bj][m][0] * sc[bj][0]; x1 += acc[ai][bj][m][1] * sc[bj][1];
;                     if constexpr (OB) { u32x4 o; o[0] = pack2(x0[0], x0[1]); o[1] = pack2(x0[2], x0[3]); o[2] = pack2(x1[0], x1[1]); o[3] = pack2(x1[2], x1[3]);
;                         *(u32x4*)((bf16_t*)Xout + ro + bj * HALF) = o; }
;                     else { *(f32x4*)((float*)Xout + ro + bj * HALF) = x0; *(f32x4*)((float*)Xout + ro + bj * HALF + 4) = x1; } } }
	s_nop 1
	v_mov_b32_e32 v120, v166
	v_mov_b32_e32 v121, v167
	v_mov_b32_e32 v122, v168
	v_mov_b32_e32 v123, v169
	s_waitcnt lgkmcnt(0)
	v_lshlrev_b32_e32 v124, 16, v120
	v_and_b32_e32 v125, 0xffff0000, v120
	v_lshlrev_b32_e32 v120, 16, v121
	v_and_b32_e32 v121, 0xffff0000, v121
	v_lshlrev_b32_e32 v126, 16, v122
	v_and_b32_e32 v127, 0xffff0000, v122
	v_lshlrev_b32_e32 v122, 16, v123
	v_and_b32_e32 v123, 0xffff0000, v123
	v_pk_add_f32 v[118:119], v[118:119], v[120:121]
	v_pk_add_f32 v[116:117], v[116:117], v[124:125]
	v_pk_add_f32 v[114:115], v[114:115], v[122:123]
	v_pk_add_f32 v[112:113], v[112:113], v[126:127]
	global_store_dwordx4 v[152:153], v[116:119], off offset:512
	global_store_dwordx4 v[152:153], v[112:115], off offset:528
	s_nop 0
	v_lshl_add_u64 v[116:117], v[144:145], 0, s[8:9]
	v_lshl_add_u64 v[118:119], v[116:117], 1, s[6:7]
	s_waitcnt vmcnt(16)
	s_nop 1
	v_mov_b32_e32 v112, v170
	v_mov_b32_e32 v113, v171
	v_mov_b32_e32 v114, v172
	v_mov_b32_e32 v115, v173
	s_mov_b64 s[8:9], 0x10000
	s_waitcnt lgkmcnt(0)
	v_lshlrev_b32_e32 v120, 16, v112
	v_and_b32_e32 v121, 0xffff0000, v112
	v_lshlrev_b32_e32 v112, 16, v113
	v_and_b32_e32 v113, 0xffff0000, v113
	v_lshlrev_b32_e32 v122, 16, v114
	v_and_b32_e32 v123, 0xffff0000, v114
	v_lshlrev_b32_e32 v114, 16, v115
	v_and_b32_e32 v115, 0xffff0000, v115
	v_pk_add_f32 v[110:111], v[110:111], v[112:113]
	v_pk_add_f32 v[108:109], v[108:109], v[120:121]
	v_lshl_add_u64 v[112:113], v[116:117], 2, s[4:5]
	v_pk_add_f32 v[106:107], v[106:107], v[114:115]
	v_pk_add_f32 v[104:105], v[104:105], v[122:123]
	global_store_dwordx4 v[112:113], v[108:111], off
	global_store_dwordx4 v[112:113], v[104:107], off offset:16
	s_waitcnt vmcnt(17)
	s_nop 1
	v_mov_b32_e32 v104, v174
	v_mov_b32_e32 v105, v175
	v_mov_b32_e32 v106, v176
	v_mov_b32_e32 v107, v177
	s_waitcnt lgkmcnt(0)
	v_lshlrev_b32_e32 v108, 16, v104
	v_and_b32_e32 v109, 0xffff0000, v104
	v_lshlrev_b32_e32 v104, 16, v105
	v_and_b32_e32 v105, 0xffff0000, v105
	v_lshlrev_b32_e32 v110, 16, v106
	v_and_b32_e32 v111, 0xffff0000, v106
	v_lshlrev_b32_e32 v106, 16, v107
	v_and_b32_e32 v107, 0xffff0000, v107
	v_pk_add_f32 v[102:103], v[102:103], v[104:105]
	v_pk_add_f32 v[100:101], v[100:101], v[108:109]
	v_pk_add_f32 v[98:99], v[98:99], v[106:107]
	v_pk_add_f32 v[96:97], v[96:97], v[110:111]
	global_store_dwordx4 v[112:113], v[100:103], off offset:512
	global_store_dwordx4 v[112:113], v[96:99], off offset:528
	s_nop 0
	v_lshl_add_u64 v[100:101], v[144:145], 0, s[8:9]
	v_lshl_add_u64 v[102:103], v[100:101], 1, s[6:7]
	s_waitcnt vmcnt(18)
	s_nop 1
	v_mov_b32_e32 v96, v178
	v_mov_b32_e32 v97, v179
	v_mov_b32_e32 v98, v180
	v_mov_b32_e32 v99, v181
	s_mov_b64 s[8:9], 0x18000
	s_waitcnt lgkmcnt(0)
	v_lshlrev_b32_e32 v104, 16, v96
	v_and_b32_e32 v105, 0xffff0000, v96
	v_lshlrev_b32_e32 v96, 16, v97
	v_and_b32_e32 v97, 0xffff0000, v97
	v_lshlrev_b32_e32 v106, 16, v98
	v_and_b32_e32 v107, 0xffff0000, v98
	v_lshlrev_b32_e32 v98, 16, v99
	v_and_b32_e32 v99, 0xffff0000, v99
	v_pk_add_f32 v[94:95], v[94:95], v[96:97]
	v_pk_add_f32 v[92:93], v[92:93], v[104:105]
	v_lshl_add_u64 v[96:97], v[100:101], 2, s[4:5]
	v_pk_add_f32 v[90:91], v[90:91], v[98:99]
	v_pk_add_f32 v[88:89], v[88:89], v[106:107]
	global_store_dwordx4 v[96:97], v[92:95], off
	global_store_dwordx4 v[96:97], v[88:91], off offset:16
	s_waitcnt vmcnt(19)
	s_nop 1
	v_mov_b32_e32 v88, v182
	v_mov_b32_e32 v89, v183
	v_mov_b32_e32 v90, v184
	v_mov_b32_e32 v91, v185
	s_waitcnt lgkmcnt(0)
	v_lshlrev_b32_e32 v92, 16, v88
	v_and_b32_e32 v93, 0xffff0000, v88
	v_lshlrev_b32_e32 v88, 16, v89
	v_and_b32_e32 v89, 0xffff0000, v89
	v_lshlrev_b32_e32 v94, 16, v90
	v_and_b32_e32 v95, 0xffff0000, v90
	v_lshlrev_b32_e32 v90, 16, v91
	v_and_b32_e32 v91, 0xffff0000, v91
	v_pk_add_f32 v[86:87], v[86:87], v[88:89]
	v_pk_add_f32 v[84:85], v[84:85], v[92:93]
	v_pk_add_f32 v[82:83], v[82:83], v[90:91]
	v_pk_add_f32 v[80:81], v[80:81], v[94:95]
	global_store_dwordx4 v[96:97], v[84:87], off offset:512
	global_store_dwordx4 v[96:97], v[80:83], off offset:528
	s_nop 0
	v_lshl_add_u64 v[84:85], v[144:145], 0, s[8:9]
	v_lshl_add_u64 v[86:87], v[84:85], 1, s[6:7]
	s_waitcnt vmcnt(20)
	s_nop 1
	v_mov_b32_e32 v80, v186
	v_mov_b32_e32 v81, v187
	v_mov_b32_e32 v82, v188
	v_mov_b32_e32 v83, v189
	s_mov_b64 s[8:9], 0x40000
	s_waitcnt lgkmcnt(0)
	v_lshlrev_b32_e32 v88, 16, v80
	v_and_b32_e32 v89, 0xffff0000, v80
	v_lshlrev_b32_e32 v80, 16, v81
	v_and_b32_e32 v81, 0xffff0000, v81
	v_lshlrev_b32_e32 v90, 16, v82
	v_and_b32_e32 v91, 0xffff0000, v82
	v_lshlrev_b32_e32 v82, 16, v83
	v_and_b32_e32 v83, 0xffff0000, v83
	v_pk_add_f32 v[78:79], v[78:79], v[80:81]
	v_pk_add_f32 v[76:77], v[76:77], v[88:89]
	v_lshl_add_u64 v[80:81], v[84:85], 2, s[4:5]
	v_pk_add_f32 v[74:75], v[74:75], v[82:83]
	v_pk_add_f32 v[72:73], v[72:73], v[90:91]
	global_store_dwordx4 v[80:81], v[76:79], off
	global_store_dwordx4 v[80:81], v[72:75], off offset:16
	s_waitcnt vmcnt(21)
	s_nop 1
	v_mov_b32_e32 v72, v190
	v_mov_b32_e32 v73, v191
	v_mov_b32_e32 v74, v192
	v_mov_b32_e32 v75, v193
	s_waitcnt lgkmcnt(0)
	v_lshlrev_b32_e32 v76, 16, v72
	v_and_b32_e32 v77, 0xffff0000, v72
	v_lshlrev_b32_e32 v72, 16, v73
	v_and_b32_e32 v73, 0xffff0000, v73
	v_lshlrev_b32_e32 v78, 16, v74
	v_and_b32_e32 v79, 0xffff0000, v74
	v_lshlrev_b32_e32 v74, 16, v75
	v_and_b32_e32 v75, 0xffff0000, v75
	v_pk_add_f32 v[70:71], v[70:71], v[72:73]
	v_pk_add_f32 v[68:69], v[68:69], v[76:77]
	v_pk_add_f32 v[66:67], v[66:67], v[74:75]
	v_pk_add_f32 v[64:65], v[64:65], v[78:79]
	global_store_dwordx4 v[80:81], v[68:71], off offset:512
	global_store_dwordx4 v[80:81], v[64:67], off offset:528
	s_nop 0
	v_lshl_add_u64 v[68:69], v[144:145], 0, s[8:9]
	v_lshl_add_u64 v[70:71], v[68:69], 1, s[6:7]
	s_waitcnt vmcnt(22)
; DI unsigned pack2(float a, float b) { f32x2 v = {a, b}; hwbf16x2 r = __builtin_convertvector(v, hwbf16x2); return __builtin_bit_cast(unsigned, r); }
; DI float bflo(unsigned w) { return __uint_as_float(w << 16); }
; DI float bfhi(unsigned w) { return __uint_as_float(w & 0xffff0000u); }
;     DI const char* a(const Unit& u) const { return (const char*)(A + (size_t)u.pm * BM * lda); }
;     DI const char* a(const Unit& u) const { return (const char*)(A + (size_t)u.pm * BM * 2048 + (u.pn >> 1) * 512); }
;     DI void operator()(const f32x4 (&acc)[2][2][4][2], const Unit& u, int wr, int wc, int fr, int fq) const {
;     ...
;         for (int ai = 0; ai < 2; ++ai)
; #pragma unroll
;             for (int m = 0; m < 4; ++m) { const size_t ro = (size_t)(row0 + ai * HALF + m * 16) * D + col0;
; #pragma unroll
;                 for (int bj = 0; bj < 2; ++bj) {
;                     f32x4 x0, x1;
;                     if constexpr (IB) { const u32x4 w = *(const u32x4*)((const bf16_t*)Xin + ro + bj * HALF);
;                         x0 = (f32x4){bflo(w[0]), bfhi(w[0]), bflo(w[1]), bfhi(w[1])}; x1 = (f32x4){bflo(w[2]), bfhi(w[2]), bflo(w[3]), bfhi(w[3])}; }
;                     else { x0 = *(const f32x4*)((const float*)Xin + ro + bj * HALF); x1 = *(const f32x4*)((const float*)Xin + ro + bj * HALF + 4); }
;                     x0 += acc[ai][bj][m][0] * sc[bj][0]; x1 += acc[ai][bj][m][1] * sc[bj][1];
;                     if constexpr (OB) { u32x4 o; o[0] = pack2(x0[0], x0[1]); o[1] = pack2(x0[2], x0[3]); o[2] = pack2(x1[0], x1[1]); o[3] = pack2(x1[2], x1[3]);
;                         *(u32x4*)((bf16_t*)Xout + ro + bj * HALF) = o; }
;                     else { *(f32x4*)((float*)Xout + ro + bj * HALF) = x0; *(f32x4*)((float*)Xout + ro + bj * HALF + 4) = x1; } } }
; template <class Map, class Epi>
; DI void gemm_phase(LAS unsigned char* lds, const Map& MP, const Epi& E, const int nM, const int nN, const int K, const int lda, const int ldb) {
;     ...
;         if (!has_next) break;
; #pragma unroll
;         for (int a = 0; a < 2; ++a)
; #pragma unroll
;             for (int b = 0; b < 2; ++b)
; #pragma unroll
;                 for (int m = 0; m < 4; ++m)
; #pragma unroll
;                     for (int n = 0; n < 2; ++n) acc[a][b][m][n] = (f32x4){0.f, 0.f, 0.f, 0.f};
;         cur = nxt; cA = nA; cB = nB; ++ui;
;     }
;     PG8_WAIT_V(0);
;     if (wr == 0) PG8_BAR;
;     PG8_BAR;
	s_nop 1
	v_mov_b32_e32 v64, v194
	v_mov_b32_e32 v65, v195
	v_mov_b32_e32 v66, v196
	v_mov_b32_e32 v67, v197
	s_mov_b64 s[8:9], 0x48000
	s_waitcnt lgkmcnt(0)
	v_lshlrev_b32_e32 v72, 16, v64
	v_and_b32_e32 v73, 0xffff0000, v64
	v_lshlrev_b32_e32 v64, 16, v65
	v_and_b32_e32 v65, 0xffff0000, v65
	v_lshlrev_b32_e32 v74, 16, v66
	v_and_b32_e32 v75, 0xffff0000, v66
	v_lshlrev_b32_e32 v66, 16, v67
	v_and_b32_e32 v67, 0xffff0000, v67
	v_pk_add_f32 v[62:63], v[62:63], v[64:65]
	v_pk_add_f32 v[60:61], v[60:61], v[72:73]
	v_lshl_add_u64 v[64:65], v[68:69], 2, s[4:5]
	v_pk_add_f32 v[58:59], v[58:59], v[66:67]
	v_pk_add_f32 v[56:57], v[56:57], v[74:75]
	global_store_dwordx4 v[64:65], v[60:63], off
	global_store_dwordx4 v[64:65], v[56:59], off offset:16
	s_waitcnt vmcnt(23)
	s_nop 1
	v_mov_b32_e32 v56, v198
	v_mov_b32_e32 v57, v199
	v_mov_b32_e32 v58, v200
	v_mov_b32_e32 v59, v201
	s_waitcnt lgkmcnt(0)
	v_lshlrev_b32_e32 v60, 16, v56
	v_and_b32_e32 v61, 0xffff0000, v56
	v_lshlrev_b32_e32 v56, 16, v57
	v_and_b32_e32 v57, 0xffff0000, v57
	v_lshlrev_b32_e32 v62, 16, v58
	v_and_b32_e32 v63, 0xffff0000, v58
	v_lshlrev_b32_e32 v58, 16, v59
	v_and_b32_e32 v59, 0xffff0000, v59
	v_pk_add_f32 v[54:55], v[54:55], v[56:57]
	v_pk_add_f32 v[52:53], v[52:53], v[60:61]
	v_pk_add_f32 v[50:51], v[50:51], v[58:59]
	v_pk_add_f32 v[48:49], v[48:49], v[62:63]
	global_store_dwordx4 v[64:65], v[52:55], off offset:512
	global_store_dwordx4 v[64:65], v[48:51], off offset:528
	s_nop 0
	v_lshl_add_u64 v[52:53], v[144:145], 0, s[8:9]
	v_lshl_add_u64 v[54:55], v[52:53], 1, s[6:7]
	s_waitcnt vmcnt(24)
	s_nop 1
	v_mov_b32_e32 v48, v202
	v_mov_b32_e32 v49, v203
	v_mov_b32_e32 v50, v204
	v_mov_b32_e32 v51, v205
	s_mov_b64 s[8:9], 0x50000
	s_waitcnt lgkmcnt(0)
	v_lshlrev_b32_e32 v56, 16, v48
	v_and_b32_e32 v57, 0xffff0000, v48
	v_lshlrev_b32_e32 v48, 16, v49
	v_and_b32_e32 v49, 0xffff0000, v49
	v_lshlrev_b32_e32 v58, 16, v50
	v_and_b32_e32 v59, 0xffff0000, v50
	v_lshlrev_b32_e32 v50, 16, v51
	v_and_b32_e32 v51, 0xffff0000, v51
	v_pk_add_f32 v[46:47], v[46:47], v[48:49]
	v_pk_add_f32 v[44:45], v[44:45], v[56:57]
	v_lshl_add_u64 v[48:49], v[52:53], 2, s[4:5]
	v_pk_add_f32 v[42:43], v[42:43], v[50:51]
	v_pk_add_f32 v[40:41], v[40:41], v[58:59]
	global_store_dwordx4 v[48:49], v[44:47], off
	global_store_dwordx4 v[48:49], v[40:43], off offset:16
	s_waitcnt vmcnt(25)
	s_nop 1
	v_mov_b32_e32 v40, v206
	v_mov_b32_e32 v41, v207
	v_mov_b32_e32 v42, v208
	v_mov_b32_e32 v43, v209
	s_waitcnt lgkmcnt(0)
	v_lshlrev_b32_e32 v44, 16, v40
	v_and_b32_e32 v45, 0xffff0000, v40
	v_lshlrev_b32_e32 v40, 16, v41
	v_and_b32_e32 v41, 0xffff0000, v41
	v_lshlrev_b32_e32 v46, 16, v42
	v_and_b32_e32 v47, 0xffff0000, v42
	v_lshlrev_b32_e32 v42, 16, v43
	v_and_b32_e32 v43, 0xffff0000, v43
	v_pk_add_f32 v[38:39], v[38:39], v[40:41]
	v_pk_add_f32 v[36:37], v[36:37], v[44:45]
	v_pk_add_f32 v[34:35], v[34:35], v[42:43]
	v_pk_add_f32 v[32:33], v[32:33], v[46:47]
	global_store_dwordx4 v[48:49], v[36:39], off offset:512
	global_store_dwordx4 v[48:49], v[32:35], off offset:528
	s_nop 0
	v_lshl_add_u64 v[36:37], v[144:145], 0, s[8:9]
	v_lshl_add_u64 v[38:39], v[36:37], 1, s[6:7]
	s_waitcnt vmcnt(26)
	s_nop 1
	v_mov_b32_e32 v32, v210
	v_mov_b32_e32 v33, v211
	v_mov_b32_e32 v34, v212
	v_mov_b32_e32 v35, v213
	s_mov_b64 s[8:9], 0x58000
	s_waitcnt lgkmcnt(0)
	v_lshlrev_b32_e32 v40, 16, v32
	v_and_b32_e32 v41, 0xffff0000, v32
	v_lshlrev_b32_e32 v32, 16, v33
	v_and_b32_e32 v33, 0xffff0000, v33
	v_lshlrev_b32_e32 v42, 16, v34
	v_and_b32_e32 v43, 0xffff0000, v34
	v_lshlrev_b32_e32 v34, 16, v35
	v_and_b32_e32 v35, 0xffff0000, v35
	v_pk_add_f32 v[30:31], v[30:31], v[32:33]
	v_pk_add_f32 v[28:29], v[28:29], v[40:41]
	v_lshl_add_u64 v[32:33], v[36:37], 2, s[4:5]
	v_pk_add_f32 v[26:27], v[26:27], v[34:35]
	v_pk_add_f32 v[24:25], v[24:25], v[42:43]
	global_store_dwordx4 v[32:33], v[28:31], off
	global_store_dwordx4 v[32:33], v[24:27], off offset:16
	s_waitcnt vmcnt(27)
	s_nop 1
	v_mov_b32_e32 v24, v248
	v_mov_b32_e32 v25, v249
	v_mov_b32_e32 v26, v250
	v_mov_b32_e32 v27, v251
	s_waitcnt lgkmcnt(0)
	v_lshlrev_b32_e32 v28, 16, v24
	v_and_b32_e32 v29, 0xffff0000, v24
	v_lshlrev_b32_e32 v24, 16, v25
	v_and_b32_e32 v25, 0xffff0000, v25
	v_lshlrev_b32_e32 v30, 16, v26
	v_and_b32_e32 v31, 0xffff0000, v26
	v_lshlrev_b32_e32 v26, 16, v27
	v_and_b32_e32 v27, 0xffff0000, v27
	v_pk_add_f32 v[22:23], v[22:23], v[24:25]
	v_pk_add_f32 v[20:21], v[20:21], v[28:29]
	v_pk_add_f32 v[18:19], v[18:19], v[26:27]
	v_pk_add_f32 v[16:17], v[16:17], v[30:31]
	global_store_dwordx4 v[32:33], v[20:23], off offset:512
	global_store_dwordx4 v[32:33], v[16:19], off offset:528
	s_nop 0
	v_lshl_add_u64 v[20:21], v[144:145], 0, s[8:9]
	v_lshl_add_u64 v[22:23], v[20:21], 1, s[6:7]
	s_waitcnt vmcnt(28)
	s_nop 1
	v_mov_b32_e32 v16, v252
	v_mov_b32_e32 v17, v253
	v_mov_b32_e32 v18, v254
	v_mov_b32_e32 v19, v255
	s_mov_b64 s[8:9], s[42:43]
	s_waitcnt lgkmcnt(0)
	v_lshlrev_b32_e32 v24, 16, v16
	v_and_b32_e32 v25, 0xffff0000, v16
	v_lshlrev_b32_e32 v16, 16, v17
	v_and_b32_e32 v17, 0xffff0000, v17
	v_lshlrev_b32_e32 v26, 16, v18
	v_and_b32_e32 v27, 0xffff0000, v18
	v_lshlrev_b32_e32 v18, 16, v19
	v_and_b32_e32 v19, 0xffff0000, v19
	v_pk_add_f32 v[14:15], v[14:15], v[16:17]
	v_pk_add_f32 v[12:13], v[12:13], v[24:25]
	v_lshl_add_u64 v[16:17], v[20:21], 2, s[4:5]
	v_pk_add_f32 v[10:11], v[10:11], v[18:19]
	v_pk_add_f32 v[8:9], v[8:9], v[26:27]
	global_store_dwordx4 v[16:17], v[12:15], off
	global_store_dwordx4 v[16:17], v[8:11], off offset:16
	global_load_dwordx4 v[8:11], v[22:23], off offset:256
	s_waitcnt vmcnt(0) lgkmcnt(0)
	v_lshlrev_b32_e32 v12, 16, v8
	v_and_b32_e32 v13, 0xffff0000, v8
	v_lshlrev_b32_e32 v8, 16, v9
	v_and_b32_e32 v9, 0xffff0000, v9
	v_lshlrev_b32_e32 v14, 16, v10
	v_and_b32_e32 v15, 0xffff0000, v10
	v_lshlrev_b32_e32 v10, 16, v11
	v_and_b32_e32 v11, 0xffff0000, v11
	v_pk_add_f32 v[6:7], v[6:7], v[8:9]
	v_pk_add_f32 v[4:5], v[4:5], v[12:13]
	v_pk_add_f32 v[2:3], v[2:3], v[10:11]
	v_pk_add_f32 v[0:1], v[0:1], v[14:15]
	global_store_dwordx4 v[16:17], v[4:7], off offset:512
	global_store_dwordx4 v[16:17], v[0:3], off offset:528
	s_cbranch_vccz .LBB1_2646
	s_waitcnt vmcnt(0)
	s_cmpk_gt_u32 s3, 0xff
	s_cbranch_scc1 .LBB1_2657
	s_barrier
